# GEMM K-loops: first iteration of each unit peeled, its first MFMA per accumulator takes C=0, the 128 accumulator-clearing moves per unit removed
# speedup vs baseline: 1.0037x; 1.0037x over previous
;     __host__ __device__ bool next(int i, Unit& u) const { const bool ok = StaticOrder::next(i, u); u.pm = 0; u.pn = 0; return ok; }
; #define PG8_STAGE(bufoff, gbase, voff) do { _Pragma("unroll") for (int _i = 0; _i < 2; ++_i) \
;         __builtin_amdgcn_global_load_lds((const unsigned*)((const char*)(gbase) + (voff)[_i]), (PG8_LAS unsigned*)(lds + (bufoff) + ldsw + _i * 8192), 16, 0, 0); } while (0)
; #define PG8_LDA(dst, b, h) do { _Pragma("unroll") for (int m = 0; m < 4; ++m) _Pragma("unroll") for (int k = 0; k < 2; ++k) dst[m][k] = *(const PG8_LAS bf16x8*)(lds + PG8_SA(b, h) + aoff + m * 2048 + k * 1024); } while (0)
; #define PG8_WAIT_V(n) asm volatile("s_waitcnt vmcnt(" #n ")" ::: "memory")
; #define PG8_BAR __builtin_amdgcn_s_barrier()
; template <class Epi, class Sched, bool ALIGN_EPI = false, bool SP2 = false>
; __device__ __forceinline__ void gemm_phase(PG8_LAS unsigned char* lds, const Gemm g, const Sched& S, const Epi& E, const int wave_in) {
;     ...
;     for (;;) {
;         const bool has_next = S.next(ui + 1, nxt);
;         const char* nA = has_next ? (const char*)g.A + (size_t)nxt.pm * tstepA : cA; const char* nB = has_next ? (const char*)g.Bt + (size_t)nxt.pn * tstepB : cB;
;         for (int t = 0; t < nt; t += 2) {
;             const bool last = (t == nt - 2);
;             const char* a1 = cA + (size_t)(t + 1) * kstep;
;             const char* a2 = last ? nA : cA + (size_t)(t + 2) * kstep; const char* b2 = last ? nB : cB + (size_t)(t + 2) * kstep;
;             const char* a3 = a2 + kstep; const char* b3 = b2 + kstep;
;             if (last && has_next) S.a_ready(nxt);
;             if constexpr (SP2) {
;             PG8_LDB(B0, 0, 0); PG8_LDB(B1, 0, 1); PG8_SCHED; PG8_LDA(At, 0, 0); PG8_STAGE(PG8_SA(1, 1), a1 + hstepA, voffA);
;             PG8_WAIT_V(8); PG8_WAIT_L(0); PG8_BAR; PG8_MMA(0, 0, At, B0); PG8_MMA(0, 1, At, B1); PG8_BAR; PG8_SCHED;
;             PG8_LDA(At, 0, 1); PG8_STAGE(PG8_SB(0, 0), b2, voffB); PG8_STAGE(PG8_SB(0, 1), b2 + hstepB, voffB); PG8_STAGE(PG8_SA(0, 0), a2, voffA);
;     ...
; #pragma unroll
;         for (int a = 0; a < 2; ++a)
; #pragma unroll
;             for (int b = 0; b < 2; ++b)
; #pragma unroll
;                 for (int m = 0; m < 4; ++m)
; #pragma unroll
;                     for (int n = 0; n < 2; ++n) acc[a][b][m][n] = (f32x4){0.f, 0.f, 0.f, 0.f};
;         cur = nxt; cA = nA; cB = nB; ++ui;
.LBB0_157:
	s_ashr_i32 s15, s14, 31
	s_lshl_b64 s[16:17], s[14:15], 20
	s_add_u32 s16, s28, s16
	s_addc_u32 s17, s29, s17
	s_and_b64 s[18:19], s[2:3], exec
	s_cselect_b32 s5, s17, s23
	s_cselect_b32 s15, s16, s22
	s_ashr_i32 s13, s12, 31
	s_lshl_b64 s[18:19], s[12:13], 20
	s_add_u32 s18, s30, s18
	s_addc_u32 s19, s31, s19
	s_and_b64 s[26:27], s[2:3], exec
	s_cselect_b32 s13, s19, s25
	s_cselect_b32 s46, s18, s24
	s_add_u32 s22, s22, 0x80080
	s_addc_u32 s23, s23, 0
	s_add_u32 s47, s24, 0x100
	v_mov_b32_e32 v0, 0
	s_addc_u32 s48, s25, 0
	s_mov_b32 s49, -2
	ds_read_b128 v[144:147], v151
	ds_read_b128 v[154:157], v151 offset:1024
	ds_read_b128 v[158:161], v151 offset:2048
	ds_read_b128 v[162:165], v151 offset:3072
	ds_read_b128 v[166:169], v152
	ds_read_b128 v[170:173], v152 offset:1024
	ds_read_b128 v[174:177], v152 offset:2048
	ds_read_b128 v[178:181], v152 offset:3072
	s_add_u32 s24, s22, 0xfff80080
	s_addc_u32 s25, s23, -1
	s_cmp_eq_u32 s49, 28
	s_cselect_b32 s27, s5, s25
	s_cselect_b32 s26, s15, s24
	s_cselect_b32 s25, s13, s48
	s_cselect_b32 s24, s46, s47
	v_lshl_add_u64 v[214:215], s[22:23], 0, v[136:137]
	s_add_i32 m0, s21, 0xc000
	ds_read_b128 v[182:185], v153
	ds_read_b128 v[186:189], v153 offset:1024
	ds_read_b128 v[190:193], v153 offset:2048
	ds_read_b128 v[194:197], v153 offset:3072
	ds_read_b128 v[198:201], v153 offset:4096
	ds_read_b128 v[202:205], v153 offset:5120
	ds_read_b128 v[206:209], v153 offset:6144
	ds_read_b128 v[210:213], v153 offset:7168
	global_load_lds_dwordx4 v[214:215], off
	v_lshl_add_u64 v[214:215], s[22:23], 0, v[138:139]
	s_add_i32 m0, s21, 0xe000
	s_nop 0
	global_load_lds_dwordx4 v[214:215], off
	s_waitcnt vmcnt(8)
	s_waitcnt lgkmcnt(0)
	s_barrier
	s_setprio 1
	s_waitcnt lgkmcnt(0)
	v_mfma_f32_16x16x32_bf16 v[124:127], v[144:147], v[182:185], 0
	v_mfma_f32_16x16x32_bf16 v[120:123], v[158:161], v[182:185], 0
	v_mfma_f32_16x16x32_bf16 v[108:111], v[144:147], v[190:193], 0
	v_mfma_f32_16x16x32_bf16 v[104:107], v[158:161], v[190:193], 0
	v_mfma_f32_16x16x32_bf16 v[92:95], v[144:147], v[198:201], 0
	v_mfma_f32_16x16x32_bf16 v[88:91], v[158:161], v[198:201], 0
	v_mfma_f32_16x16x32_bf16 v[76:79], v[144:147], v[206:209], 0
	v_mfma_f32_16x16x32_bf16 v[72:75], v[158:161], v[206:209], 0
	v_mfma_f32_16x16x32_bf16 v[124:127], v[154:157], v[186:189], v[124:127]
	v_mfma_f32_16x16x32_bf16 v[120:123], v[162:165], v[186:189], v[120:123]
	v_mfma_f32_16x16x32_bf16 v[108:111], v[154:157], v[194:197], v[108:111]
	v_mfma_f32_16x16x32_bf16 v[104:107], v[162:165], v[194:197], v[104:107]
	v_mfma_f32_16x16x32_bf16 v[92:95], v[154:157], v[202:205], v[92:95]
	v_mfma_f32_16x16x32_bf16 v[88:91], v[162:165], v[202:205], v[88:91]
	v_mfma_f32_16x16x32_bf16 v[76:79], v[154:157], v[210:213], v[76:79]
	v_mfma_f32_16x16x32_bf16 v[72:75], v[162:165], v[210:213], v[72:75]
	s_setprio 0
	s_setprio 1
	v_mfma_f32_16x16x32_bf16 v[116:119], v[166:169], v[182:185], 0
	v_mfma_f32_16x16x32_bf16 v[112:115], v[174:177], v[182:185], 0
	v_mfma_f32_16x16x32_bf16 v[100:103], v[166:169], v[190:193], 0
	v_mfma_f32_16x16x32_bf16 v[96:99], v[174:177], v[190:193], 0
	v_mfma_f32_16x16x32_bf16 v[84:87], v[166:169], v[198:201], 0
	v_mfma_f32_16x16x32_bf16 v[80:83], v[174:177], v[198:201], 0
	v_mfma_f32_16x16x32_bf16 v[68:71], v[166:169], v[206:209], 0
	v_mfma_f32_16x16x32_bf16 v[64:67], v[174:177], v[206:209], 0
	v_mfma_f32_16x16x32_bf16 v[116:119], v[170:173], v[186:189], v[116:119]
	v_mfma_f32_16x16x32_bf16 v[112:115], v[178:181], v[186:189], v[112:115]
	v_mfma_f32_16x16x32_bf16 v[100:103], v[170:173], v[194:197], v[100:103]
	v_mfma_f32_16x16x32_bf16 v[96:99], v[178:181], v[194:197], v[96:99]
	v_mfma_f32_16x16x32_bf16 v[84:87], v[170:173], v[202:205], v[84:87]
	v_mfma_f32_16x16x32_bf16 v[80:83], v[178:181], v[202:205], v[80:83]
	v_mfma_f32_16x16x32_bf16 v[68:71], v[170:173], v[210:213], v[68:71]
	v_mfma_f32_16x16x32_bf16 v[64:67], v[178:181], v[210:213], v[64:67]
	s_setprio 0
	s_barrier
	s_add_i32 s50, s43, s34
	v_lshl_add_u64 v[214:215], s[24:25], 0, v[130:131]
	s_mov_b32 m0, s50
	ds_read_b128 v[182:185], v153 offset:16384
	ds_read_b128 v[186:189], v153 offset:17408
	ds_read_b128 v[190:193], v153 offset:18432
	ds_read_b128 v[194:197], v153 offset:19456
	ds_read_b128 v[198:201], v153 offset:20480
	ds_read_b128 v[202:205], v153 offset:21504
	ds_read_b128 v[206:209], v153 offset:22528
	ds_read_b128 v[210:213], v153 offset:23552
	global_load_lds_dwordx4 v[214:215], off
	s_add_i32 m0, s50, 0x2000
	s_add_u32 s50, s24, 0x80000
	v_lshl_add_u64 v[216:217], s[24:25], 0, v[134:135]
	s_addc_u32 s51, s25, 0
	s_add_i32 s52, s44, s34
	global_load_lds_dwordx4 v[216:217], off
	v_lshl_add_u64 v[218:219], s[50:51], 0, v[130:131]
	s_mov_b32 m0, s52
	v_lshl_add_u64 v[220:221], s[26:27], 0, v[132:133]
	global_load_lds_dwordx4 v[218:219], off
	v_lshl_add_u64 v[218:219], s[50:51], 0, v[134:135]
	s_add_i32 m0, s52, 0x2000
	s_nop 0
	global_load_lds_dwordx4 v[218:219], off
	v_lshl_add_u64 v[218:219], s[26:27], 0, v[128:129]
	s_mov_b32 m0, s21
	s_nop 0
	global_load_lds_dwordx4 v[218:219], off
	s_mov_b32 m0, s35
	s_nop 0
	global_load_lds_dwordx4 v[220:221], off
	s_waitcnt vmcnt(8)
	s_waitcnt lgkmcnt(0)
	s_barrier
; #define PG8_STAGE(bufoff, gbase, voff) do { _Pragma("unroll") for (int _i = 0; _i < 2; ++_i) \
;         __builtin_amdgcn_global_load_lds((const unsigned*)((const char*)(gbase) + (voff)[_i]), (PG8_LAS unsigned*)(lds + (bufoff) + ldsw + _i * 8192), 16, 0, 0); } while (0)
; #define PG8_LDA(dst, b, h) do { _Pragma("unroll") for (int m = 0; m < 4; ++m) _Pragma("unroll") for (int k = 0; k < 2; ++k) dst[m][k] = *(const PG8_LAS bf16x8*)(lds + PG8_SA(b, h) + aoff + m * 2048 + k * 1024); } while (0)
; #define PG8_LDB(dst, b, h) do { _Pragma("unroll") for (int n = 0; n < 2; ++n) _Pragma("unroll") for (int k = 0; k < 2; ++k) dst[n][k] = *(const PG8_LAS bf16x8*)(lds + PG8_SB(b, h) + boff + n * 2048 + k * 1024); } while (0)
; #define PG8_MMA(ai, bj, At, Bt) do { __builtin_amdgcn_s_setprio(1); _Pragma("unroll") for (int m = 0; m < 4; ++m) _Pragma("unroll") for (int n = 0; n < 2; ++n) _Pragma("unroll") for (int k = 0; k < 2; ++k) \
;         acc[ai][bj][m][n] = __builtin_amdgcn_mfma_f32_16x16x32_bf16(Bt[n][k], At[m][k], acc[ai][bj][m][n], 0, 0, 0); __builtin_amdgcn_s_setprio(0); } while (0)
; #define PG8_WAIT_V(n) asm volatile("s_waitcnt vmcnt(" #n ")" ::: "memory")
; #define PG8_WAIT_L(n) asm volatile("s_waitcnt lgkmcnt(" #n ")" ::: "memory")
; #define PG8_BAR __builtin_amdgcn_s_barrier()
; #define PG8_SCHED __builtin_amdgcn_sched_barrier(0)
; template <class Epi, class Sched, bool ALIGN_EPI = false, bool SP2 = false>
; __device__ __forceinline__ void gemm_phase(PG8_LAS unsigned char* lds, const Gemm g, const Sched& S, const Epi& E, const int wave_in) {
;     ...
;             PG8_WAIT_V(8); PG8_WAIT_L(0); PG8_BAR; PG8_MMA(1, 0, At, B0); PG8_MMA(1, 1, At, B1); PG8_BAR; PG8_SCHED;
;             PG8_LDB(B0, 1, 0); PG8_LDB(B1, 1, 1); PG8_SCHED; PG8_LDA(At, 1, 0); PG8_STAGE(PG8_SA(0, 1), a2 + hstepA, voffA);
;             PG8_WAIT_V(8); PG8_WAIT_L(0); PG8_BAR; PG8_MMA(0, 0, At, B0); PG8_MMA(0, 1, At, B1); PG8_BAR; PG8_SCHED;
	s_setprio 1
	s_waitcnt lgkmcnt(0)
	v_mfma_f32_16x16x32_bf16 v[60:63], v[144:147], v[182:185], 0
	v_mfma_f32_16x16x32_bf16 v[56:59], v[158:161], v[182:185], 0
	v_mfma_f32_16x16x32_bf16 v[44:47], v[144:147], v[190:193], 0
	v_mfma_f32_16x16x32_bf16 v[40:43], v[158:161], v[190:193], 0
	v_mfma_f32_16x16x32_bf16 v[28:31], v[144:147], v[198:201], 0
	v_mfma_f32_16x16x32_bf16 v[24:27], v[158:161], v[198:201], 0
	v_mfma_f32_16x16x32_bf16 v[12:15], v[144:147], v[206:209], 0
	v_mfma_f32_16x16x32_bf16 v[8:11], v[158:161], v[206:209], 0
	v_mfma_f32_16x16x32_bf16 v[60:63], v[154:157], v[186:189], v[60:63]
	v_mfma_f32_16x16x32_bf16 v[56:59], v[162:165], v[186:189], v[56:59]
	v_mfma_f32_16x16x32_bf16 v[44:47], v[154:157], v[194:197], v[44:47]
	v_mfma_f32_16x16x32_bf16 v[40:43], v[162:165], v[194:197], v[40:43]
	v_mfma_f32_16x16x32_bf16 v[28:31], v[154:157], v[202:205], v[28:31]
	v_mfma_f32_16x16x32_bf16 v[24:27], v[162:165], v[202:205], v[24:27]
	v_mfma_f32_16x16x32_bf16 v[12:15], v[154:157], v[210:213], v[12:15]
	v_mfma_f32_16x16x32_bf16 v[8:11], v[162:165], v[210:213], v[8:11]
	s_setprio 0
	s_setprio 1
	v_mfma_f32_16x16x32_bf16 v[52:55], v[166:169], v[182:185], 0
	v_mfma_f32_16x16x32_bf16 v[48:51], v[174:177], v[182:185], 0
	v_mfma_f32_16x16x32_bf16 v[36:39], v[166:169], v[190:193], 0
	v_mfma_f32_16x16x32_bf16 v[32:35], v[174:177], v[190:193], 0
	v_mfma_f32_16x16x32_bf16 v[20:23], v[166:169], v[198:201], 0
	v_mfma_f32_16x16x32_bf16 v[16:19], v[174:177], v[198:201], 0
	v_mfma_f32_16x16x32_bf16 v[4:7], v[166:169], v[206:209], 0
	v_mfma_f32_16x16x32_bf16 v[0:3], v[174:177], v[206:209], 0
	v_mfma_f32_16x16x32_bf16 v[52:55], v[170:173], v[186:189], v[52:55]
	v_mfma_f32_16x16x32_bf16 v[48:51], v[178:181], v[186:189], v[48:51]
	v_mfma_f32_16x16x32_bf16 v[36:39], v[170:173], v[194:197], v[36:39]
	v_mfma_f32_16x16x32_bf16 v[32:35], v[178:181], v[194:197], v[32:35]
	v_mfma_f32_16x16x32_bf16 v[20:23], v[170:173], v[202:205], v[20:23]
	v_mfma_f32_16x16x32_bf16 v[16:19], v[178:181], v[202:205], v[16:19]
	v_mfma_f32_16x16x32_bf16 v[4:7], v[170:173], v[210:213], v[4:7]
	v_mfma_f32_16x16x32_bf16 v[0:3], v[178:181], v[210:213], v[0:3]
	s_setprio 0
	s_barrier
	s_add_i32 s50, 0, 0x18000
	s_add_i32 s51, 0, 0x1c000
	v_add_u32_e32 v162, s50, v149
	v_add_u32_e32 v178, s51, v149
	ds_read_b128 v[144:147], v162
	ds_read_b128 v[154:157], v162 offset:1024
	ds_read_b128 v[158:161], v162 offset:2048
	ds_read_b128 v[162:165], v162 offset:3072
	ds_read_b128 v[166:169], v178
	ds_read_b128 v[170:173], v178 offset:1024
	ds_read_b128 v[174:177], v178 offset:2048
	ds_read_b128 v[178:181], v178 offset:3072
	s_add_u32 s26, s26, 0x80000
	s_addc_u32 s27, s27, 0
	s_mov_b32 m0, s36
	v_lshl_add_u64 v[222:223], s[26:27], 0, v[128:129]
	ds_read_b128 v[182:185], v153 offset:32768
	ds_read_b128 v[186:189], v153 offset:33792
	ds_read_b128 v[190:193], v153 offset:34816
	ds_read_b128 v[194:197], v153 offset:35840
	ds_read_b128 v[198:201], v153 offset:36864
	ds_read_b128 v[202:205], v153 offset:37888
	ds_read_b128 v[206:209], v153 offset:38912
	ds_read_b128 v[210:213], v153 offset:39936
	global_load_lds_dwordx4 v[222:223], off
	v_lshl_add_u64 v[222:223], s[26:27], 0, v[132:133]
	s_mov_b32 m0, s37
	s_nop 0
	global_load_lds_dwordx4 v[222:223], off
	s_waitcnt vmcnt(8)
	s_waitcnt lgkmcnt(0)
	s_barrier
	s_setprio 1
	s_waitcnt lgkmcnt(0)
	v_mfma_f32_16x16x32_bf16 v[124:127], v[144:147], v[182:185], v[124:127]
	v_mfma_f32_16x16x32_bf16 v[120:123], v[158:161], v[182:185], v[120:123]
	v_mfma_f32_16x16x32_bf16 v[108:111], v[144:147], v[190:193], v[108:111]
	v_mfma_f32_16x16x32_bf16 v[104:107], v[158:161], v[190:193], v[104:107]
	v_mfma_f32_16x16x32_bf16 v[92:95], v[144:147], v[198:201], v[92:95]
	v_mfma_f32_16x16x32_bf16 v[88:91], v[158:161], v[198:201], v[88:91]
	v_mfma_f32_16x16x32_bf16 v[76:79], v[144:147], v[206:209], v[76:79]
	v_mfma_f32_16x16x32_bf16 v[72:75], v[158:161], v[206:209], v[72:75]
	v_mfma_f32_16x16x32_bf16 v[124:127], v[154:157], v[186:189], v[124:127]
	v_mfma_f32_16x16x32_bf16 v[120:123], v[162:165], v[186:189], v[120:123]
	v_mfma_f32_16x16x32_bf16 v[108:111], v[154:157], v[194:197], v[108:111]
	v_mfma_f32_16x16x32_bf16 v[104:107], v[162:165], v[194:197], v[104:107]
	v_mfma_f32_16x16x32_bf16 v[92:95], v[154:157], v[202:205], v[92:95]
	v_mfma_f32_16x16x32_bf16 v[88:91], v[162:165], v[202:205], v[88:91]
	v_mfma_f32_16x16x32_bf16 v[76:79], v[154:157], v[210:213], v[76:79]
	v_mfma_f32_16x16x32_bf16 v[72:75], v[162:165], v[210:213], v[72:75]
	s_setprio 0
	s_setprio 1
	v_mfma_f32_16x16x32_bf16 v[116:119], v[166:169], v[182:185], v[116:119]
	v_mfma_f32_16x16x32_bf16 v[112:115], v[174:177], v[182:185], v[112:115]
	v_mfma_f32_16x16x32_bf16 v[100:103], v[166:169], v[190:193], v[100:103]
	v_mfma_f32_16x16x32_bf16 v[96:99], v[174:177], v[190:193], v[96:99]
	v_mfma_f32_16x16x32_bf16 v[84:87], v[166:169], v[198:201], v[84:87]
	v_mfma_f32_16x16x32_bf16 v[80:83], v[174:177], v[198:201], v[80:83]
	v_mfma_f32_16x16x32_bf16 v[68:71], v[166:169], v[206:209], v[68:71]
	v_mfma_f32_16x16x32_bf16 v[64:67], v[174:177], v[206:209], v[64:67]
	v_mfma_f32_16x16x32_bf16 v[116:119], v[170:173], v[186:189], v[116:119]
	v_mfma_f32_16x16x32_bf16 v[112:115], v[178:181], v[186:189], v[112:115]
	v_mfma_f32_16x16x32_bf16 v[100:103], v[170:173], v[194:197], v[100:103]
	v_mfma_f32_16x16x32_bf16 v[96:99], v[178:181], v[194:197], v[96:99]
	v_mfma_f32_16x16x32_bf16 v[84:87], v[170:173], v[202:205], v[84:87]
	v_mfma_f32_16x16x32_bf16 v[80:83], v[178:181], v[202:205], v[80:83]
	v_mfma_f32_16x16x32_bf16 v[68:71], v[170:173], v[210:213], v[68:71]
	v_mfma_f32_16x16x32_bf16 v[64:67], v[178:181], v[210:213], v[64:67]
	s_setprio 0
	s_barrier
; #define PG8_STAGE(bufoff, gbase, voff) do { _Pragma("unroll") for (int _i = 0; _i < 2; ++_i) \
;         __builtin_amdgcn_global_load_lds((const unsigned*)((const char*)(gbase) + (voff)[_i]), (PG8_LAS unsigned*)(lds + (bufoff) + ldsw + _i * 8192), 16, 0, 0); } while (0)
; #define PG8_LDA(dst, b, h) do { _Pragma("unroll") for (int m = 0; m < 4; ++m) _Pragma("unroll") for (int k = 0; k < 2; ++k) dst[m][k] = *(const PG8_LAS bf16x8*)(lds + PG8_SA(b, h) + aoff + m * 2048 + k * 1024); } while (0)
; #define PG8_MMA(ai, bj, At, Bt) do { __builtin_amdgcn_s_setprio(1); _Pragma("unroll") for (int m = 0; m < 4; ++m) _Pragma("unroll") for (int n = 0; n < 2; ++n) _Pragma("unroll") for (int k = 0; k < 2; ++k) \
;         acc[ai][bj][m][n] = __builtin_amdgcn_mfma_f32_16x16x32_bf16(Bt[n][k], At[m][k], acc[ai][bj][m][n], 0, 0, 0); __builtin_amdgcn_s_setprio(0); } while (0)
; #define PG8_WAIT_V(n) asm volatile("s_waitcnt vmcnt(" #n ")" ::: "memory")
; #define PG8_WAIT_L(n) asm volatile("s_waitcnt lgkmcnt(" #n ")" ::: "memory")
; #define PG8_BAR __builtin_amdgcn_s_barrier()
; #define PG8_SCHED __builtin_amdgcn_sched_barrier(0)
; template <class Epi, class Sched, bool ALIGN_EPI = false, bool SP2 = false>
; __device__ __forceinline__ void gemm_phase(PG8_LAS unsigned char* lds, const Gemm g, const Sched& S, const Epi& E, const int wave_in) {
;     ...
;             PG8_LDA(At, 1, 1); PG8_STAGE(PG8_SB(1, 0), b3, voffB); PG8_STAGE(PG8_SB(1, 1), b3 + hstepB, voffB); PG8_STAGE(PG8_SA(1, 0), a3, voffA);
;             PG8_WAIT_V(8); PG8_WAIT_L(0); PG8_BAR; PG8_MMA(1, 0, At, B0); PG8_MMA(1, 1, At, B1); PG8_BAR; PG8_SCHED;
	s_add_i32 s26, s50, s34
	v_lshl_add_u64 v[214:215], v[214:215], 0, s[8:9]
	s_mov_b32 m0, s26
	ds_read_b128 v[182:185], v153 offset:49152
	ds_read_b128 v[186:189], v153 offset:50176
	ds_read_b128 v[190:193], v153 offset:51200
	ds_read_b128 v[194:197], v153 offset:52224
	ds_read_b128 v[198:201], v153 offset:53248
	ds_read_b128 v[202:205], v153 offset:54272
	ds_read_b128 v[206:209], v153 offset:55296
	ds_read_b128 v[210:213], v153 offset:56320
	global_load_lds_dwordx4 v[214:215], off
	s_add_i32 m0, s26, 0x2000
	s_add_u32 s24, s24, 0x80080
	v_lshl_add_u64 v[214:215], v[216:217], 0, s[8:9]
	s_addc_u32 s25, s25, 0
	s_add_i32 s26, s51, s34
	global_load_lds_dwordx4 v[214:215], off
	v_lshl_add_u64 v[214:215], s[24:25], 0, v[130:131]
	s_mov_b32 m0, s26
	s_nop 0
	global_load_lds_dwordx4 v[214:215], off
	v_lshl_add_u64 v[214:215], s[24:25], 0, v[134:135]
	s_add_i32 m0, s26, 0x2000
	s_nop 0
	global_load_lds_dwordx4 v[214:215], off
	v_lshl_add_u64 v[214:215], v[218:219], 0, s[8:9]
	s_mov_b32 m0, s39
	s_nop 0
	global_load_lds_dwordx4 v[214:215], off
	v_lshl_add_u64 v[214:215], v[220:221], 0, s[8:9]
	s_mov_b32 m0, s40
	s_nop 0
	global_load_lds_dwordx4 v[214:215], off
	s_waitcnt vmcnt(8)
	s_waitcnt lgkmcnt(0)
	s_barrier
	s_setprio 1
	s_waitcnt lgkmcnt(0)
	v_mfma_f32_16x16x32_bf16 v[60:63], v[144:147], v[182:185], v[60:63]
	v_mfma_f32_16x16x32_bf16 v[56:59], v[158:161], v[182:185], v[56:59]
	v_mfma_f32_16x16x32_bf16 v[44:47], v[144:147], v[190:193], v[44:47]
	v_mfma_f32_16x16x32_bf16 v[40:43], v[158:161], v[190:193], v[40:43]
	v_mfma_f32_16x16x32_bf16 v[28:31], v[144:147], v[198:201], v[28:31]
	v_mfma_f32_16x16x32_bf16 v[24:27], v[158:161], v[198:201], v[24:27]
	v_mfma_f32_16x16x32_bf16 v[12:15], v[144:147], v[206:209], v[12:15]
	v_mfma_f32_16x16x32_bf16 v[8:11], v[158:161], v[206:209], v[8:11]
	v_mfma_f32_16x16x32_bf16 v[60:63], v[154:157], v[186:189], v[60:63]
	v_mfma_f32_16x16x32_bf16 v[56:59], v[162:165], v[186:189], v[56:59]
	v_mfma_f32_16x16x32_bf16 v[44:47], v[154:157], v[194:197], v[44:47]
	v_mfma_f32_16x16x32_bf16 v[40:43], v[162:165], v[194:197], v[40:43]
	v_mfma_f32_16x16x32_bf16 v[28:31], v[154:157], v[202:205], v[28:31]
	v_mfma_f32_16x16x32_bf16 v[24:27], v[162:165], v[202:205], v[24:27]
	v_mfma_f32_16x16x32_bf16 v[12:15], v[154:157], v[210:213], v[12:15]
	v_mfma_f32_16x16x32_bf16 v[8:11], v[162:165], v[210:213], v[8:11]
	s_setprio 0
	s_setprio 1
	v_mfma_f32_16x16x32_bf16 v[52:55], v[166:169], v[182:185], v[52:55]
	v_mfma_f32_16x16x32_bf16 v[48:51], v[174:177], v[182:185], v[48:51]
	v_mfma_f32_16x16x32_bf16 v[36:39], v[166:169], v[190:193], v[36:39]
	v_mfma_f32_16x16x32_bf16 v[32:35], v[174:177], v[190:193], v[32:35]
	v_mfma_f32_16x16x32_bf16 v[20:23], v[166:169], v[198:201], v[20:23]
	v_mfma_f32_16x16x32_bf16 v[16:19], v[174:177], v[198:201], v[16:19]
	v_mfma_f32_16x16x32_bf16 v[4:7], v[166:169], v[206:209], v[4:7]
	v_mfma_f32_16x16x32_bf16 v[0:3], v[174:177], v[206:209], v[0:3]
	v_mfma_f32_16x16x32_bf16 v[52:55], v[170:173], v[186:189], v[52:55]
	v_mfma_f32_16x16x32_bf16 v[48:51], v[178:181], v[186:189], v[48:51]
	v_mfma_f32_16x16x32_bf16 v[36:39], v[170:173], v[194:197], v[36:39]
	v_mfma_f32_16x16x32_bf16 v[32:35], v[178:181], v[194:197], v[32:35]
	v_mfma_f32_16x16x32_bf16 v[20:23], v[170:173], v[202:205], v[20:23]
	v_mfma_f32_16x16x32_bf16 v[16:19], v[178:181], v[202:205], v[16:19]
	v_mfma_f32_16x16x32_bf16 v[4:7], v[170:173], v[210:213], v[4:7]
	v_mfma_f32_16x16x32_bf16 v[0:3], v[178:181], v[210:213], v[0:3]
	s_setprio 0
	s_barrier
	s_add_i32 s49, s49, 2
	s_add_u32 s22, s22, 0x100
	s_addc_u32 s23, s23, 0
	s_add_u32 s47, s47, 0x100
	s_addc_u32 s48, s48, 0
	s_cmp_gt_u32 s49, 29
	s_cbranch_scc0 .LBB0_158
	s_branch .Lkx_2

; #define PG8_BAR __builtin_amdgcn_s_barrier()
; template <class Epi, class Sched, bool ALIGN_EPI = false, bool SP2 = false>
; __device__ __forceinline__ void gemm_phase(PG8_LAS unsigned char* lds, const Gemm g, const Sched& S, const Epi& E, const int wave_in) {
;     ...
;         if constexpr (ALIGN_EPI) { if (wr == 0) PG8_BAR; }
.Lkx_2:
	s_and_b64 vcc, exec, s[10:11]
	s_cbranch_vccz .LBB0_161
	s_barrier

;     __host__ __device__ bool next(int i, Unit& u) const { const bool ok = StaticOrder::next(i, u); u.pm = 0; u.pn = 0; return ok; }
; #define PG8_STAGE(bufoff, gbase, voff) do { _Pragma("unroll") for (int _i = 0; _i < 2; ++_i) \
;         __builtin_amdgcn_global_load_lds((const unsigned*)((const char*)(gbase) + (voff)[_i]), (PG8_LAS unsigned*)(lds + (bufoff) + ldsw + _i * 8192), 16, 0, 0); } while (0)
; #define PG8_LDA(dst, b, h) do { _Pragma("unroll") for (int m = 0; m < 4; ++m) _Pragma("unroll") for (int k = 0; k < 2; ++k) dst[m][k] = *(const PG8_LAS bf16x8*)(lds + PG8_SA(b, h) + aoff + m * 2048 + k * 1024); } while (0)
; #define PG8_LDB(dst, b, h) do { _Pragma("unroll") for (int n = 0; n < 2; ++n) _Pragma("unroll") for (int k = 0; k < 2; ++k) dst[n][k] = *(const PG8_LAS bf16x8*)(lds + PG8_SB(b, h) + boff + n * 2048 + k * 1024); } while (0)
; #define PG8_WAIT_V(n) asm volatile("s_waitcnt vmcnt(" #n ")" ::: "memory")
; #define PG8_BAR __builtin_amdgcn_s_barrier()
; template <class Epi, class Sched, bool ALIGN_EPI = false, bool SP2 = false>
; __device__ __forceinline__ void gemm_phase(PG8_LAS unsigned char* lds, const Gemm g, const Sched& S, const Epi& E, const int wave_in) {
;     ...
;         const bool has_next = S.next(ui + 1, nxt);
;         const char* nA = has_next ? (const char*)g.A + (size_t)nxt.pm * tstepA : cA; const char* nB = has_next ? (const char*)g.Bt + (size_t)nxt.pn * tstepB : cB;
;         for (int t = 0; t < nt; t += 2) {
;             const bool last = (t == nt - 2);
;             const char* a1 = cA + (size_t)(t + 1) * kstep;
;             const char* a2 = last ? nA : cA + (size_t)(t + 2) * kstep; const char* b2 = last ? nB : cB + (size_t)(t + 2) * kstep;
;             const char* a3 = a2 + kstep; const char* b3 = b2 + kstep;
;             if (last && has_next) S.a_ready(nxt);
;             if constexpr (SP2) {
;             PG8_LDB(B0, 0, 0); PG8_LDB(B1, 0, 1); PG8_SCHED; PG8_LDA(At, 0, 0); PG8_STAGE(PG8_SA(1, 1), a1 + hstepA, voffA);
;             PG8_WAIT_V(8); PG8_WAIT_L(0); PG8_BAR; PG8_MMA(0, 0, At, B0); PG8_MMA(0, 1, At, B1); PG8_BAR; PG8_SCHED;
;             PG8_LDA(At, 0, 1); PG8_STAGE(PG8_SB(0, 0), b2, voffB); PG8_STAGE(PG8_SB(0, 1), b2 + hstepB, voffB); PG8_STAGE(PG8_SA(0, 0), a2, voffA);
;             PG8_WAIT_V(8); PG8_WAIT_L(0); PG8_BAR; PG8_MMA(1, 0, At, B0); PG8_MMA(1, 1, At, B1); PG8_BAR; PG8_SCHED;
.LBB0_352:
	s_ashr_i32 s15, s14, 31
	s_lshl_b64 s[18:19], s[14:15], 20
	s_add_u32 s18, s30, s18
	s_addc_u32 s19, s31, s19
	s_and_b64 s[4:5], s[4:5], exec
	s_cselect_b32 s15, s19, s25
	s_cselect_b32 s21, s18, s24
	s_add_u32 s51, s24, 0x100
	v_mov_b32_e32 v0, 0
	s_addc_u32 s52, s25, 0
	s_mov_b32 s53, -2
	ds_read_b128 v[128:131], v168
	ds_read_b128 v[132:135], v168 offset:1024
	ds_read_b128 v[136:139], v168 offset:2048
	ds_read_b128 v[140:143], v168 offset:3072
	ds_read_b128 v[162:165], v169
	ds_read_b128 v[172:175], v169 offset:1024
	ds_read_b128 v[176:179], v169 offset:2048
	ds_read_b128 v[180:183], v169 offset:3072
	s_add_u32 s4, s22, 0x100
	s_addc_u32 s5, s23, 0
	s_cmp_eq_u32 s53, 28
	s_cselect_b32 s27, s17, s5
	s_cselect_b32 s26, s16, s4
	s_cselect_b32 s25, s15, s52
	s_cselect_b32 s24, s21, s51
	v_lshl_add_u64 v[216:217], s[22:23], 0, v[154:155]
	s_add_i32 m0, s37, 0xc000
	ds_read_b128 v[184:187], v170
	ds_read_b128 v[188:191], v170 offset:1024
	ds_read_b128 v[192:195], v170 offset:2048
	ds_read_b128 v[196:199], v170 offset:3072
	ds_read_b128 v[200:203], v170 offset:4096
	ds_read_b128 v[204:207], v170 offset:5120
	ds_read_b128 v[208:211], v170 offset:6144
	ds_read_b128 v[212:215], v170 offset:7168
	global_load_lds_dwordx4 v[216:217], off
	v_lshl_add_u64 v[216:217], s[22:23], 0, v[156:157]
	s_add_i32 m0, s37, 0xe000
	s_nop 0
	global_load_lds_dwordx4 v[216:217], off
	s_waitcnt vmcnt(8)
	s_waitcnt lgkmcnt(0)
	s_barrier
	s_setprio 1
	s_waitcnt lgkmcnt(0)
	v_mfma_f32_16x16x32_bf16 v[124:127], v[128:131], v[184:187], 0
	v_mfma_f32_16x16x32_bf16 v[120:123], v[136:139], v[184:187], 0
	v_mfma_f32_16x16x32_bf16 v[116:119], v[128:131], v[192:195], 0
	v_mfma_f32_16x16x32_bf16 v[112:115], v[136:139], v[192:195], 0
	v_mfma_f32_16x16x32_bf16 v[92:95], v[128:131], v[200:203], 0
	v_mfma_f32_16x16x32_bf16 v[88:91], v[136:139], v[200:203], 0
	v_mfma_f32_16x16x32_bf16 v[84:87], v[128:131], v[208:211], 0
	v_mfma_f32_16x16x32_bf16 v[76:79], v[136:139], v[208:211], 0
	v_mfma_f32_16x16x32_bf16 v[124:127], v[132:135], v[188:191], v[124:127]
	v_mfma_f32_16x16x32_bf16 v[120:123], v[140:143], v[188:191], v[120:123]
	v_mfma_f32_16x16x32_bf16 v[116:119], v[132:135], v[196:199], v[116:119]
	v_mfma_f32_16x16x32_bf16 v[112:115], v[140:143], v[196:199], v[112:115]
	v_mfma_f32_16x16x32_bf16 v[92:95], v[132:135], v[204:207], v[92:95]
	v_mfma_f32_16x16x32_bf16 v[88:91], v[140:143], v[204:207], v[88:91]
	v_mfma_f32_16x16x32_bf16 v[84:87], v[132:135], v[212:215], v[84:87]
	v_mfma_f32_16x16x32_bf16 v[76:79], v[140:143], v[212:215], v[76:79]
	s_setprio 0
	s_setprio 1
	v_mfma_f32_16x16x32_bf16 v[108:111], v[162:165], v[184:187], 0
	v_mfma_f32_16x16x32_bf16 v[104:107], v[176:179], v[184:187], 0
	v_mfma_f32_16x16x32_bf16 v[100:103], v[162:165], v[192:195], 0
	v_mfma_f32_16x16x32_bf16 v[96:99], v[176:179], v[192:195], 0
	v_mfma_f32_16x16x32_bf16 v[80:83], v[162:165], v[200:203], 0
	v_mfma_f32_16x16x32_bf16 v[72:75], v[176:179], v[200:203], 0
	v_mfma_f32_16x16x32_bf16 v[68:71], v[162:165], v[208:211], 0
	v_mfma_f32_16x16x32_bf16 v[64:67], v[176:179], v[208:211], 0
	v_mfma_f32_16x16x32_bf16 v[108:111], v[172:175], v[188:191], v[108:111]
	v_mfma_f32_16x16x32_bf16 v[104:107], v[180:183], v[188:191], v[104:107]
	v_mfma_f32_16x16x32_bf16 v[100:103], v[172:175], v[196:199], v[100:103]
	v_mfma_f32_16x16x32_bf16 v[96:99], v[180:183], v[196:199], v[96:99]
	v_mfma_f32_16x16x32_bf16 v[80:83], v[172:175], v[204:207], v[80:83]
	v_mfma_f32_16x16x32_bf16 v[72:75], v[180:183], v[204:207], v[72:75]
	v_mfma_f32_16x16x32_bf16 v[68:71], v[172:175], v[212:215], v[68:71]
	v_mfma_f32_16x16x32_bf16 v[64:67], v[180:183], v[212:215], v[64:67]
	s_setprio 0
	s_barrier
	s_add_i32 s22, s47, s34
	v_lshl_add_u64 v[216:217], s[24:25], 0, v[148:149]
	s_mov_b32 m0, s22
	ds_read_b128 v[184:187], v170 offset:16384
	ds_read_b128 v[188:191], v170 offset:17408
	ds_read_b128 v[192:195], v170 offset:18432
	ds_read_b128 v[196:199], v170 offset:19456
	ds_read_b128 v[200:203], v170 offset:20480
	ds_read_b128 v[204:207], v170 offset:21504
	ds_read_b128 v[208:211], v170 offset:22528
	ds_read_b128 v[212:215], v170 offset:23552
	global_load_lds_dwordx4 v[216:217], off
	s_add_i32 m0, s22, 0x2000
	s_add_u32 s22, s24, 0x80000
	v_lshl_add_u64 v[218:219], s[24:25], 0, v[144:145]
	s_addc_u32 s23, s25, 0
	s_add_i32 s54, s48, s34
	global_load_lds_dwordx4 v[218:219], off
	v_lshl_add_u64 v[220:221], s[22:23], 0, v[148:149]
	s_mov_b32 m0, s54
	v_lshl_add_u64 v[222:223], s[26:27], 0, v[146:147]
	global_load_lds_dwordx4 v[220:221], off
	v_lshl_add_u64 v[220:221], s[22:23], 0, v[144:145]
	s_add_i32 m0, s54, 0x2000
	s_nop 0
	global_load_lds_dwordx4 v[220:221], off
	v_lshl_add_u64 v[220:221], s[26:27], 0, v[150:151]
	s_mov_b32 m0, s37
	s_nop 0
	global_load_lds_dwordx4 v[220:221], off
	s_mov_b32 m0, s38
	s_nop 0
	global_load_lds_dwordx4 v[222:223], off
	s_waitcnt vmcnt(8)
	s_waitcnt lgkmcnt(0)
	s_barrier
; #define PG8_STAGE(bufoff, gbase, voff) do { _Pragma("unroll") for (int _i = 0; _i < 2; ++_i) \
;         __builtin_amdgcn_global_load_lds((const unsigned*)((const char*)(gbase) + (voff)[_i]), (PG8_LAS unsigned*)(lds + (bufoff) + ldsw + _i * 8192), 16, 0, 0); } while (0)
; #define PG8_LDA(dst, b, h) do { _Pragma("unroll") for (int m = 0; m < 4; ++m) _Pragma("unroll") for (int k = 0; k < 2; ++k) dst[m][k] = *(const PG8_LAS bf16x8*)(lds + PG8_SA(b, h) + aoff + m * 2048 + k * 1024); } while (0)
; #define PG8_LDB(dst, b, h) do { _Pragma("unroll") for (int n = 0; n < 2; ++n) _Pragma("unroll") for (int k = 0; k < 2; ++k) dst[n][k] = *(const PG8_LAS bf16x8*)(lds + PG8_SB(b, h) + boff + n * 2048 + k * 1024); } while (0)
; #define PG8_MMA(ai, bj, At, Bt) do { __builtin_amdgcn_s_setprio(1); _Pragma("unroll") for (int m = 0; m < 4; ++m) _Pragma("unroll") for (int n = 0; n < 2; ++n) _Pragma("unroll") for (int k = 0; k < 2; ++k) \
;         acc[ai][bj][m][n] = __builtin_amdgcn_mfma_f32_16x16x32_bf16(Bt[n][k], At[m][k], acc[ai][bj][m][n], 0, 0, 0); __builtin_amdgcn_s_setprio(0); } while (0)
; #define PG8_WAIT_V(n) asm volatile("s_waitcnt vmcnt(" #n ")" ::: "memory")
; #define PG8_WAIT_L(n) asm volatile("s_waitcnt lgkmcnt(" #n ")" ::: "memory")
; #define PG8_BAR __builtin_amdgcn_s_barrier()
; #define PG8_SCHED __builtin_amdgcn_sched_barrier(0)
; template <class Epi, class Sched, bool ALIGN_EPI = false, bool SP2 = false>
; __device__ __forceinline__ void gemm_phase(PG8_LAS unsigned char* lds, const Gemm g, const Sched& S, const Epi& E, const int wave_in) {
;     ...
;             PG8_WAIT_V(8); PG8_WAIT_L(0); PG8_BAR; PG8_MMA(1, 0, At, B0); PG8_MMA(1, 1, At, B1); PG8_BAR; PG8_SCHED;
;             PG8_LDB(B0, 1, 0); PG8_LDB(B1, 1, 1); PG8_SCHED; PG8_LDA(At, 1, 0); PG8_STAGE(PG8_SA(0, 1), a2 + hstepA, voffA);
;             PG8_WAIT_V(8); PG8_WAIT_L(0); PG8_BAR; PG8_MMA(0, 0, At, B0); PG8_MMA(0, 1, At, B1); PG8_BAR; PG8_SCHED;
	s_setprio 1
	s_waitcnt lgkmcnt(0)
	v_mfma_f32_16x16x32_bf16 v[60:63], v[128:131], v[184:187], 0
	v_mfma_f32_16x16x32_bf16 v[56:59], v[136:139], v[184:187], 0
	v_mfma_f32_16x16x32_bf16 v[52:55], v[128:131], v[192:195], 0
	v_mfma_f32_16x16x32_bf16 v[44:47], v[136:139], v[192:195], 0
	v_mfma_f32_16x16x32_bf16 v[36:39], v[128:131], v[200:203], 0
	v_mfma_f32_16x16x32_bf16 v[28:31], v[136:139], v[200:203], 0
	v_mfma_f32_16x16x32_bf16 v[20:23], v[128:131], v[208:211], 0
	v_mfma_f32_16x16x32_bf16 v[12:15], v[136:139], v[208:211], 0
	v_mfma_f32_16x16x32_bf16 v[60:63], v[132:135], v[188:191], v[60:63]
	v_mfma_f32_16x16x32_bf16 v[56:59], v[140:143], v[188:191], v[56:59]
	v_mfma_f32_16x16x32_bf16 v[52:55], v[132:135], v[196:199], v[52:55]
	v_mfma_f32_16x16x32_bf16 v[44:47], v[140:143], v[196:199], v[44:47]
	v_mfma_f32_16x16x32_bf16 v[36:39], v[132:135], v[204:207], v[36:39]
	v_mfma_f32_16x16x32_bf16 v[28:31], v[140:143], v[204:207], v[28:31]
	v_mfma_f32_16x16x32_bf16 v[20:23], v[132:135], v[212:215], v[20:23]
	v_mfma_f32_16x16x32_bf16 v[12:15], v[140:143], v[212:215], v[12:15]
	s_setprio 0
	s_setprio 1
	v_mfma_f32_16x16x32_bf16 v[48:51], v[162:165], v[184:187], 0
	v_mfma_f32_16x16x32_bf16 v[40:43], v[176:179], v[184:187], 0
	v_mfma_f32_16x16x32_bf16 v[32:35], v[162:165], v[192:195], 0
	v_mfma_f32_16x16x32_bf16 v[24:27], v[176:179], v[192:195], 0
	v_mfma_f32_16x16x32_bf16 v[16:19], v[162:165], v[200:203], 0
	v_mfma_f32_16x16x32_bf16 v[8:11], v[176:179], v[200:203], 0
	v_mfma_f32_16x16x32_bf16 v[4:7], v[162:165], v[208:211], 0
	v_mfma_f32_16x16x32_bf16 v[0:3], v[176:179], v[208:211], 0
	v_mfma_f32_16x16x32_bf16 v[48:51], v[172:175], v[188:191], v[48:51]
	v_mfma_f32_16x16x32_bf16 v[40:43], v[180:183], v[188:191], v[40:43]
	v_mfma_f32_16x16x32_bf16 v[32:35], v[172:175], v[196:199], v[32:35]
	v_mfma_f32_16x16x32_bf16 v[24:27], v[180:183], v[196:199], v[24:27]
	v_mfma_f32_16x16x32_bf16 v[16:19], v[172:175], v[204:207], v[16:19]
	v_mfma_f32_16x16x32_bf16 v[8:11], v[180:183], v[204:207], v[8:11]
	v_mfma_f32_16x16x32_bf16 v[4:7], v[172:175], v[212:215], v[4:7]
	v_mfma_f32_16x16x32_bf16 v[0:3], v[180:183], v[212:215], v[0:3]
	s_setprio 0
	s_barrier
	s_add_i32 s54, 0, 0x18000
	s_add_i32 s55, 0, 0x1c000
	v_add_u32_e32 v140, s54, v166
	v_add_u32_e32 v171, s55, v166
	ds_read_b128 v[128:131], v140
	ds_read_b128 v[132:135], v140 offset:1024
	ds_read_b128 v[136:139], v140 offset:2048
	ds_read_b128 v[140:143], v140 offset:3072
	ds_read_b128 v[162:165], v171
	ds_read_b128 v[172:175], v171 offset:1024
	ds_read_b128 v[176:179], v171 offset:2048
	ds_read_b128 v[180:183], v171 offset:3072
	s_add_u32 s22, s26, 0x280000
	s_addc_u32 s23, s27, 0
	s_mov_b32 m0, s39
	v_lshl_add_u64 v[224:225], s[22:23], 0, v[150:151]
	ds_read_b128 v[184:187], v170 offset:32768
	ds_read_b128 v[188:191], v170 offset:33792
	ds_read_b128 v[192:195], v170 offset:34816
	ds_read_b128 v[196:199], v170 offset:35840
	ds_read_b128 v[200:203], v170 offset:36864
	ds_read_b128 v[204:207], v170 offset:37888
	ds_read_b128 v[208:211], v170 offset:38912
	ds_read_b128 v[212:215], v170 offset:39936
	global_load_lds_dwordx4 v[224:225], off
	v_lshl_add_u64 v[224:225], s[22:23], 0, v[146:147]
	s_mov_b32 m0, s40
	s_nop 0
	global_load_lds_dwordx4 v[224:225], off
	s_waitcnt vmcnt(8)
	s_waitcnt lgkmcnt(0)
	s_barrier
	s_setprio 1
	s_waitcnt lgkmcnt(0)
	v_mfma_f32_16x16x32_bf16 v[124:127], v[128:131], v[184:187], v[124:127]
	v_mfma_f32_16x16x32_bf16 v[120:123], v[136:139], v[184:187], v[120:123]
	v_mfma_f32_16x16x32_bf16 v[116:119], v[128:131], v[192:195], v[116:119]
	v_mfma_f32_16x16x32_bf16 v[112:115], v[136:139], v[192:195], v[112:115]
	v_mfma_f32_16x16x32_bf16 v[92:95], v[128:131], v[200:203], v[92:95]
	v_mfma_f32_16x16x32_bf16 v[88:91], v[136:139], v[200:203], v[88:91]
	v_mfma_f32_16x16x32_bf16 v[84:87], v[128:131], v[208:211], v[84:87]
	v_mfma_f32_16x16x32_bf16 v[76:79], v[136:139], v[208:211], v[76:79]
	v_mfma_f32_16x16x32_bf16 v[124:127], v[132:135], v[188:191], v[124:127]
	v_mfma_f32_16x16x32_bf16 v[120:123], v[140:143], v[188:191], v[120:123]
	v_mfma_f32_16x16x32_bf16 v[116:119], v[132:135], v[196:199], v[116:119]
	v_mfma_f32_16x16x32_bf16 v[112:115], v[140:143], v[196:199], v[112:115]
	v_mfma_f32_16x16x32_bf16 v[92:95], v[132:135], v[204:207], v[92:95]
	v_mfma_f32_16x16x32_bf16 v[88:91], v[140:143], v[204:207], v[88:91]
	v_mfma_f32_16x16x32_bf16 v[84:87], v[132:135], v[212:215], v[84:87]
	v_mfma_f32_16x16x32_bf16 v[76:79], v[140:143], v[212:215], v[76:79]
	s_setprio 0
	s_setprio 1
	v_mfma_f32_16x16x32_bf16 v[108:111], v[162:165], v[184:187], v[108:111]
	v_mfma_f32_16x16x32_bf16 v[104:107], v[176:179], v[184:187], v[104:107]
	v_mfma_f32_16x16x32_bf16 v[100:103], v[162:165], v[192:195], v[100:103]
	v_mfma_f32_16x16x32_bf16 v[96:99], v[176:179], v[192:195], v[96:99]
	v_mfma_f32_16x16x32_bf16 v[80:83], v[162:165], v[200:203], v[80:83]
	v_mfma_f32_16x16x32_bf16 v[72:75], v[176:179], v[200:203], v[72:75]
	v_mfma_f32_16x16x32_bf16 v[68:71], v[162:165], v[208:211], v[68:71]
	v_mfma_f32_16x16x32_bf16 v[64:67], v[176:179], v[208:211], v[64:67]
	v_mfma_f32_16x16x32_bf16 v[108:111], v[172:175], v[188:191], v[108:111]
	v_mfma_f32_16x16x32_bf16 v[104:107], v[180:183], v[188:191], v[104:107]
	v_mfma_f32_16x16x32_bf16 v[100:103], v[172:175], v[196:199], v[100:103]
	v_mfma_f32_16x16x32_bf16 v[96:99], v[180:183], v[196:199], v[96:99]
	v_mfma_f32_16x16x32_bf16 v[80:83], v[172:175], v[204:207], v[80:83]
	v_mfma_f32_16x16x32_bf16 v[72:75], v[180:183], v[204:207], v[72:75]
	v_mfma_f32_16x16x32_bf16 v[68:71], v[172:175], v[212:215], v[68:71]
	v_mfma_f32_16x16x32_bf16 v[64:67], v[180:183], v[212:215], v[64:67]
	s_setprio 0
	s_barrier
; #define PG8_STAGE(bufoff, gbase, voff) do { _Pragma("unroll") for (int _i = 0; _i < 2; ++_i) \
;         __builtin_amdgcn_global_load_lds((const unsigned*)((const char*)(gbase) + (voff)[_i]), (PG8_LAS unsigned*)(lds + (bufoff) + ldsw + _i * 8192), 16, 0, 0); } while (0)
; #define PG8_LDA(dst, b, h) do { _Pragma("unroll") for (int m = 0; m < 4; ++m) _Pragma("unroll") for (int k = 0; k < 2; ++k) dst[m][k] = *(const PG8_LAS bf16x8*)(lds + PG8_SA(b, h) + aoff + m * 2048 + k * 1024); } while (0)
; #define PG8_MMA(ai, bj, At, Bt) do { __builtin_amdgcn_s_setprio(1); _Pragma("unroll") for (int m = 0; m < 4; ++m) _Pragma("unroll") for (int n = 0; n < 2; ++n) _Pragma("unroll") for (int k = 0; k < 2; ++k) \
;         acc[ai][bj][m][n] = __builtin_amdgcn_mfma_f32_16x16x32_bf16(Bt[n][k], At[m][k], acc[ai][bj][m][n], 0, 0, 0); __builtin_amdgcn_s_setprio(0); } while (0)
; #define PG8_WAIT_V(n) asm volatile("s_waitcnt vmcnt(" #n ")" ::: "memory")
; #define PG8_WAIT_L(n) asm volatile("s_waitcnt lgkmcnt(" #n ")" ::: "memory")
; #define PG8_BAR __builtin_amdgcn_s_barrier()
; #define PG8_SCHED __builtin_amdgcn_sched_barrier(0)
; template <class Epi, class Sched, bool ALIGN_EPI = false, bool SP2 = false>
; __device__ __forceinline__ void gemm_phase(PG8_LAS unsigned char* lds, const Gemm g, const Sched& S, const Epi& E, const int wave_in) {
;     ...
;             PG8_LDA(At, 1, 1); PG8_STAGE(PG8_SB(1, 0), b3, voffB); PG8_STAGE(PG8_SB(1, 1), b3 + hstepB, voffB); PG8_STAGE(PG8_SA(1, 0), a3, voffA);
;             PG8_WAIT_V(8); PG8_WAIT_L(0); PG8_BAR; PG8_MMA(1, 0, At, B0); PG8_MMA(1, 1, At, B1); PG8_BAR; PG8_SCHED;
	s_add_i32 s22, s54, s34
	v_lshl_add_u64 v[216:217], v[216:217], 0, s[10:11]
	s_mov_b32 m0, s22
	ds_read_b128 v[184:187], v170 offset:49152
	ds_read_b128 v[188:191], v170 offset:50176
	ds_read_b128 v[192:195], v170 offset:51200
	ds_read_b128 v[196:199], v170 offset:52224
	ds_read_b128 v[200:203], v170 offset:53248
	ds_read_b128 v[204:207], v170 offset:54272
	ds_read_b128 v[208:211], v170 offset:55296
	ds_read_b128 v[212:215], v170 offset:56320
	global_load_lds_dwordx4 v[216:217], off
	s_add_i32 m0, s22, 0x2000
	s_add_u32 s22, s24, 0x80080
	v_lshl_add_u64 v[216:217], v[218:219], 0, s[10:11]
	s_addc_u32 s23, s25, 0
	s_add_i32 s24, s55, s34
	global_load_lds_dwordx4 v[216:217], off
	v_lshl_add_u64 v[216:217], s[22:23], 0, v[148:149]
	s_mov_b32 m0, s24
	s_nop 0
	global_load_lds_dwordx4 v[216:217], off
	v_lshl_add_u64 v[216:217], s[22:23], 0, v[144:145]
	s_add_i32 m0, s24, 0x2000
	s_nop 0
	global_load_lds_dwordx4 v[216:217], off
	v_lshl_add_u64 v[216:217], v[220:221], 0, s[10:11]
	s_mov_b32 m0, s44
	s_nop 0
	global_load_lds_dwordx4 v[216:217], off
	v_lshl_add_u64 v[216:217], v[222:223], 0, s[10:11]
	s_mov_b32 m0, s45
	s_nop 0
	global_load_lds_dwordx4 v[216:217], off
	s_waitcnt vmcnt(8)
	s_waitcnt lgkmcnt(0)
	s_barrier
	s_setprio 1
	s_waitcnt lgkmcnt(0)
	v_mfma_f32_16x16x32_bf16 v[60:63], v[128:131], v[184:187], v[60:63]
	v_mfma_f32_16x16x32_bf16 v[56:59], v[136:139], v[184:187], v[56:59]
	v_mfma_f32_16x16x32_bf16 v[52:55], v[128:131], v[192:195], v[52:55]
	v_mfma_f32_16x16x32_bf16 v[44:47], v[136:139], v[192:195], v[44:47]
	v_mfma_f32_16x16x32_bf16 v[36:39], v[128:131], v[200:203], v[36:39]
	v_mfma_f32_16x16x32_bf16 v[28:31], v[136:139], v[200:203], v[28:31]
	v_mfma_f32_16x16x32_bf16 v[20:23], v[128:131], v[208:211], v[20:23]
	v_mfma_f32_16x16x32_bf16 v[12:15], v[136:139], v[208:211], v[12:15]
	v_mfma_f32_16x16x32_bf16 v[60:63], v[132:135], v[188:191], v[60:63]
	v_mfma_f32_16x16x32_bf16 v[56:59], v[140:143], v[188:191], v[56:59]
	v_mfma_f32_16x16x32_bf16 v[52:55], v[132:135], v[196:199], v[52:55]
	v_mfma_f32_16x16x32_bf16 v[44:47], v[140:143], v[196:199], v[44:47]
	v_mfma_f32_16x16x32_bf16 v[36:39], v[132:135], v[204:207], v[36:39]
	v_mfma_f32_16x16x32_bf16 v[28:31], v[140:143], v[204:207], v[28:31]
	v_mfma_f32_16x16x32_bf16 v[20:23], v[132:135], v[212:215], v[20:23]
	v_mfma_f32_16x16x32_bf16 v[12:15], v[140:143], v[212:215], v[12:15]
	s_setprio 0
	s_setprio 1
	v_mfma_f32_16x16x32_bf16 v[48:51], v[162:165], v[184:187], v[48:51]
	v_mfma_f32_16x16x32_bf16 v[40:43], v[176:179], v[184:187], v[40:43]
	v_mfma_f32_16x16x32_bf16 v[32:35], v[162:165], v[192:195], v[32:35]
	v_mfma_f32_16x16x32_bf16 v[24:27], v[176:179], v[192:195], v[24:27]
	v_mfma_f32_16x16x32_bf16 v[16:19], v[162:165], v[200:203], v[16:19]
	v_mfma_f32_16x16x32_bf16 v[8:11], v[176:179], v[200:203], v[8:11]
	v_mfma_f32_16x16x32_bf16 v[4:7], v[162:165], v[208:211], v[4:7]
	v_mfma_f32_16x16x32_bf16 v[0:3], v[176:179], v[208:211], v[0:3]
	v_mfma_f32_16x16x32_bf16 v[48:51], v[172:175], v[188:191], v[48:51]
	v_mfma_f32_16x16x32_bf16 v[40:43], v[180:183], v[188:191], v[40:43]
	v_mfma_f32_16x16x32_bf16 v[32:35], v[172:175], v[196:199], v[32:35]
	v_mfma_f32_16x16x32_bf16 v[24:27], v[180:183], v[196:199], v[24:27]
	v_mfma_f32_16x16x32_bf16 v[16:19], v[172:175], v[204:207], v[16:19]
	v_mfma_f32_16x16x32_bf16 v[8:11], v[180:183], v[204:207], v[8:11]
	v_mfma_f32_16x16x32_bf16 v[4:7], v[172:175], v[212:215], v[4:7]
	v_mfma_f32_16x16x32_bf16 v[0:3], v[180:183], v[212:215], v[0:3]
	s_setprio 0
	s_barrier
	s_add_i32 s53, s53, 2
	s_add_u32 s51, s51, 0x100
	s_addc_u32 s52, s52, 0
	s_cmp_gt_u32 s53, 29
	s_mov_b64 s[22:23], s[4:5]
	s_cbranch_scc0 .LBB0_353
	s_branch .Lkx_4

; #define PG8_BAR __builtin_amdgcn_s_barrier()
; template <class Epi, class Sched, bool ALIGN_EPI = false, bool SP2 = false>
; __device__ __forceinline__ void gemm_phase(PG8_LAS unsigned char* lds, const Gemm g, const Sched& S, const Epi& E, const int wave_in) {
;     ...
;         if constexpr (ALIGN_EPI) { if (wr == 0) PG8_BAR; }
;         if constexpr (!Epi::AFTER_DRAIN) { E(acc, cur, wr, wc, fr, fq); S.done(cur); }
.Lkx_4:
	s_load_dwordx2 s[52:53], s[94:95], 0xe0
	s_and_b64 vcc, exec, s[12:13]
	s_cbranch_vccz .LBB0_356
	s_barrier

;     __host__ __device__ bool next(int i, Unit& u) const { const bool ok = StaticOrder::next(i, u); u.pm = 0; u.pn = 0; return ok; }
; #define PG8_STAGE(bufoff, gbase, voff) do { _Pragma("unroll") for (int _i = 0; _i < 2; ++_i) \
;         __builtin_amdgcn_global_load_lds((const unsigned*)((const char*)(gbase) + (voff)[_i]), (PG8_LAS unsigned*)(lds + (bufoff) + ldsw + _i * 8192), 16, 0, 0); } while (0)
; #define PG8_LDA(dst, b, h) do { _Pragma("unroll") for (int m = 0; m < 4; ++m) _Pragma("unroll") for (int k = 0; k < 2; ++k) dst[m][k] = *(const PG8_LAS bf16x8*)(lds + PG8_SA(b, h) + aoff + m * 2048 + k * 1024); } while (0)
; #define PG8_LDB(dst, b, h) do { _Pragma("unroll") for (int n = 0; n < 2; ++n) _Pragma("unroll") for (int k = 0; k < 2; ++k) dst[n][k] = *(const PG8_LAS bf16x8*)(lds + PG8_SB(b, h) + boff + n * 2048 + k * 1024); } while (0)
; #define PG8_WAIT_V(n) asm volatile("s_waitcnt vmcnt(" #n ")" ::: "memory")
; #define PG8_BAR __builtin_amdgcn_s_barrier()
; template <class Epi, class Sched, bool ALIGN_EPI = false, bool SP2 = false>
; __device__ __forceinline__ void gemm_phase(PG8_LAS unsigned char* lds, const Gemm g, const Sched& S, const Epi& E, const int wave_in) {
;     ...
;         const bool has_next = S.next(ui + 1, nxt);
;         const char* nA = has_next ? (const char*)g.A + (size_t)nxt.pm * tstepA : cA; const char* nB = has_next ? (const char*)g.Bt + (size_t)nxt.pn * tstepB : cB;
;         for (int t = 0; t < nt; t += 2) {
;             const bool last = (t == nt - 2);
;             const char* a1 = cA + (size_t)(t + 1) * kstep;
;             const char* a2 = last ? nA : cA + (size_t)(t + 2) * kstep; const char* b2 = last ? nB : cB + (size_t)(t + 2) * kstep;
;             const char* a3 = a2 + kstep; const char* b3 = b2 + kstep;
;             if (last && has_next) S.a_ready(nxt);
;             if constexpr (SP2) {
;             PG8_LDB(B0, 0, 0); PG8_LDB(B1, 0, 1); PG8_SCHED; PG8_LDA(At, 0, 0); PG8_STAGE(PG8_SA(1, 1), a1 + hstepA, voffA);
;             PG8_WAIT_V(8); PG8_WAIT_L(0); PG8_BAR; PG8_MMA(0, 0, At, B0); PG8_MMA(0, 1, At, B1); PG8_BAR; PG8_SCHED;
;             PG8_LDA(At, 0, 1); PG8_STAGE(PG8_SB(0, 0), b2, voffB); PG8_STAGE(PG8_SB(0, 1), b2 + hstepB, voffB); PG8_STAGE(PG8_SA(0, 0), a2, voffA);
;             PG8_WAIT_V(8); PG8_WAIT_L(0); PG8_BAR; PG8_MMA(1, 0, At, B0); PG8_MMA(1, 1, At, B1); PG8_BAR; PG8_SCHED;
.LBB0_478:
	s_ashr_i32 s41, s40, 31
	s_lshl_b64 s[42:43], s[40:41], 20
	s_add_u32 s42, s52, s42
	s_addc_u32 s43, s53, s43
	s_and_b64 s[44:45], s[10:11], exec
	s_cselect_b32 s1, s43, s47
	s_cselect_b32 s13, s42, s46
	s_ashr_i32 s39, s38, 31
	s_lshl_b64 s[44:45], s[38:39], 20
	s_add_u32 s44, s54, s44
	s_addc_u32 s45, s55, s45
	s_and_b64 s[50:51], s[10:11], exec
	s_cselect_b32 s39, s45, s49
	s_cselect_b32 s41, s44, s48
	s_add_u32 s46, s46, 0x80080
	s_addc_u32 s47, s47, 0
	s_add_u32 s72, s48, 0x100
	v_mov_b32_e32 v0, 0
	s_addc_u32 s73, s49, 0
	s_mov_b32 s74, -2
	ds_read_b128 v[44:47], v189
	ds_read_b128 v[48:51], v189 offset:1024
	ds_read_b128 v[52:55], v189 offset:2048
	ds_read_b128 v[56:59], v189 offset:3072
	ds_read_b128 v[60:63], v197
	ds_read_b128 v[64:67], v197 offset:1024
	ds_read_b128 v[80:83], v197 offset:2048
	ds_read_b128 v[84:87], v197 offset:3072
	s_add_u32 s48, s46, 0xfff80080
	s_addc_u32 s49, s47, -1
	s_cmp_eq_u32 s74, 28
	s_cselect_b32 s51, s1, s49
	s_cselect_b32 s50, s13, s48
	s_cselect_b32 s49, s39, s73
	s_cselect_b32 s48, s41, s72
	v_lshl_add_u64 v[224:225], s[46:47], 0, v[206:207]
	s_add_i32 m0, s57, 0xc000
	ds_read_b128 v[88:91], v199
	ds_read_b128 v[92:95], v199 offset:1024
	ds_read_b128 v[96:99], v199 offset:2048
	ds_read_b128 v[100:103], v199 offset:3072
	ds_read_b128 v[176:179], v199 offset:4096
	ds_read_b128 v[212:215], v199 offset:5120
	ds_read_b128 v[216:219], v199 offset:6144
	ds_read_b128 v[220:223], v199 offset:7168
	global_load_lds_dwordx4 v[224:225], off
	v_lshl_add_u64 v[224:225], s[46:47], 0, v[208:209]
	s_add_i32 m0, s57, 0xe000
	s_nop 0
	global_load_lds_dwordx4 v[224:225], off
	s_waitcnt vmcnt(8)
	s_waitcnt lgkmcnt(0)
	s_barrier
	s_setprio 1
	s_waitcnt lgkmcnt(0)
	v_mfma_f32_16x16x32_bf16 v[172:175], v[44:47], v[88:91], 0
	v_mfma_f32_16x16x32_bf16 v[164:167], v[52:55], v[88:91], 0
	v_mfma_f32_16x16x32_bf16 v[156:159], v[44:47], v[96:99], 0
	v_mfma_f32_16x16x32_bf16 v[148:151], v[52:55], v[96:99], 0
	v_mfma_f32_16x16x32_bf16 v[140:143], v[44:47], v[176:179], 0
	v_mfma_f32_16x16x32_bf16 v[132:135], v[52:55], v[176:179], 0
	v_mfma_f32_16x16x32_bf16 v[124:127], v[44:47], v[216:219], 0
	v_mfma_f32_16x16x32_bf16 v[120:123], v[52:55], v[216:219], 0
	v_mfma_f32_16x16x32_bf16 v[172:175], v[48:51], v[92:95], v[172:175]
	v_mfma_f32_16x16x32_bf16 v[164:167], v[56:59], v[92:95], v[164:167]
	v_mfma_f32_16x16x32_bf16 v[156:159], v[48:51], v[100:103], v[156:159]
	v_mfma_f32_16x16x32_bf16 v[148:151], v[56:59], v[100:103], v[148:151]
	v_mfma_f32_16x16x32_bf16 v[140:143], v[48:51], v[212:215], v[140:143]
	v_mfma_f32_16x16x32_bf16 v[132:135], v[56:59], v[212:215], v[132:135]
	v_mfma_f32_16x16x32_bf16 v[124:127], v[48:51], v[220:223], v[124:127]
	v_mfma_f32_16x16x32_bf16 v[120:123], v[56:59], v[220:223], v[120:123]
	s_setprio 0
	s_setprio 1
	v_mfma_f32_16x16x32_bf16 v[168:171], v[60:63], v[88:91], 0
	v_mfma_f32_16x16x32_bf16 v[88:91], v[80:83], v[88:91], 0
	v_mfma_f32_16x16x32_bf16 v[168:171], v[64:67], v[92:95], v[168:171]
	v_mfma_f32_16x16x32_bf16 v[88:91], v[84:87], v[92:95], v[88:91]
	v_mfma_f32_16x16x32_bf16 v[92:95], v[60:63], v[96:99], 0
	v_mfma_f32_16x16x32_bf16 v[96:99], v[80:83], v[96:99], 0
	v_mfma_f32_16x16x32_bf16 v[128:131], v[80:83], v[176:179], 0
	v_mfma_f32_16x16x32_bf16 v[116:119], v[60:63], v[216:219], 0
	v_mfma_f32_16x16x32_bf16 v[112:115], v[80:83], v[216:219], 0
	v_mfma_f32_16x16x32_bf16 v[92:95], v[64:67], v[100:103], v[92:95]
	v_mfma_f32_16x16x32_bf16 v[96:99], v[84:87], v[100:103], v[96:99]
	v_mfma_f32_16x16x32_bf16 v[100:103], v[60:63], v[176:179], 0
	v_mfma_f32_16x16x32_bf16 v[128:131], v[84:87], v[212:215], v[128:131]
	v_mfma_f32_16x16x32_bf16 v[116:119], v[64:67], v[220:223], v[116:119]
	v_mfma_f32_16x16x32_bf16 v[112:115], v[84:87], v[220:223], v[112:115]
	v_mfma_f32_16x16x32_bf16 v[100:103], v[64:67], v[212:215], v[100:103]
	s_setprio 0
	s_barrier
	s_add_i32 s75, s68, s56
	v_lshl_add_u64 v[232:233], s[48:49], 0, v[182:183]
	s_mov_b32 m0, s75
	ds_read_b128 v[136:139], v199 offset:16384
	ds_read_b128 v[144:147], v199 offset:17408
	ds_read_b128 v[152:155], v199 offset:18432
	ds_read_b128 v[160:163], v199 offset:19456
	ds_read_b128 v[176:179], v199 offset:20480
	ds_read_b128 v[212:215], v199 offset:21504
	ds_read_b128 v[216:219], v199 offset:22528
	ds_read_b128 v[220:223], v199 offset:23552
	global_load_lds_dwordx4 v[232:233], off
	s_add_i32 m0, s75, 0x2000
	s_add_u32 s76, s48, 0x80000
	v_lshl_add_u64 v[234:235], s[48:49], 0, v[186:187]
	s_addc_u32 s77, s49, 0
	s_add_i32 s75, s69, s56
	global_load_lds_dwordx4 v[234:235], off
	v_lshl_add_u64 v[224:225], s[76:77], 0, v[182:183]
	s_mov_b32 m0, s75
	v_lshl_add_u64 v[236:237], s[50:51], 0, v[180:181]
	global_load_lds_dwordx4 v[224:225], off
	v_lshl_add_u64 v[224:225], s[76:77], 0, v[186:187]
	s_add_i32 m0, s75, 0x2000
	v_lshl_add_u64 v[238:239], s[50:51], 0, v[184:185]
	global_load_lds_dwordx4 v[224:225], off
	s_mov_b32 m0, s57
	s_nop 0
	global_load_lds_dwordx4 v[236:237], off
	s_mov_b32 m0, s58
	s_nop 0
	global_load_lds_dwordx4 v[238:239], off
	s_waitcnt vmcnt(8)
	s_waitcnt lgkmcnt(0)
	s_barrier
; #define PG8_STAGE(bufoff, gbase, voff) do { _Pragma("unroll") for (int _i = 0; _i < 2; ++_i) \
;         __builtin_amdgcn_global_load_lds((const unsigned*)((const char*)(gbase) + (voff)[_i]), (PG8_LAS unsigned*)(lds + (bufoff) + ldsw + _i * 8192), 16, 0, 0); } while (0)
; #define PG8_LDA(dst, b, h) do { _Pragma("unroll") for (int m = 0; m < 4; ++m) _Pragma("unroll") for (int k = 0; k < 2; ++k) dst[m][k] = *(const PG8_LAS bf16x8*)(lds + PG8_SA(b, h) + aoff + m * 2048 + k * 1024); } while (0)
; #define PG8_LDB(dst, b, h) do { _Pragma("unroll") for (int n = 0; n < 2; ++n) _Pragma("unroll") for (int k = 0; k < 2; ++k) dst[n][k] = *(const PG8_LAS bf16x8*)(lds + PG8_SB(b, h) + boff + n * 2048 + k * 1024); } while (0)
; #define PG8_MMA(ai, bj, At, Bt) do { __builtin_amdgcn_s_setprio(1); _Pragma("unroll") for (int m = 0; m < 4; ++m) _Pragma("unroll") for (int n = 0; n < 2; ++n) _Pragma("unroll") for (int k = 0; k < 2; ++k) \
;         acc[ai][bj][m][n] = __builtin_amdgcn_mfma_f32_16x16x32_bf16(Bt[n][k], At[m][k], acc[ai][bj][m][n], 0, 0, 0); __builtin_amdgcn_s_setprio(0); } while (0)
; #define PG8_WAIT_V(n) asm volatile("s_waitcnt vmcnt(" #n ")" ::: "memory")
; #define PG8_WAIT_L(n) asm volatile("s_waitcnt lgkmcnt(" #n ")" ::: "memory")
; #define PG8_BAR __builtin_amdgcn_s_barrier()
; #define PG8_SCHED __builtin_amdgcn_sched_barrier(0)
; template <class Epi, class Sched, bool ALIGN_EPI = false, bool SP2 = false>
; __device__ __forceinline__ void gemm_phase(PG8_LAS unsigned char* lds, const Gemm g, const Sched& S, const Epi& E, const int wave_in) {
;     ...
;             PG8_WAIT_V(8); PG8_WAIT_L(0); PG8_BAR; PG8_MMA(1, 0, At, B0); PG8_MMA(1, 1, At, B1); PG8_BAR; PG8_SCHED;
;             PG8_LDB(B0, 1, 0); PG8_LDB(B1, 1, 1); PG8_SCHED; PG8_LDA(At, 1, 0); PG8_STAGE(PG8_SA(0, 1), a2 + hstepA, voffA);
;             PG8_WAIT_V(8); PG8_WAIT_L(0); PG8_BAR; PG8_MMA(0, 0, At, B0); PG8_MMA(0, 1, At, B1); PG8_BAR; PG8_SCHED;
	s_setprio 1
	s_waitcnt lgkmcnt(0)
	v_mfma_f32_16x16x32_bf16 v[108:111], v[44:47], v[136:139], 0
	v_mfma_f32_16x16x32_bf16 v[76:79], v[52:55], v[136:139], 0
	v_mfma_f32_16x16x32_bf16 v[68:71], v[44:47], v[152:155], 0
	v_mfma_f32_16x16x32_bf16 v[36:39], v[52:55], v[152:155], 0
	v_mfma_f32_16x16x32_bf16 v[28:31], v[44:47], v[176:179], 0
	v_mfma_f32_16x16x32_bf16 v[20:23], v[52:55], v[176:179], 0
	v_mfma_f32_16x16x32_bf16 v[12:15], v[44:47], v[216:219], 0
	v_mfma_f32_16x16x32_bf16 v[8:11], v[52:55], v[216:219], 0
	v_mfma_f32_16x16x32_bf16 v[108:111], v[48:51], v[144:147], v[108:111]
	v_mfma_f32_16x16x32_bf16 v[76:79], v[56:59], v[144:147], v[76:79]
	v_mfma_f32_16x16x32_bf16 v[68:71], v[48:51], v[160:163], v[68:71]
	v_mfma_f32_16x16x32_bf16 v[36:39], v[56:59], v[160:163], v[36:39]
	v_mfma_f32_16x16x32_bf16 v[28:31], v[48:51], v[212:215], v[28:31]
	v_mfma_f32_16x16x32_bf16 v[20:23], v[56:59], v[212:215], v[20:23]
	v_mfma_f32_16x16x32_bf16 v[12:15], v[48:51], v[220:223], v[12:15]
	v_mfma_f32_16x16x32_bf16 v[8:11], v[56:59], v[220:223], v[8:11]
	s_setprio 0
	s_setprio 1
	v_mfma_f32_16x16x32_bf16 v[40:43], v[60:63], v[152:155], 0
	v_mfma_f32_16x16x32_bf16 v[32:35], v[80:83], v[152:155], 0
	v_mfma_f32_16x16x32_bf16 v[24:27], v[60:63], v[176:179], 0
	v_mfma_f32_16x16x32_bf16 v[16:19], v[80:83], v[176:179], 0
	v_mfma_f32_16x16x32_bf16 v[4:7], v[60:63], v[216:219], 0
	v_mfma_f32_16x16x32_bf16 v[0:3], v[80:83], v[216:219], 0
	v_mfma_f32_16x16x32_bf16 v[44:47], v[60:63], v[136:139], 0
	v_mfma_f32_16x16x32_bf16 v[48:51], v[80:83], v[136:139], 0
	v_mfma_f32_16x16x32_bf16 v[40:43], v[64:67], v[160:163], v[40:43]
	v_mfma_f32_16x16x32_bf16 v[32:35], v[84:87], v[160:163], v[32:35]
	v_mfma_f32_16x16x32_bf16 v[24:27], v[64:67], v[212:215], v[24:27]
	v_mfma_f32_16x16x32_bf16 v[16:19], v[84:87], v[212:215], v[16:19]
	v_mfma_f32_16x16x32_bf16 v[4:7], v[64:67], v[220:223], v[4:7]
	v_mfma_f32_16x16x32_bf16 v[0:3], v[84:87], v[220:223], v[0:3]
	v_mfma_f32_16x16x32_bf16 v[44:47], v[64:67], v[144:147], v[44:47]
	v_mfma_f32_16x16x32_bf16 v[48:51], v[84:87], v[144:147], v[48:51]
	s_setprio 0
	s_barrier
	s_add_i32 s75, 0, 0x18000
	s_add_i32 s76, 0, 0x1c000
	v_add_u32_e32 v64, s75, v195
	v_add_u32_e32 v72, s76, v195
	ds_read_b128 v[52:55], v64
	ds_read_b128 v[56:59], v64 offset:1024
	ds_read_b128 v[60:63], v64 offset:2048
	ds_read_b128 v[64:67], v64 offset:3072
	ds_read_b128 v[80:83], v72
	ds_read_b128 v[84:87], v72 offset:1024
	ds_read_b128 v[176:179], v72 offset:2048
	ds_read_b128 v[212:215], v72 offset:3072
	s_add_u32 s50, s50, 0x80000
	s_addc_u32 s51, s51, 0
	s_mov_b32 m0, s59
	v_lshl_add_u64 v[152:153], s[50:51], 0, v[180:181]
	ds_read_b128 v[72:75], v199 offset:32768
	ds_read_b128 v[104:107], v199 offset:33792
	ds_read_b128 v[136:139], v199 offset:34816
	ds_read_b128 v[144:147], v199 offset:35840
	ds_read_b128 v[216:219], v199 offset:36864
	ds_read_b128 v[220:223], v199 offset:37888
	ds_read_b128 v[224:227], v199 offset:38912
	ds_read_b128 v[228:231], v199 offset:39936
	global_load_lds_dwordx4 v[152:153], off
	v_lshl_add_u64 v[152:153], s[50:51], 0, v[184:185]
	s_mov_b32 m0, s60
	s_nop 0
	global_load_lds_dwordx4 v[152:153], off
	s_waitcnt vmcnt(8)
	s_waitcnt lgkmcnt(0)
	s_barrier
	s_setprio 1
	s_waitcnt lgkmcnt(0)
	v_mfma_f32_16x16x32_bf16 v[152:155], v[52:55], v[72:75], v[172:175]
	v_mfma_f32_16x16x32_bf16 v[172:175], v[56:59], v[104:107], v[152:155]
	v_mfma_f32_16x16x32_bf16 v[152:155], v[60:63], v[72:75], v[164:167]
	v_mfma_f32_16x16x32_bf16 v[164:167], v[64:67], v[104:107], v[152:155]
	v_mfma_f32_16x16x32_bf16 v[152:155], v[52:55], v[136:139], v[156:159]
	v_mfma_f32_16x16x32_bf16 v[148:151], v[60:63], v[136:139], v[148:151]
	v_mfma_f32_16x16x32_bf16 v[140:143], v[52:55], v[216:219], v[140:143]
	v_mfma_f32_16x16x32_bf16 v[132:135], v[60:63], v[216:219], v[132:135]
	v_mfma_f32_16x16x32_bf16 v[124:127], v[52:55], v[224:227], v[124:127]
	v_mfma_f32_16x16x32_bf16 v[120:123], v[60:63], v[224:227], v[120:123]
	v_mfma_f32_16x16x32_bf16 v[156:159], v[56:59], v[144:147], v[152:155]
	v_mfma_f32_16x16x32_bf16 v[148:151], v[64:67], v[144:147], v[148:151]
	v_mfma_f32_16x16x32_bf16 v[140:143], v[56:59], v[220:223], v[140:143]
	v_mfma_f32_16x16x32_bf16 v[132:135], v[64:67], v[220:223], v[132:135]
	v_mfma_f32_16x16x32_bf16 v[124:127], v[56:59], v[228:231], v[124:127]
	v_mfma_f32_16x16x32_bf16 v[120:123], v[64:67], v[228:231], v[120:123]
	s_setprio 0
	s_setprio 1
	v_mfma_f32_16x16x32_bf16 v[152:155], v[80:83], v[72:75], v[168:171]
	v_mfma_f32_16x16x32_bf16 v[72:75], v[176:179], v[72:75], v[88:91]
	v_mfma_f32_16x16x32_bf16 v[160:163], v[212:215], v[104:107], v[72:75]
	v_mfma_f32_16x16x32_bf16 v[72:75], v[80:83], v[136:139], v[92:95]
	v_mfma_f32_16x16x32_bf16 v[168:171], v[84:87], v[104:107], v[152:155]
	v_mfma_f32_16x16x32_bf16 v[152:155], v[84:87], v[144:147], v[72:75]
	v_mfma_f32_16x16x32_bf16 v[72:75], v[176:179], v[136:139], v[96:99]
	v_mfma_f32_16x16x32_bf16 v[144:147], v[212:215], v[144:147], v[72:75]
	v_mfma_f32_16x16x32_bf16 v[72:75], v[80:83], v[216:219], v[100:103]
	v_mfma_f32_16x16x32_bf16 v[136:139], v[84:87], v[220:223], v[72:75]
	v_mfma_f32_16x16x32_bf16 v[72:75], v[176:179], v[216:219], v[128:131]
	v_mfma_f32_16x16x32_bf16 v[128:131], v[212:215], v[220:223], v[72:75]
	v_mfma_f32_16x16x32_bf16 v[72:75], v[80:83], v[224:227], v[116:119]
	v_mfma_f32_16x16x32_bf16 v[116:119], v[84:87], v[228:231], v[72:75]
	v_mfma_f32_16x16x32_bf16 v[72:75], v[176:179], v[224:227], v[112:115]
	v_mfma_f32_16x16x32_bf16 v[112:115], v[212:215], v[228:231], v[72:75]
	s_setprio 0
	s_barrier
; #define PG8_STAGE(bufoff, gbase, voff) do { _Pragma("unroll") for (int _i = 0; _i < 2; ++_i) \
;         __builtin_amdgcn_global_load_lds((const unsigned*)((const char*)(gbase) + (voff)[_i]), (PG8_LAS unsigned*)(lds + (bufoff) + ldsw + _i * 8192), 16, 0, 0); } while (0)
; #define PG8_LDA(dst, b, h) do { _Pragma("unroll") for (int m = 0; m < 4; ++m) _Pragma("unroll") for (int k = 0; k < 2; ++k) dst[m][k] = *(const PG8_LAS bf16x8*)(lds + PG8_SA(b, h) + aoff + m * 2048 + k * 1024); } while (0)
; #define PG8_MMA(ai, bj, At, Bt) do { __builtin_amdgcn_s_setprio(1); _Pragma("unroll") for (int m = 0; m < 4; ++m) _Pragma("unroll") for (int n = 0; n < 2; ++n) _Pragma("unroll") for (int k = 0; k < 2; ++k) \
;         acc[ai][bj][m][n] = __builtin_amdgcn_mfma_f32_16x16x32_bf16(Bt[n][k], At[m][k], acc[ai][bj][m][n], 0, 0, 0); __builtin_amdgcn_s_setprio(0); } while (0)
; #define PG8_WAIT_V(n) asm volatile("s_waitcnt vmcnt(" #n ")" ::: "memory")
; #define PG8_WAIT_L(n) asm volatile("s_waitcnt lgkmcnt(" #n ")" ::: "memory")
; #define PG8_BAR __builtin_amdgcn_s_barrier()
; #define PG8_SCHED __builtin_amdgcn_sched_barrier(0)
; template <class Epi, class Sched, bool ALIGN_EPI = false, bool SP2 = false>
; __device__ __forceinline__ void gemm_phase(PG8_LAS unsigned char* lds, const Gemm g, const Sched& S, const Epi& E, const int wave_in) {
;     ...
;             PG8_LDA(At, 1, 1); PG8_STAGE(PG8_SB(1, 0), b3, voffB); PG8_STAGE(PG8_SB(1, 1), b3 + hstepB, voffB); PG8_STAGE(PG8_SA(1, 0), a3, voffA);
;             PG8_WAIT_V(8); PG8_WAIT_L(0); PG8_BAR; PG8_MMA(1, 0, At, B0); PG8_MMA(1, 1, At, B1); PG8_BAR; PG8_SCHED;
	s_add_i32 s50, s75, s56
	v_lshl_add_u64 v[104:105], v[232:233], 0, s[22:23]
	s_mov_b32 m0, s50
	s_nop 1
	ds_read_b128 v[72:75], v199 offset:49152
	ds_read_b128 v[88:91], v199 offset:50176
	ds_read_b128 v[92:95], v199 offset:51200
	ds_read_b128 v[96:99], v199 offset:52224
	ds_read_b128 v[100:103], v199 offset:53248
	ds_read_b128 v[216:219], v199 offset:54272
	ds_read_b128 v[220:223], v199 offset:55296
	ds_read_b128 v[224:227], v199 offset:56320
	global_load_lds_dwordx4 v[104:105], off
	s_add_i32 m0, s50, 0x2000
	s_add_u32 s48, s48, 0x80080
	v_lshl_add_u64 v[104:105], v[234:235], 0, s[22:23]
	s_addc_u32 s49, s49, 0
	s_add_i32 s50, s76, s56
	global_load_lds_dwordx4 v[104:105], off
	v_lshl_add_u64 v[104:105], s[48:49], 0, v[182:183]
	s_mov_b32 m0, s50
	s_nop 0
	global_load_lds_dwordx4 v[104:105], off
	v_lshl_add_u64 v[104:105], s[48:49], 0, v[186:187]
	s_add_i32 m0, s50, 0x2000
	s_nop 0
	global_load_lds_dwordx4 v[104:105], off
	v_lshl_add_u64 v[104:105], v[236:237], 0, s[22:23]
	s_mov_b32 m0, s63
	s_nop 0
	global_load_lds_dwordx4 v[104:105], off
	v_lshl_add_u64 v[104:105], v[238:239], 0, s[22:23]
	s_mov_b32 m0, s64
	s_nop 0
	global_load_lds_dwordx4 v[104:105], off
	s_waitcnt vmcnt(8)
	s_waitcnt lgkmcnt(0)
	s_barrier
	s_setprio 1
	s_waitcnt lgkmcnt(0)
	v_mfma_f32_16x16x32_bf16 v[104:107], v[52:55], v[72:75], v[108:111]
	v_mfma_f32_16x16x32_bf16 v[76:79], v[60:63], v[72:75], v[76:79]
	v_mfma_f32_16x16x32_bf16 v[68:71], v[52:55], v[92:95], v[68:71]
	v_mfma_f32_16x16x32_bf16 v[36:39], v[60:63], v[92:95], v[36:39]
	v_mfma_f32_16x16x32_bf16 v[28:31], v[52:55], v[100:103], v[28:31]
	v_mfma_f32_16x16x32_bf16 v[20:23], v[60:63], v[100:103], v[20:23]
	v_mfma_f32_16x16x32_bf16 v[12:15], v[52:55], v[220:223], v[12:15]
	v_mfma_f32_16x16x32_bf16 v[8:11], v[60:63], v[220:223], v[8:11]
	v_mfma_f32_16x16x32_bf16 v[108:111], v[56:59], v[88:91], v[104:107]
	v_mfma_f32_16x16x32_bf16 v[76:79], v[64:67], v[88:91], v[76:79]
	v_mfma_f32_16x16x32_bf16 v[68:71], v[56:59], v[96:99], v[68:71]
	v_mfma_f32_16x16x32_bf16 v[36:39], v[64:67], v[96:99], v[36:39]
	v_mfma_f32_16x16x32_bf16 v[28:31], v[56:59], v[216:219], v[28:31]
	v_mfma_f32_16x16x32_bf16 v[20:23], v[64:67], v[216:219], v[20:23]
	v_mfma_f32_16x16x32_bf16 v[12:15], v[56:59], v[224:227], v[12:15]
	v_mfma_f32_16x16x32_bf16 v[8:11], v[64:67], v[224:227], v[8:11]
	s_setprio 0
	s_setprio 1
	v_mfma_f32_16x16x32_bf16 v[44:47], v[80:83], v[72:75], v[44:47]
	v_mfma_f32_16x16x32_bf16 v[104:107], v[84:87], v[88:91], v[44:47]
	v_mfma_f32_16x16x32_bf16 v[44:47], v[176:179], v[72:75], v[48:51]
	v_mfma_f32_16x16x32_bf16 v[40:43], v[80:83], v[92:95], v[40:43]
	v_mfma_f32_16x16x32_bf16 v[32:35], v[176:179], v[92:95], v[32:35]
	v_mfma_f32_16x16x32_bf16 v[24:27], v[80:83], v[100:103], v[24:27]
	v_mfma_f32_16x16x32_bf16 v[16:19], v[176:179], v[100:103], v[16:19]
	v_mfma_f32_16x16x32_bf16 v[4:7], v[80:83], v[220:223], v[4:7]
	v_mfma_f32_16x16x32_bf16 v[0:3], v[176:179], v[220:223], v[0:3]
	v_mfma_f32_16x16x32_bf16 v[72:75], v[212:215], v[88:91], v[44:47]
	v_mfma_f32_16x16x32_bf16 v[40:43], v[84:87], v[96:99], v[40:43]
	v_mfma_f32_16x16x32_bf16 v[32:35], v[212:215], v[96:99], v[32:35]
	v_mfma_f32_16x16x32_bf16 v[24:27], v[84:87], v[216:219], v[24:27]
	v_mfma_f32_16x16x32_bf16 v[16:19], v[212:215], v[216:219], v[16:19]
	v_mfma_f32_16x16x32_bf16 v[4:7], v[84:87], v[224:227], v[4:7]
	v_mfma_f32_16x16x32_bf16 v[0:3], v[212:215], v[224:227], v[0:3]
	s_setprio 0
	s_barrier
	s_add_i32 s74, s74, 2
	s_add_u32 s46, s46, 0x100
	s_addc_u32 s47, s47, 0
	s_add_u32 s72, s72, 0x100
	s_addc_u32 s73, s73, 0
	s_cmp_gt_u32 s74, 29
	s_cbranch_scc0 .LBB0_479
	s_branch .Lkx_6

; #define PG8_BAR __builtin_amdgcn_s_barrier()
; template <class Epi, class Sched, bool ALIGN_EPI = false, bool SP2 = false>
; __device__ __forceinline__ void gemm_phase(PG8_LAS unsigned char* lds, const Gemm g, const Sched& S, const Epi& E, const int wave_in) {
;     ...
;         if constexpr (ALIGN_EPI) { if (wr == 0) PG8_BAR; }
.Lkx_6:
	s_and_b64 vcc, exec, s[24:25]
	s_cbranch_vccz .LBB0_482
	s_barrier

; #define PG8_STAGE(bufoff, gbase, voff) do { _Pragma("unroll") for (int _i = 0; _i < 2; ++_i) \
;         __builtin_amdgcn_global_load_lds((const unsigned*)((const char*)(gbase) + (voff)[_i]), (PG8_LAS unsigned*)(lds + (bufoff) + ldsw + _i * 8192), 16, 0, 0); } while (0)
; #define PG8_LDA(dst, b, h) do { _Pragma("unroll") for (int m = 0; m < 4; ++m) _Pragma("unroll") for (int k = 0; k < 2; ++k) dst[m][k] = *(const PG8_LAS bf16x8*)(lds + PG8_SA(b, h) + aoff + m * 2048 + k * 1024); } while (0)
; #define PG8_LDB(dst, b, h) do { _Pragma("unroll") for (int n = 0; n < 2; ++n) _Pragma("unroll") for (int k = 0; k < 2; ++k) dst[n][k] = *(const PG8_LAS bf16x8*)(lds + PG8_SB(b, h) + boff + n * 2048 + k * 1024); } while (0)
; #define PG8_MMA(ai, bj, At, Bt) do { __builtin_amdgcn_s_setprio(1); _Pragma("unroll") for (int m = 0; m < 4; ++m) _Pragma("unroll") for (int n = 0; n < 2; ++n) _Pragma("unroll") for (int k = 0; k < 2; ++k) \
;         acc[ai][bj][m][n] = __builtin_amdgcn_mfma_f32_16x16x32_bf16(Bt[n][k], At[m][k], acc[ai][bj][m][n], 0, 0, 0); __builtin_amdgcn_s_setprio(0); } while (0)
; #define PG8_WAIT_V(n) asm volatile("s_waitcnt vmcnt(" #n ")" ::: "memory")
; #define PG8_BAR __builtin_amdgcn_s_barrier()
; template <class Epi, class Sched, bool ALIGN_EPI = false, bool SP2 = false>
; __device__ __forceinline__ void gemm_phase(PG8_LAS unsigned char* lds, const Gemm g, const Sched& S, const Epi& E, const int wave_in) {
;     ...
;         for (int t = 0; t < nt; t += 2) {
;             const bool last = (t == nt - 2);
;             const char* a1 = cA + (size_t)(t + 1) * kstep;
;             const char* a2 = last ? nA : cA + (size_t)(t + 2) * kstep; const char* b2 = last ? nB : cB + (size_t)(t + 2) * kstep;
;             const char* a3 = a2 + kstep; const char* b3 = b2 + kstep;
;             if (last && has_next) S.a_ready(nxt);
;             if constexpr (SP2) {
;             PG8_LDB(B0, 0, 0); PG8_LDB(B1, 0, 1); PG8_SCHED; PG8_LDA(At, 0, 0); PG8_STAGE(PG8_SA(1, 1), a1 + hstepA, voffA);
;             PG8_WAIT_V(8); PG8_WAIT_L(0); PG8_BAR; PG8_MMA(0, 0, At, B0); PG8_MMA(0, 1, At, B1); PG8_BAR; PG8_SCHED;
;             PG8_LDA(At, 0, 1); PG8_STAGE(PG8_SB(0, 0), b2, voffB); PG8_STAGE(PG8_SB(0, 1), b2 + hstepB, voffB); PG8_STAGE(PG8_SA(0, 0), a2, voffA);
;             PG8_WAIT_V(8); PG8_WAIT_L(0); PG8_BAR; PG8_MMA(1, 0, At, B0); PG8_MMA(1, 1, At, B1); PG8_BAR; PG8_SCHED;
.LBB0_634:
	s_add_u32 s17, s20, 0x100
	v_mov_b32_e32 v0, 0
	s_addc_u32 s52, s21, 0
	s_mov_b32 s53, -2
	ds_read_b128 v[64:67], v230
	ds_read_b128 v[68:71], v230 offset:1024
	ds_read_b128 v[72:75], v230 offset:2048
	ds_read_b128 v[76:79], v230 offset:3072
	ds_read_b128 v[144:147], v231
	ds_read_b128 v[148:151], v231 offset:1024
	ds_read_b128 v[170:173], v231 offset:2048
	ds_read_b128 v[174:177], v231 offset:3072
	s_add_u32 s20, s18, 0x100
	s_addc_u32 s21, s19, 0
	s_cmpk_eq_i32 s53, 0x52
	s_cselect_b32 s25, s5, s21
	s_cselect_b32 s24, s4, s20
	s_cselect_b32 s23, s15, s52
	s_cselect_b32 s22, s14, s17
	v_lshl_add_u64 v[210:211], s[18:19], 0, v[162:163]
	s_add_i32 m0, s35, 0xc000
	ds_read_b128 v[178:181], v232
	ds_read_b128 v[182:185], v232 offset:1024
	ds_read_b128 v[186:189], v232 offset:2048
	ds_read_b128 v[190:193], v232 offset:3072
	ds_read_b128 v[194:197], v232 offset:4096
	ds_read_b128 v[198:201], v232 offset:5120
	ds_read_b128 v[202:205], v232 offset:6144
	ds_read_b128 v[206:209], v232 offset:7168
	global_load_lds_dwordx4 v[210:211], off
	v_lshl_add_u64 v[210:211], s[18:19], 0, v[164:165]
	s_add_i32 m0, s35, 0xe000
	s_nop 0
	global_load_lds_dwordx4 v[210:211], off
	s_waitcnt vmcnt(8)
	s_waitcnt lgkmcnt(0)
	s_barrier
	s_setprio 1
	s_waitcnt lgkmcnt(0)
	v_mfma_f32_16x16x32_bf16 v[140:143], v[64:67], v[178:181], 0
	v_mfma_f32_16x16x32_bf16 v[136:139], v[72:75], v[178:181], 0
	v_mfma_f32_16x16x32_bf16 v[128:131], v[64:67], v[186:189], 0
	v_mfma_f32_16x16x32_bf16 v[120:123], v[72:75], v[186:189], 0
	v_mfma_f32_16x16x32_bf16 v[116:119], v[64:67], v[194:197], 0
	v_mfma_f32_16x16x32_bf16 v[112:115], v[72:75], v[194:197], 0
	v_mfma_f32_16x16x32_bf16 v[100:103], v[64:67], v[202:205], 0
	v_mfma_f32_16x16x32_bf16 v[96:99], v[72:75], v[202:205], 0
	v_mfma_f32_16x16x32_bf16 v[140:143], v[68:71], v[182:185], v[140:143]
	v_mfma_f32_16x16x32_bf16 v[136:139], v[76:79], v[182:185], v[136:139]
	v_mfma_f32_16x16x32_bf16 v[128:131], v[68:71], v[190:193], v[128:131]
	v_mfma_f32_16x16x32_bf16 v[120:123], v[76:79], v[190:193], v[120:123]
	v_mfma_f32_16x16x32_bf16 v[116:119], v[68:71], v[198:201], v[116:119]
	v_mfma_f32_16x16x32_bf16 v[112:115], v[76:79], v[198:201], v[112:115]
	v_mfma_f32_16x16x32_bf16 v[100:103], v[68:71], v[206:209], v[100:103]
	v_mfma_f32_16x16x32_bf16 v[96:99], v[76:79], v[206:209], v[96:99]
	s_setprio 0
	s_setprio 1
	v_mfma_f32_16x16x32_bf16 v[132:135], v[144:147], v[178:181], 0
	v_mfma_f32_16x16x32_bf16 v[124:127], v[170:173], v[178:181], 0
	v_mfma_f32_16x16x32_bf16 v[108:111], v[144:147], v[186:189], 0
	v_mfma_f32_16x16x32_bf16 v[104:107], v[170:173], v[186:189], 0
	v_mfma_f32_16x16x32_bf16 v[92:95], v[144:147], v[194:197], 0
	v_mfma_f32_16x16x32_bf16 v[88:91], v[170:173], v[194:197], 0
	v_mfma_f32_16x16x32_bf16 v[84:87], v[144:147], v[202:205], 0
	v_mfma_f32_16x16x32_bf16 v[80:83], v[170:173], v[202:205], 0
	v_mfma_f32_16x16x32_bf16 v[132:135], v[148:151], v[182:185], v[132:135]
	v_mfma_f32_16x16x32_bf16 v[124:127], v[174:177], v[182:185], v[124:127]
	v_mfma_f32_16x16x32_bf16 v[108:111], v[148:151], v[190:193], v[108:111]
	v_mfma_f32_16x16x32_bf16 v[104:107], v[174:177], v[190:193], v[104:107]
	v_mfma_f32_16x16x32_bf16 v[92:95], v[148:151], v[198:201], v[92:95]
	v_mfma_f32_16x16x32_bf16 v[88:91], v[174:177], v[198:201], v[88:91]
	v_mfma_f32_16x16x32_bf16 v[84:87], v[148:151], v[206:209], v[84:87]
	v_mfma_f32_16x16x32_bf16 v[80:83], v[174:177], v[206:209], v[80:83]
	s_setprio 0
	s_barrier
	s_add_i32 s18, s45, s30
	v_lshl_add_u64 v[210:211], s[22:23], 0, v[156:157]
	s_mov_b32 m0, s18
	ds_read_b128 v[178:181], v232 offset:16384
	ds_read_b128 v[182:185], v232 offset:17408
	ds_read_b128 v[186:189], v232 offset:18432
	ds_read_b128 v[190:193], v232 offset:19456
	ds_read_b128 v[194:197], v232 offset:20480
	ds_read_b128 v[198:201], v232 offset:21504
	ds_read_b128 v[202:205], v232 offset:22528
	ds_read_b128 v[206:209], v232 offset:23552
	global_load_lds_dwordx4 v[210:211], off
	s_add_i32 m0, s18, 0x2000
	s_add_u32 s18, s22, 0x158000
	v_lshl_add_u64 v[212:213], s[22:23], 0, v[152:153]
	s_addc_u32 s19, s23, 0
	s_add_i32 s54, s46, s30
	global_load_lds_dwordx4 v[212:213], off
	v_lshl_add_u64 v[214:215], s[18:19], 0, v[156:157]
	s_mov_b32 m0, s54
	v_lshl_add_u64 v[216:217], s[24:25], 0, v[154:155]
	global_load_lds_dwordx4 v[214:215], off
	v_lshl_add_u64 v[214:215], s[18:19], 0, v[152:153]
	s_add_i32 m0, s54, 0x2000
	s_nop 0
	global_load_lds_dwordx4 v[214:215], off
	v_lshl_add_u64 v[214:215], s[24:25], 0, v[158:159]
	s_mov_b32 m0, s35
	s_nop 0
	global_load_lds_dwordx4 v[214:215], off
	s_mov_b32 m0, s36
	s_nop 0
	global_load_lds_dwordx4 v[216:217], off
	s_waitcnt vmcnt(8)
	s_waitcnt lgkmcnt(0)
	s_barrier
; #define PG8_STAGE(bufoff, gbase, voff) do { _Pragma("unroll") for (int _i = 0; _i < 2; ++_i) \
;         __builtin_amdgcn_global_load_lds((const unsigned*)((const char*)(gbase) + (voff)[_i]), (PG8_LAS unsigned*)(lds + (bufoff) + ldsw + _i * 8192), 16, 0, 0); } while (0)
; #define PG8_LDA(dst, b, h) do { _Pragma("unroll") for (int m = 0; m < 4; ++m) _Pragma("unroll") for (int k = 0; k < 2; ++k) dst[m][k] = *(const PG8_LAS bf16x8*)(lds + PG8_SA(b, h) + aoff + m * 2048 + k * 1024); } while (0)
; #define PG8_LDB(dst, b, h) do { _Pragma("unroll") for (int n = 0; n < 2; ++n) _Pragma("unroll") for (int k = 0; k < 2; ++k) dst[n][k] = *(const PG8_LAS bf16x8*)(lds + PG8_SB(b, h) + boff + n * 2048 + k * 1024); } while (0)
; #define PG8_MMA(ai, bj, At, Bt) do { __builtin_amdgcn_s_setprio(1); _Pragma("unroll") for (int m = 0; m < 4; ++m) _Pragma("unroll") for (int n = 0; n < 2; ++n) _Pragma("unroll") for (int k = 0; k < 2; ++k) \
;         acc[ai][bj][m][n] = __builtin_amdgcn_mfma_f32_16x16x32_bf16(Bt[n][k], At[m][k], acc[ai][bj][m][n], 0, 0, 0); __builtin_amdgcn_s_setprio(0); } while (0)
; #define PG8_WAIT_V(n) asm volatile("s_waitcnt vmcnt(" #n ")" ::: "memory")
; #define PG8_WAIT_L(n) asm volatile("s_waitcnt lgkmcnt(" #n ")" ::: "memory")
; #define PG8_BAR __builtin_amdgcn_s_barrier()
; #define PG8_SCHED __builtin_amdgcn_sched_barrier(0)
; template <class Epi, class Sched, bool ALIGN_EPI = false, bool SP2 = false>
; __device__ __forceinline__ void gemm_phase(PG8_LAS unsigned char* lds, const Gemm g, const Sched& S, const Epi& E, const int wave_in) {
;     ...
;             PG8_WAIT_V(8); PG8_WAIT_L(0); PG8_BAR; PG8_MMA(1, 0, At, B0); PG8_MMA(1, 1, At, B1); PG8_BAR; PG8_SCHED;
;             PG8_LDB(B0, 1, 0); PG8_LDB(B1, 1, 1); PG8_SCHED; PG8_LDA(At, 1, 0); PG8_STAGE(PG8_SA(0, 1), a2 + hstepA, voffA);
;             PG8_WAIT_V(8); PG8_WAIT_L(0); PG8_BAR; PG8_MMA(0, 0, At, B0); PG8_MMA(0, 1, At, B1); PG8_BAR; PG8_SCHED;
	s_setprio 1
	s_waitcnt lgkmcnt(0)
	v_mfma_f32_16x16x32_bf16 v[60:63], v[64:67], v[178:181], 0
	v_mfma_f32_16x16x32_bf16 v[56:59], v[72:75], v[178:181], 0
	v_mfma_f32_16x16x32_bf16 v[48:51], v[64:67], v[186:189], 0
	v_mfma_f32_16x16x32_bf16 v[40:43], v[72:75], v[186:189], 0
	v_mfma_f32_16x16x32_bf16 v[32:35], v[64:67], v[194:197], 0
	v_mfma_f32_16x16x32_bf16 v[24:27], v[72:75], v[194:197], 0
	v_mfma_f32_16x16x32_bf16 v[16:19], v[64:67], v[202:205], 0
	v_mfma_f32_16x16x32_bf16 v[8:11], v[72:75], v[202:205], 0
	v_mfma_f32_16x16x32_bf16 v[60:63], v[68:71], v[182:185], v[60:63]
	v_mfma_f32_16x16x32_bf16 v[56:59], v[76:79], v[182:185], v[56:59]
	v_mfma_f32_16x16x32_bf16 v[48:51], v[68:71], v[190:193], v[48:51]
	v_mfma_f32_16x16x32_bf16 v[40:43], v[76:79], v[190:193], v[40:43]
	v_mfma_f32_16x16x32_bf16 v[32:35], v[68:71], v[198:201], v[32:35]
	v_mfma_f32_16x16x32_bf16 v[24:27], v[76:79], v[198:201], v[24:27]
	v_mfma_f32_16x16x32_bf16 v[16:19], v[68:71], v[206:209], v[16:19]
	v_mfma_f32_16x16x32_bf16 v[8:11], v[76:79], v[206:209], v[8:11]
	s_setprio 0
	s_setprio 1
	v_mfma_f32_16x16x32_bf16 v[52:55], v[144:147], v[178:181], 0
	v_mfma_f32_16x16x32_bf16 v[44:47], v[170:173], v[178:181], 0
	v_mfma_f32_16x16x32_bf16 v[36:39], v[144:147], v[186:189], 0
	v_mfma_f32_16x16x32_bf16 v[28:31], v[170:173], v[186:189], 0
	v_mfma_f32_16x16x32_bf16 v[20:23], v[144:147], v[194:197], 0
	v_mfma_f32_16x16x32_bf16 v[12:15], v[170:173], v[194:197], 0
	v_mfma_f32_16x16x32_bf16 v[4:7], v[144:147], v[202:205], 0
	v_mfma_f32_16x16x32_bf16 v[0:3], v[170:173], v[202:205], 0
	v_mfma_f32_16x16x32_bf16 v[52:55], v[148:151], v[182:185], v[52:55]
	v_mfma_f32_16x16x32_bf16 v[44:47], v[174:177], v[182:185], v[44:47]
	v_mfma_f32_16x16x32_bf16 v[36:39], v[148:151], v[190:193], v[36:39]
	v_mfma_f32_16x16x32_bf16 v[28:31], v[174:177], v[190:193], v[28:31]
	v_mfma_f32_16x16x32_bf16 v[20:23], v[148:151], v[198:201], v[20:23]
	v_mfma_f32_16x16x32_bf16 v[12:15], v[174:177], v[198:201], v[12:15]
	v_mfma_f32_16x16x32_bf16 v[4:7], v[148:151], v[206:209], v[4:7]
	v_mfma_f32_16x16x32_bf16 v[0:3], v[174:177], v[206:209], v[0:3]
	s_setprio 0
	s_barrier
	s_add_i32 s54, 0, 0x18000
	s_add_i32 s55, 0, 0x1c000
	v_add_u32_e32 v76, s54, v228
	v_add_u32_e32 v174, s55, v228
	ds_read_b128 v[64:67], v76
	ds_read_b128 v[68:71], v76 offset:1024
	ds_read_b128 v[72:75], v76 offset:2048
	ds_read_b128 v[76:79], v76 offset:3072
	ds_read_b128 v[144:147], v174
	ds_read_b128 v[148:151], v174 offset:1024
	ds_read_b128 v[170:173], v174 offset:2048
	ds_read_b128 v[174:177], v174 offset:3072
	s_add_u32 s18, s24, 0x158000
	s_addc_u32 s19, s25, 0
	s_mov_b32 m0, s37
	v_lshl_add_u64 v[218:219], s[18:19], 0, v[158:159]
	ds_read_b128 v[178:181], v232 offset:32768
	ds_read_b128 v[182:185], v232 offset:33792
	ds_read_b128 v[186:189], v232 offset:34816
	ds_read_b128 v[190:193], v232 offset:35840
	ds_read_b128 v[194:197], v232 offset:36864
	ds_read_b128 v[198:201], v232 offset:37888
	ds_read_b128 v[202:205], v232 offset:38912
	ds_read_b128 v[206:209], v232 offset:39936
	global_load_lds_dwordx4 v[218:219], off
	v_lshl_add_u64 v[218:219], s[18:19], 0, v[154:155]
	s_mov_b32 m0, s38
	s_nop 0
	global_load_lds_dwordx4 v[218:219], off
	s_waitcnt vmcnt(8)
	s_waitcnt lgkmcnt(0)
	s_barrier
	s_setprio 1
	s_waitcnt lgkmcnt(0)
	v_mfma_f32_16x16x32_bf16 v[140:143], v[64:67], v[178:181], v[140:143]
	v_mfma_f32_16x16x32_bf16 v[136:139], v[72:75], v[178:181], v[136:139]
	v_mfma_f32_16x16x32_bf16 v[128:131], v[64:67], v[186:189], v[128:131]
	v_mfma_f32_16x16x32_bf16 v[120:123], v[72:75], v[186:189], v[120:123]
	v_mfma_f32_16x16x32_bf16 v[116:119], v[64:67], v[194:197], v[116:119]
	v_mfma_f32_16x16x32_bf16 v[112:115], v[72:75], v[194:197], v[112:115]
	v_mfma_f32_16x16x32_bf16 v[100:103], v[64:67], v[202:205], v[100:103]
	v_mfma_f32_16x16x32_bf16 v[96:99], v[72:75], v[202:205], v[96:99]
	v_mfma_f32_16x16x32_bf16 v[140:143], v[68:71], v[182:185], v[140:143]
	v_mfma_f32_16x16x32_bf16 v[136:139], v[76:79], v[182:185], v[136:139]
	v_mfma_f32_16x16x32_bf16 v[128:131], v[68:71], v[190:193], v[128:131]
	v_mfma_f32_16x16x32_bf16 v[120:123], v[76:79], v[190:193], v[120:123]
	v_mfma_f32_16x16x32_bf16 v[116:119], v[68:71], v[198:201], v[116:119]
	v_mfma_f32_16x16x32_bf16 v[112:115], v[76:79], v[198:201], v[112:115]
	v_mfma_f32_16x16x32_bf16 v[100:103], v[68:71], v[206:209], v[100:103]
	v_mfma_f32_16x16x32_bf16 v[96:99], v[76:79], v[206:209], v[96:99]
	s_setprio 0
	s_setprio 1
	v_mfma_f32_16x16x32_bf16 v[132:135], v[144:147], v[178:181], v[132:135]
	v_mfma_f32_16x16x32_bf16 v[124:127], v[170:173], v[178:181], v[124:127]
	v_mfma_f32_16x16x32_bf16 v[108:111], v[144:147], v[186:189], v[108:111]
	v_mfma_f32_16x16x32_bf16 v[104:107], v[170:173], v[186:189], v[104:107]
	v_mfma_f32_16x16x32_bf16 v[92:95], v[144:147], v[194:197], v[92:95]
	v_mfma_f32_16x16x32_bf16 v[88:91], v[170:173], v[194:197], v[88:91]
	v_mfma_f32_16x16x32_bf16 v[84:87], v[144:147], v[202:205], v[84:87]
	v_mfma_f32_16x16x32_bf16 v[80:83], v[170:173], v[202:205], v[80:83]
	v_mfma_f32_16x16x32_bf16 v[132:135], v[148:151], v[182:185], v[132:135]
	v_mfma_f32_16x16x32_bf16 v[124:127], v[174:177], v[182:185], v[124:127]
	v_mfma_f32_16x16x32_bf16 v[108:111], v[148:151], v[190:193], v[108:111]
	v_mfma_f32_16x16x32_bf16 v[104:107], v[174:177], v[190:193], v[104:107]
	v_mfma_f32_16x16x32_bf16 v[92:95], v[148:151], v[198:201], v[92:95]
	v_mfma_f32_16x16x32_bf16 v[88:91], v[174:177], v[198:201], v[88:91]
	v_mfma_f32_16x16x32_bf16 v[84:87], v[148:151], v[206:209], v[84:87]
	v_mfma_f32_16x16x32_bf16 v[80:83], v[174:177], v[206:209], v[80:83]
	s_setprio 0
	s_barrier
; #define PG8_STAGE(bufoff, gbase, voff) do { _Pragma("unroll") for (int _i = 0; _i < 2; ++_i) \
;         __builtin_amdgcn_global_load_lds((const unsigned*)((const char*)(gbase) + (voff)[_i]), (PG8_LAS unsigned*)(lds + (bufoff) + ldsw + _i * 8192), 16, 0, 0); } while (0)
; #define PG8_LDA(dst, b, h) do { _Pragma("unroll") for (int m = 0; m < 4; ++m) _Pragma("unroll") for (int k = 0; k < 2; ++k) dst[m][k] = *(const PG8_LAS bf16x8*)(lds + PG8_SA(b, h) + aoff + m * 2048 + k * 1024); } while (0)
; #define PG8_MMA(ai, bj, At, Bt) do { __builtin_amdgcn_s_setprio(1); _Pragma("unroll") for (int m = 0; m < 4; ++m) _Pragma("unroll") for (int n = 0; n < 2; ++n) _Pragma("unroll") for (int k = 0; k < 2; ++k) \
;         acc[ai][bj][m][n] = __builtin_amdgcn_mfma_f32_16x16x32_bf16(Bt[n][k], At[m][k], acc[ai][bj][m][n], 0, 0, 0); __builtin_amdgcn_s_setprio(0); } while (0)
; #define PG8_WAIT_V(n) asm volatile("s_waitcnt vmcnt(" #n ")" ::: "memory")
; #define PG8_WAIT_L(n) asm volatile("s_waitcnt lgkmcnt(" #n ")" ::: "memory")
; #define PG8_BAR __builtin_amdgcn_s_barrier()
; #define PG8_SCHED __builtin_amdgcn_sched_barrier(0)
; template <class Epi, class Sched, bool ALIGN_EPI = false, bool SP2 = false>
; __device__ __forceinline__ void gemm_phase(PG8_LAS unsigned char* lds, const Gemm g, const Sched& S, const Epi& E, const int wave_in) {
;     ...
;             PG8_LDA(At, 1, 1); PG8_STAGE(PG8_SB(1, 0), b3, voffB); PG8_STAGE(PG8_SB(1, 1), b3 + hstepB, voffB); PG8_STAGE(PG8_SA(1, 0), a3, voffA);
;             PG8_WAIT_V(8); PG8_WAIT_L(0); PG8_BAR; PG8_MMA(1, 0, At, B0); PG8_MMA(1, 1, At, B1); PG8_BAR; PG8_SCHED;
	s_add_i32 s18, s54, s30
	v_lshl_add_u64 v[210:211], v[210:211], 0, s[6:7]
	s_mov_b32 m0, s18
	ds_read_b128 v[178:181], v232 offset:49152
	ds_read_b128 v[182:185], v232 offset:50176
	ds_read_b128 v[186:189], v232 offset:51200
	ds_read_b128 v[190:193], v232 offset:52224
	ds_read_b128 v[194:197], v232 offset:53248
	ds_read_b128 v[198:201], v232 offset:54272
	ds_read_b128 v[202:205], v232 offset:55296
	ds_read_b128 v[206:209], v232 offset:56320
	global_load_lds_dwordx4 v[210:211], off
	s_add_i32 m0, s18, 0x2000
	s_add_u32 s18, s22, 0x158080
	v_lshl_add_u64 v[210:211], v[212:213], 0, s[6:7]
	s_addc_u32 s19, s23, 0
	s_add_i32 s22, s55, s30
	global_load_lds_dwordx4 v[210:211], off
	v_lshl_add_u64 v[210:211], s[18:19], 0, v[156:157]
	s_mov_b32 m0, s22
	s_nop 0
	global_load_lds_dwordx4 v[210:211], off
	v_lshl_add_u64 v[210:211], s[18:19], 0, v[152:153]
	s_add_i32 m0, s22, 0x2000
	s_nop 0
	global_load_lds_dwordx4 v[210:211], off
	v_lshl_add_u64 v[210:211], v[214:215], 0, s[6:7]
	s_mov_b32 m0, s42
	s_nop 0
	global_load_lds_dwordx4 v[210:211], off
	v_lshl_add_u64 v[210:211], v[216:217], 0, s[6:7]
	s_mov_b32 m0, s43
	s_nop 0
	global_load_lds_dwordx4 v[210:211], off
	s_waitcnt vmcnt(8)
	s_waitcnt lgkmcnt(0)
	s_barrier
	s_setprio 1
	s_waitcnt lgkmcnt(0)
	v_mfma_f32_16x16x32_bf16 v[60:63], v[64:67], v[178:181], v[60:63]
	v_mfma_f32_16x16x32_bf16 v[56:59], v[72:75], v[178:181], v[56:59]
	v_mfma_f32_16x16x32_bf16 v[48:51], v[64:67], v[186:189], v[48:51]
	v_mfma_f32_16x16x32_bf16 v[40:43], v[72:75], v[186:189], v[40:43]
	v_mfma_f32_16x16x32_bf16 v[32:35], v[64:67], v[194:197], v[32:35]
	v_mfma_f32_16x16x32_bf16 v[24:27], v[72:75], v[194:197], v[24:27]
	v_mfma_f32_16x16x32_bf16 v[16:19], v[64:67], v[202:205], v[16:19]
	v_mfma_f32_16x16x32_bf16 v[8:11], v[72:75], v[202:205], v[8:11]
	v_mfma_f32_16x16x32_bf16 v[60:63], v[68:71], v[182:185], v[60:63]
	v_mfma_f32_16x16x32_bf16 v[56:59], v[76:79], v[182:185], v[56:59]
	v_mfma_f32_16x16x32_bf16 v[48:51], v[68:71], v[190:193], v[48:51]
	v_mfma_f32_16x16x32_bf16 v[40:43], v[76:79], v[190:193], v[40:43]
	v_mfma_f32_16x16x32_bf16 v[32:35], v[68:71], v[198:201], v[32:35]
	v_mfma_f32_16x16x32_bf16 v[24:27], v[76:79], v[198:201], v[24:27]
	v_mfma_f32_16x16x32_bf16 v[16:19], v[68:71], v[206:209], v[16:19]
	v_mfma_f32_16x16x32_bf16 v[8:11], v[76:79], v[206:209], v[8:11]
	s_setprio 0
	s_setprio 1
	v_mfma_f32_16x16x32_bf16 v[52:55], v[144:147], v[178:181], v[52:55]
	v_mfma_f32_16x16x32_bf16 v[44:47], v[170:173], v[178:181], v[44:47]
	v_mfma_f32_16x16x32_bf16 v[36:39], v[144:147], v[186:189], v[36:39]
	v_mfma_f32_16x16x32_bf16 v[28:31], v[170:173], v[186:189], v[28:31]
	v_mfma_f32_16x16x32_bf16 v[20:23], v[144:147], v[194:197], v[20:23]
	v_mfma_f32_16x16x32_bf16 v[12:15], v[170:173], v[194:197], v[12:15]
	v_mfma_f32_16x16x32_bf16 v[4:7], v[144:147], v[202:205], v[4:7]
	v_mfma_f32_16x16x32_bf16 v[0:3], v[170:173], v[202:205], v[0:3]
	v_mfma_f32_16x16x32_bf16 v[52:55], v[148:151], v[182:185], v[52:55]
	v_mfma_f32_16x16x32_bf16 v[44:47], v[174:177], v[182:185], v[44:47]
	v_mfma_f32_16x16x32_bf16 v[36:39], v[148:151], v[190:193], v[36:39]
	v_mfma_f32_16x16x32_bf16 v[28:31], v[174:177], v[190:193], v[28:31]
	v_mfma_f32_16x16x32_bf16 v[20:23], v[148:151], v[198:201], v[20:23]
	v_mfma_f32_16x16x32_bf16 v[12:15], v[174:177], v[198:201], v[12:15]
	v_mfma_f32_16x16x32_bf16 v[4:7], v[148:151], v[206:209], v[4:7]
	v_mfma_f32_16x16x32_bf16 v[0:3], v[174:177], v[206:209], v[0:3]
	s_setprio 0
	s_barrier
	s_add_i32 s53, s53, 2
	s_add_u32 s17, s17, 0x100
	s_addc_u32 s52, s52, 0
	s_cmpk_gt_u32 s53, 0x53
	s_mov_b64 s[18:19], s[20:21]
	s_cbranch_scc0 .LBB0_635
	s_branch .Lkx_8

; #define PG8_BAR __builtin_amdgcn_s_barrier()
; template <class Epi, class Sched, bool ALIGN_EPI = false, bool SP2 = false>
; __device__ __forceinline__ void gemm_phase(PG8_LAS unsigned char* lds, const Gemm g, const Sched& S, const Epi& E, const int wave_in) {
;     ...
;         if constexpr (ALIGN_EPI) { if (wr == 0) PG8_BAR; }
.Lkx_8:
	s_and_b64 vcc, exec, s[8:9]
	s_cbranch_vccz .LBB0_638
	s_barrier

;     __host__ __device__ bool next(int i, Unit& u) const { const bool ok = StaticOrder::next(i, u); u.pm = 0; u.pn = 0; return ok; }
; #define PG8_STAGE(bufoff, gbase, voff) do { _Pragma("unroll") for (int _i = 0; _i < 2; ++_i) \
;         __builtin_amdgcn_global_load_lds((const unsigned*)((const char*)(gbase) + (voff)[_i]), (PG8_LAS unsigned*)(lds + (bufoff) + ldsw + _i * 8192), 16, 0, 0); } while (0)
; #define PG8_LDA(dst, b, h) do { _Pragma("unroll") for (int m = 0; m < 4; ++m) _Pragma("unroll") for (int k = 0; k < 2; ++k) dst[m][k] = *(const PG8_LAS bf16x8*)(lds + PG8_SA(b, h) + aoff + m * 2048 + k * 1024); } while (0)
; #define PG8_LDB(dst, b, h) do { _Pragma("unroll") for (int n = 0; n < 2; ++n) _Pragma("unroll") for (int k = 0; k < 2; ++k) dst[n][k] = *(const PG8_LAS bf16x8*)(lds + PG8_SB(b, h) + boff + n * 2048 + k * 1024); } while (0)
; #define PG8_WAIT_V(n) asm volatile("s_waitcnt vmcnt(" #n ")" ::: "memory")
; #define PG8_BAR __builtin_amdgcn_s_barrier()
; template <class Epi, class Sched, bool ALIGN_EPI = false, bool SP2 = false>
; __device__ __forceinline__ void gemm_phase(PG8_LAS unsigned char* lds, const Gemm g, const Sched& S, const Epi& E, const int wave_in) {
;     ...
;         const bool has_next = S.next(ui + 1, nxt);
;         const char* nA = has_next ? (const char*)g.A + (size_t)nxt.pm * tstepA : cA; const char* nB = has_next ? (const char*)g.Bt + (size_t)nxt.pn * tstepB : cB;
;         for (int t = 0; t < nt; t += 2) {
;             const bool last = (t == nt - 2);
;             const char* a1 = cA + (size_t)(t + 1) * kstep;
;             const char* a2 = last ? nA : cA + (size_t)(t + 2) * kstep; const char* b2 = last ? nB : cB + (size_t)(t + 2) * kstep;
;             const char* a3 = a2 + kstep; const char* b3 = b2 + kstep;
;             if (last && has_next) S.a_ready(nxt);
;             if constexpr (SP2) {
;             PG8_LDB(B0, 0, 0); PG8_LDB(B1, 0, 1); PG8_SCHED; PG8_LDA(At, 0, 0); PG8_STAGE(PG8_SA(1, 1), a1 + hstepA, voffA);
;             PG8_WAIT_V(8); PG8_WAIT_L(0); PG8_BAR; PG8_MMA(0, 0, At, B0); PG8_MMA(0, 1, At, B1); PG8_BAR; PG8_SCHED;
;             PG8_LDA(At, 0, 1); PG8_STAGE(PG8_SB(0, 0), b2, voffB); PG8_STAGE(PG8_SB(0, 1), b2 + hstepB, voffB); PG8_STAGE(PG8_SA(0, 0), a2, voffA);
;             PG8_WAIT_V(8); PG8_WAIT_L(0); PG8_BAR; PG8_MMA(1, 0, At, B0); PG8_MMA(1, 1, At, B1); PG8_BAR; PG8_SCHED;
.LBB0_1092:
	s_ashr_i32 s15, s14, 31
	s_lshl_b64 s[18:19], s[14:15], 21
	s_add_u32 s18, s30, s18
	s_addc_u32 s19, s31, s19
	s_and_b64 s[4:5], s[4:5], exec
	s_cselect_b32 s15, s19, s25
	s_cselect_b32 s21, s18, s24
	s_add_u32 s53, s24, 0x100
	v_mov_b32_e32 v0, 0
	s_addc_u32 s54, s25, 0
	s_mov_b32 s55, -2
	ds_read_b128 v[128:131], v214
	ds_read_b128 v[132:135], v214 offset:1024
	ds_read_b128 v[136:139], v214 offset:2048
	ds_read_b128 v[140:143], v214 offset:3072
	ds_read_b128 v[162:165], v215
	ds_read_b128 v[166:169], v215 offset:1024
	ds_read_b128 v[170:173], v215 offset:2048
	ds_read_b128 v[174:177], v215 offset:3072
	s_add_u32 s4, s22, 0x100
	s_addc_u32 s5, s23, 0
	s_cmp_eq_u32 s55, 60
	s_cselect_b32 s27, s17, s5
	s_cselect_b32 s26, s16, s4
	s_cselect_b32 s25, s15, s54
	s_cselect_b32 s24, s21, s53
	v_lshl_add_u64 v[210:211], s[22:23], 0, v[154:155]
	s_add_i32 m0, s37, 0xc000
	ds_read_b128 v[178:181], v216
	ds_read_b128 v[182:185], v216 offset:1024
	ds_read_b128 v[186:189], v216 offset:2048
	ds_read_b128 v[190:193], v216 offset:3072
	ds_read_b128 v[194:197], v216 offset:4096
	ds_read_b128 v[198:201], v216 offset:5120
	ds_read_b128 v[202:205], v216 offset:6144
	ds_read_b128 v[206:209], v216 offset:7168
	global_load_lds_dwordx4 v[210:211], off
	v_lshl_add_u64 v[210:211], s[22:23], 0, v[156:157]
	s_add_i32 m0, s37, 0xe000
	s_nop 0
	global_load_lds_dwordx4 v[210:211], off
	s_waitcnt vmcnt(8)
	s_waitcnt lgkmcnt(0)
	s_barrier
	s_setprio 1
	s_waitcnt lgkmcnt(0)
	v_mfma_f32_16x16x32_bf16 v[124:127], v[128:131], v[178:181], 0
	v_mfma_f32_16x16x32_bf16 v[120:123], v[136:139], v[178:181], 0
	v_mfma_f32_16x16x32_bf16 v[112:115], v[128:131], v[186:189], 0
	v_mfma_f32_16x16x32_bf16 v[104:107], v[136:139], v[186:189], 0
	v_mfma_f32_16x16x32_bf16 v[100:103], v[128:131], v[194:197], 0
	v_mfma_f32_16x16x32_bf16 v[96:99], v[136:139], v[194:197], 0
	v_mfma_f32_16x16x32_bf16 v[76:79], v[128:131], v[202:205], 0
	v_mfma_f32_16x16x32_bf16 v[72:75], v[136:139], v[202:205], 0
	v_mfma_f32_16x16x32_bf16 v[124:127], v[132:135], v[182:185], v[124:127]
	v_mfma_f32_16x16x32_bf16 v[120:123], v[140:143], v[182:185], v[120:123]
	v_mfma_f32_16x16x32_bf16 v[112:115], v[132:135], v[190:193], v[112:115]
	v_mfma_f32_16x16x32_bf16 v[104:107], v[140:143], v[190:193], v[104:107]
	v_mfma_f32_16x16x32_bf16 v[100:103], v[132:135], v[198:201], v[100:103]
	v_mfma_f32_16x16x32_bf16 v[96:99], v[140:143], v[198:201], v[96:99]
	v_mfma_f32_16x16x32_bf16 v[76:79], v[132:135], v[206:209], v[76:79]
	v_mfma_f32_16x16x32_bf16 v[72:75], v[140:143], v[206:209], v[72:75]
	s_setprio 0
	s_setprio 1
	v_mfma_f32_16x16x32_bf16 v[116:119], v[162:165], v[178:181], 0
	v_mfma_f32_16x16x32_bf16 v[108:111], v[170:173], v[178:181], 0
	v_mfma_f32_16x16x32_bf16 v[92:95], v[162:165], v[186:189], 0
	v_mfma_f32_16x16x32_bf16 v[88:91], v[170:173], v[186:189], 0
	v_mfma_f32_16x16x32_bf16 v[84:87], v[162:165], v[194:197], 0
	v_mfma_f32_16x16x32_bf16 v[80:83], v[170:173], v[194:197], 0
	v_mfma_f32_16x16x32_bf16 v[68:71], v[162:165], v[202:205], 0
	v_mfma_f32_16x16x32_bf16 v[64:67], v[170:173], v[202:205], 0
	v_mfma_f32_16x16x32_bf16 v[116:119], v[166:169], v[182:185], v[116:119]
	v_mfma_f32_16x16x32_bf16 v[108:111], v[174:177], v[182:185], v[108:111]
	v_mfma_f32_16x16x32_bf16 v[92:95], v[166:169], v[190:193], v[92:95]
	v_mfma_f32_16x16x32_bf16 v[88:91], v[174:177], v[190:193], v[88:91]
	v_mfma_f32_16x16x32_bf16 v[84:87], v[166:169], v[198:201], v[84:87]
	v_mfma_f32_16x16x32_bf16 v[80:83], v[174:177], v[198:201], v[80:83]
	v_mfma_f32_16x16x32_bf16 v[68:71], v[166:169], v[206:209], v[68:71]
	v_mfma_f32_16x16x32_bf16 v[64:67], v[174:177], v[206:209], v[64:67]
	s_setprio 0
	s_barrier
	s_add_i32 s22, s47, s34
	v_lshl_add_u64 v[210:211], s[24:25], 0, v[148:149]
	s_mov_b32 m0, s22
	ds_read_b128 v[178:181], v216 offset:16384
	ds_read_b128 v[182:185], v216 offset:17408
	ds_read_b128 v[186:189], v216 offset:18432
	ds_read_b128 v[190:193], v216 offset:19456
	ds_read_b128 v[194:197], v216 offset:20480
	ds_read_b128 v[198:201], v216 offset:21504
	ds_read_b128 v[202:205], v216 offset:22528
	ds_read_b128 v[206:209], v216 offset:23552
	global_load_lds_dwordx4 v[210:211], off
	s_add_i32 m0, s22, 0x2000
	s_add_u32 s22, s24, 0x100000
	v_lshl_add_u64 v[218:219], s[24:25], 0, v[144:145]
	s_addc_u32 s23, s25, 0
	s_add_i32 s56, s48, s34
	global_load_lds_dwordx4 v[218:219], off
	v_lshl_add_u64 v[220:221], s[22:23], 0, v[148:149]
	s_mov_b32 m0, s56
	v_lshl_add_u64 v[222:223], s[26:27], 0, v[146:147]
	global_load_lds_dwordx4 v[220:221], off
	v_lshl_add_u64 v[220:221], s[22:23], 0, v[144:145]
	s_add_i32 m0, s56, 0x2000
	s_nop 0
	global_load_lds_dwordx4 v[220:221], off
	v_lshl_add_u64 v[220:221], s[26:27], 0, v[150:151]
	s_mov_b32 m0, s37
	s_nop 0
	global_load_lds_dwordx4 v[220:221], off
	s_mov_b32 m0, s38
	s_nop 0
	global_load_lds_dwordx4 v[222:223], off
	s_waitcnt vmcnt(8)
	s_waitcnt lgkmcnt(0)
	s_barrier
; #define PG8_STAGE(bufoff, gbase, voff) do { _Pragma("unroll") for (int _i = 0; _i < 2; ++_i) \
;         __builtin_amdgcn_global_load_lds((const unsigned*)((const char*)(gbase) + (voff)[_i]), (PG8_LAS unsigned*)(lds + (bufoff) + ldsw + _i * 8192), 16, 0, 0); } while (0)
; #define PG8_LDA(dst, b, h) do { _Pragma("unroll") for (int m = 0; m < 4; ++m) _Pragma("unroll") for (int k = 0; k < 2; ++k) dst[m][k] = *(const PG8_LAS bf16x8*)(lds + PG8_SA(b, h) + aoff + m * 2048 + k * 1024); } while (0)
; #define PG8_LDB(dst, b, h) do { _Pragma("unroll") for (int n = 0; n < 2; ++n) _Pragma("unroll") for (int k = 0; k < 2; ++k) dst[n][k] = *(const PG8_LAS bf16x8*)(lds + PG8_SB(b, h) + boff + n * 2048 + k * 1024); } while (0)
; #define PG8_MMA(ai, bj, At, Bt) do { __builtin_amdgcn_s_setprio(1); _Pragma("unroll") for (int m = 0; m < 4; ++m) _Pragma("unroll") for (int n = 0; n < 2; ++n) _Pragma("unroll") for (int k = 0; k < 2; ++k) \
;         acc[ai][bj][m][n] = __builtin_amdgcn_mfma_f32_16x16x32_bf16(Bt[n][k], At[m][k], acc[ai][bj][m][n], 0, 0, 0); __builtin_amdgcn_s_setprio(0); } while (0)
; #define PG8_WAIT_V(n) asm volatile("s_waitcnt vmcnt(" #n ")" ::: "memory")
; #define PG8_WAIT_L(n) asm volatile("s_waitcnt lgkmcnt(" #n ")" ::: "memory")
; #define PG8_BAR __builtin_amdgcn_s_barrier()
; #define PG8_SCHED __builtin_amdgcn_sched_barrier(0)
; template <class Epi, class Sched, bool ALIGN_EPI = false, bool SP2 = false>
; __device__ __forceinline__ void gemm_phase(PG8_LAS unsigned char* lds, const Gemm g, const Sched& S, const Epi& E, const int wave_in) {
;     ...
;             PG8_WAIT_V(8); PG8_WAIT_L(0); PG8_BAR; PG8_MMA(1, 0, At, B0); PG8_MMA(1, 1, At, B1); PG8_BAR; PG8_SCHED;
;             PG8_LDB(B0, 1, 0); PG8_LDB(B1, 1, 1); PG8_SCHED; PG8_LDA(At, 1, 0); PG8_STAGE(PG8_SA(0, 1), a2 + hstepA, voffA);
;             PG8_WAIT_V(8); PG8_WAIT_L(0); PG8_BAR; PG8_MMA(0, 0, At, B0); PG8_MMA(0, 1, At, B1); PG8_BAR; PG8_SCHED;
	s_setprio 1
	s_waitcnt lgkmcnt(0)
	v_mfma_f32_16x16x32_bf16 v[60:63], v[128:131], v[178:181], 0
	v_mfma_f32_16x16x32_bf16 v[56:59], v[136:139], v[178:181], 0
	v_mfma_f32_16x16x32_bf16 v[48:51], v[128:131], v[186:189], 0
	v_mfma_f32_16x16x32_bf16 v[40:43], v[136:139], v[186:189], 0
	v_mfma_f32_16x16x32_bf16 v[32:35], v[128:131], v[194:197], 0
	v_mfma_f32_16x16x32_bf16 v[24:27], v[136:139], v[194:197], 0
	v_mfma_f32_16x16x32_bf16 v[16:19], v[128:131], v[202:205], 0
	v_mfma_f32_16x16x32_bf16 v[8:11], v[136:139], v[202:205], 0
	v_mfma_f32_16x16x32_bf16 v[60:63], v[132:135], v[182:185], v[60:63]
	v_mfma_f32_16x16x32_bf16 v[56:59], v[140:143], v[182:185], v[56:59]
	v_mfma_f32_16x16x32_bf16 v[48:51], v[132:135], v[190:193], v[48:51]
	v_mfma_f32_16x16x32_bf16 v[40:43], v[140:143], v[190:193], v[40:43]
	v_mfma_f32_16x16x32_bf16 v[32:35], v[132:135], v[198:201], v[32:35]
	v_mfma_f32_16x16x32_bf16 v[24:27], v[140:143], v[198:201], v[24:27]
	v_mfma_f32_16x16x32_bf16 v[16:19], v[132:135], v[206:209], v[16:19]
	v_mfma_f32_16x16x32_bf16 v[8:11], v[140:143], v[206:209], v[8:11]
	s_setprio 0
	s_setprio 1
	v_mfma_f32_16x16x32_bf16 v[52:55], v[162:165], v[178:181], 0
	v_mfma_f32_16x16x32_bf16 v[44:47], v[170:173], v[178:181], 0
	v_mfma_f32_16x16x32_bf16 v[36:39], v[162:165], v[186:189], 0
	v_mfma_f32_16x16x32_bf16 v[28:31], v[170:173], v[186:189], 0
	v_mfma_f32_16x16x32_bf16 v[20:23], v[162:165], v[194:197], 0
	v_mfma_f32_16x16x32_bf16 v[12:15], v[170:173], v[194:197], 0
	v_mfma_f32_16x16x32_bf16 v[4:7], v[162:165], v[202:205], 0
	v_mfma_f32_16x16x32_bf16 v[0:3], v[170:173], v[202:205], 0
	v_mfma_f32_16x16x32_bf16 v[52:55], v[166:169], v[182:185], v[52:55]
	v_mfma_f32_16x16x32_bf16 v[44:47], v[174:177], v[182:185], v[44:47]
	v_mfma_f32_16x16x32_bf16 v[36:39], v[166:169], v[190:193], v[36:39]
	v_mfma_f32_16x16x32_bf16 v[28:31], v[174:177], v[190:193], v[28:31]
	v_mfma_f32_16x16x32_bf16 v[20:23], v[166:169], v[198:201], v[20:23]
	v_mfma_f32_16x16x32_bf16 v[12:15], v[174:177], v[198:201], v[12:15]
	v_mfma_f32_16x16x32_bf16 v[4:7], v[166:169], v[206:209], v[4:7]
	v_mfma_f32_16x16x32_bf16 v[0:3], v[174:177], v[206:209], v[0:3]
	s_setprio 0
	s_barrier
	s_add_i32 s56, 0, 0x18000
	s_add_i32 s57, 0, 0x1c000
	v_add_u32_e32 v140, s56, v212
	v_add_u32_e32 v174, s57, v212
	ds_read_b128 v[128:131], v140
	ds_read_b128 v[132:135], v140 offset:1024
	ds_read_b128 v[136:139], v140 offset:2048
	ds_read_b128 v[140:143], v140 offset:3072
	ds_read_b128 v[162:165], v174
	ds_read_b128 v[166:169], v174 offset:1024
	ds_read_b128 v[170:173], v174 offset:2048
	ds_read_b128 v[174:177], v174 offset:3072
	s_add_u32 s22, s26, 0x310000
	s_addc_u32 s23, s27, 0
	s_mov_b32 m0, s39
	v_lshl_add_u64 v[224:225], s[22:23], 0, v[150:151]
	ds_read_b128 v[178:181], v216 offset:32768
	ds_read_b128 v[182:185], v216 offset:33792
	ds_read_b128 v[186:189], v216 offset:34816
	ds_read_b128 v[190:193], v216 offset:35840
	ds_read_b128 v[194:197], v216 offset:36864
	ds_read_b128 v[198:201], v216 offset:37888
	ds_read_b128 v[202:205], v216 offset:38912
	ds_read_b128 v[206:209], v216 offset:39936
	global_load_lds_dwordx4 v[224:225], off
	v_lshl_add_u64 v[224:225], s[22:23], 0, v[146:147]
	s_mov_b32 m0, s40
	s_nop 0
	global_load_lds_dwordx4 v[224:225], off
	s_waitcnt vmcnt(8)
	s_waitcnt lgkmcnt(0)
	s_barrier
	s_setprio 1
	s_waitcnt lgkmcnt(0)
	v_mfma_f32_16x16x32_bf16 v[124:127], v[128:131], v[178:181], v[124:127]
	v_mfma_f32_16x16x32_bf16 v[120:123], v[136:139], v[178:181], v[120:123]
	v_mfma_f32_16x16x32_bf16 v[112:115], v[128:131], v[186:189], v[112:115]
	v_mfma_f32_16x16x32_bf16 v[104:107], v[136:139], v[186:189], v[104:107]
	v_mfma_f32_16x16x32_bf16 v[100:103], v[128:131], v[194:197], v[100:103]
	v_mfma_f32_16x16x32_bf16 v[96:99], v[136:139], v[194:197], v[96:99]
	v_mfma_f32_16x16x32_bf16 v[76:79], v[128:131], v[202:205], v[76:79]
	v_mfma_f32_16x16x32_bf16 v[72:75], v[136:139], v[202:205], v[72:75]
	v_mfma_f32_16x16x32_bf16 v[124:127], v[132:135], v[182:185], v[124:127]
	v_mfma_f32_16x16x32_bf16 v[120:123], v[140:143], v[182:185], v[120:123]
	v_mfma_f32_16x16x32_bf16 v[112:115], v[132:135], v[190:193], v[112:115]
	v_mfma_f32_16x16x32_bf16 v[104:107], v[140:143], v[190:193], v[104:107]
	v_mfma_f32_16x16x32_bf16 v[100:103], v[132:135], v[198:201], v[100:103]
	v_mfma_f32_16x16x32_bf16 v[96:99], v[140:143], v[198:201], v[96:99]
	v_mfma_f32_16x16x32_bf16 v[76:79], v[132:135], v[206:209], v[76:79]
	v_mfma_f32_16x16x32_bf16 v[72:75], v[140:143], v[206:209], v[72:75]
	s_setprio 0
	s_setprio 1
	v_mfma_f32_16x16x32_bf16 v[116:119], v[162:165], v[178:181], v[116:119]
	v_mfma_f32_16x16x32_bf16 v[108:111], v[170:173], v[178:181], v[108:111]
	v_mfma_f32_16x16x32_bf16 v[92:95], v[162:165], v[186:189], v[92:95]
	v_mfma_f32_16x16x32_bf16 v[88:91], v[170:173], v[186:189], v[88:91]
	v_mfma_f32_16x16x32_bf16 v[84:87], v[162:165], v[194:197], v[84:87]
	v_mfma_f32_16x16x32_bf16 v[80:83], v[170:173], v[194:197], v[80:83]
	v_mfma_f32_16x16x32_bf16 v[68:71], v[162:165], v[202:205], v[68:71]
	v_mfma_f32_16x16x32_bf16 v[64:67], v[170:173], v[202:205], v[64:67]
	v_mfma_f32_16x16x32_bf16 v[116:119], v[166:169], v[182:185], v[116:119]
	v_mfma_f32_16x16x32_bf16 v[108:111], v[174:177], v[182:185], v[108:111]
	v_mfma_f32_16x16x32_bf16 v[92:95], v[166:169], v[190:193], v[92:95]
	v_mfma_f32_16x16x32_bf16 v[88:91], v[174:177], v[190:193], v[88:91]
	v_mfma_f32_16x16x32_bf16 v[84:87], v[166:169], v[198:201], v[84:87]
	v_mfma_f32_16x16x32_bf16 v[80:83], v[174:177], v[198:201], v[80:83]
	v_mfma_f32_16x16x32_bf16 v[68:71], v[166:169], v[206:209], v[68:71]
	v_mfma_f32_16x16x32_bf16 v[64:67], v[174:177], v[206:209], v[64:67]
	s_setprio 0
	s_barrier
; #define PG8_STAGE(bufoff, gbase, voff) do { _Pragma("unroll") for (int _i = 0; _i < 2; ++_i) \
;         __builtin_amdgcn_global_load_lds((const unsigned*)((const char*)(gbase) + (voff)[_i]), (PG8_LAS unsigned*)(lds + (bufoff) + ldsw + _i * 8192), 16, 0, 0); } while (0)
; #define PG8_LDA(dst, b, h) do { _Pragma("unroll") for (int m = 0; m < 4; ++m) _Pragma("unroll") for (int k = 0; k < 2; ++k) dst[m][k] = *(const PG8_LAS bf16x8*)(lds + PG8_SA(b, h) + aoff + m * 2048 + k * 1024); } while (0)
; #define PG8_MMA(ai, bj, At, Bt) do { __builtin_amdgcn_s_setprio(1); _Pragma("unroll") for (int m = 0; m < 4; ++m) _Pragma("unroll") for (int n = 0; n < 2; ++n) _Pragma("unroll") for (int k = 0; k < 2; ++k) \
;         acc[ai][bj][m][n] = __builtin_amdgcn_mfma_f32_16x16x32_bf16(Bt[n][k], At[m][k], acc[ai][bj][m][n], 0, 0, 0); __builtin_amdgcn_s_setprio(0); } while (0)
; #define PG8_WAIT_V(n) asm volatile("s_waitcnt vmcnt(" #n ")" ::: "memory")
; #define PG8_WAIT_L(n) asm volatile("s_waitcnt lgkmcnt(" #n ")" ::: "memory")
; #define PG8_BAR __builtin_amdgcn_s_barrier()
; #define PG8_SCHED __builtin_amdgcn_sched_barrier(0)
; template <class Epi, class Sched, bool ALIGN_EPI = false, bool SP2 = false>
; __device__ __forceinline__ void gemm_phase(PG8_LAS unsigned char* lds, const Gemm g, const Sched& S, const Epi& E, const int wave_in) {
;     ...
;             PG8_LDA(At, 1, 1); PG8_STAGE(PG8_SB(1, 0), b3, voffB); PG8_STAGE(PG8_SB(1, 1), b3 + hstepB, voffB); PG8_STAGE(PG8_SA(1, 0), a3, voffA);
;             PG8_WAIT_V(8); PG8_WAIT_L(0); PG8_BAR; PG8_MMA(1, 0, At, B0); PG8_MMA(1, 1, At, B1); PG8_BAR; PG8_SCHED;
	s_add_i32 s22, s56, s34
	v_lshl_add_u64 v[210:211], v[210:211], 0, s[6:7]
	s_mov_b32 m0, s22
	ds_read_b128 v[178:181], v216 offset:49152
	ds_read_b128 v[182:185], v216 offset:50176
	ds_read_b128 v[186:189], v216 offset:51200
	ds_read_b128 v[190:193], v216 offset:52224
	ds_read_b128 v[194:197], v216 offset:53248
	ds_read_b128 v[198:201], v216 offset:54272
	ds_read_b128 v[202:205], v216 offset:55296
	ds_read_b128 v[206:209], v216 offset:56320
	global_load_lds_dwordx4 v[210:211], off
	s_add_i32 m0, s22, 0x2000
	s_add_u32 s22, s24, 0x100080
	v_lshl_add_u64 v[210:211], v[218:219], 0, s[6:7]
	s_addc_u32 s23, s25, 0
	s_add_i32 s24, s57, s34
	global_load_lds_dwordx4 v[210:211], off
	v_lshl_add_u64 v[210:211], s[22:23], 0, v[148:149]
	s_mov_b32 m0, s24
	s_nop 0
	global_load_lds_dwordx4 v[210:211], off
	v_lshl_add_u64 v[210:211], s[22:23], 0, v[144:145]
	s_add_i32 m0, s24, 0x2000
	s_nop 0
	global_load_lds_dwordx4 v[210:211], off
	v_lshl_add_u64 v[210:211], v[220:221], 0, s[6:7]
	s_mov_b32 m0, s44
	s_nop 0
	global_load_lds_dwordx4 v[210:211], off
	v_lshl_add_u64 v[210:211], v[222:223], 0, s[6:7]
	s_mov_b32 m0, s45
	s_nop 0
	global_load_lds_dwordx4 v[210:211], off
	s_waitcnt vmcnt(8)
	s_waitcnt lgkmcnt(0)
	s_barrier
	s_setprio 1
	s_waitcnt lgkmcnt(0)
	v_mfma_f32_16x16x32_bf16 v[60:63], v[128:131], v[178:181], v[60:63]
	v_mfma_f32_16x16x32_bf16 v[56:59], v[136:139], v[178:181], v[56:59]
	v_mfma_f32_16x16x32_bf16 v[48:51], v[128:131], v[186:189], v[48:51]
	v_mfma_f32_16x16x32_bf16 v[40:43], v[136:139], v[186:189], v[40:43]
	v_mfma_f32_16x16x32_bf16 v[32:35], v[128:131], v[194:197], v[32:35]
	v_mfma_f32_16x16x32_bf16 v[24:27], v[136:139], v[194:197], v[24:27]
	v_mfma_f32_16x16x32_bf16 v[16:19], v[128:131], v[202:205], v[16:19]
	v_mfma_f32_16x16x32_bf16 v[8:11], v[136:139], v[202:205], v[8:11]
	v_mfma_f32_16x16x32_bf16 v[60:63], v[132:135], v[182:185], v[60:63]
	v_mfma_f32_16x16x32_bf16 v[56:59], v[140:143], v[182:185], v[56:59]
	v_mfma_f32_16x16x32_bf16 v[48:51], v[132:135], v[190:193], v[48:51]
	v_mfma_f32_16x16x32_bf16 v[40:43], v[140:143], v[190:193], v[40:43]
	v_mfma_f32_16x16x32_bf16 v[32:35], v[132:135], v[198:201], v[32:35]
	v_mfma_f32_16x16x32_bf16 v[24:27], v[140:143], v[198:201], v[24:27]
	v_mfma_f32_16x16x32_bf16 v[16:19], v[132:135], v[206:209], v[16:19]
	v_mfma_f32_16x16x32_bf16 v[8:11], v[140:143], v[206:209], v[8:11]
	s_setprio 0
	s_setprio 1
	v_mfma_f32_16x16x32_bf16 v[52:55], v[162:165], v[178:181], v[52:55]
	v_mfma_f32_16x16x32_bf16 v[44:47], v[170:173], v[178:181], v[44:47]
	v_mfma_f32_16x16x32_bf16 v[36:39], v[162:165], v[186:189], v[36:39]
	v_mfma_f32_16x16x32_bf16 v[28:31], v[170:173], v[186:189], v[28:31]
	v_mfma_f32_16x16x32_bf16 v[20:23], v[162:165], v[194:197], v[20:23]
	v_mfma_f32_16x16x32_bf16 v[12:15], v[170:173], v[194:197], v[12:15]
	v_mfma_f32_16x16x32_bf16 v[4:7], v[162:165], v[202:205], v[4:7]
	v_mfma_f32_16x16x32_bf16 v[0:3], v[170:173], v[202:205], v[0:3]
	v_mfma_f32_16x16x32_bf16 v[52:55], v[166:169], v[182:185], v[52:55]
	v_mfma_f32_16x16x32_bf16 v[44:47], v[174:177], v[182:185], v[44:47]
	v_mfma_f32_16x16x32_bf16 v[36:39], v[166:169], v[190:193], v[36:39]
	v_mfma_f32_16x16x32_bf16 v[28:31], v[174:177], v[190:193], v[28:31]
	v_mfma_f32_16x16x32_bf16 v[20:23], v[166:169], v[198:201], v[20:23]
	v_mfma_f32_16x16x32_bf16 v[12:15], v[174:177], v[198:201], v[12:15]
	v_mfma_f32_16x16x32_bf16 v[4:7], v[166:169], v[206:209], v[4:7]
	v_mfma_f32_16x16x32_bf16 v[0:3], v[174:177], v[206:209], v[0:3]
	s_setprio 0
	s_barrier
	s_add_i32 s55, s55, 2
	s_add_u32 s53, s53, 0x100
	s_addc_u32 s54, s54, 0
	s_cmp_gt_u32 s55, 61
	s_mov_b64 s[22:23], s[4:5]
	s_cbranch_scc0 .LBB0_1093
	s_branch .Lkx_12

; #define PG8_STAGE(bufoff, gbase, voff) do { _Pragma("unroll") for (int _i = 0; _i < 2; ++_i) \
;         __builtin_amdgcn_global_load_lds((const unsigned*)((const char*)(gbase) + (voff)[_i]), (PG8_LAS unsigned*)(lds + (bufoff) + ldsw + _i * 8192), 16, 0, 0); } while (0)
; #define PG8_LDA(dst, b, h) do { _Pragma("unroll") for (int m = 0; m < 4; ++m) _Pragma("unroll") for (int k = 0; k < 2; ++k) dst[m][k] = *(const PG8_LAS bf16x8*)(lds + PG8_SA(b, h) + aoff + m * 2048 + k * 1024); } while (0)
; #define PG8_LDB(dst, b, h) do { _Pragma("unroll") for (int n = 0; n < 2; ++n) _Pragma("unroll") for (int k = 0; k < 2; ++k) dst[n][k] = *(const PG8_LAS bf16x8*)(lds + PG8_SB(b, h) + boff + n * 2048 + k * 1024); } while (0)
; #define PG8_MMA(ai, bj, At, Bt) do { __builtin_amdgcn_s_setprio(1); _Pragma("unroll") for (int m = 0; m < 4; ++m) _Pragma("unroll") for (int n = 0; n < 2; ++n) _Pragma("unroll") for (int k = 0; k < 2; ++k) \
;         acc[ai][bj][m][n] = __builtin_amdgcn_mfma_f32_16x16x32_bf16(Bt[n][k], At[m][k], acc[ai][bj][m][n], 0, 0, 0); __builtin_amdgcn_s_setprio(0); } while (0)
; #define PG8_WAIT_V(n) asm volatile("s_waitcnt vmcnt(" #n ")" ::: "memory")
; #define PG8_BAR __builtin_amdgcn_s_barrier()
; template <class Epi, class Sched, bool ALIGN_EPI = false, bool SP2 = false>
; __device__ __forceinline__ void gemm_phase(PG8_LAS unsigned char* lds, const Gemm g, const Sched& S, const Epi& E, const int wave_in) {
;     ...
;         for (int t = 0; t < nt; t += 2) {
;             const bool last = (t == nt - 2);
;             const char* a1 = cA + (size_t)(t + 1) * kstep;
;             const char* a2 = last ? nA : cA + (size_t)(t + 2) * kstep; const char* b2 = last ? nB : cB + (size_t)(t + 2) * kstep;
;             const char* a3 = a2 + kstep; const char* b3 = b2 + kstep;
;             if (last && has_next) S.a_ready(nxt);
;             if constexpr (SP2) {
;             PG8_LDB(B0, 0, 0); PG8_LDB(B1, 0, 1); PG8_SCHED; PG8_LDA(At, 0, 0); PG8_STAGE(PG8_SA(1, 1), a1 + hstepA, voffA);
;             PG8_WAIT_V(8); PG8_WAIT_L(0); PG8_BAR; PG8_MMA(0, 0, At, B0); PG8_MMA(0, 1, At, B1); PG8_BAR; PG8_SCHED;
;             PG8_LDA(At, 0, 1); PG8_STAGE(PG8_SB(0, 0), b2, voffB); PG8_STAGE(PG8_SB(0, 1), b2 + hstepB, voffB); PG8_STAGE(PG8_SA(0, 0), a2, voffA);
;             PG8_WAIT_V(8); PG8_WAIT_L(0); PG8_BAR; PG8_MMA(1, 0, At, B0); PG8_MMA(1, 1, At, B1); PG8_BAR; PG8_SCHED;
.LBB0_1374:
	s_add_u32 s17, s20, 0x100
	v_mov_b32_e32 v0, 0
	s_addc_u32 s53, s21, 0
	s_mov_b32 s54, -2
	ds_read_b128 v[128:131], v214
	ds_read_b128 v[132:135], v214 offset:1024
	ds_read_b128 v[136:139], v214 offset:2048
	ds_read_b128 v[140:143], v214 offset:3072
	ds_read_b128 v[162:165], v215
	ds_read_b128 v[166:169], v215 offset:1024
	ds_read_b128 v[170:173], v215 offset:2048
	ds_read_b128 v[174:177], v215 offset:3072
	s_add_u32 s20, s18, 0x100
	s_addc_u32 s21, s19, 0
	s_cmpk_eq_i32 s54, 0x52
	s_cselect_b32 s25, s5, s21
	s_cselect_b32 s24, s4, s20
	s_cselect_b32 s23, s15, s53
	s_cselect_b32 s22, s14, s17
	v_lshl_add_u64 v[210:211], s[18:19], 0, v[154:155]
	s_add_i32 m0, s35, 0xc000
	ds_read_b128 v[178:181], v216
	ds_read_b128 v[182:185], v216 offset:1024
	ds_read_b128 v[186:189], v216 offset:2048
	ds_read_b128 v[190:193], v216 offset:3072
	ds_read_b128 v[194:197], v216 offset:4096
	ds_read_b128 v[198:201], v216 offset:5120
	ds_read_b128 v[202:205], v216 offset:6144
	ds_read_b128 v[206:209], v216 offset:7168
	global_load_lds_dwordx4 v[210:211], off
	v_lshl_add_u64 v[210:211], s[18:19], 0, v[156:157]
	s_add_i32 m0, s35, 0xe000
	s_nop 0
	global_load_lds_dwordx4 v[210:211], off
	s_waitcnt vmcnt(8)
	s_waitcnt lgkmcnt(0)
	s_barrier
	s_setprio 1
	s_waitcnt lgkmcnt(0)
	v_mfma_f32_16x16x32_bf16 v[124:127], v[128:131], v[178:181], 0
	v_mfma_f32_16x16x32_bf16 v[120:123], v[136:139], v[178:181], 0
	v_mfma_f32_16x16x32_bf16 v[112:115], v[128:131], v[186:189], 0
	v_mfma_f32_16x16x32_bf16 v[104:107], v[136:139], v[186:189], 0
	v_mfma_f32_16x16x32_bf16 v[100:103], v[128:131], v[194:197], 0
	v_mfma_f32_16x16x32_bf16 v[96:99], v[136:139], v[194:197], 0
	v_mfma_f32_16x16x32_bf16 v[76:79], v[128:131], v[202:205], 0
	v_mfma_f32_16x16x32_bf16 v[72:75], v[136:139], v[202:205], 0
	v_mfma_f32_16x16x32_bf16 v[124:127], v[132:135], v[182:185], v[124:127]
	v_mfma_f32_16x16x32_bf16 v[120:123], v[140:143], v[182:185], v[120:123]
	v_mfma_f32_16x16x32_bf16 v[112:115], v[132:135], v[190:193], v[112:115]
	v_mfma_f32_16x16x32_bf16 v[104:107], v[140:143], v[190:193], v[104:107]
	v_mfma_f32_16x16x32_bf16 v[100:103], v[132:135], v[198:201], v[100:103]
	v_mfma_f32_16x16x32_bf16 v[96:99], v[140:143], v[198:201], v[96:99]
	v_mfma_f32_16x16x32_bf16 v[76:79], v[132:135], v[206:209], v[76:79]
	v_mfma_f32_16x16x32_bf16 v[72:75], v[140:143], v[206:209], v[72:75]
	s_setprio 0
	s_setprio 1
	v_mfma_f32_16x16x32_bf16 v[116:119], v[162:165], v[178:181], 0
	v_mfma_f32_16x16x32_bf16 v[108:111], v[170:173], v[178:181], 0
	v_mfma_f32_16x16x32_bf16 v[92:95], v[162:165], v[186:189], 0
	v_mfma_f32_16x16x32_bf16 v[88:91], v[170:173], v[186:189], 0
	v_mfma_f32_16x16x32_bf16 v[84:87], v[162:165], v[194:197], 0
	v_mfma_f32_16x16x32_bf16 v[80:83], v[170:173], v[194:197], 0
	v_mfma_f32_16x16x32_bf16 v[68:71], v[162:165], v[202:205], 0
	v_mfma_f32_16x16x32_bf16 v[64:67], v[170:173], v[202:205], 0
	v_mfma_f32_16x16x32_bf16 v[116:119], v[166:169], v[182:185], v[116:119]
	v_mfma_f32_16x16x32_bf16 v[108:111], v[174:177], v[182:185], v[108:111]
	v_mfma_f32_16x16x32_bf16 v[92:95], v[166:169], v[190:193], v[92:95]
	v_mfma_f32_16x16x32_bf16 v[88:91], v[174:177], v[190:193], v[88:91]
	v_mfma_f32_16x16x32_bf16 v[84:87], v[166:169], v[198:201], v[84:87]
	v_mfma_f32_16x16x32_bf16 v[80:83], v[174:177], v[198:201], v[80:83]
	v_mfma_f32_16x16x32_bf16 v[68:71], v[166:169], v[206:209], v[68:71]
	v_mfma_f32_16x16x32_bf16 v[64:67], v[174:177], v[206:209], v[64:67]
	s_setprio 0
	s_barrier
	s_add_i32 s18, s45, s30
	v_lshl_add_u64 v[210:211], s[22:23], 0, v[148:149]
	s_mov_b32 m0, s18
	ds_read_b128 v[178:181], v216 offset:16384
	ds_read_b128 v[182:185], v216 offset:17408
	ds_read_b128 v[186:189], v216 offset:18432
	ds_read_b128 v[190:193], v216 offset:19456
	ds_read_b128 v[194:197], v216 offset:20480
	ds_read_b128 v[198:201], v216 offset:21504
	ds_read_b128 v[202:205], v216 offset:22528
	ds_read_b128 v[206:209], v216 offset:23552
	global_load_lds_dwordx4 v[210:211], off
	s_add_i32 m0, s18, 0x2000
	s_add_u32 s18, s22, 0x158000
	v_lshl_add_u64 v[218:219], s[22:23], 0, v[144:145]
	s_addc_u32 s19, s23, 0
	s_add_i32 s55, s46, s30
	global_load_lds_dwordx4 v[218:219], off
	v_lshl_add_u64 v[220:221], s[18:19], 0, v[148:149]
	s_mov_b32 m0, s55
	v_lshl_add_u64 v[222:223], s[24:25], 0, v[146:147]
	global_load_lds_dwordx4 v[220:221], off
	v_lshl_add_u64 v[220:221], s[18:19], 0, v[144:145]
	s_add_i32 m0, s55, 0x2000
	s_nop 0
	global_load_lds_dwordx4 v[220:221], off
	v_lshl_add_u64 v[220:221], s[24:25], 0, v[150:151]
	s_mov_b32 m0, s35
	s_nop 0
	global_load_lds_dwordx4 v[220:221], off
	s_mov_b32 m0, s36
	s_nop 0
	global_load_lds_dwordx4 v[222:223], off
	s_waitcnt vmcnt(8)
	s_waitcnt lgkmcnt(0)
	s_barrier
; #define PG8_STAGE(bufoff, gbase, voff) do { _Pragma("unroll") for (int _i = 0; _i < 2; ++_i) \
;         __builtin_amdgcn_global_load_lds((const unsigned*)((const char*)(gbase) + (voff)[_i]), (PG8_LAS unsigned*)(lds + (bufoff) + ldsw + _i * 8192), 16, 0, 0); } while (0)
; #define PG8_LDA(dst, b, h) do { _Pragma("unroll") for (int m = 0; m < 4; ++m) _Pragma("unroll") for (int k = 0; k < 2; ++k) dst[m][k] = *(const PG8_LAS bf16x8*)(lds + PG8_SA(b, h) + aoff + m * 2048 + k * 1024); } while (0)
; #define PG8_LDB(dst, b, h) do { _Pragma("unroll") for (int n = 0; n < 2; ++n) _Pragma("unroll") for (int k = 0; k < 2; ++k) dst[n][k] = *(const PG8_LAS bf16x8*)(lds + PG8_SB(b, h) + boff + n * 2048 + k * 1024); } while (0)
; #define PG8_MMA(ai, bj, At, Bt) do { __builtin_amdgcn_s_setprio(1); _Pragma("unroll") for (int m = 0; m < 4; ++m) _Pragma("unroll") for (int n = 0; n < 2; ++n) _Pragma("unroll") for (int k = 0; k < 2; ++k) \
;         acc[ai][bj][m][n] = __builtin_amdgcn_mfma_f32_16x16x32_bf16(Bt[n][k], At[m][k], acc[ai][bj][m][n], 0, 0, 0); __builtin_amdgcn_s_setprio(0); } while (0)
; #define PG8_WAIT_V(n) asm volatile("s_waitcnt vmcnt(" #n ")" ::: "memory")
; #define PG8_WAIT_L(n) asm volatile("s_waitcnt lgkmcnt(" #n ")" ::: "memory")
; #define PG8_BAR __builtin_amdgcn_s_barrier()
; #define PG8_SCHED __builtin_amdgcn_sched_barrier(0)
; template <class Epi, class Sched, bool ALIGN_EPI = false, bool SP2 = false>
; __device__ __forceinline__ void gemm_phase(PG8_LAS unsigned char* lds, const Gemm g, const Sched& S, const Epi& E, const int wave_in) {
;     ...
;             PG8_WAIT_V(8); PG8_WAIT_L(0); PG8_BAR; PG8_MMA(1, 0, At, B0); PG8_MMA(1, 1, At, B1); PG8_BAR; PG8_SCHED;
;             PG8_LDB(B0, 1, 0); PG8_LDB(B1, 1, 1); PG8_SCHED; PG8_LDA(At, 1, 0); PG8_STAGE(PG8_SA(0, 1), a2 + hstepA, voffA);
;             PG8_WAIT_V(8); PG8_WAIT_L(0); PG8_BAR; PG8_MMA(0, 0, At, B0); PG8_MMA(0, 1, At, B1); PG8_BAR; PG8_SCHED;
	s_setprio 1
	s_waitcnt lgkmcnt(0)
	v_mfma_f32_16x16x32_bf16 v[60:63], v[128:131], v[178:181], 0
	v_mfma_f32_16x16x32_bf16 v[56:59], v[136:139], v[178:181], 0
	v_mfma_f32_16x16x32_bf16 v[48:51], v[128:131], v[186:189], 0
	v_mfma_f32_16x16x32_bf16 v[40:43], v[136:139], v[186:189], 0
	v_mfma_f32_16x16x32_bf16 v[32:35], v[128:131], v[194:197], 0
	v_mfma_f32_16x16x32_bf16 v[24:27], v[136:139], v[194:197], 0
	v_mfma_f32_16x16x32_bf16 v[16:19], v[128:131], v[202:205], 0
	v_mfma_f32_16x16x32_bf16 v[8:11], v[136:139], v[202:205], 0
	v_mfma_f32_16x16x32_bf16 v[60:63], v[132:135], v[182:185], v[60:63]
	v_mfma_f32_16x16x32_bf16 v[56:59], v[140:143], v[182:185], v[56:59]
	v_mfma_f32_16x16x32_bf16 v[48:51], v[132:135], v[190:193], v[48:51]
	v_mfma_f32_16x16x32_bf16 v[40:43], v[140:143], v[190:193], v[40:43]
	v_mfma_f32_16x16x32_bf16 v[32:35], v[132:135], v[198:201], v[32:35]
	v_mfma_f32_16x16x32_bf16 v[24:27], v[140:143], v[198:201], v[24:27]
	v_mfma_f32_16x16x32_bf16 v[16:19], v[132:135], v[206:209], v[16:19]
	v_mfma_f32_16x16x32_bf16 v[8:11], v[140:143], v[206:209], v[8:11]
	s_setprio 0
	s_setprio 1
	v_mfma_f32_16x16x32_bf16 v[52:55], v[162:165], v[178:181], 0
	v_mfma_f32_16x16x32_bf16 v[44:47], v[170:173], v[178:181], 0
	v_mfma_f32_16x16x32_bf16 v[36:39], v[162:165], v[186:189], 0
	v_mfma_f32_16x16x32_bf16 v[28:31], v[170:173], v[186:189], 0
	v_mfma_f32_16x16x32_bf16 v[20:23], v[162:165], v[194:197], 0
	v_mfma_f32_16x16x32_bf16 v[12:15], v[170:173], v[194:197], 0
	v_mfma_f32_16x16x32_bf16 v[4:7], v[162:165], v[202:205], 0
	v_mfma_f32_16x16x32_bf16 v[0:3], v[170:173], v[202:205], 0
	v_mfma_f32_16x16x32_bf16 v[52:55], v[166:169], v[182:185], v[52:55]
	v_mfma_f32_16x16x32_bf16 v[44:47], v[174:177], v[182:185], v[44:47]
	v_mfma_f32_16x16x32_bf16 v[36:39], v[166:169], v[190:193], v[36:39]
	v_mfma_f32_16x16x32_bf16 v[28:31], v[174:177], v[190:193], v[28:31]
	v_mfma_f32_16x16x32_bf16 v[20:23], v[166:169], v[198:201], v[20:23]
	v_mfma_f32_16x16x32_bf16 v[12:15], v[174:177], v[198:201], v[12:15]
	v_mfma_f32_16x16x32_bf16 v[4:7], v[166:169], v[206:209], v[4:7]
	v_mfma_f32_16x16x32_bf16 v[0:3], v[174:177], v[206:209], v[0:3]
	s_setprio 0
	s_barrier
	s_add_i32 s55, 0, 0x18000
	s_add_i32 s56, 0, 0x1c000
	v_add_u32_e32 v140, s55, v212
	v_add_u32_e32 v174, s56, v212
	ds_read_b128 v[128:131], v140
	ds_read_b128 v[132:135], v140 offset:1024
	ds_read_b128 v[136:139], v140 offset:2048
	ds_read_b128 v[140:143], v140 offset:3072
	ds_read_b128 v[162:165], v174
	ds_read_b128 v[166:169], v174 offset:1024
	ds_read_b128 v[170:173], v174 offset:2048
	ds_read_b128 v[174:177], v174 offset:3072
	s_add_u32 s18, s24, 0x158000
	s_addc_u32 s19, s25, 0
	s_mov_b32 m0, s37
	v_lshl_add_u64 v[224:225], s[18:19], 0, v[150:151]
	ds_read_b128 v[178:181], v216 offset:32768
	ds_read_b128 v[182:185], v216 offset:33792
	ds_read_b128 v[186:189], v216 offset:34816
	ds_read_b128 v[190:193], v216 offset:35840
	ds_read_b128 v[194:197], v216 offset:36864
	ds_read_b128 v[198:201], v216 offset:37888
	ds_read_b128 v[202:205], v216 offset:38912
	ds_read_b128 v[206:209], v216 offset:39936
	global_load_lds_dwordx4 v[224:225], off
	v_lshl_add_u64 v[224:225], s[18:19], 0, v[146:147]
	s_mov_b32 m0, s38
	s_nop 0
	global_load_lds_dwordx4 v[224:225], off
	s_waitcnt vmcnt(8)
	s_waitcnt lgkmcnt(0)
	s_barrier
	s_setprio 1
	s_waitcnt lgkmcnt(0)
	v_mfma_f32_16x16x32_bf16 v[124:127], v[128:131], v[178:181], v[124:127]
	v_mfma_f32_16x16x32_bf16 v[120:123], v[136:139], v[178:181], v[120:123]
	v_mfma_f32_16x16x32_bf16 v[112:115], v[128:131], v[186:189], v[112:115]
	v_mfma_f32_16x16x32_bf16 v[104:107], v[136:139], v[186:189], v[104:107]
	v_mfma_f32_16x16x32_bf16 v[100:103], v[128:131], v[194:197], v[100:103]
	v_mfma_f32_16x16x32_bf16 v[96:99], v[136:139], v[194:197], v[96:99]
	v_mfma_f32_16x16x32_bf16 v[76:79], v[128:131], v[202:205], v[76:79]
	v_mfma_f32_16x16x32_bf16 v[72:75], v[136:139], v[202:205], v[72:75]
	v_mfma_f32_16x16x32_bf16 v[124:127], v[132:135], v[182:185], v[124:127]
	v_mfma_f32_16x16x32_bf16 v[120:123], v[140:143], v[182:185], v[120:123]
	v_mfma_f32_16x16x32_bf16 v[112:115], v[132:135], v[190:193], v[112:115]
	v_mfma_f32_16x16x32_bf16 v[104:107], v[140:143], v[190:193], v[104:107]
	v_mfma_f32_16x16x32_bf16 v[100:103], v[132:135], v[198:201], v[100:103]
	v_mfma_f32_16x16x32_bf16 v[96:99], v[140:143], v[198:201], v[96:99]
	v_mfma_f32_16x16x32_bf16 v[76:79], v[132:135], v[206:209], v[76:79]
	v_mfma_f32_16x16x32_bf16 v[72:75], v[140:143], v[206:209], v[72:75]
	s_setprio 0
	s_setprio 1
	v_mfma_f32_16x16x32_bf16 v[116:119], v[162:165], v[178:181], v[116:119]
	v_mfma_f32_16x16x32_bf16 v[108:111], v[170:173], v[178:181], v[108:111]
	v_mfma_f32_16x16x32_bf16 v[92:95], v[162:165], v[186:189], v[92:95]
	v_mfma_f32_16x16x32_bf16 v[88:91], v[170:173], v[186:189], v[88:91]
	v_mfma_f32_16x16x32_bf16 v[84:87], v[162:165], v[194:197], v[84:87]
	v_mfma_f32_16x16x32_bf16 v[80:83], v[170:173], v[194:197], v[80:83]
	v_mfma_f32_16x16x32_bf16 v[68:71], v[162:165], v[202:205], v[68:71]
	v_mfma_f32_16x16x32_bf16 v[64:67], v[170:173], v[202:205], v[64:67]
	v_mfma_f32_16x16x32_bf16 v[116:119], v[166:169], v[182:185], v[116:119]
	v_mfma_f32_16x16x32_bf16 v[108:111], v[174:177], v[182:185], v[108:111]
	v_mfma_f32_16x16x32_bf16 v[92:95], v[166:169], v[190:193], v[92:95]
	v_mfma_f32_16x16x32_bf16 v[88:91], v[174:177], v[190:193], v[88:91]
	v_mfma_f32_16x16x32_bf16 v[84:87], v[166:169], v[198:201], v[84:87]
	v_mfma_f32_16x16x32_bf16 v[80:83], v[174:177], v[198:201], v[80:83]
	v_mfma_f32_16x16x32_bf16 v[68:71], v[166:169], v[206:209], v[68:71]
	v_mfma_f32_16x16x32_bf16 v[64:67], v[174:177], v[206:209], v[64:67]
	s_setprio 0
	s_barrier
; #define PG8_STAGE(bufoff, gbase, voff) do { _Pragma("unroll") for (int _i = 0; _i < 2; ++_i) \
;         __builtin_amdgcn_global_load_lds((const unsigned*)((const char*)(gbase) + (voff)[_i]), (PG8_LAS unsigned*)(lds + (bufoff) + ldsw + _i * 8192), 16, 0, 0); } while (0)
; #define PG8_LDA(dst, b, h) do { _Pragma("unroll") for (int m = 0; m < 4; ++m) _Pragma("unroll") for (int k = 0; k < 2; ++k) dst[m][k] = *(const PG8_LAS bf16x8*)(lds + PG8_SA(b, h) + aoff + m * 2048 + k * 1024); } while (0)
; #define PG8_MMA(ai, bj, At, Bt) do { __builtin_amdgcn_s_setprio(1); _Pragma("unroll") for (int m = 0; m < 4; ++m) _Pragma("unroll") for (int n = 0; n < 2; ++n) _Pragma("unroll") for (int k = 0; k < 2; ++k) \
;         acc[ai][bj][m][n] = __builtin_amdgcn_mfma_f32_16x16x32_bf16(Bt[n][k], At[m][k], acc[ai][bj][m][n], 0, 0, 0); __builtin_amdgcn_s_setprio(0); } while (0)
; #define PG8_WAIT_V(n) asm volatile("s_waitcnt vmcnt(" #n ")" ::: "memory")
; #define PG8_WAIT_L(n) asm volatile("s_waitcnt lgkmcnt(" #n ")" ::: "memory")
; #define PG8_BAR __builtin_amdgcn_s_barrier()
; #define PG8_SCHED __builtin_amdgcn_sched_barrier(0)
; template <class Epi, class Sched, bool ALIGN_EPI = false, bool SP2 = false>
; __device__ __forceinline__ void gemm_phase(PG8_LAS unsigned char* lds, const Gemm g, const Sched& S, const Epi& E, const int wave_in) {
;     ...
;             PG8_LDA(At, 1, 1); PG8_STAGE(PG8_SB(1, 0), b3, voffB); PG8_STAGE(PG8_SB(1, 1), b3 + hstepB, voffB); PG8_STAGE(PG8_SA(1, 0), a3, voffA);
;             PG8_WAIT_V(8); PG8_WAIT_L(0); PG8_BAR; PG8_MMA(1, 0, At, B0); PG8_MMA(1, 1, At, B1); PG8_BAR; PG8_SCHED;
	s_add_i32 s18, s55, s30
	v_lshl_add_u64 v[210:211], v[210:211], 0, s[6:7]
	s_mov_b32 m0, s18
	ds_read_b128 v[178:181], v216 offset:49152
	ds_read_b128 v[182:185], v216 offset:50176
	ds_read_b128 v[186:189], v216 offset:51200
	ds_read_b128 v[190:193], v216 offset:52224
	ds_read_b128 v[194:197], v216 offset:53248
	ds_read_b128 v[198:201], v216 offset:54272
	ds_read_b128 v[202:205], v216 offset:55296
	ds_read_b128 v[206:209], v216 offset:56320
	global_load_lds_dwordx4 v[210:211], off
	s_add_i32 m0, s18, 0x2000
	s_add_u32 s18, s22, 0x158080
	v_lshl_add_u64 v[210:211], v[218:219], 0, s[6:7]
	s_addc_u32 s19, s23, 0
	s_add_i32 s22, s56, s30
	global_load_lds_dwordx4 v[210:211], off
	v_lshl_add_u64 v[210:211], s[18:19], 0, v[148:149]
	s_mov_b32 m0, s22
	s_nop 0
	global_load_lds_dwordx4 v[210:211], off
	v_lshl_add_u64 v[210:211], s[18:19], 0, v[144:145]
	s_add_i32 m0, s22, 0x2000
	s_nop 0
	global_load_lds_dwordx4 v[210:211], off
	v_lshl_add_u64 v[210:211], v[220:221], 0, s[6:7]
	s_mov_b32 m0, s42
	s_nop 0
	global_load_lds_dwordx4 v[210:211], off
	v_lshl_add_u64 v[210:211], v[222:223], 0, s[6:7]
	s_mov_b32 m0, s43
	s_nop 0
	global_load_lds_dwordx4 v[210:211], off
	s_waitcnt vmcnt(8)
	s_waitcnt lgkmcnt(0)
	s_barrier
	s_setprio 1
	s_waitcnt lgkmcnt(0)
	v_mfma_f32_16x16x32_bf16 v[60:63], v[128:131], v[178:181], v[60:63]
	v_mfma_f32_16x16x32_bf16 v[56:59], v[136:139], v[178:181], v[56:59]
	v_mfma_f32_16x16x32_bf16 v[48:51], v[128:131], v[186:189], v[48:51]
	v_mfma_f32_16x16x32_bf16 v[40:43], v[136:139], v[186:189], v[40:43]
	v_mfma_f32_16x16x32_bf16 v[32:35], v[128:131], v[194:197], v[32:35]
	v_mfma_f32_16x16x32_bf16 v[24:27], v[136:139], v[194:197], v[24:27]
	v_mfma_f32_16x16x32_bf16 v[16:19], v[128:131], v[202:205], v[16:19]
	v_mfma_f32_16x16x32_bf16 v[8:11], v[136:139], v[202:205], v[8:11]
	v_mfma_f32_16x16x32_bf16 v[60:63], v[132:135], v[182:185], v[60:63]
	v_mfma_f32_16x16x32_bf16 v[56:59], v[140:143], v[182:185], v[56:59]
	v_mfma_f32_16x16x32_bf16 v[48:51], v[132:135], v[190:193], v[48:51]
	v_mfma_f32_16x16x32_bf16 v[40:43], v[140:143], v[190:193], v[40:43]
	v_mfma_f32_16x16x32_bf16 v[32:35], v[132:135], v[198:201], v[32:35]
	v_mfma_f32_16x16x32_bf16 v[24:27], v[140:143], v[198:201], v[24:27]
	v_mfma_f32_16x16x32_bf16 v[16:19], v[132:135], v[206:209], v[16:19]
	v_mfma_f32_16x16x32_bf16 v[8:11], v[140:143], v[206:209], v[8:11]
	s_setprio 0
	s_setprio 1
	v_mfma_f32_16x16x32_bf16 v[52:55], v[162:165], v[178:181], v[52:55]
	v_mfma_f32_16x16x32_bf16 v[44:47], v[170:173], v[178:181], v[44:47]
	v_mfma_f32_16x16x32_bf16 v[36:39], v[162:165], v[186:189], v[36:39]
	v_mfma_f32_16x16x32_bf16 v[28:31], v[170:173], v[186:189], v[28:31]
	v_mfma_f32_16x16x32_bf16 v[20:23], v[162:165], v[194:197], v[20:23]
	v_mfma_f32_16x16x32_bf16 v[12:15], v[170:173], v[194:197], v[12:15]
	v_mfma_f32_16x16x32_bf16 v[4:7], v[162:165], v[202:205], v[4:7]
	v_mfma_f32_16x16x32_bf16 v[0:3], v[170:173], v[202:205], v[0:3]
	v_mfma_f32_16x16x32_bf16 v[52:55], v[166:169], v[182:185], v[52:55]
	v_mfma_f32_16x16x32_bf16 v[44:47], v[174:177], v[182:185], v[44:47]
	v_mfma_f32_16x16x32_bf16 v[36:39], v[166:169], v[190:193], v[36:39]
	v_mfma_f32_16x16x32_bf16 v[28:31], v[174:177], v[190:193], v[28:31]
	v_mfma_f32_16x16x32_bf16 v[20:23], v[166:169], v[198:201], v[20:23]
	v_mfma_f32_16x16x32_bf16 v[12:15], v[174:177], v[198:201], v[12:15]
	v_mfma_f32_16x16x32_bf16 v[4:7], v[166:169], v[206:209], v[4:7]
	v_mfma_f32_16x16x32_bf16 v[0:3], v[174:177], v[206:209], v[0:3]
	s_setprio 0
	s_barrier
	s_add_i32 s54, s54, 2
	s_add_u32 s17, s17, 0x100
	s_addc_u32 s53, s53, 0
	s_cmpk_gt_u32 s54, 0x53
	s_mov_b64 s[18:19], s[20:21]
	s_cbranch_scc0 .LBB0_1375
	s_branch .Lkx_16

;     __host__ __device__ bool next(int i, Unit& u) const { const bool ok = StaticOrder::next(i, u); u.pm = 0; u.pn = 0; return ok; }
; #define PG8_STAGE(bufoff, gbase, voff) do { _Pragma("unroll") for (int _i = 0; _i < 2; ++_i) \
;         __builtin_amdgcn_global_load_lds((const unsigned*)((const char*)(gbase) + (voff)[_i]), (PG8_LAS unsigned*)(lds + (bufoff) + ldsw + _i * 8192), 16, 0, 0); } while (0)
; #define PG8_LDA(dst, b, h) do { _Pragma("unroll") for (int m = 0; m < 4; ++m) _Pragma("unroll") for (int k = 0; k < 2; ++k) dst[m][k] = *(const PG8_LAS bf16x8*)(lds + PG8_SA(b, h) + aoff + m * 2048 + k * 1024); } while (0)
; #define PG8_LDB(dst, b, h) do { _Pragma("unroll") for (int n = 0; n < 2; ++n) _Pragma("unroll") for (int k = 0; k < 2; ++k) dst[n][k] = *(const PG8_LAS bf16x8*)(lds + PG8_SB(b, h) + boff + n * 2048 + k * 1024); } while (0)
; #define PG8_WAIT_V(n) asm volatile("s_waitcnt vmcnt(" #n ")" ::: "memory")
; #define PG8_BAR __builtin_amdgcn_s_barrier()
; template <class Epi, class Sched, bool ALIGN_EPI = false, bool SP2 = false>
; __device__ __forceinline__ void gemm_phase(PG8_LAS unsigned char* lds, const Gemm g, const Sched& S, const Epi& E, const int wave_in) {
;     ...
;         const bool has_next = S.next(ui + 1, nxt);
;         const char* nA = has_next ? (const char*)g.A + (size_t)nxt.pm * tstepA : cA; const char* nB = has_next ? (const char*)g.Bt + (size_t)nxt.pn * tstepB : cB;
;         for (int t = 0; t < nt; t += 2) {
;             const bool last = (t == nt - 2);
;             const char* a1 = cA + (size_t)(t + 1) * kstep;
;             const char* a2 = last ? nA : cA + (size_t)(t + 2) * kstep; const char* b2 = last ? nB : cB + (size_t)(t + 2) * kstep;
;             const char* a3 = a2 + kstep; const char* b3 = b2 + kstep;
;             if (last && has_next) S.a_ready(nxt);
;             if constexpr (SP2) {
;             PG8_LDB(B0, 0, 0); PG8_LDB(B1, 0, 1); PG8_SCHED; PG8_LDA(At, 0, 0); PG8_STAGE(PG8_SA(1, 1), a1 + hstepA, voffA);
;             PG8_WAIT_V(8); PG8_WAIT_L(0); PG8_BAR; PG8_MMA(0, 0, At, B0); PG8_MMA(0, 1, At, B1); PG8_BAR; PG8_SCHED;
;             PG8_LDA(At, 0, 1); PG8_STAGE(PG8_SB(0, 0), b2, voffB); PG8_STAGE(PG8_SB(0, 1), b2 + hstepB, voffB); PG8_STAGE(PG8_SA(0, 0), a2, voffA);
;             PG8_WAIT_V(8); PG8_WAIT_L(0); PG8_BAR; PG8_MMA(1, 0, At, B0); PG8_MMA(1, 1, At, B1); PG8_BAR; PG8_SCHED;
.LBB0_1512:
	s_ashr_i32 s13, s12, 31
	s_lshl_b64 s[14:15], s[12:13], 20
	s_add_u32 s14, s26, s14
	s_addc_u32 s15, s27, s15
	s_and_b64 s[16:17], s[2:3], exec
	s_cselect_b32 s13, s15, s21
	s_cselect_b32 s46, s14, s20
	s_ashr_i32 s11, s10, 31
	s_lshl_b64 s[16:17], s[10:11], 20
	s_add_u32 s16, s28, s16
	s_addc_u32 s17, s29, s17
	s_and_b64 s[24:25], s[2:3], exec
	s_cselect_b32 s11, s17, s23
	s_cselect_b32 s47, s16, s22
	s_add_u32 s20, s20, 0x80080
	s_addc_u32 s21, s21, 0
	s_add_u32 s48, s22, 0x100
	v_mov_b32_e32 v0, 0
	s_addc_u32 s49, s23, 0
	s_mov_b32 s50, -2
	ds_read_b128 v[144:147], v151
	ds_read_b128 v[154:157], v151 offset:1024
	ds_read_b128 v[158:161], v151 offset:2048
	ds_read_b128 v[162:165], v151 offset:3072
	ds_read_b128 v[166:169], v152
	ds_read_b128 v[170:173], v152 offset:1024
	ds_read_b128 v[174:177], v152 offset:2048
	ds_read_b128 v[178:181], v152 offset:3072
	s_add_u32 s22, s20, 0xfff80080
	s_addc_u32 s23, s21, -1
	s_cmp_eq_u32 s50, 28
	s_cselect_b32 s25, s13, s23
	s_cselect_b32 s24, s46, s22
	s_cselect_b32 s23, s11, s49
	s_cselect_b32 s22, s47, s48
	v_lshl_add_u64 v[214:215], s[20:21], 0, v[136:137]
	s_add_i32 m0, s19, 0xc000
	ds_read_b128 v[182:185], v153
	ds_read_b128 v[186:189], v153 offset:1024
	ds_read_b128 v[190:193], v153 offset:2048
	ds_read_b128 v[194:197], v153 offset:3072
	ds_read_b128 v[198:201], v153 offset:4096
	ds_read_b128 v[202:205], v153 offset:5120
	ds_read_b128 v[206:209], v153 offset:6144
	ds_read_b128 v[210:213], v153 offset:7168
	global_load_lds_dwordx4 v[214:215], off
	v_lshl_add_u64 v[214:215], s[20:21], 0, v[138:139]
	s_add_i32 m0, s19, 0xe000
	s_nop 0
	global_load_lds_dwordx4 v[214:215], off
	s_waitcnt vmcnt(8)
	s_waitcnt lgkmcnt(0)
	s_barrier
	s_setprio 1
	s_waitcnt lgkmcnt(0)
	v_mfma_f32_16x16x32_bf16 v[124:127], v[144:147], v[182:185], 0
	v_mfma_f32_16x16x32_bf16 v[120:123], v[158:161], v[182:185], 0
	v_mfma_f32_16x16x32_bf16 v[116:119], v[144:147], v[190:193], 0
	v_mfma_f32_16x16x32_bf16 v[108:111], v[158:161], v[190:193], 0
	v_mfma_f32_16x16x32_bf16 v[100:103], v[144:147], v[198:201], 0
	v_mfma_f32_16x16x32_bf16 v[92:95], v[158:161], v[198:201], 0
	v_mfma_f32_16x16x32_bf16 v[84:87], v[144:147], v[206:209], 0
	v_mfma_f32_16x16x32_bf16 v[76:79], v[158:161], v[206:209], 0
	v_mfma_f32_16x16x32_bf16 v[124:127], v[154:157], v[186:189], v[124:127]
	v_mfma_f32_16x16x32_bf16 v[120:123], v[162:165], v[186:189], v[120:123]
	v_mfma_f32_16x16x32_bf16 v[116:119], v[154:157], v[194:197], v[116:119]
	v_mfma_f32_16x16x32_bf16 v[108:111], v[162:165], v[194:197], v[108:111]
	v_mfma_f32_16x16x32_bf16 v[100:103], v[154:157], v[202:205], v[100:103]
	v_mfma_f32_16x16x32_bf16 v[92:95], v[162:165], v[202:205], v[92:95]
	v_mfma_f32_16x16x32_bf16 v[84:87], v[154:157], v[210:213], v[84:87]
	v_mfma_f32_16x16x32_bf16 v[76:79], v[162:165], v[210:213], v[76:79]
	s_setprio 0
	s_setprio 1
	v_mfma_f32_16x16x32_bf16 v[112:115], v[166:169], v[182:185], 0
	v_mfma_f32_16x16x32_bf16 v[104:107], v[174:177], v[182:185], 0
	v_mfma_f32_16x16x32_bf16 v[96:99], v[166:169], v[190:193], 0
	v_mfma_f32_16x16x32_bf16 v[88:91], v[174:177], v[190:193], 0
	v_mfma_f32_16x16x32_bf16 v[80:83], v[166:169], v[198:201], 0
	v_mfma_f32_16x16x32_bf16 v[72:75], v[174:177], v[198:201], 0
	v_mfma_f32_16x16x32_bf16 v[68:71], v[166:169], v[206:209], 0
	v_mfma_f32_16x16x32_bf16 v[64:67], v[174:177], v[206:209], 0
	v_mfma_f32_16x16x32_bf16 v[112:115], v[170:173], v[186:189], v[112:115]
	v_mfma_f32_16x16x32_bf16 v[104:107], v[178:181], v[186:189], v[104:107]
	v_mfma_f32_16x16x32_bf16 v[96:99], v[170:173], v[194:197], v[96:99]
	v_mfma_f32_16x16x32_bf16 v[88:91], v[178:181], v[194:197], v[88:91]
	v_mfma_f32_16x16x32_bf16 v[80:83], v[170:173], v[202:205], v[80:83]
	v_mfma_f32_16x16x32_bf16 v[72:75], v[178:181], v[202:205], v[72:75]
	v_mfma_f32_16x16x32_bf16 v[68:71], v[170:173], v[210:213], v[68:71]
	v_mfma_f32_16x16x32_bf16 v[64:67], v[178:181], v[210:213], v[64:67]
	s_setprio 0
	s_barrier
	s_add_i32 s51, s42, s30
	v_lshl_add_u64 v[214:215], s[22:23], 0, v[132:133]
	s_mov_b32 m0, s51
	ds_read_b128 v[182:185], v153 offset:16384
	ds_read_b128 v[186:189], v153 offset:17408
	ds_read_b128 v[190:193], v153 offset:18432
	ds_read_b128 v[194:197], v153 offset:19456
	ds_read_b128 v[198:201], v153 offset:20480
	ds_read_b128 v[202:205], v153 offset:21504
	ds_read_b128 v[206:209], v153 offset:22528
	ds_read_b128 v[210:213], v153 offset:23552
	global_load_lds_dwordx4 v[214:215], off
	s_add_i32 m0, s51, 0x2000
	s_add_u32 s52, s22, 0x80000
	v_lshl_add_u64 v[216:217], s[22:23], 0, v[128:129]
	s_addc_u32 s53, s23, 0
	s_add_i32 s51, s43, s30
	global_load_lds_dwordx4 v[216:217], off
	v_lshl_add_u64 v[218:219], s[52:53], 0, v[132:133]
	s_mov_b32 m0, s51
	v_lshl_add_u64 v[220:221], s[24:25], 0, v[130:131]
	global_load_lds_dwordx4 v[218:219], off
	v_lshl_add_u64 v[218:219], s[52:53], 0, v[128:129]
	s_add_i32 m0, s51, 0x2000
	s_nop 0
	global_load_lds_dwordx4 v[218:219], off
	v_lshl_add_u64 v[218:219], s[24:25], 0, v[134:135]
	s_mov_b32 m0, s19
	s_nop 0
	global_load_lds_dwordx4 v[218:219], off
	s_mov_b32 m0, s35
	s_nop 0
	global_load_lds_dwordx4 v[220:221], off
	s_waitcnt vmcnt(8)
	s_waitcnt lgkmcnt(0)
	s_barrier
; #define PG8_STAGE(bufoff, gbase, voff) do { _Pragma("unroll") for (int _i = 0; _i < 2; ++_i) \
;         __builtin_amdgcn_global_load_lds((const unsigned*)((const char*)(gbase) + (voff)[_i]), (PG8_LAS unsigned*)(lds + (bufoff) + ldsw + _i * 8192), 16, 0, 0); } while (0)
; #define PG8_LDA(dst, b, h) do { _Pragma("unroll") for (int m = 0; m < 4; ++m) _Pragma("unroll") for (int k = 0; k < 2; ++k) dst[m][k] = *(const PG8_LAS bf16x8*)(lds + PG8_SA(b, h) + aoff + m * 2048 + k * 1024); } while (0)
; #define PG8_LDB(dst, b, h) do { _Pragma("unroll") for (int n = 0; n < 2; ++n) _Pragma("unroll") for (int k = 0; k < 2; ++k) dst[n][k] = *(const PG8_LAS bf16x8*)(lds + PG8_SB(b, h) + boff + n * 2048 + k * 1024); } while (0)
; #define PG8_MMA(ai, bj, At, Bt) do { __builtin_amdgcn_s_setprio(1); _Pragma("unroll") for (int m = 0; m < 4; ++m) _Pragma("unroll") for (int n = 0; n < 2; ++n) _Pragma("unroll") for (int k = 0; k < 2; ++k) \
;         acc[ai][bj][m][n] = __builtin_amdgcn_mfma_f32_16x16x32_bf16(Bt[n][k], At[m][k], acc[ai][bj][m][n], 0, 0, 0); __builtin_amdgcn_s_setprio(0); } while (0)
; #define PG8_WAIT_V(n) asm volatile("s_waitcnt vmcnt(" #n ")" ::: "memory")
; #define PG8_WAIT_L(n) asm volatile("s_waitcnt lgkmcnt(" #n ")" ::: "memory")
; #define PG8_BAR __builtin_amdgcn_s_barrier()
; #define PG8_SCHED __builtin_amdgcn_sched_barrier(0)
; template <class Epi, class Sched, bool ALIGN_EPI = false, bool SP2 = false>
; __device__ __forceinline__ void gemm_phase(PG8_LAS unsigned char* lds, const Gemm g, const Sched& S, const Epi& E, const int wave_in) {
;     ...
;             PG8_WAIT_V(8); PG8_WAIT_L(0); PG8_BAR; PG8_MMA(1, 0, At, B0); PG8_MMA(1, 1, At, B1); PG8_BAR; PG8_SCHED;
;             PG8_LDB(B0, 1, 0); PG8_LDB(B1, 1, 1); PG8_SCHED; PG8_LDA(At, 1, 0); PG8_STAGE(PG8_SA(0, 1), a2 + hstepA, voffA);
;             PG8_WAIT_V(8); PG8_WAIT_L(0); PG8_BAR; PG8_MMA(0, 0, At, B0); PG8_MMA(0, 1, At, B1); PG8_BAR; PG8_SCHED;
	s_setprio 1
	s_waitcnt lgkmcnt(0)
	v_mfma_f32_16x16x32_bf16 v[60:63], v[144:147], v[182:185], 0
	v_mfma_f32_16x16x32_bf16 v[56:59], v[158:161], v[182:185], 0
	v_mfma_f32_16x16x32_bf16 v[52:55], v[144:147], v[190:193], 0
	v_mfma_f32_16x16x32_bf16 v[44:47], v[158:161], v[190:193], 0
	v_mfma_f32_16x16x32_bf16 v[36:39], v[144:147], v[198:201], 0
	v_mfma_f32_16x16x32_bf16 v[28:31], v[158:161], v[198:201], 0
	v_mfma_f32_16x16x32_bf16 v[20:23], v[144:147], v[206:209], 0
	v_mfma_f32_16x16x32_bf16 v[12:15], v[158:161], v[206:209], 0
	v_mfma_f32_16x16x32_bf16 v[60:63], v[154:157], v[186:189], v[60:63]
	v_mfma_f32_16x16x32_bf16 v[56:59], v[162:165], v[186:189], v[56:59]
	v_mfma_f32_16x16x32_bf16 v[52:55], v[154:157], v[194:197], v[52:55]
	v_mfma_f32_16x16x32_bf16 v[44:47], v[162:165], v[194:197], v[44:47]
	v_mfma_f32_16x16x32_bf16 v[36:39], v[154:157], v[202:205], v[36:39]
	v_mfma_f32_16x16x32_bf16 v[28:31], v[162:165], v[202:205], v[28:31]
	v_mfma_f32_16x16x32_bf16 v[20:23], v[154:157], v[210:213], v[20:23]
	v_mfma_f32_16x16x32_bf16 v[12:15], v[162:165], v[210:213], v[12:15]
	s_setprio 0
	s_setprio 1
	v_mfma_f32_16x16x32_bf16 v[48:51], v[166:169], v[182:185], 0
	v_mfma_f32_16x16x32_bf16 v[40:43], v[174:177], v[182:185], 0
	v_mfma_f32_16x16x32_bf16 v[32:35], v[166:169], v[190:193], 0
	v_mfma_f32_16x16x32_bf16 v[24:27], v[174:177], v[190:193], 0
	v_mfma_f32_16x16x32_bf16 v[16:19], v[166:169], v[198:201], 0
	v_mfma_f32_16x16x32_bf16 v[8:11], v[174:177], v[198:201], 0
	v_mfma_f32_16x16x32_bf16 v[4:7], v[166:169], v[206:209], 0
	v_mfma_f32_16x16x32_bf16 v[0:3], v[174:177], v[206:209], 0
	v_mfma_f32_16x16x32_bf16 v[48:51], v[170:173], v[186:189], v[48:51]
	v_mfma_f32_16x16x32_bf16 v[40:43], v[178:181], v[186:189], v[40:43]
	v_mfma_f32_16x16x32_bf16 v[32:35], v[170:173], v[194:197], v[32:35]
	v_mfma_f32_16x16x32_bf16 v[24:27], v[178:181], v[194:197], v[24:27]
	v_mfma_f32_16x16x32_bf16 v[16:19], v[170:173], v[202:205], v[16:19]
	v_mfma_f32_16x16x32_bf16 v[8:11], v[178:181], v[202:205], v[8:11]
	v_mfma_f32_16x16x32_bf16 v[4:7], v[170:173], v[210:213], v[4:7]
	v_mfma_f32_16x16x32_bf16 v[0:3], v[178:181], v[210:213], v[0:3]
	s_setprio 0
	s_barrier
	s_add_i32 s51, 0, 0x18000
	s_add_i32 s52, 0, 0x1c000
	v_add_u32_e32 v162, s51, v149
	v_add_u32_e32 v178, s52, v149
	ds_read_b128 v[144:147], v162
	ds_read_b128 v[154:157], v162 offset:1024
	ds_read_b128 v[158:161], v162 offset:2048
	ds_read_b128 v[162:165], v162 offset:3072
	ds_read_b128 v[166:169], v178
	ds_read_b128 v[170:173], v178 offset:1024
	ds_read_b128 v[174:177], v178 offset:2048
	ds_read_b128 v[178:181], v178 offset:3072
	s_add_u32 s24, s24, 0x80000
	s_addc_u32 s25, s25, 0
	s_mov_b32 m0, s36
	v_lshl_add_u64 v[222:223], s[24:25], 0, v[134:135]
	ds_read_b128 v[182:185], v153 offset:32768
	ds_read_b128 v[186:189], v153 offset:33792
	ds_read_b128 v[190:193], v153 offset:34816
	ds_read_b128 v[194:197], v153 offset:35840
	ds_read_b128 v[198:201], v153 offset:36864
	ds_read_b128 v[202:205], v153 offset:37888
	ds_read_b128 v[206:209], v153 offset:38912
	ds_read_b128 v[210:213], v153 offset:39936
	global_load_lds_dwordx4 v[222:223], off
	v_lshl_add_u64 v[222:223], s[24:25], 0, v[130:131]
	s_mov_b32 m0, s37
	s_nop 0
	global_load_lds_dwordx4 v[222:223], off
	s_waitcnt vmcnt(8)
	s_waitcnt lgkmcnt(0)
	s_barrier
	s_setprio 1
	s_waitcnt lgkmcnt(0)
	v_mfma_f32_16x16x32_bf16 v[124:127], v[144:147], v[182:185], v[124:127]
	v_mfma_f32_16x16x32_bf16 v[120:123], v[158:161], v[182:185], v[120:123]
	v_mfma_f32_16x16x32_bf16 v[116:119], v[144:147], v[190:193], v[116:119]
	v_mfma_f32_16x16x32_bf16 v[108:111], v[158:161], v[190:193], v[108:111]
	v_mfma_f32_16x16x32_bf16 v[100:103], v[144:147], v[198:201], v[100:103]
	v_mfma_f32_16x16x32_bf16 v[92:95], v[158:161], v[198:201], v[92:95]
	v_mfma_f32_16x16x32_bf16 v[84:87], v[144:147], v[206:209], v[84:87]
	v_mfma_f32_16x16x32_bf16 v[76:79], v[158:161], v[206:209], v[76:79]
	v_mfma_f32_16x16x32_bf16 v[124:127], v[154:157], v[186:189], v[124:127]
	v_mfma_f32_16x16x32_bf16 v[120:123], v[162:165], v[186:189], v[120:123]
	v_mfma_f32_16x16x32_bf16 v[116:119], v[154:157], v[194:197], v[116:119]
	v_mfma_f32_16x16x32_bf16 v[108:111], v[162:165], v[194:197], v[108:111]
	v_mfma_f32_16x16x32_bf16 v[100:103], v[154:157], v[202:205], v[100:103]
	v_mfma_f32_16x16x32_bf16 v[92:95], v[162:165], v[202:205], v[92:95]
	v_mfma_f32_16x16x32_bf16 v[84:87], v[154:157], v[210:213], v[84:87]
	v_mfma_f32_16x16x32_bf16 v[76:79], v[162:165], v[210:213], v[76:79]
	s_setprio 0
	s_setprio 1
	v_mfma_f32_16x16x32_bf16 v[112:115], v[166:169], v[182:185], v[112:115]
	v_mfma_f32_16x16x32_bf16 v[104:107], v[174:177], v[182:185], v[104:107]
	v_mfma_f32_16x16x32_bf16 v[96:99], v[166:169], v[190:193], v[96:99]
	v_mfma_f32_16x16x32_bf16 v[88:91], v[174:177], v[190:193], v[88:91]
	v_mfma_f32_16x16x32_bf16 v[80:83], v[166:169], v[198:201], v[80:83]
	v_mfma_f32_16x16x32_bf16 v[72:75], v[174:177], v[198:201], v[72:75]
	v_mfma_f32_16x16x32_bf16 v[68:71], v[166:169], v[206:209], v[68:71]
	v_mfma_f32_16x16x32_bf16 v[64:67], v[174:177], v[206:209], v[64:67]
	v_mfma_f32_16x16x32_bf16 v[112:115], v[170:173], v[186:189], v[112:115]
	v_mfma_f32_16x16x32_bf16 v[104:107], v[178:181], v[186:189], v[104:107]
	v_mfma_f32_16x16x32_bf16 v[96:99], v[170:173], v[194:197], v[96:99]
	v_mfma_f32_16x16x32_bf16 v[88:91], v[178:181], v[194:197], v[88:91]
	v_mfma_f32_16x16x32_bf16 v[80:83], v[170:173], v[202:205], v[80:83]
	v_mfma_f32_16x16x32_bf16 v[72:75], v[178:181], v[202:205], v[72:75]
	v_mfma_f32_16x16x32_bf16 v[68:71], v[170:173], v[210:213], v[68:71]
	v_mfma_f32_16x16x32_bf16 v[64:67], v[178:181], v[210:213], v[64:67]
	s_setprio 0
	s_barrier
; #define PG8_STAGE(bufoff, gbase, voff) do { _Pragma("unroll") for (int _i = 0; _i < 2; ++_i) \
;         __builtin_amdgcn_global_load_lds((const unsigned*)((const char*)(gbase) + (voff)[_i]), (PG8_LAS unsigned*)(lds + (bufoff) + ldsw + _i * 8192), 16, 0, 0); } while (0)
; #define PG8_LDA(dst, b, h) do { _Pragma("unroll") for (int m = 0; m < 4; ++m) _Pragma("unroll") for (int k = 0; k < 2; ++k) dst[m][k] = *(const PG8_LAS bf16x8*)(lds + PG8_SA(b, h) + aoff + m * 2048 + k * 1024); } while (0)
; #define PG8_MMA(ai, bj, At, Bt) do { __builtin_amdgcn_s_setprio(1); _Pragma("unroll") for (int m = 0; m < 4; ++m) _Pragma("unroll") for (int n = 0; n < 2; ++n) _Pragma("unroll") for (int k = 0; k < 2; ++k) \
;         acc[ai][bj][m][n] = __builtin_amdgcn_mfma_f32_16x16x32_bf16(Bt[n][k], At[m][k], acc[ai][bj][m][n], 0, 0, 0); __builtin_amdgcn_s_setprio(0); } while (0)
; #define PG8_WAIT_V(n) asm volatile("s_waitcnt vmcnt(" #n ")" ::: "memory")
; #define PG8_WAIT_L(n) asm volatile("s_waitcnt lgkmcnt(" #n ")" ::: "memory")
; #define PG8_BAR __builtin_amdgcn_s_barrier()
; #define PG8_SCHED __builtin_amdgcn_sched_barrier(0)
; template <class Epi, class Sched, bool ALIGN_EPI = false, bool SP2 = false>
; __device__ __forceinline__ void gemm_phase(PG8_LAS unsigned char* lds, const Gemm g, const Sched& S, const Epi& E, const int wave_in) {
;     ...
;             PG8_LDA(At, 1, 1); PG8_STAGE(PG8_SB(1, 0), b3, voffB); PG8_STAGE(PG8_SB(1, 1), b3 + hstepB, voffB); PG8_STAGE(PG8_SA(1, 0), a3, voffA);
;             PG8_WAIT_V(8); PG8_WAIT_L(0); PG8_BAR; PG8_MMA(1, 0, At, B0); PG8_MMA(1, 1, At, B1); PG8_BAR; PG8_SCHED;
	s_add_i32 s24, s51, s30
	v_lshl_add_u64 v[214:215], v[214:215], 0, s[6:7]
	s_mov_b32 m0, s24
	ds_read_b128 v[182:185], v153 offset:49152
	ds_read_b128 v[186:189], v153 offset:50176
	ds_read_b128 v[190:193], v153 offset:51200
	ds_read_b128 v[194:197], v153 offset:52224
	ds_read_b128 v[198:201], v153 offset:53248
	ds_read_b128 v[202:205], v153 offset:54272
	ds_read_b128 v[206:209], v153 offset:55296
	ds_read_b128 v[210:213], v153 offset:56320
	global_load_lds_dwordx4 v[214:215], off
	s_add_i32 m0, s24, 0x2000
	s_add_u32 s22, s22, 0x80080
	v_lshl_add_u64 v[214:215], v[216:217], 0, s[6:7]
	s_addc_u32 s23, s23, 0
	s_add_i32 s24, s52, s30
	global_load_lds_dwordx4 v[214:215], off
	v_lshl_add_u64 v[214:215], s[22:23], 0, v[132:133]
	s_mov_b32 m0, s24
	s_nop 0
	global_load_lds_dwordx4 v[214:215], off
	v_lshl_add_u64 v[214:215], s[22:23], 0, v[128:129]
	s_add_i32 m0, s24, 0x2000
	s_nop 0
	global_load_lds_dwordx4 v[214:215], off
	v_lshl_add_u64 v[214:215], v[218:219], 0, s[6:7]
	s_mov_b32 m0, s39
	s_nop 0
	global_load_lds_dwordx4 v[214:215], off
	v_lshl_add_u64 v[214:215], v[220:221], 0, s[6:7]
	s_mov_b32 m0, s40
	s_nop 0
	global_load_lds_dwordx4 v[214:215], off
	s_waitcnt vmcnt(8)
	s_waitcnt lgkmcnt(0)
	s_barrier
	s_setprio 1
	s_waitcnt lgkmcnt(0)
	v_mfma_f32_16x16x32_bf16 v[60:63], v[144:147], v[182:185], v[60:63]
	v_mfma_f32_16x16x32_bf16 v[56:59], v[158:161], v[182:185], v[56:59]
	v_mfma_f32_16x16x32_bf16 v[52:55], v[144:147], v[190:193], v[52:55]
	v_mfma_f32_16x16x32_bf16 v[44:47], v[158:161], v[190:193], v[44:47]
	v_mfma_f32_16x16x32_bf16 v[36:39], v[144:147], v[198:201], v[36:39]
	v_mfma_f32_16x16x32_bf16 v[28:31], v[158:161], v[198:201], v[28:31]
	v_mfma_f32_16x16x32_bf16 v[20:23], v[144:147], v[206:209], v[20:23]
	v_mfma_f32_16x16x32_bf16 v[12:15], v[158:161], v[206:209], v[12:15]
	v_mfma_f32_16x16x32_bf16 v[60:63], v[154:157], v[186:189], v[60:63]
	v_mfma_f32_16x16x32_bf16 v[56:59], v[162:165], v[186:189], v[56:59]
	v_mfma_f32_16x16x32_bf16 v[52:55], v[154:157], v[194:197], v[52:55]
	v_mfma_f32_16x16x32_bf16 v[44:47], v[162:165], v[194:197], v[44:47]
	v_mfma_f32_16x16x32_bf16 v[36:39], v[154:157], v[202:205], v[36:39]
	v_mfma_f32_16x16x32_bf16 v[28:31], v[162:165], v[202:205], v[28:31]
	v_mfma_f32_16x16x32_bf16 v[20:23], v[154:157], v[210:213], v[20:23]
	v_mfma_f32_16x16x32_bf16 v[12:15], v[162:165], v[210:213], v[12:15]
	s_setprio 0
	s_setprio 1
	v_mfma_f32_16x16x32_bf16 v[48:51], v[166:169], v[182:185], v[48:51]
	v_mfma_f32_16x16x32_bf16 v[40:43], v[174:177], v[182:185], v[40:43]
	v_mfma_f32_16x16x32_bf16 v[32:35], v[166:169], v[190:193], v[32:35]
	v_mfma_f32_16x16x32_bf16 v[24:27], v[174:177], v[190:193], v[24:27]
	v_mfma_f32_16x16x32_bf16 v[16:19], v[166:169], v[198:201], v[16:19]
	v_mfma_f32_16x16x32_bf16 v[8:11], v[174:177], v[198:201], v[8:11]
	v_mfma_f32_16x16x32_bf16 v[4:7], v[166:169], v[206:209], v[4:7]
	v_mfma_f32_16x16x32_bf16 v[0:3], v[174:177], v[206:209], v[0:3]
	v_mfma_f32_16x16x32_bf16 v[48:51], v[170:173], v[186:189], v[48:51]
	v_mfma_f32_16x16x32_bf16 v[40:43], v[178:181], v[186:189], v[40:43]
	v_mfma_f32_16x16x32_bf16 v[32:35], v[170:173], v[194:197], v[32:35]
	v_mfma_f32_16x16x32_bf16 v[24:27], v[178:181], v[194:197], v[24:27]
	v_mfma_f32_16x16x32_bf16 v[16:19], v[170:173], v[202:205], v[16:19]
	v_mfma_f32_16x16x32_bf16 v[8:11], v[178:181], v[202:205], v[8:11]
	v_mfma_f32_16x16x32_bf16 v[4:7], v[170:173], v[210:213], v[4:7]
	v_mfma_f32_16x16x32_bf16 v[0:3], v[178:181], v[210:213], v[0:3]
	s_setprio 0
	s_barrier
	s_add_i32 s50, s50, 2
	s_add_u32 s20, s20, 0x100
	s_addc_u32 s21, s21, 0
	s_add_u32 s48, s48, 0x100
	s_addc_u32 s49, s49, 0
	s_cmp_gt_u32 s50, 29
	s_cbranch_scc0 .LBB0_1513
	s_branch .Lkx_18

;     __host__ __device__ bool next(int i, Unit& u) const { const bool ok = StaticOrder::next(i, u); u.pm = 0; u.pn = 0; return ok; }
; #define PG8_STAGE(bufoff, gbase, voff) do { _Pragma("unroll") for (int _i = 0; _i < 2; ++_i) \
;         __builtin_amdgcn_global_load_lds((const unsigned*)((const char*)(gbase) + (voff)[_i]), (PG8_LAS unsigned*)(lds + (bufoff) + ldsw + _i * 8192), 16, 0, 0); } while (0)
; #define PG8_LDA(dst, b, h) do { _Pragma("unroll") for (int m = 0; m < 4; ++m) _Pragma("unroll") for (int k = 0; k < 2; ++k) dst[m][k] = *(const PG8_LAS bf16x8*)(lds + PG8_SA(b, h) + aoff + m * 2048 + k * 1024); } while (0)
; #define PG8_LDB(dst, b, h) do { _Pragma("unroll") for (int n = 0; n < 2; ++n) _Pragma("unroll") for (int k = 0; k < 2; ++k) dst[n][k] = *(const PG8_LAS bf16x8*)(lds + PG8_SB(b, h) + boff + n * 2048 + k * 1024); } while (0)
; #define PG8_WAIT_V(n) asm volatile("s_waitcnt vmcnt(" #n ")" ::: "memory")
; #define PG8_BAR __builtin_amdgcn_s_barrier()
; template <class Epi, class Sched, bool ALIGN_EPI = false, bool SP2 = false>
; __device__ __forceinline__ void gemm_phase(PG8_LAS unsigned char* lds, const Gemm g, const Sched& S, const Epi& E, const int wave_in) {
;     ...
;         const bool has_next = S.next(ui + 1, nxt);
;         const char* nA = has_next ? (const char*)g.A + (size_t)nxt.pm * tstepA : cA; const char* nB = has_next ? (const char*)g.Bt + (size_t)nxt.pn * tstepB : cB;
;         for (int t = 0; t < nt; t += 2) {
;             const bool last = (t == nt - 2);
;             const char* a1 = cA + (size_t)(t + 1) * kstep;
;             const char* a2 = last ? nA : cA + (size_t)(t + 2) * kstep; const char* b2 = last ? nB : cB + (size_t)(t + 2) * kstep;
;             const char* a3 = a2 + kstep; const char* b3 = b2 + kstep;
;             if (last && has_next) S.a_ready(nxt);
;             if constexpr (SP2) {
;             PG8_LDB(B0, 0, 0); PG8_LDB(B1, 0, 1); PG8_SCHED; PG8_LDA(At, 0, 0); PG8_STAGE(PG8_SA(1, 1), a1 + hstepA, voffA);
;             PG8_WAIT_V(8); PG8_WAIT_L(0); PG8_BAR; PG8_MMA(0, 0, At, B0); PG8_MMA(0, 1, At, B1); PG8_BAR; PG8_SCHED;
;             PG8_LDA(At, 0, 1); PG8_STAGE(PG8_SB(0, 0), b2, voffB); PG8_STAGE(PG8_SB(0, 1), b2 + hstepB, voffB); PG8_STAGE(PG8_SA(0, 0), a2, voffA);
;             PG8_WAIT_V(8); PG8_WAIT_L(0); PG8_BAR; PG8_MMA(1, 0, At, B0); PG8_MMA(1, 1, At, B1); PG8_BAR; PG8_SCHED;
.LBB0_1824:
	s_ashr_i32 s19, s18, 31
	s_lshl_b64 s[20:21], s[18:19], 20
	s_add_u32 s20, s34, s20
	s_addc_u32 s21, s35, s21
	s_and_b64 s[22:23], s[2:3], exec
	s_cselect_b32 s19, s21, s27
	s_cselect_b32 s25, s20, s26
	s_ashr_i32 s17, s16, 31
	s_lshl_b64 s[22:23], s[16:17], 20
	s_add_u32 s22, s36, s22
	s_addc_u32 s23, s37, s23
	s_and_b64 s[30:31], s[2:3], exec
	s_cselect_b32 s17, s23, s29
	s_cselect_b32 s58, s22, s28
	s_add_u32 s26, s26, 0x80080
	s_addc_u32 s27, s27, 0
	s_add_u32 s59, s28, 0x100
	v_mov_b32_e32 v0, 0
	s_addc_u32 s60, s29, 0
	s_mov_b32 s61, -2
	s_waitcnt vmcnt(0)
	ds_read_b128 v[128:131], v214
	ds_read_b128 v[132:135], v214 offset:1024
	ds_read_b128 v[136:139], v214 offset:2048
	ds_read_b128 v[140:143], v214 offset:3072
	ds_read_b128 v[162:165], v215
	ds_read_b128 v[166:169], v215 offset:1024
	ds_read_b128 v[170:173], v215 offset:2048
	ds_read_b128 v[174:177], v215 offset:3072
	s_add_u32 s28, s26, 0xfff80080
	s_addc_u32 s29, s27, -1
	s_cmp_eq_u32 s61, 28
	s_cselect_b32 s31, s19, s29
	s_cselect_b32 s30, s25, s28
	s_cselect_b32 s29, s17, s60
	s_cselect_b32 s28, s58, s59
	v_lshl_add_u64 v[210:211], s[26:27], 0, v[154:155]
	s_add_i32 m0, s41, 0xc000
	ds_read_b128 v[178:181], v216
	ds_read_b128 v[182:185], v216 offset:1024
	ds_read_b128 v[186:189], v216 offset:2048
	ds_read_b128 v[190:193], v216 offset:3072
	ds_read_b128 v[194:197], v216 offset:4096
	ds_read_b128 v[198:201], v216 offset:5120
	ds_read_b128 v[202:205], v216 offset:6144
	ds_read_b128 v[206:209], v216 offset:7168
	global_load_lds_dwordx4 v[210:211], off
	v_lshl_add_u64 v[210:211], s[26:27], 0, v[156:157]
	s_add_i32 m0, s41, 0xe000
	s_nop 0
	global_load_lds_dwordx4 v[210:211], off
	s_waitcnt vmcnt(8)
	s_waitcnt lgkmcnt(0)
	s_barrier
	s_setprio 1
	s_waitcnt lgkmcnt(0)
	v_mfma_f32_16x16x32_bf16 v[124:127], v[128:131], v[178:181], 0
	v_mfma_f32_16x16x32_bf16 v[120:123], v[136:139], v[178:181], 0
	v_mfma_f32_16x16x32_bf16 v[112:115], v[128:131], v[186:189], 0
	v_mfma_f32_16x16x32_bf16 v[104:107], v[136:139], v[186:189], 0
	v_mfma_f32_16x16x32_bf16 v[100:103], v[128:131], v[194:197], 0
	v_mfma_f32_16x16x32_bf16 v[96:99], v[136:139], v[194:197], 0
	v_mfma_f32_16x16x32_bf16 v[76:79], v[128:131], v[202:205], 0
	v_mfma_f32_16x16x32_bf16 v[72:75], v[136:139], v[202:205], 0
	v_mfma_f32_16x16x32_bf16 v[124:127], v[132:135], v[182:185], v[124:127]
	v_mfma_f32_16x16x32_bf16 v[120:123], v[140:143], v[182:185], v[120:123]
	v_mfma_f32_16x16x32_bf16 v[112:115], v[132:135], v[190:193], v[112:115]
	v_mfma_f32_16x16x32_bf16 v[104:107], v[140:143], v[190:193], v[104:107]
	v_mfma_f32_16x16x32_bf16 v[100:103], v[132:135], v[198:201], v[100:103]
	v_mfma_f32_16x16x32_bf16 v[96:99], v[140:143], v[198:201], v[96:99]
	v_mfma_f32_16x16x32_bf16 v[76:79], v[132:135], v[206:209], v[76:79]
	v_mfma_f32_16x16x32_bf16 v[72:75], v[140:143], v[206:209], v[72:75]
	s_setprio 0
	s_setprio 1
	v_mfma_f32_16x16x32_bf16 v[116:119], v[162:165], v[178:181], 0
	v_mfma_f32_16x16x32_bf16 v[108:111], v[170:173], v[178:181], 0
	v_mfma_f32_16x16x32_bf16 v[92:95], v[162:165], v[186:189], 0
	v_mfma_f32_16x16x32_bf16 v[88:91], v[170:173], v[186:189], 0
	v_mfma_f32_16x16x32_bf16 v[84:87], v[162:165], v[194:197], 0
	v_mfma_f32_16x16x32_bf16 v[80:83], v[170:173], v[194:197], 0
	v_mfma_f32_16x16x32_bf16 v[68:71], v[162:165], v[202:205], 0
	v_mfma_f32_16x16x32_bf16 v[64:67], v[170:173], v[202:205], 0
	v_mfma_f32_16x16x32_bf16 v[116:119], v[166:169], v[182:185], v[116:119]
	v_mfma_f32_16x16x32_bf16 v[108:111], v[174:177], v[182:185], v[108:111]
	v_mfma_f32_16x16x32_bf16 v[92:95], v[166:169], v[190:193], v[92:95]
	v_mfma_f32_16x16x32_bf16 v[88:91], v[174:177], v[190:193], v[88:91]
	v_mfma_f32_16x16x32_bf16 v[84:87], v[166:169], v[198:201], v[84:87]
	v_mfma_f32_16x16x32_bf16 v[80:83], v[174:177], v[198:201], v[80:83]
	v_mfma_f32_16x16x32_bf16 v[68:71], v[166:169], v[206:209], v[68:71]
	v_mfma_f32_16x16x32_bf16 v[64:67], v[174:177], v[206:209], v[64:67]
	s_setprio 0
	s_barrier
	s_add_i32 s62, s51, s38
	v_lshl_add_u64 v[210:211], s[28:29], 0, v[148:149]
	s_mov_b32 m0, s62
	ds_read_b128 v[178:181], v216 offset:16384
	ds_read_b128 v[182:185], v216 offset:17408
	ds_read_b128 v[186:189], v216 offset:18432
	ds_read_b128 v[190:193], v216 offset:19456
	ds_read_b128 v[194:197], v216 offset:20480
	ds_read_b128 v[198:201], v216 offset:21504
	ds_read_b128 v[202:205], v216 offset:22528
	ds_read_b128 v[206:209], v216 offset:23552
	global_load_lds_dwordx4 v[210:211], off
	s_add_i32 m0, s62, 0x2000
	s_add_u32 s62, s28, 0x80000
	v_lshl_add_u64 v[218:219], s[28:29], 0, v[144:145]
	s_addc_u32 s63, s29, 0
	s_add_i32 s64, s52, s38
	global_load_lds_dwordx4 v[218:219], off
	v_lshl_add_u64 v[220:221], s[62:63], 0, v[148:149]
	s_mov_b32 m0, s64
	v_lshl_add_u64 v[222:223], s[30:31], 0, v[146:147]
	global_load_lds_dwordx4 v[220:221], off
	v_lshl_add_u64 v[220:221], s[62:63], 0, v[144:145]
	s_add_i32 m0, s64, 0x2000
	s_nop 0
	global_load_lds_dwordx4 v[220:221], off
	v_lshl_add_u64 v[220:221], s[30:31], 0, v[150:151]
	s_mov_b32 m0, s41
	s_nop 0
	global_load_lds_dwordx4 v[220:221], off
	s_mov_b32 m0, s42
	s_nop 0
	global_load_lds_dwordx4 v[222:223], off
	s_waitcnt vmcnt(8)
	s_waitcnt lgkmcnt(0)
	s_barrier
; #define PG8_STAGE(bufoff, gbase, voff) do { _Pragma("unroll") for (int _i = 0; _i < 2; ++_i) \
;         __builtin_amdgcn_global_load_lds((const unsigned*)((const char*)(gbase) + (voff)[_i]), (PG8_LAS unsigned*)(lds + (bufoff) + ldsw + _i * 8192), 16, 0, 0); } while (0)
; #define PG8_LDA(dst, b, h) do { _Pragma("unroll") for (int m = 0; m < 4; ++m) _Pragma("unroll") for (int k = 0; k < 2; ++k) dst[m][k] = *(const PG8_LAS bf16x8*)(lds + PG8_SA(b, h) + aoff + m * 2048 + k * 1024); } while (0)
; #define PG8_LDB(dst, b, h) do { _Pragma("unroll") for (int n = 0; n < 2; ++n) _Pragma("unroll") for (int k = 0; k < 2; ++k) dst[n][k] = *(const PG8_LAS bf16x8*)(lds + PG8_SB(b, h) + boff + n * 2048 + k * 1024); } while (0)
; #define PG8_MMA(ai, bj, At, Bt) do { __builtin_amdgcn_s_setprio(1); _Pragma("unroll") for (int m = 0; m < 4; ++m) _Pragma("unroll") for (int n = 0; n < 2; ++n) _Pragma("unroll") for (int k = 0; k < 2; ++k) \
;         acc[ai][bj][m][n] = __builtin_amdgcn_mfma_f32_16x16x32_bf16(Bt[n][k], At[m][k], acc[ai][bj][m][n], 0, 0, 0); __builtin_amdgcn_s_setprio(0); } while (0)
; #define PG8_WAIT_V(n) asm volatile("s_waitcnt vmcnt(" #n ")" ::: "memory")
; #define PG8_WAIT_L(n) asm volatile("s_waitcnt lgkmcnt(" #n ")" ::: "memory")
; #define PG8_BAR __builtin_amdgcn_s_barrier()
; #define PG8_SCHED __builtin_amdgcn_sched_barrier(0)
; template <class Epi, class Sched, bool ALIGN_EPI = false, bool SP2 = false>
; __device__ __forceinline__ void gemm_phase(PG8_LAS unsigned char* lds, const Gemm g, const Sched& S, const Epi& E, const int wave_in) {
;     ...
;             PG8_WAIT_V(8); PG8_WAIT_L(0); PG8_BAR; PG8_MMA(1, 0, At, B0); PG8_MMA(1, 1, At, B1); PG8_BAR; PG8_SCHED;
;             PG8_LDB(B0, 1, 0); PG8_LDB(B1, 1, 1); PG8_SCHED; PG8_LDA(At, 1, 0); PG8_STAGE(PG8_SA(0, 1), a2 + hstepA, voffA);
;             PG8_WAIT_V(8); PG8_WAIT_L(0); PG8_BAR; PG8_MMA(0, 0, At, B0); PG8_MMA(0, 1, At, B1); PG8_BAR; PG8_SCHED;
	s_setprio 1
	s_waitcnt lgkmcnt(0)
	v_mfma_f32_16x16x32_bf16 v[60:63], v[128:131], v[178:181], 0
	v_mfma_f32_16x16x32_bf16 v[56:59], v[136:139], v[178:181], 0
	v_mfma_f32_16x16x32_bf16 v[48:51], v[128:131], v[186:189], 0
	v_mfma_f32_16x16x32_bf16 v[40:43], v[136:139], v[186:189], 0
	v_mfma_f32_16x16x32_bf16 v[32:35], v[128:131], v[194:197], 0
	v_mfma_f32_16x16x32_bf16 v[24:27], v[136:139], v[194:197], 0
	v_mfma_f32_16x16x32_bf16 v[16:19], v[128:131], v[202:205], 0
	v_mfma_f32_16x16x32_bf16 v[8:11], v[136:139], v[202:205], 0
	v_mfma_f32_16x16x32_bf16 v[60:63], v[132:135], v[182:185], v[60:63]
	v_mfma_f32_16x16x32_bf16 v[56:59], v[140:143], v[182:185], v[56:59]
	v_mfma_f32_16x16x32_bf16 v[48:51], v[132:135], v[190:193], v[48:51]
	v_mfma_f32_16x16x32_bf16 v[40:43], v[140:143], v[190:193], v[40:43]
	v_mfma_f32_16x16x32_bf16 v[32:35], v[132:135], v[198:201], v[32:35]
	v_mfma_f32_16x16x32_bf16 v[24:27], v[140:143], v[198:201], v[24:27]
	v_mfma_f32_16x16x32_bf16 v[16:19], v[132:135], v[206:209], v[16:19]
	v_mfma_f32_16x16x32_bf16 v[8:11], v[140:143], v[206:209], v[8:11]
	s_setprio 0
	s_setprio 1
	v_mfma_f32_16x16x32_bf16 v[52:55], v[162:165], v[178:181], 0
	v_mfma_f32_16x16x32_bf16 v[44:47], v[170:173], v[178:181], 0
	v_mfma_f32_16x16x32_bf16 v[36:39], v[162:165], v[186:189], 0
	v_mfma_f32_16x16x32_bf16 v[28:31], v[170:173], v[186:189], 0
	v_mfma_f32_16x16x32_bf16 v[20:23], v[162:165], v[194:197], 0
	v_mfma_f32_16x16x32_bf16 v[12:15], v[170:173], v[194:197], 0
	v_mfma_f32_16x16x32_bf16 v[4:7], v[162:165], v[202:205], 0
	v_mfma_f32_16x16x32_bf16 v[0:3], v[170:173], v[202:205], 0
	v_mfma_f32_16x16x32_bf16 v[52:55], v[166:169], v[182:185], v[52:55]
	v_mfma_f32_16x16x32_bf16 v[44:47], v[174:177], v[182:185], v[44:47]
	v_mfma_f32_16x16x32_bf16 v[36:39], v[166:169], v[190:193], v[36:39]
	v_mfma_f32_16x16x32_bf16 v[28:31], v[174:177], v[190:193], v[28:31]
	v_mfma_f32_16x16x32_bf16 v[20:23], v[166:169], v[198:201], v[20:23]
	v_mfma_f32_16x16x32_bf16 v[12:15], v[174:177], v[198:201], v[12:15]
	v_mfma_f32_16x16x32_bf16 v[4:7], v[166:169], v[206:209], v[4:7]
	v_mfma_f32_16x16x32_bf16 v[0:3], v[174:177], v[206:209], v[0:3]
	s_setprio 0
	s_barrier
	s_add_i32 s62, 0, 0x18000
	s_add_i32 s63, 0, 0x1c000
	v_add_u32_e32 v140, s62, v212
	v_add_u32_e32 v174, s63, v212
	ds_read_b128 v[128:131], v140
	ds_read_b128 v[132:135], v140 offset:1024
	ds_read_b128 v[136:139], v140 offset:2048
	ds_read_b128 v[140:143], v140 offset:3072
	ds_read_b128 v[162:165], v174
	ds_read_b128 v[166:169], v174 offset:1024
	ds_read_b128 v[170:173], v174 offset:2048
	ds_read_b128 v[174:177], v174 offset:3072
	s_add_u32 s30, s30, 0x80000
	s_addc_u32 s31, s31, 0
	s_mov_b32 m0, s43
	v_lshl_add_u64 v[224:225], s[30:31], 0, v[150:151]
	ds_read_b128 v[178:181], v216 offset:32768
	ds_read_b128 v[182:185], v216 offset:33792
	ds_read_b128 v[186:189], v216 offset:34816
	ds_read_b128 v[190:193], v216 offset:35840
	ds_read_b128 v[194:197], v216 offset:36864
	ds_read_b128 v[198:201], v216 offset:37888
	ds_read_b128 v[202:205], v216 offset:38912
	ds_read_b128 v[206:209], v216 offset:39936
	global_load_lds_dwordx4 v[224:225], off
	v_lshl_add_u64 v[224:225], s[30:31], 0, v[146:147]
	s_mov_b32 m0, s44
	s_nop 0
	global_load_lds_dwordx4 v[224:225], off
	s_waitcnt vmcnt(8)
	s_waitcnt lgkmcnt(0)
	s_barrier
	s_setprio 1
	s_waitcnt lgkmcnt(0)
	v_mfma_f32_16x16x32_bf16 v[124:127], v[128:131], v[178:181], v[124:127]
	v_mfma_f32_16x16x32_bf16 v[120:123], v[136:139], v[178:181], v[120:123]
	v_mfma_f32_16x16x32_bf16 v[112:115], v[128:131], v[186:189], v[112:115]
	v_mfma_f32_16x16x32_bf16 v[104:107], v[136:139], v[186:189], v[104:107]
	v_mfma_f32_16x16x32_bf16 v[100:103], v[128:131], v[194:197], v[100:103]
	v_mfma_f32_16x16x32_bf16 v[96:99], v[136:139], v[194:197], v[96:99]
	v_mfma_f32_16x16x32_bf16 v[76:79], v[128:131], v[202:205], v[76:79]
	v_mfma_f32_16x16x32_bf16 v[72:75], v[136:139], v[202:205], v[72:75]
	v_mfma_f32_16x16x32_bf16 v[124:127], v[132:135], v[182:185], v[124:127]
	v_mfma_f32_16x16x32_bf16 v[120:123], v[140:143], v[182:185], v[120:123]
	v_mfma_f32_16x16x32_bf16 v[112:115], v[132:135], v[190:193], v[112:115]
	v_mfma_f32_16x16x32_bf16 v[104:107], v[140:143], v[190:193], v[104:107]
	v_mfma_f32_16x16x32_bf16 v[100:103], v[132:135], v[198:201], v[100:103]
	v_mfma_f32_16x16x32_bf16 v[96:99], v[140:143], v[198:201], v[96:99]
	v_mfma_f32_16x16x32_bf16 v[76:79], v[132:135], v[206:209], v[76:79]
	v_mfma_f32_16x16x32_bf16 v[72:75], v[140:143], v[206:209], v[72:75]
	s_setprio 0
	s_setprio 1
	v_mfma_f32_16x16x32_bf16 v[116:119], v[162:165], v[178:181], v[116:119]
	v_mfma_f32_16x16x32_bf16 v[108:111], v[170:173], v[178:181], v[108:111]
	v_mfma_f32_16x16x32_bf16 v[92:95], v[162:165], v[186:189], v[92:95]
	v_mfma_f32_16x16x32_bf16 v[88:91], v[170:173], v[186:189], v[88:91]
	v_mfma_f32_16x16x32_bf16 v[84:87], v[162:165], v[194:197], v[84:87]
	v_mfma_f32_16x16x32_bf16 v[80:83], v[170:173], v[194:197], v[80:83]
	v_mfma_f32_16x16x32_bf16 v[68:71], v[162:165], v[202:205], v[68:71]
	v_mfma_f32_16x16x32_bf16 v[64:67], v[170:173], v[202:205], v[64:67]
	v_mfma_f32_16x16x32_bf16 v[116:119], v[166:169], v[182:185], v[116:119]
	v_mfma_f32_16x16x32_bf16 v[108:111], v[174:177], v[182:185], v[108:111]
	v_mfma_f32_16x16x32_bf16 v[92:95], v[166:169], v[190:193], v[92:95]
	v_mfma_f32_16x16x32_bf16 v[88:91], v[174:177], v[190:193], v[88:91]
	v_mfma_f32_16x16x32_bf16 v[84:87], v[166:169], v[198:201], v[84:87]
	v_mfma_f32_16x16x32_bf16 v[80:83], v[174:177], v[198:201], v[80:83]
	v_mfma_f32_16x16x32_bf16 v[68:71], v[166:169], v[206:209], v[68:71]
	v_mfma_f32_16x16x32_bf16 v[64:67], v[174:177], v[206:209], v[64:67]
	s_setprio 0
	s_barrier
; #define PG8_STAGE(bufoff, gbase, voff) do { _Pragma("unroll") for (int _i = 0; _i < 2; ++_i) \
;         __builtin_amdgcn_global_load_lds((const unsigned*)((const char*)(gbase) + (voff)[_i]), (PG8_LAS unsigned*)(lds + (bufoff) + ldsw + _i * 8192), 16, 0, 0); } while (0)
; #define PG8_LDA(dst, b, h) do { _Pragma("unroll") for (int m = 0; m < 4; ++m) _Pragma("unroll") for (int k = 0; k < 2; ++k) dst[m][k] = *(const PG8_LAS bf16x8*)(lds + PG8_SA(b, h) + aoff + m * 2048 + k * 1024); } while (0)
; #define PG8_MMA(ai, bj, At, Bt) do { __builtin_amdgcn_s_setprio(1); _Pragma("unroll") for (int m = 0; m < 4; ++m) _Pragma("unroll") for (int n = 0; n < 2; ++n) _Pragma("unroll") for (int k = 0; k < 2; ++k) \
;         acc[ai][bj][m][n] = __builtin_amdgcn_mfma_f32_16x16x32_bf16(Bt[n][k], At[m][k], acc[ai][bj][m][n], 0, 0, 0); __builtin_amdgcn_s_setprio(0); } while (0)
; #define PG8_WAIT_V(n) asm volatile("s_waitcnt vmcnt(" #n ")" ::: "memory")
; #define PG8_WAIT_L(n) asm volatile("s_waitcnt lgkmcnt(" #n ")" ::: "memory")
; #define PG8_BAR __builtin_amdgcn_s_barrier()
; #define PG8_SCHED __builtin_amdgcn_sched_barrier(0)
; template <class Epi, class Sched, bool ALIGN_EPI = false, bool SP2 = false>
; __device__ __forceinline__ void gemm_phase(PG8_LAS unsigned char* lds, const Gemm g, const Sched& S, const Epi& E, const int wave_in) {
;     ...
;             PG8_LDA(At, 1, 1); PG8_STAGE(PG8_SB(1, 0), b3, voffB); PG8_STAGE(PG8_SB(1, 1), b3 + hstepB, voffB); PG8_STAGE(PG8_SA(1, 0), a3, voffA);
;             PG8_WAIT_V(8); PG8_WAIT_L(0); PG8_BAR; PG8_MMA(1, 0, At, B0); PG8_MMA(1, 1, At, B1); PG8_BAR; PG8_SCHED;
	s_add_i32 s30, s62, s38
	v_lshl_add_u64 v[210:211], v[210:211], 0, s[6:7]
	s_mov_b32 m0, s30
	ds_read_b128 v[178:181], v216 offset:49152
	ds_read_b128 v[182:185], v216 offset:50176
	ds_read_b128 v[186:189], v216 offset:51200
	ds_read_b128 v[190:193], v216 offset:52224
	ds_read_b128 v[194:197], v216 offset:53248
	ds_read_b128 v[198:201], v216 offset:54272
	ds_read_b128 v[202:205], v216 offset:55296
	ds_read_b128 v[206:209], v216 offset:56320
	global_load_lds_dwordx4 v[210:211], off
	s_add_i32 m0, s30, 0x2000
	s_add_u32 s28, s28, 0x80080
	v_lshl_add_u64 v[210:211], v[218:219], 0, s[6:7]
	s_addc_u32 s29, s29, 0
	s_add_i32 s30, s63, s38
	global_load_lds_dwordx4 v[210:211], off
	v_lshl_add_u64 v[210:211], s[28:29], 0, v[148:149]
	s_mov_b32 m0, s30
	s_nop 0
	global_load_lds_dwordx4 v[210:211], off
	v_lshl_add_u64 v[210:211], s[28:29], 0, v[144:145]
	s_add_i32 m0, s30, 0x2000
	s_nop 0
	global_load_lds_dwordx4 v[210:211], off
	v_lshl_add_u64 v[210:211], v[220:221], 0, s[6:7]
	s_mov_b32 m0, s48
	s_nop 0
	global_load_lds_dwordx4 v[210:211], off
	v_lshl_add_u64 v[210:211], v[222:223], 0, s[6:7]
	s_mov_b32 m0, s49
	s_nop 0
	global_load_lds_dwordx4 v[210:211], off
	s_waitcnt vmcnt(8)
	s_waitcnt lgkmcnt(0)
	s_barrier
	s_setprio 1
	s_waitcnt lgkmcnt(0)
	v_mfma_f32_16x16x32_bf16 v[60:63], v[128:131], v[178:181], v[60:63]
	v_mfma_f32_16x16x32_bf16 v[56:59], v[136:139], v[178:181], v[56:59]
	v_mfma_f32_16x16x32_bf16 v[48:51], v[128:131], v[186:189], v[48:51]
	v_mfma_f32_16x16x32_bf16 v[40:43], v[136:139], v[186:189], v[40:43]
	v_mfma_f32_16x16x32_bf16 v[32:35], v[128:131], v[194:197], v[32:35]
	v_mfma_f32_16x16x32_bf16 v[24:27], v[136:139], v[194:197], v[24:27]
	v_mfma_f32_16x16x32_bf16 v[16:19], v[128:131], v[202:205], v[16:19]
	v_mfma_f32_16x16x32_bf16 v[8:11], v[136:139], v[202:205], v[8:11]
	v_mfma_f32_16x16x32_bf16 v[60:63], v[132:135], v[182:185], v[60:63]
	v_mfma_f32_16x16x32_bf16 v[56:59], v[140:143], v[182:185], v[56:59]
	v_mfma_f32_16x16x32_bf16 v[48:51], v[132:135], v[190:193], v[48:51]
	v_mfma_f32_16x16x32_bf16 v[40:43], v[140:143], v[190:193], v[40:43]
	v_mfma_f32_16x16x32_bf16 v[32:35], v[132:135], v[198:201], v[32:35]
	v_mfma_f32_16x16x32_bf16 v[24:27], v[140:143], v[198:201], v[24:27]
	v_mfma_f32_16x16x32_bf16 v[16:19], v[132:135], v[206:209], v[16:19]
	v_mfma_f32_16x16x32_bf16 v[8:11], v[140:143], v[206:209], v[8:11]
	s_setprio 0
	s_setprio 1
	v_mfma_f32_16x16x32_bf16 v[52:55], v[162:165], v[178:181], v[52:55]
	v_mfma_f32_16x16x32_bf16 v[44:47], v[170:173], v[178:181], v[44:47]
	v_mfma_f32_16x16x32_bf16 v[36:39], v[162:165], v[186:189], v[36:39]
	v_mfma_f32_16x16x32_bf16 v[28:31], v[170:173], v[186:189], v[28:31]
	v_mfma_f32_16x16x32_bf16 v[20:23], v[162:165], v[194:197], v[20:23]
	v_mfma_f32_16x16x32_bf16 v[12:15], v[170:173], v[194:197], v[12:15]
	v_mfma_f32_16x16x32_bf16 v[4:7], v[162:165], v[202:205], v[4:7]
	v_mfma_f32_16x16x32_bf16 v[0:3], v[170:173], v[202:205], v[0:3]
	v_mfma_f32_16x16x32_bf16 v[52:55], v[166:169], v[182:185], v[52:55]
	v_mfma_f32_16x16x32_bf16 v[44:47], v[174:177], v[182:185], v[44:47]
	v_mfma_f32_16x16x32_bf16 v[36:39], v[166:169], v[190:193], v[36:39]
	v_mfma_f32_16x16x32_bf16 v[28:31], v[174:177], v[190:193], v[28:31]
	v_mfma_f32_16x16x32_bf16 v[20:23], v[166:169], v[198:201], v[20:23]
	v_mfma_f32_16x16x32_bf16 v[12:15], v[174:177], v[198:201], v[12:15]
	v_mfma_f32_16x16x32_bf16 v[4:7], v[166:169], v[206:209], v[4:7]
	v_mfma_f32_16x16x32_bf16 v[0:3], v[174:177], v[206:209], v[0:3]
	s_setprio 0
	s_barrier
	s_add_i32 s61, s61, 2
	s_add_u32 s26, s26, 0x100
	s_addc_u32 s27, s27, 0
	s_add_u32 s59, s59, 0x100
	s_addc_u32 s60, s60, 0
	s_cmp_gt_u32 s61, 29
	s_cbranch_scc0 .LBB0_1825
	s_branch .Lkx_20

;     __host__ __device__ bool next(int i, Unit& u) const { const bool ok = StaticOrder::next(i, u); u.pm = 0; u.pn = 0; return ok; }
; #define PG8_STAGE(bufoff, gbase, voff) do { _Pragma("unroll") for (int _i = 0; _i < 2; ++_i) \
;         __builtin_amdgcn_global_load_lds((const unsigned*)((const char*)(gbase) + (voff)[_i]), (PG8_LAS unsigned*)(lds + (bufoff) + ldsw + _i * 8192), 16, 0, 0); } while (0)
; #define PG8_LDA(dst, b, h) do { _Pragma("unroll") for (int m = 0; m < 4; ++m) _Pragma("unroll") for (int k = 0; k < 2; ++k) dst[m][k] = *(const PG8_LAS bf16x8*)(lds + PG8_SA(b, h) + aoff + m * 2048 + k * 1024); } while (0)
; #define PG8_LDB(dst, b, h) do { _Pragma("unroll") for (int n = 0; n < 2; ++n) _Pragma("unroll") for (int k = 0; k < 2; ++k) dst[n][k] = *(const PG8_LAS bf16x8*)(lds + PG8_SB(b, h) + boff + n * 2048 + k * 1024); } while (0)
; #define PG8_WAIT_V(n) asm volatile("s_waitcnt vmcnt(" #n ")" ::: "memory")
; #define PG8_BAR __builtin_amdgcn_s_barrier()
; template <class Epi, class Sched, bool ALIGN_EPI = false, bool SP2 = false>
; __device__ __forceinline__ void gemm_phase(PG8_LAS unsigned char* lds, const Gemm g, const Sched& S, const Epi& E, const int wave_in) {
;     ...
;         const bool has_next = S.next(ui + 1, nxt);
;         const char* nA = has_next ? (const char*)g.A + (size_t)nxt.pm * tstepA : cA; const char* nB = has_next ? (const char*)g.Bt + (size_t)nxt.pn * tstepB : cB;
;         for (int t = 0; t < nt; t += 2) {
;             const bool last = (t == nt - 2);
;             const char* a1 = cA + (size_t)(t + 1) * kstep;
;             const char* a2 = last ? nA : cA + (size_t)(t + 2) * kstep; const char* b2 = last ? nB : cB + (size_t)(t + 2) * kstep;
;             const char* a3 = a2 + kstep; const char* b3 = b2 + kstep;
;             if (last && has_next) S.a_ready(nxt);
;             if constexpr (SP2) {
;             PG8_LDB(B0, 0, 0); PG8_LDB(B1, 0, 1); PG8_SCHED; PG8_LDA(At, 0, 0); PG8_STAGE(PG8_SA(1, 1), a1 + hstepA, voffA);
;             PG8_WAIT_V(8); PG8_WAIT_L(0); PG8_BAR; PG8_MMA(0, 0, At, B0); PG8_MMA(0, 1, At, B1); PG8_BAR; PG8_SCHED;
;             PG8_LDA(At, 0, 1); PG8_STAGE(PG8_SB(0, 0), b2, voffB); PG8_STAGE(PG8_SB(0, 1), b2 + hstepB, voffB); PG8_STAGE(PG8_SA(0, 0), a2, voffA);
;             PG8_WAIT_V(8); PG8_WAIT_L(0); PG8_BAR; PG8_MMA(1, 0, At, B0); PG8_MMA(1, 1, At, B1); PG8_BAR; PG8_SCHED;
.LBB0_1950:
	s_ashr_i32 s41, s40, 31
	s_lshl_b64 s[42:43], s[40:41], 20
	s_add_u32 s42, s52, s42
	s_addc_u32 s43, s53, s43
	s_and_b64 s[44:45], s[10:11], exec
	s_cselect_b32 s1, s43, s47
	s_cselect_b32 s13, s42, s46
	s_ashr_i32 s39, s38, 31
	s_lshl_b64 s[44:45], s[38:39], 20
	s_add_u32 s44, s54, s44
	s_addc_u32 s45, s55, s45
	s_and_b64 s[50:51], s[10:11], exec
	s_cselect_b32 s39, s45, s49
	s_cselect_b32 s41, s44, s48
	s_add_u32 s46, s46, 0x80080
	s_addc_u32 s47, s47, 0
	s_add_u32 s72, s48, 0x100
	v_mov_b32_e32 v0, 0
	s_addc_u32 s73, s49, 0
	s_mov_b32 s74, -2
	s_waitcnt vmcnt(0)
	ds_read_b128 v[44:47], v189
	ds_read_b128 v[48:51], v189 offset:1024
	ds_read_b128 v[52:55], v189 offset:2048
	ds_read_b128 v[56:59], v189 offset:3072
	ds_read_b128 v[60:63], v197
	ds_read_b128 v[64:67], v197 offset:1024
	ds_read_b128 v[80:83], v197 offset:2048
	ds_read_b128 v[84:87], v197 offset:3072
	s_add_u32 s48, s46, 0xfff80080
	s_addc_u32 s49, s47, -1
	s_cmp_eq_u32 s74, 28
	s_cselect_b32 s51, s1, s49
	s_cselect_b32 s50, s13, s48
	s_cselect_b32 s49, s39, s73
	s_cselect_b32 s48, s41, s72
	v_lshl_add_u64 v[224:225], s[46:47], 0, v[206:207]
	s_add_i32 m0, s57, 0xc000
	ds_read_b128 v[88:91], v199
	ds_read_b128 v[92:95], v199 offset:1024
	ds_read_b128 v[96:99], v199 offset:2048
	ds_read_b128 v[100:103], v199 offset:3072
	ds_read_b128 v[176:179], v199 offset:4096
	ds_read_b128 v[212:215], v199 offset:5120
	ds_read_b128 v[216:219], v199 offset:6144
	ds_read_b128 v[220:223], v199 offset:7168
	global_load_lds_dwordx4 v[224:225], off
	v_lshl_add_u64 v[224:225], s[46:47], 0, v[208:209]
	s_add_i32 m0, s57, 0xe000
	s_nop 0
	global_load_lds_dwordx4 v[224:225], off
	s_waitcnt vmcnt(8)
	s_waitcnt lgkmcnt(0)
	s_barrier
	s_setprio 1
	s_waitcnt lgkmcnt(0)
	v_mfma_f32_16x16x32_bf16 v[172:175], v[44:47], v[88:91], 0
	v_mfma_f32_16x16x32_bf16 v[164:167], v[52:55], v[88:91], 0
	v_mfma_f32_16x16x32_bf16 v[156:159], v[44:47], v[96:99], 0
	v_mfma_f32_16x16x32_bf16 v[148:151], v[52:55], v[96:99], 0
	v_mfma_f32_16x16x32_bf16 v[140:143], v[44:47], v[176:179], 0
	v_mfma_f32_16x16x32_bf16 v[132:135], v[52:55], v[176:179], 0
	v_mfma_f32_16x16x32_bf16 v[124:127], v[44:47], v[216:219], 0
	v_mfma_f32_16x16x32_bf16 v[120:123], v[52:55], v[216:219], 0
	v_mfma_f32_16x16x32_bf16 v[172:175], v[48:51], v[92:95], v[172:175]
	v_mfma_f32_16x16x32_bf16 v[164:167], v[56:59], v[92:95], v[164:167]
	v_mfma_f32_16x16x32_bf16 v[156:159], v[48:51], v[100:103], v[156:159]
	v_mfma_f32_16x16x32_bf16 v[148:151], v[56:59], v[100:103], v[148:151]
	v_mfma_f32_16x16x32_bf16 v[140:143], v[48:51], v[212:215], v[140:143]
	v_mfma_f32_16x16x32_bf16 v[132:135], v[56:59], v[212:215], v[132:135]
	v_mfma_f32_16x16x32_bf16 v[124:127], v[48:51], v[220:223], v[124:127]
	v_mfma_f32_16x16x32_bf16 v[120:123], v[56:59], v[220:223], v[120:123]
	s_setprio 0
	s_setprio 1
	v_mfma_f32_16x16x32_bf16 v[168:171], v[60:63], v[88:91], 0
	v_mfma_f32_16x16x32_bf16 v[88:91], v[80:83], v[88:91], 0
	v_mfma_f32_16x16x32_bf16 v[168:171], v[64:67], v[92:95], v[168:171]
	v_mfma_f32_16x16x32_bf16 v[88:91], v[84:87], v[92:95], v[88:91]
	v_mfma_f32_16x16x32_bf16 v[92:95], v[60:63], v[96:99], 0
	v_mfma_f32_16x16x32_bf16 v[96:99], v[80:83], v[96:99], 0
	v_mfma_f32_16x16x32_bf16 v[128:131], v[80:83], v[176:179], 0
	v_mfma_f32_16x16x32_bf16 v[116:119], v[60:63], v[216:219], 0
	v_mfma_f32_16x16x32_bf16 v[112:115], v[80:83], v[216:219], 0
	v_mfma_f32_16x16x32_bf16 v[92:95], v[64:67], v[100:103], v[92:95]
	v_mfma_f32_16x16x32_bf16 v[96:99], v[84:87], v[100:103], v[96:99]
	v_mfma_f32_16x16x32_bf16 v[100:103], v[60:63], v[176:179], 0
	v_mfma_f32_16x16x32_bf16 v[128:131], v[84:87], v[212:215], v[128:131]
	v_mfma_f32_16x16x32_bf16 v[116:119], v[64:67], v[220:223], v[116:119]
	v_mfma_f32_16x16x32_bf16 v[112:115], v[84:87], v[220:223], v[112:115]
	v_mfma_f32_16x16x32_bf16 v[100:103], v[64:67], v[212:215], v[100:103]
	s_setprio 0
	s_barrier
	s_add_i32 s75, s68, s56
	v_lshl_add_u64 v[232:233], s[48:49], 0, v[182:183]
	s_mov_b32 m0, s75
	ds_read_b128 v[136:139], v199 offset:16384
	ds_read_b128 v[144:147], v199 offset:17408
	ds_read_b128 v[152:155], v199 offset:18432
	ds_read_b128 v[160:163], v199 offset:19456
	ds_read_b128 v[176:179], v199 offset:20480
	ds_read_b128 v[212:215], v199 offset:21504
	ds_read_b128 v[216:219], v199 offset:22528
	ds_read_b128 v[220:223], v199 offset:23552
	global_load_lds_dwordx4 v[232:233], off
	s_add_i32 m0, s75, 0x2000
	s_add_u32 s76, s48, 0x80000
	v_lshl_add_u64 v[234:235], s[48:49], 0, v[186:187]
	s_addc_u32 s77, s49, 0
	s_add_i32 s75, s69, s56
	global_load_lds_dwordx4 v[234:235], off
	v_lshl_add_u64 v[224:225], s[76:77], 0, v[182:183]
	s_mov_b32 m0, s75
	v_lshl_add_u64 v[236:237], s[50:51], 0, v[180:181]
	global_load_lds_dwordx4 v[224:225], off
	v_lshl_add_u64 v[224:225], s[76:77], 0, v[186:187]
	s_add_i32 m0, s75, 0x2000
	v_lshl_add_u64 v[238:239], s[50:51], 0, v[184:185]
	global_load_lds_dwordx4 v[224:225], off
	s_mov_b32 m0, s57
	s_nop 0
	global_load_lds_dwordx4 v[236:237], off
	s_mov_b32 m0, s58
	s_nop 0
	global_load_lds_dwordx4 v[238:239], off
	s_waitcnt vmcnt(8)
	s_waitcnt lgkmcnt(0)
	s_barrier
; #define PG8_STAGE(bufoff, gbase, voff) do { _Pragma("unroll") for (int _i = 0; _i < 2; ++_i) \
;         __builtin_amdgcn_global_load_lds((const unsigned*)((const char*)(gbase) + (voff)[_i]), (PG8_LAS unsigned*)(lds + (bufoff) + ldsw + _i * 8192), 16, 0, 0); } while (0)
; #define PG8_LDA(dst, b, h) do { _Pragma("unroll") for (int m = 0; m < 4; ++m) _Pragma("unroll") for (int k = 0; k < 2; ++k) dst[m][k] = *(const PG8_LAS bf16x8*)(lds + PG8_SA(b, h) + aoff + m * 2048 + k * 1024); } while (0)
; #define PG8_LDB(dst, b, h) do { _Pragma("unroll") for (int n = 0; n < 2; ++n) _Pragma("unroll") for (int k = 0; k < 2; ++k) dst[n][k] = *(const PG8_LAS bf16x8*)(lds + PG8_SB(b, h) + boff + n * 2048 + k * 1024); } while (0)
; #define PG8_MMA(ai, bj, At, Bt) do { __builtin_amdgcn_s_setprio(1); _Pragma("unroll") for (int m = 0; m < 4; ++m) _Pragma("unroll") for (int n = 0; n < 2; ++n) _Pragma("unroll") for (int k = 0; k < 2; ++k) \
;         acc[ai][bj][m][n] = __builtin_amdgcn_mfma_f32_16x16x32_bf16(Bt[n][k], At[m][k], acc[ai][bj][m][n], 0, 0, 0); __builtin_amdgcn_s_setprio(0); } while (0)
; #define PG8_WAIT_V(n) asm volatile("s_waitcnt vmcnt(" #n ")" ::: "memory")
; #define PG8_WAIT_L(n) asm volatile("s_waitcnt lgkmcnt(" #n ")" ::: "memory")
; #define PG8_BAR __builtin_amdgcn_s_barrier()
; #define PG8_SCHED __builtin_amdgcn_sched_barrier(0)
; template <class Epi, class Sched, bool ALIGN_EPI = false, bool SP2 = false>
; __device__ __forceinline__ void gemm_phase(PG8_LAS unsigned char* lds, const Gemm g, const Sched& S, const Epi& E, const int wave_in) {
;     ...
;             PG8_WAIT_V(8); PG8_WAIT_L(0); PG8_BAR; PG8_MMA(1, 0, At, B0); PG8_MMA(1, 1, At, B1); PG8_BAR; PG8_SCHED;
;             PG8_LDB(B0, 1, 0); PG8_LDB(B1, 1, 1); PG8_SCHED; PG8_LDA(At, 1, 0); PG8_STAGE(PG8_SA(0, 1), a2 + hstepA, voffA);
;             PG8_WAIT_V(8); PG8_WAIT_L(0); PG8_BAR; PG8_MMA(0, 0, At, B0); PG8_MMA(0, 1, At, B1); PG8_BAR; PG8_SCHED;
	s_setprio 1
	s_waitcnt lgkmcnt(0)
	v_mfma_f32_16x16x32_bf16 v[108:111], v[44:47], v[136:139], 0
	v_mfma_f32_16x16x32_bf16 v[76:79], v[52:55], v[136:139], 0
	v_mfma_f32_16x16x32_bf16 v[68:71], v[44:47], v[152:155], 0
	v_mfma_f32_16x16x32_bf16 v[36:39], v[52:55], v[152:155], 0
	v_mfma_f32_16x16x32_bf16 v[28:31], v[44:47], v[176:179], 0
	v_mfma_f32_16x16x32_bf16 v[20:23], v[52:55], v[176:179], 0
	v_mfma_f32_16x16x32_bf16 v[12:15], v[44:47], v[216:219], 0
	v_mfma_f32_16x16x32_bf16 v[8:11], v[52:55], v[216:219], 0
	v_mfma_f32_16x16x32_bf16 v[108:111], v[48:51], v[144:147], v[108:111]
	v_mfma_f32_16x16x32_bf16 v[76:79], v[56:59], v[144:147], v[76:79]
	v_mfma_f32_16x16x32_bf16 v[68:71], v[48:51], v[160:163], v[68:71]
	v_mfma_f32_16x16x32_bf16 v[36:39], v[56:59], v[160:163], v[36:39]
	v_mfma_f32_16x16x32_bf16 v[28:31], v[48:51], v[212:215], v[28:31]
	v_mfma_f32_16x16x32_bf16 v[20:23], v[56:59], v[212:215], v[20:23]
	v_mfma_f32_16x16x32_bf16 v[12:15], v[48:51], v[220:223], v[12:15]
	v_mfma_f32_16x16x32_bf16 v[8:11], v[56:59], v[220:223], v[8:11]
	s_setprio 0
	s_setprio 1
	v_mfma_f32_16x16x32_bf16 v[40:43], v[60:63], v[152:155], 0
	v_mfma_f32_16x16x32_bf16 v[32:35], v[80:83], v[152:155], 0
	v_mfma_f32_16x16x32_bf16 v[24:27], v[60:63], v[176:179], 0
	v_mfma_f32_16x16x32_bf16 v[16:19], v[80:83], v[176:179], 0
	v_mfma_f32_16x16x32_bf16 v[4:7], v[60:63], v[216:219], 0
	v_mfma_f32_16x16x32_bf16 v[0:3], v[80:83], v[216:219], 0
	v_mfma_f32_16x16x32_bf16 v[44:47], v[60:63], v[136:139], 0
	v_mfma_f32_16x16x32_bf16 v[48:51], v[80:83], v[136:139], 0
	v_mfma_f32_16x16x32_bf16 v[40:43], v[64:67], v[160:163], v[40:43]
	v_mfma_f32_16x16x32_bf16 v[32:35], v[84:87], v[160:163], v[32:35]
	v_mfma_f32_16x16x32_bf16 v[24:27], v[64:67], v[212:215], v[24:27]
	v_mfma_f32_16x16x32_bf16 v[16:19], v[84:87], v[212:215], v[16:19]
	v_mfma_f32_16x16x32_bf16 v[4:7], v[64:67], v[220:223], v[4:7]
	v_mfma_f32_16x16x32_bf16 v[0:3], v[84:87], v[220:223], v[0:3]
	v_mfma_f32_16x16x32_bf16 v[44:47], v[64:67], v[144:147], v[44:47]
	v_mfma_f32_16x16x32_bf16 v[48:51], v[84:87], v[144:147], v[48:51]
	s_setprio 0
	s_barrier
	s_add_i32 s75, 0, 0x18000
	s_add_i32 s76, 0, 0x1c000
	v_add_u32_e32 v64, s75, v195
	v_add_u32_e32 v72, s76, v195
	ds_read_b128 v[52:55], v64
	ds_read_b128 v[56:59], v64 offset:1024
	ds_read_b128 v[60:63], v64 offset:2048
	ds_read_b128 v[64:67], v64 offset:3072
	ds_read_b128 v[80:83], v72
	ds_read_b128 v[84:87], v72 offset:1024
	ds_read_b128 v[176:179], v72 offset:2048
	ds_read_b128 v[212:215], v72 offset:3072
	s_add_u32 s50, s50, 0x80000
	s_addc_u32 s51, s51, 0
	s_mov_b32 m0, s59
	v_lshl_add_u64 v[152:153], s[50:51], 0, v[180:181]
	ds_read_b128 v[72:75], v199 offset:32768
	ds_read_b128 v[104:107], v199 offset:33792
	ds_read_b128 v[136:139], v199 offset:34816
	ds_read_b128 v[144:147], v199 offset:35840
	ds_read_b128 v[216:219], v199 offset:36864
	ds_read_b128 v[220:223], v199 offset:37888
	ds_read_b128 v[224:227], v199 offset:38912
	ds_read_b128 v[228:231], v199 offset:39936
	global_load_lds_dwordx4 v[152:153], off
	v_lshl_add_u64 v[152:153], s[50:51], 0, v[184:185]
	s_mov_b32 m0, s60
	s_nop 0
	global_load_lds_dwordx4 v[152:153], off
	s_waitcnt vmcnt(8)
	s_waitcnt lgkmcnt(0)
	s_barrier
	s_setprio 1
	s_waitcnt lgkmcnt(0)
	v_mfma_f32_16x16x32_bf16 v[152:155], v[52:55], v[72:75], v[172:175]
	v_mfma_f32_16x16x32_bf16 v[172:175], v[56:59], v[104:107], v[152:155]
	v_mfma_f32_16x16x32_bf16 v[152:155], v[60:63], v[72:75], v[164:167]
	v_mfma_f32_16x16x32_bf16 v[164:167], v[64:67], v[104:107], v[152:155]
	v_mfma_f32_16x16x32_bf16 v[152:155], v[52:55], v[136:139], v[156:159]
	v_mfma_f32_16x16x32_bf16 v[148:151], v[60:63], v[136:139], v[148:151]
	v_mfma_f32_16x16x32_bf16 v[140:143], v[52:55], v[216:219], v[140:143]
	v_mfma_f32_16x16x32_bf16 v[132:135], v[60:63], v[216:219], v[132:135]
	v_mfma_f32_16x16x32_bf16 v[124:127], v[52:55], v[224:227], v[124:127]
	v_mfma_f32_16x16x32_bf16 v[120:123], v[60:63], v[224:227], v[120:123]
	v_mfma_f32_16x16x32_bf16 v[156:159], v[56:59], v[144:147], v[152:155]
	v_mfma_f32_16x16x32_bf16 v[148:151], v[64:67], v[144:147], v[148:151]
	v_mfma_f32_16x16x32_bf16 v[140:143], v[56:59], v[220:223], v[140:143]
	v_mfma_f32_16x16x32_bf16 v[132:135], v[64:67], v[220:223], v[132:135]
	v_mfma_f32_16x16x32_bf16 v[124:127], v[56:59], v[228:231], v[124:127]
	v_mfma_f32_16x16x32_bf16 v[120:123], v[64:67], v[228:231], v[120:123]
	s_setprio 0
	s_setprio 1
	v_mfma_f32_16x16x32_bf16 v[152:155], v[80:83], v[72:75], v[168:171]
	v_mfma_f32_16x16x32_bf16 v[72:75], v[176:179], v[72:75], v[88:91]
	v_mfma_f32_16x16x32_bf16 v[160:163], v[212:215], v[104:107], v[72:75]
	v_mfma_f32_16x16x32_bf16 v[72:75], v[80:83], v[136:139], v[92:95]
	v_mfma_f32_16x16x32_bf16 v[168:171], v[84:87], v[104:107], v[152:155]
	v_mfma_f32_16x16x32_bf16 v[152:155], v[84:87], v[144:147], v[72:75]
	v_mfma_f32_16x16x32_bf16 v[72:75], v[176:179], v[136:139], v[96:99]
	v_mfma_f32_16x16x32_bf16 v[144:147], v[212:215], v[144:147], v[72:75]
	v_mfma_f32_16x16x32_bf16 v[72:75], v[80:83], v[216:219], v[100:103]
	v_mfma_f32_16x16x32_bf16 v[136:139], v[84:87], v[220:223], v[72:75]
	v_mfma_f32_16x16x32_bf16 v[72:75], v[176:179], v[216:219], v[128:131]
	v_mfma_f32_16x16x32_bf16 v[128:131], v[212:215], v[220:223], v[72:75]
	v_mfma_f32_16x16x32_bf16 v[72:75], v[80:83], v[224:227], v[116:119]
	v_mfma_f32_16x16x32_bf16 v[116:119], v[84:87], v[228:231], v[72:75]
	v_mfma_f32_16x16x32_bf16 v[72:75], v[176:179], v[224:227], v[112:115]
	v_mfma_f32_16x16x32_bf16 v[112:115], v[212:215], v[228:231], v[72:75]
	s_setprio 0
	s_barrier
; #define PG8_STAGE(bufoff, gbase, voff) do { _Pragma("unroll") for (int _i = 0; _i < 2; ++_i) \
;         __builtin_amdgcn_global_load_lds((const unsigned*)((const char*)(gbase) + (voff)[_i]), (PG8_LAS unsigned*)(lds + (bufoff) + ldsw + _i * 8192), 16, 0, 0); } while (0)
; #define PG8_LDA(dst, b, h) do { _Pragma("unroll") for (int m = 0; m < 4; ++m) _Pragma("unroll") for (int k = 0; k < 2; ++k) dst[m][k] = *(const PG8_LAS bf16x8*)(lds + PG8_SA(b, h) + aoff + m * 2048 + k * 1024); } while (0)
; #define PG8_MMA(ai, bj, At, Bt) do { __builtin_amdgcn_s_setprio(1); _Pragma("unroll") for (int m = 0; m < 4; ++m) _Pragma("unroll") for (int n = 0; n < 2; ++n) _Pragma("unroll") for (int k = 0; k < 2; ++k) \
;         acc[ai][bj][m][n] = __builtin_amdgcn_mfma_f32_16x16x32_bf16(Bt[n][k], At[m][k], acc[ai][bj][m][n], 0, 0, 0); __builtin_amdgcn_s_setprio(0); } while (0)
; #define PG8_WAIT_V(n) asm volatile("s_waitcnt vmcnt(" #n ")" ::: "memory")
; #define PG8_WAIT_L(n) asm volatile("s_waitcnt lgkmcnt(" #n ")" ::: "memory")
; #define PG8_BAR __builtin_amdgcn_s_barrier()
; #define PG8_SCHED __builtin_amdgcn_sched_barrier(0)
; template <class Epi, class Sched, bool ALIGN_EPI = false, bool SP2 = false>
; __device__ __forceinline__ void gemm_phase(PG8_LAS unsigned char* lds, const Gemm g, const Sched& S, const Epi& E, const int wave_in) {
;     ...
;         for (int t = 0; t < nt; t += 2) {
;             const bool last = (t == nt - 2);
;     ...
;             PG8_LDA(At, 1, 1); PG8_STAGE(PG8_SB(1, 0), b3, voffB); PG8_STAGE(PG8_SB(1, 1), b3 + hstepB, voffB); PG8_STAGE(PG8_SA(1, 0), a3, voffA);
;             PG8_WAIT_V(8); PG8_WAIT_L(0); PG8_BAR; PG8_MMA(1, 0, At, B0); PG8_MMA(1, 1, At, B1); PG8_BAR; PG8_SCHED;
	s_add_i32 s50, s75, s56
	v_lshl_add_u64 v[104:105], v[232:233], 0, s[22:23]
	s_mov_b32 m0, s50
	s_nop 1
	ds_read_b128 v[72:75], v199 offset:49152
	ds_read_b128 v[88:91], v199 offset:50176
	ds_read_b128 v[92:95], v199 offset:51200
	ds_read_b128 v[96:99], v199 offset:52224
	ds_read_b128 v[100:103], v199 offset:53248
	ds_read_b128 v[216:219], v199 offset:54272
	ds_read_b128 v[220:223], v199 offset:55296
	ds_read_b128 v[224:227], v199 offset:56320
	global_load_lds_dwordx4 v[104:105], off
	s_add_i32 m0, s50, 0x2000
	s_add_u32 s48, s48, 0x80080
	v_lshl_add_u64 v[104:105], v[234:235], 0, s[22:23]
	s_addc_u32 s49, s49, 0
	s_add_i32 s50, s76, s56
	global_load_lds_dwordx4 v[104:105], off
	v_lshl_add_u64 v[104:105], s[48:49], 0, v[182:183]
	s_mov_b32 m0, s50
	s_nop 0
	global_load_lds_dwordx4 v[104:105], off
	v_lshl_add_u64 v[104:105], s[48:49], 0, v[186:187]
	s_add_i32 m0, s50, 0x2000
	s_nop 0
	global_load_lds_dwordx4 v[104:105], off
	v_lshl_add_u64 v[104:105], v[236:237], 0, s[22:23]
	s_mov_b32 m0, s63
	s_nop 0
	global_load_lds_dwordx4 v[104:105], off
	v_lshl_add_u64 v[104:105], v[238:239], 0, s[22:23]
	s_mov_b32 m0, s64
	s_nop 0
	global_load_lds_dwordx4 v[104:105], off
	s_waitcnt vmcnt(8)
	s_waitcnt lgkmcnt(0)
	s_barrier
	s_setprio 1
	s_waitcnt lgkmcnt(0)
	v_mfma_f32_16x16x32_bf16 v[104:107], v[52:55], v[72:75], v[108:111]
	v_mfma_f32_16x16x32_bf16 v[76:79], v[60:63], v[72:75], v[76:79]
	v_mfma_f32_16x16x32_bf16 v[68:71], v[52:55], v[92:95], v[68:71]
	v_mfma_f32_16x16x32_bf16 v[36:39], v[60:63], v[92:95], v[36:39]
	v_mfma_f32_16x16x32_bf16 v[28:31], v[52:55], v[100:103], v[28:31]
	v_mfma_f32_16x16x32_bf16 v[20:23], v[60:63], v[100:103], v[20:23]
	v_mfma_f32_16x16x32_bf16 v[12:15], v[52:55], v[220:223], v[12:15]
	v_mfma_f32_16x16x32_bf16 v[8:11], v[60:63], v[220:223], v[8:11]
	v_mfma_f32_16x16x32_bf16 v[108:111], v[56:59], v[88:91], v[104:107]
	v_mfma_f32_16x16x32_bf16 v[76:79], v[64:67], v[88:91], v[76:79]
	v_mfma_f32_16x16x32_bf16 v[68:71], v[56:59], v[96:99], v[68:71]
	v_mfma_f32_16x16x32_bf16 v[36:39], v[64:67], v[96:99], v[36:39]
	v_mfma_f32_16x16x32_bf16 v[28:31], v[56:59], v[216:219], v[28:31]
	v_mfma_f32_16x16x32_bf16 v[20:23], v[64:67], v[216:219], v[20:23]
	v_mfma_f32_16x16x32_bf16 v[12:15], v[56:59], v[224:227], v[12:15]
	v_mfma_f32_16x16x32_bf16 v[8:11], v[64:67], v[224:227], v[8:11]
	s_setprio 0
	s_setprio 1
	v_mfma_f32_16x16x32_bf16 v[44:47], v[80:83], v[72:75], v[44:47]
	v_mfma_f32_16x16x32_bf16 v[104:107], v[84:87], v[88:91], v[44:47]
	v_mfma_f32_16x16x32_bf16 v[44:47], v[176:179], v[72:75], v[48:51]
	v_mfma_f32_16x16x32_bf16 v[40:43], v[80:83], v[92:95], v[40:43]
	v_mfma_f32_16x16x32_bf16 v[32:35], v[176:179], v[92:95], v[32:35]
	v_mfma_f32_16x16x32_bf16 v[24:27], v[80:83], v[100:103], v[24:27]
	v_mfma_f32_16x16x32_bf16 v[16:19], v[176:179], v[100:103], v[16:19]
	v_mfma_f32_16x16x32_bf16 v[4:7], v[80:83], v[220:223], v[4:7]
	v_mfma_f32_16x16x32_bf16 v[0:3], v[176:179], v[220:223], v[0:3]
	v_mfma_f32_16x16x32_bf16 v[72:75], v[212:215], v[88:91], v[44:47]
	v_mfma_f32_16x16x32_bf16 v[40:43], v[84:87], v[96:99], v[40:43]
	v_mfma_f32_16x16x32_bf16 v[32:35], v[212:215], v[96:99], v[32:35]
	v_mfma_f32_16x16x32_bf16 v[24:27], v[84:87], v[216:219], v[24:27]
	v_mfma_f32_16x16x32_bf16 v[16:19], v[212:215], v[216:219], v[16:19]
	v_mfma_f32_16x16x32_bf16 v[4:7], v[84:87], v[224:227], v[4:7]
	v_mfma_f32_16x16x32_bf16 v[0:3], v[212:215], v[224:227], v[0:3]
	s_setprio 0
	s_barrier
	s_add_i32 s74, s74, 2
	s_add_u32 s46, s46, 0x100
	s_addc_u32 s47, s47, 0
	s_add_u32 s72, s72, 0x100
	s_addc_u32 s73, s73, 0
	s_cmp_gt_u32 s74, 29
	s_cbranch_scc0 .LBB0_1951
	s_branch .Lkx_22

; #define PG8_STAGE(bufoff, gbase, voff) do { _Pragma("unroll") for (int _i = 0; _i < 2; ++_i) \
;         __builtin_amdgcn_global_load_lds((const unsigned*)((const char*)(gbase) + (voff)[_i]), (PG8_LAS unsigned*)(lds + (bufoff) + ldsw + _i * 8192), 16, 0, 0); } while (0)
; #define PG8_LDA(dst, b, h) do { _Pragma("unroll") for (int m = 0; m < 4; ++m) _Pragma("unroll") for (int k = 0; k < 2; ++k) dst[m][k] = *(const PG8_LAS bf16x8*)(lds + PG8_SA(b, h) + aoff + m * 2048 + k * 1024); } while (0)
; #define PG8_LDB(dst, b, h) do { _Pragma("unroll") for (int n = 0; n < 2; ++n) _Pragma("unroll") for (int k = 0; k < 2; ++k) dst[n][k] = *(const PG8_LAS bf16x8*)(lds + PG8_SB(b, h) + boff + n * 2048 + k * 1024); } while (0)
; #define PG8_MMA(ai, bj, At, Bt) do { __builtin_amdgcn_s_setprio(1); _Pragma("unroll") for (int m = 0; m < 4; ++m) _Pragma("unroll") for (int n = 0; n < 2; ++n) _Pragma("unroll") for (int k = 0; k < 2; ++k) \
;         acc[ai][bj][m][n] = __builtin_amdgcn_mfma_f32_16x16x32_bf16(Bt[n][k], At[m][k], acc[ai][bj][m][n], 0, 0, 0); __builtin_amdgcn_s_setprio(0); } while (0)
; #define PG8_WAIT_V(n) asm volatile("s_waitcnt vmcnt(" #n ")" ::: "memory")
; #define PG8_WAIT_L(n) asm volatile("s_waitcnt lgkmcnt(" #n ")" ::: "memory")
; #define PG8_BAR __builtin_amdgcn_s_barrier()
; #define PG8_SCHED __builtin_amdgcn_sched_barrier(0)
; template <class Epi, class Sched, bool ALIGN_EPI = false, bool SP2 = false>
; __device__ __forceinline__ void gemm_phase(PG8_LAS unsigned char* lds, const Gemm g, const Sched& S, const Epi& E, const int wave_in) {
;     ...
;             if constexpr (SP2) {
;             PG8_LDB(B0, 0, 0); PG8_LDB(B1, 0, 1); PG8_SCHED; PG8_LDA(At, 0, 0); PG8_STAGE(PG8_SA(1, 1), a1 + hstepA, voffA);
;             PG8_WAIT_V(8); PG8_WAIT_L(0); PG8_BAR; PG8_MMA(0, 0, At, B0); PG8_MMA(0, 1, At, B1); PG8_BAR; PG8_SCHED;
;             PG8_LDA(At, 0, 1); PG8_STAGE(PG8_SB(0, 0), b2, voffB); PG8_STAGE(PG8_SB(0, 1), b2 + hstepB, voffB); PG8_STAGE(PG8_SA(0, 0), a2, voffA);
;     ...
; #pragma unroll
;         for (int a = 0; a < 2; ++a)
; #pragma unroll
;             for (int b = 0; b < 2; ++b)
; #pragma unroll
;                 for (int m = 0; m < 4; ++m)
; #pragma unroll
;                     for (int n = 0; n < 2; ++n) acc[a][b][m][n] = (f32x4){0.f, 0.f, 0.f, 0.f};
.LBB0_2106:
	s_add_u32 s21, s24, 0x100
	v_mov_b32_e32 v0, 0
	s_addc_u32 s58, s25, 0
	s_mov_b32 s59, -2
	s_waitcnt vmcnt(0)
	ds_read_b128 v[128:131], v214
	ds_read_b128 v[132:135], v214 offset:1024
	ds_read_b128 v[136:139], v214 offset:2048
	ds_read_b128 v[140:143], v214 offset:3072
	ds_read_b128 v[162:165], v215
	ds_read_b128 v[166:169], v215 offset:1024
	ds_read_b128 v[170:173], v215 offset:2048
	ds_read_b128 v[174:177], v215 offset:3072
	s_add_u32 s24, s22, 0x100
	s_addc_u32 s25, s23, 0
	s_cmpk_eq_i32 s59, 0x52
	s_cselect_b32 s29, s5, s25
	s_cselect_b32 s28, s4, s24
	s_cselect_b32 s27, s19, s58
	s_cselect_b32 s26, s18, s21
	v_lshl_add_u64 v[210:211], s[22:23], 0, v[154:155]
	s_add_i32 m0, s39, 0xc000
	ds_read_b128 v[178:181], v216
	ds_read_b128 v[182:185], v216 offset:1024
	ds_read_b128 v[186:189], v216 offset:2048
	ds_read_b128 v[190:193], v216 offset:3072
	ds_read_b128 v[194:197], v216 offset:4096
	ds_read_b128 v[198:201], v216 offset:5120
	ds_read_b128 v[202:205], v216 offset:6144
	ds_read_b128 v[206:209], v216 offset:7168
	global_load_lds_dwordx4 v[210:211], off
	v_lshl_add_u64 v[210:211], s[22:23], 0, v[156:157]
	s_add_i32 m0, s39, 0xe000
	s_nop 0
	global_load_lds_dwordx4 v[210:211], off
	s_waitcnt vmcnt(8)
	s_waitcnt lgkmcnt(0)
	s_barrier
	s_setprio 1
	s_waitcnt lgkmcnt(0)
	v_mfma_f32_16x16x32_bf16 v[124:127], v[128:131], v[178:181], 0
	v_mfma_f32_16x16x32_bf16 v[120:123], v[136:139], v[178:181], 0
	v_mfma_f32_16x16x32_bf16 v[112:115], v[128:131], v[186:189], 0
	v_mfma_f32_16x16x32_bf16 v[104:107], v[136:139], v[186:189], 0
	v_mfma_f32_16x16x32_bf16 v[100:103], v[128:131], v[194:197], 0
	v_mfma_f32_16x16x32_bf16 v[96:99], v[136:139], v[194:197], 0
	v_mfma_f32_16x16x32_bf16 v[76:79], v[128:131], v[202:205], 0
	v_mfma_f32_16x16x32_bf16 v[72:75], v[136:139], v[202:205], 0
	v_mfma_f32_16x16x32_bf16 v[124:127], v[132:135], v[182:185], v[124:127]
	v_mfma_f32_16x16x32_bf16 v[120:123], v[140:143], v[182:185], v[120:123]
	v_mfma_f32_16x16x32_bf16 v[112:115], v[132:135], v[190:193], v[112:115]
	v_mfma_f32_16x16x32_bf16 v[104:107], v[140:143], v[190:193], v[104:107]
	v_mfma_f32_16x16x32_bf16 v[100:103], v[132:135], v[198:201], v[100:103]
	v_mfma_f32_16x16x32_bf16 v[96:99], v[140:143], v[198:201], v[96:99]
	v_mfma_f32_16x16x32_bf16 v[76:79], v[132:135], v[206:209], v[76:79]
	v_mfma_f32_16x16x32_bf16 v[72:75], v[140:143], v[206:209], v[72:75]
	s_setprio 0
	s_setprio 1
	v_mfma_f32_16x16x32_bf16 v[116:119], v[162:165], v[178:181], 0
	v_mfma_f32_16x16x32_bf16 v[108:111], v[170:173], v[178:181], 0
	v_mfma_f32_16x16x32_bf16 v[92:95], v[162:165], v[186:189], 0
	v_mfma_f32_16x16x32_bf16 v[88:91], v[170:173], v[186:189], 0
	v_mfma_f32_16x16x32_bf16 v[84:87], v[162:165], v[194:197], 0
	v_mfma_f32_16x16x32_bf16 v[80:83], v[170:173], v[194:197], 0
	v_mfma_f32_16x16x32_bf16 v[68:71], v[162:165], v[202:205], 0
	v_mfma_f32_16x16x32_bf16 v[64:67], v[170:173], v[202:205], 0
	v_mfma_f32_16x16x32_bf16 v[116:119], v[166:169], v[182:185], v[116:119]
	v_mfma_f32_16x16x32_bf16 v[108:111], v[174:177], v[182:185], v[108:111]
	v_mfma_f32_16x16x32_bf16 v[92:95], v[166:169], v[190:193], v[92:95]
	v_mfma_f32_16x16x32_bf16 v[88:91], v[174:177], v[190:193], v[88:91]
	v_mfma_f32_16x16x32_bf16 v[84:87], v[166:169], v[198:201], v[84:87]
	v_mfma_f32_16x16x32_bf16 v[80:83], v[174:177], v[198:201], v[80:83]
	v_mfma_f32_16x16x32_bf16 v[68:71], v[166:169], v[206:209], v[68:71]
	v_mfma_f32_16x16x32_bf16 v[64:67], v[174:177], v[206:209], v[64:67]
	s_setprio 0
	s_barrier
	s_add_i32 s22, s49, s36
	v_lshl_add_u64 v[210:211], s[26:27], 0, v[148:149]
	s_mov_b32 m0, s22
	ds_read_b128 v[178:181], v216 offset:16384
	ds_read_b128 v[182:185], v216 offset:17408
	ds_read_b128 v[186:189], v216 offset:18432
	ds_read_b128 v[190:193], v216 offset:19456
	ds_read_b128 v[194:197], v216 offset:20480
	ds_read_b128 v[198:201], v216 offset:21504
	ds_read_b128 v[202:205], v216 offset:22528
	ds_read_b128 v[206:209], v216 offset:23552
	global_load_lds_dwordx4 v[210:211], off
	s_add_i32 m0, s22, 0x2000
	s_add_u32 s22, s26, 0x158000
	v_lshl_add_u64 v[218:219], s[26:27], 0, v[144:145]
	s_addc_u32 s23, s27, 0
	s_add_i32 s60, s50, s36
	global_load_lds_dwordx4 v[218:219], off
	v_lshl_add_u64 v[220:221], s[22:23], 0, v[148:149]
	s_mov_b32 m0, s60
	v_lshl_add_u64 v[222:223], s[28:29], 0, v[146:147]
	global_load_lds_dwordx4 v[220:221], off
	v_lshl_add_u64 v[220:221], s[22:23], 0, v[144:145]
	s_add_i32 m0, s60, 0x2000
	s_nop 0
	global_load_lds_dwordx4 v[220:221], off
	v_lshl_add_u64 v[220:221], s[28:29], 0, v[150:151]
	s_mov_b32 m0, s39
	s_nop 0
	global_load_lds_dwordx4 v[220:221], off
	s_mov_b32 m0, s40
	s_nop 0
	global_load_lds_dwordx4 v[222:223], off
	s_waitcnt vmcnt(8)
	s_waitcnt lgkmcnt(0)
	s_barrier
; #define PG8_STAGE(bufoff, gbase, voff) do { _Pragma("unroll") for (int _i = 0; _i < 2; ++_i) \
;         __builtin_amdgcn_global_load_lds((const unsigned*)((const char*)(gbase) + (voff)[_i]), (PG8_LAS unsigned*)(lds + (bufoff) + ldsw + _i * 8192), 16, 0, 0); } while (0)
; #define PG8_LDA(dst, b, h) do { _Pragma("unroll") for (int m = 0; m < 4; ++m) _Pragma("unroll") for (int k = 0; k < 2; ++k) dst[m][k] = *(const PG8_LAS bf16x8*)(lds + PG8_SA(b, h) + aoff + m * 2048 + k * 1024); } while (0)
; #define PG8_LDB(dst, b, h) do { _Pragma("unroll") for (int n = 0; n < 2; ++n) _Pragma("unroll") for (int k = 0; k < 2; ++k) dst[n][k] = *(const PG8_LAS bf16x8*)(lds + PG8_SB(b, h) + boff + n * 2048 + k * 1024); } while (0)
; #define PG8_MMA(ai, bj, At, Bt) do { __builtin_amdgcn_s_setprio(1); _Pragma("unroll") for (int m = 0; m < 4; ++m) _Pragma("unroll") for (int n = 0; n < 2; ++n) _Pragma("unroll") for (int k = 0; k < 2; ++k) \
;         acc[ai][bj][m][n] = __builtin_amdgcn_mfma_f32_16x16x32_bf16(Bt[n][k], At[m][k], acc[ai][bj][m][n], 0, 0, 0); __builtin_amdgcn_s_setprio(0); } while (0)
; #define PG8_WAIT_V(n) asm volatile("s_waitcnt vmcnt(" #n ")" ::: "memory")
; #define PG8_WAIT_L(n) asm volatile("s_waitcnt lgkmcnt(" #n ")" ::: "memory")
; #define PG8_BAR __builtin_amdgcn_s_barrier()
; #define PG8_SCHED __builtin_amdgcn_sched_barrier(0)
; template <class Epi, class Sched, bool ALIGN_EPI = false, bool SP2 = false>
; __device__ __forceinline__ void gemm_phase(PG8_LAS unsigned char* lds, const Gemm g, const Sched& S, const Epi& E, const int wave_in) {
;     ...
;             PG8_WAIT_V(8); PG8_WAIT_L(0); PG8_BAR; PG8_MMA(1, 0, At, B0); PG8_MMA(1, 1, At, B1); PG8_BAR; PG8_SCHED;
;             PG8_LDB(B0, 1, 0); PG8_LDB(B1, 1, 1); PG8_SCHED; PG8_LDA(At, 1, 0); PG8_STAGE(PG8_SA(0, 1), a2 + hstepA, voffA);
;             PG8_WAIT_V(8); PG8_WAIT_L(0); PG8_BAR; PG8_MMA(0, 0, At, B0); PG8_MMA(0, 1, At, B1); PG8_BAR; PG8_SCHED;
	s_setprio 1
	s_waitcnt lgkmcnt(0)
	v_mfma_f32_16x16x32_bf16 v[60:63], v[128:131], v[178:181], 0
	v_mfma_f32_16x16x32_bf16 v[56:59], v[136:139], v[178:181], 0
	v_mfma_f32_16x16x32_bf16 v[48:51], v[128:131], v[186:189], 0
	v_mfma_f32_16x16x32_bf16 v[40:43], v[136:139], v[186:189], 0
	v_mfma_f32_16x16x32_bf16 v[32:35], v[128:131], v[194:197], 0
	v_mfma_f32_16x16x32_bf16 v[24:27], v[136:139], v[194:197], 0
	v_mfma_f32_16x16x32_bf16 v[16:19], v[128:131], v[202:205], 0
	v_mfma_f32_16x16x32_bf16 v[8:11], v[136:139], v[202:205], 0
	v_mfma_f32_16x16x32_bf16 v[60:63], v[132:135], v[182:185], v[60:63]
	v_mfma_f32_16x16x32_bf16 v[56:59], v[140:143], v[182:185], v[56:59]
	v_mfma_f32_16x16x32_bf16 v[48:51], v[132:135], v[190:193], v[48:51]
	v_mfma_f32_16x16x32_bf16 v[40:43], v[140:143], v[190:193], v[40:43]
	v_mfma_f32_16x16x32_bf16 v[32:35], v[132:135], v[198:201], v[32:35]
	v_mfma_f32_16x16x32_bf16 v[24:27], v[140:143], v[198:201], v[24:27]
	v_mfma_f32_16x16x32_bf16 v[16:19], v[132:135], v[206:209], v[16:19]
	v_mfma_f32_16x16x32_bf16 v[8:11], v[140:143], v[206:209], v[8:11]
	s_setprio 0
	s_setprio 1
	v_mfma_f32_16x16x32_bf16 v[52:55], v[162:165], v[178:181], 0
	v_mfma_f32_16x16x32_bf16 v[44:47], v[170:173], v[178:181], 0
	v_mfma_f32_16x16x32_bf16 v[36:39], v[162:165], v[186:189], 0
	v_mfma_f32_16x16x32_bf16 v[28:31], v[170:173], v[186:189], 0
	v_mfma_f32_16x16x32_bf16 v[20:23], v[162:165], v[194:197], 0
	v_mfma_f32_16x16x32_bf16 v[12:15], v[170:173], v[194:197], 0
	v_mfma_f32_16x16x32_bf16 v[4:7], v[162:165], v[202:205], 0
	v_mfma_f32_16x16x32_bf16 v[0:3], v[170:173], v[202:205], 0
	v_mfma_f32_16x16x32_bf16 v[52:55], v[166:169], v[182:185], v[52:55]
	v_mfma_f32_16x16x32_bf16 v[44:47], v[174:177], v[182:185], v[44:47]
	v_mfma_f32_16x16x32_bf16 v[36:39], v[166:169], v[190:193], v[36:39]
	v_mfma_f32_16x16x32_bf16 v[28:31], v[174:177], v[190:193], v[28:31]
	v_mfma_f32_16x16x32_bf16 v[20:23], v[166:169], v[198:201], v[20:23]
	v_mfma_f32_16x16x32_bf16 v[12:15], v[174:177], v[198:201], v[12:15]
	v_mfma_f32_16x16x32_bf16 v[4:7], v[166:169], v[206:209], v[4:7]
	v_mfma_f32_16x16x32_bf16 v[0:3], v[174:177], v[206:209], v[0:3]
	s_setprio 0
	s_barrier
	s_add_i32 s60, 0, 0x18000
	s_add_i32 s61, 0, 0x1c000
	v_add_u32_e32 v140, s60, v212
	v_add_u32_e32 v174, s61, v212
	ds_read_b128 v[128:131], v140
	ds_read_b128 v[132:135], v140 offset:1024
	ds_read_b128 v[136:139], v140 offset:2048
	ds_read_b128 v[140:143], v140 offset:3072
	ds_read_b128 v[162:165], v174
	ds_read_b128 v[166:169], v174 offset:1024
	ds_read_b128 v[170:173], v174 offset:2048
	ds_read_b128 v[174:177], v174 offset:3072
	s_add_u32 s22, s28, 0x158000
	s_addc_u32 s23, s29, 0
	s_mov_b32 m0, s41
	v_lshl_add_u64 v[224:225], s[22:23], 0, v[150:151]
	ds_read_b128 v[178:181], v216 offset:32768
	ds_read_b128 v[182:185], v216 offset:33792
	ds_read_b128 v[186:189], v216 offset:34816
	ds_read_b128 v[190:193], v216 offset:35840
	ds_read_b128 v[194:197], v216 offset:36864
	ds_read_b128 v[198:201], v216 offset:37888
	ds_read_b128 v[202:205], v216 offset:38912
	ds_read_b128 v[206:209], v216 offset:39936
	global_load_lds_dwordx4 v[224:225], off
	v_lshl_add_u64 v[224:225], s[22:23], 0, v[146:147]
	s_mov_b32 m0, s42
	s_nop 0
	global_load_lds_dwordx4 v[224:225], off
	s_waitcnt vmcnt(8)
	s_waitcnt lgkmcnt(0)
	s_barrier
	s_setprio 1
	s_waitcnt lgkmcnt(0)
	v_mfma_f32_16x16x32_bf16 v[124:127], v[128:131], v[178:181], v[124:127]
	v_mfma_f32_16x16x32_bf16 v[120:123], v[136:139], v[178:181], v[120:123]
	v_mfma_f32_16x16x32_bf16 v[112:115], v[128:131], v[186:189], v[112:115]
	v_mfma_f32_16x16x32_bf16 v[104:107], v[136:139], v[186:189], v[104:107]
	v_mfma_f32_16x16x32_bf16 v[100:103], v[128:131], v[194:197], v[100:103]
	v_mfma_f32_16x16x32_bf16 v[96:99], v[136:139], v[194:197], v[96:99]
	v_mfma_f32_16x16x32_bf16 v[76:79], v[128:131], v[202:205], v[76:79]
	v_mfma_f32_16x16x32_bf16 v[72:75], v[136:139], v[202:205], v[72:75]
	v_mfma_f32_16x16x32_bf16 v[124:127], v[132:135], v[182:185], v[124:127]
	v_mfma_f32_16x16x32_bf16 v[120:123], v[140:143], v[182:185], v[120:123]
	v_mfma_f32_16x16x32_bf16 v[112:115], v[132:135], v[190:193], v[112:115]
	v_mfma_f32_16x16x32_bf16 v[104:107], v[140:143], v[190:193], v[104:107]
	v_mfma_f32_16x16x32_bf16 v[100:103], v[132:135], v[198:201], v[100:103]
	v_mfma_f32_16x16x32_bf16 v[96:99], v[140:143], v[198:201], v[96:99]
	v_mfma_f32_16x16x32_bf16 v[76:79], v[132:135], v[206:209], v[76:79]
	v_mfma_f32_16x16x32_bf16 v[72:75], v[140:143], v[206:209], v[72:75]
	s_setprio 0
	s_setprio 1
	v_mfma_f32_16x16x32_bf16 v[116:119], v[162:165], v[178:181], v[116:119]
	v_mfma_f32_16x16x32_bf16 v[108:111], v[170:173], v[178:181], v[108:111]
	v_mfma_f32_16x16x32_bf16 v[92:95], v[162:165], v[186:189], v[92:95]
	v_mfma_f32_16x16x32_bf16 v[88:91], v[170:173], v[186:189], v[88:91]
	v_mfma_f32_16x16x32_bf16 v[84:87], v[162:165], v[194:197], v[84:87]
	v_mfma_f32_16x16x32_bf16 v[80:83], v[170:173], v[194:197], v[80:83]
	v_mfma_f32_16x16x32_bf16 v[68:71], v[162:165], v[202:205], v[68:71]
	v_mfma_f32_16x16x32_bf16 v[64:67], v[170:173], v[202:205], v[64:67]
	v_mfma_f32_16x16x32_bf16 v[116:119], v[166:169], v[182:185], v[116:119]
	v_mfma_f32_16x16x32_bf16 v[108:111], v[174:177], v[182:185], v[108:111]
	v_mfma_f32_16x16x32_bf16 v[92:95], v[166:169], v[190:193], v[92:95]
	v_mfma_f32_16x16x32_bf16 v[88:91], v[174:177], v[190:193], v[88:91]
	v_mfma_f32_16x16x32_bf16 v[84:87], v[166:169], v[198:201], v[84:87]
	v_mfma_f32_16x16x32_bf16 v[80:83], v[174:177], v[198:201], v[80:83]
	v_mfma_f32_16x16x32_bf16 v[68:71], v[166:169], v[206:209], v[68:71]
	v_mfma_f32_16x16x32_bf16 v[64:67], v[174:177], v[206:209], v[64:67]
	s_setprio 0
	s_barrier
; #define PG8_STAGE(bufoff, gbase, voff) do { _Pragma("unroll") for (int _i = 0; _i < 2; ++_i) \
;         __builtin_amdgcn_global_load_lds((const unsigned*)((const char*)(gbase) + (voff)[_i]), (PG8_LAS unsigned*)(lds + (bufoff) + ldsw + _i * 8192), 16, 0, 0); } while (0)
; #define PG8_LDA(dst, b, h) do { _Pragma("unroll") for (int m = 0; m < 4; ++m) _Pragma("unroll") for (int k = 0; k < 2; ++k) dst[m][k] = *(const PG8_LAS bf16x8*)(lds + PG8_SA(b, h) + aoff + m * 2048 + k * 1024); } while (0)
; #define PG8_MMA(ai, bj, At, Bt) do { __builtin_amdgcn_s_setprio(1); _Pragma("unroll") for (int m = 0; m < 4; ++m) _Pragma("unroll") for (int n = 0; n < 2; ++n) _Pragma("unroll") for (int k = 0; k < 2; ++k) \
;         acc[ai][bj][m][n] = __builtin_amdgcn_mfma_f32_16x16x32_bf16(Bt[n][k], At[m][k], acc[ai][bj][m][n], 0, 0, 0); __builtin_amdgcn_s_setprio(0); } while (0)
; #define PG8_WAIT_V(n) asm volatile("s_waitcnt vmcnt(" #n ")" ::: "memory")
; #define PG8_WAIT_L(n) asm volatile("s_waitcnt lgkmcnt(" #n ")" ::: "memory")
; #define PG8_BAR __builtin_amdgcn_s_barrier()
; #define PG8_SCHED __builtin_amdgcn_sched_barrier(0)
; template <class Epi, class Sched, bool ALIGN_EPI = false, bool SP2 = false>
; __device__ __forceinline__ void gemm_phase(PG8_LAS unsigned char* lds, const Gemm g, const Sched& S, const Epi& E, const int wave_in) {
;     ...
;         for (int t = 0; t < nt; t += 2) {
;             const bool last = (t == nt - 2);
;     ...
;             PG8_LDA(At, 1, 1); PG8_STAGE(PG8_SB(1, 0), b3, voffB); PG8_STAGE(PG8_SB(1, 1), b3 + hstepB, voffB); PG8_STAGE(PG8_SA(1, 0), a3, voffA);
;             PG8_WAIT_V(8); PG8_WAIT_L(0); PG8_BAR; PG8_MMA(1, 0, At, B0); PG8_MMA(1, 1, At, B1); PG8_BAR; PG8_SCHED;
	s_add_i32 s22, s60, s36
	v_lshl_add_u64 v[210:211], v[210:211], 0, s[6:7]
	s_mov_b32 m0, s22
	ds_read_b128 v[178:181], v216 offset:49152
	ds_read_b128 v[182:185], v216 offset:50176
	ds_read_b128 v[186:189], v216 offset:51200
	ds_read_b128 v[190:193], v216 offset:52224
	ds_read_b128 v[194:197], v216 offset:53248
	ds_read_b128 v[198:201], v216 offset:54272
	ds_read_b128 v[202:205], v216 offset:55296
	ds_read_b128 v[206:209], v216 offset:56320
	global_load_lds_dwordx4 v[210:211], off
	s_add_i32 m0, s22, 0x2000
	s_add_u32 s22, s26, 0x158080
	v_lshl_add_u64 v[210:211], v[218:219], 0, s[6:7]
	s_addc_u32 s23, s27, 0
	s_add_i32 s26, s61, s36
	global_load_lds_dwordx4 v[210:211], off
	v_lshl_add_u64 v[210:211], s[22:23], 0, v[148:149]
	s_mov_b32 m0, s26
	s_nop 0
	global_load_lds_dwordx4 v[210:211], off
	v_lshl_add_u64 v[210:211], s[22:23], 0, v[144:145]
	s_add_i32 m0, s26, 0x2000
	s_nop 0
	global_load_lds_dwordx4 v[210:211], off
	v_lshl_add_u64 v[210:211], v[220:221], 0, s[6:7]
	s_mov_b32 m0, s46
	s_nop 0
	global_load_lds_dwordx4 v[210:211], off
	v_lshl_add_u64 v[210:211], v[222:223], 0, s[6:7]
	s_mov_b32 m0, s47
	s_nop 0
	global_load_lds_dwordx4 v[210:211], off
	s_waitcnt vmcnt(8)
	s_waitcnt lgkmcnt(0)
	s_barrier
	s_setprio 1
	s_waitcnt lgkmcnt(0)
	v_mfma_f32_16x16x32_bf16 v[60:63], v[128:131], v[178:181], v[60:63]
	v_mfma_f32_16x16x32_bf16 v[56:59], v[136:139], v[178:181], v[56:59]
	v_mfma_f32_16x16x32_bf16 v[48:51], v[128:131], v[186:189], v[48:51]
	v_mfma_f32_16x16x32_bf16 v[40:43], v[136:139], v[186:189], v[40:43]
	v_mfma_f32_16x16x32_bf16 v[32:35], v[128:131], v[194:197], v[32:35]
	v_mfma_f32_16x16x32_bf16 v[24:27], v[136:139], v[194:197], v[24:27]
	v_mfma_f32_16x16x32_bf16 v[16:19], v[128:131], v[202:205], v[16:19]
	v_mfma_f32_16x16x32_bf16 v[8:11], v[136:139], v[202:205], v[8:11]
	v_mfma_f32_16x16x32_bf16 v[60:63], v[132:135], v[182:185], v[60:63]
	v_mfma_f32_16x16x32_bf16 v[56:59], v[140:143], v[182:185], v[56:59]
	v_mfma_f32_16x16x32_bf16 v[48:51], v[132:135], v[190:193], v[48:51]
	v_mfma_f32_16x16x32_bf16 v[40:43], v[140:143], v[190:193], v[40:43]
	v_mfma_f32_16x16x32_bf16 v[32:35], v[132:135], v[198:201], v[32:35]
	v_mfma_f32_16x16x32_bf16 v[24:27], v[140:143], v[198:201], v[24:27]
	v_mfma_f32_16x16x32_bf16 v[16:19], v[132:135], v[206:209], v[16:19]
	v_mfma_f32_16x16x32_bf16 v[8:11], v[140:143], v[206:209], v[8:11]
	s_setprio 0
	s_setprio 1
	v_mfma_f32_16x16x32_bf16 v[52:55], v[162:165], v[178:181], v[52:55]
	v_mfma_f32_16x16x32_bf16 v[44:47], v[170:173], v[178:181], v[44:47]
	v_mfma_f32_16x16x32_bf16 v[36:39], v[162:165], v[186:189], v[36:39]
	v_mfma_f32_16x16x32_bf16 v[28:31], v[170:173], v[186:189], v[28:31]
	v_mfma_f32_16x16x32_bf16 v[20:23], v[162:165], v[194:197], v[20:23]
	v_mfma_f32_16x16x32_bf16 v[12:15], v[170:173], v[194:197], v[12:15]
	v_mfma_f32_16x16x32_bf16 v[4:7], v[162:165], v[202:205], v[4:7]
	v_mfma_f32_16x16x32_bf16 v[0:3], v[170:173], v[202:205], v[0:3]
	v_mfma_f32_16x16x32_bf16 v[52:55], v[166:169], v[182:185], v[52:55]
	v_mfma_f32_16x16x32_bf16 v[44:47], v[174:177], v[182:185], v[44:47]
	v_mfma_f32_16x16x32_bf16 v[36:39], v[166:169], v[190:193], v[36:39]
	v_mfma_f32_16x16x32_bf16 v[28:31], v[174:177], v[190:193], v[28:31]
	v_mfma_f32_16x16x32_bf16 v[20:23], v[166:169], v[198:201], v[20:23]
	v_mfma_f32_16x16x32_bf16 v[12:15], v[174:177], v[198:201], v[12:15]
	v_mfma_f32_16x16x32_bf16 v[4:7], v[166:169], v[206:209], v[4:7]
	v_mfma_f32_16x16x32_bf16 v[0:3], v[174:177], v[206:209], v[0:3]
	s_setprio 0
	s_barrier
	s_add_i32 s59, s59, 2
	s_add_u32 s21, s21, 0x100
	s_addc_u32 s58, s58, 0
	s_cmpk_gt_u32 s59, 0x53
	s_mov_b64 s[22:23], s[24:25]
	s_cbranch_scc0 .LBB0_2107
	s_branch .Lkx_24

;     __host__ __device__ bool next(int i, Unit& u) const { const bool ok = StaticOrder::next(i, u); u.pm = 0; u.pn = 0; return ok; }
; #define PG8_STAGE(bufoff, gbase, voff) do { _Pragma("unroll") for (int _i = 0; _i < 2; ++_i) \
;         __builtin_amdgcn_global_load_lds((const unsigned*)((const char*)(gbase) + (voff)[_i]), (PG8_LAS unsigned*)(lds + (bufoff) + ldsw + _i * 8192), 16, 0, 0); } while (0)
; #define PG8_LDA(dst, b, h) do { _Pragma("unroll") for (int m = 0; m < 4; ++m) _Pragma("unroll") for (int k = 0; k < 2; ++k) dst[m][k] = *(const PG8_LAS bf16x8*)(lds + PG8_SA(b, h) + aoff + m * 2048 + k * 1024); } while (0)
; #define PG8_WAIT_V(n) asm volatile("s_waitcnt vmcnt(" #n ")" ::: "memory")
; #define PG8_WAIT_L(n) asm volatile("s_waitcnt lgkmcnt(" #n ")" ::: "memory")
; #define PG8_BAR __builtin_amdgcn_s_barrier()
; template <class Epi, class Sched, bool ALIGN_EPI = false, bool SP2 = false>
; __device__ __forceinline__ void gemm_phase(PG8_LAS unsigned char* lds, const Gemm g, const Sched& S, const Epi& E, const int wave_in) {
;     ...
;         const bool has_next = S.next(ui + 1, nxt);
;         const char* nA = has_next ? (const char*)g.A + (size_t)nxt.pm * tstepA : cA; const char* nB = has_next ? (const char*)g.Bt + (size_t)nxt.pn * tstepB : cB;
;         for (int t = 0; t < nt; t += 2) {
;             const bool last = (t == nt - 2);
;             const char* a1 = cA + (size_t)(t + 1) * kstep;
;             const char* a2 = last ? nA : cA + (size_t)(t + 2) * kstep; const char* b2 = last ? nB : cB + (size_t)(t + 2) * kstep;
;             const char* a3 = a2 + kstep; const char* b3 = b2 + kstep;
;             if (last && has_next) S.a_ready(nxt);
;             if constexpr (SP2) {
;             PG8_LDB(B0, 0, 0); PG8_LDB(B1, 0, 1); PG8_SCHED; PG8_LDA(At, 0, 0); PG8_STAGE(PG8_SA(1, 1), a1 + hstepA, voffA);
;             PG8_WAIT_V(8); PG8_WAIT_L(0); PG8_BAR; PG8_MMA(0, 0, At, B0); PG8_MMA(0, 1, At, B1); PG8_BAR; PG8_SCHED;
;             PG8_LDA(At, 0, 1); PG8_STAGE(PG8_SB(0, 0), b2, voffB); PG8_STAGE(PG8_SB(0, 1), b2 + hstepB, voffB); PG8_STAGE(PG8_SA(0, 0), a2, voffA);
;     ...
; #pragma unroll
;         for (int a = 0; a < 2; ++a)
; #pragma unroll
;             for (int b = 0; b < 2; ++b)
; #pragma unroll
;                 for (int m = 0; m < 4; ++m)
; #pragma unroll
;                     for (int n = 0; n < 2; ++n) acc[a][b][m][n] = (f32x4){0.f, 0.f, 0.f, 0.f};
.LBB0_2247:
	s_ashr_i32 s15, s14, 31
	s_lshl_b64 s[16:17], s[14:15], 20
	s_add_u32 s16, s28, s16
	s_addc_u32 s17, s29, s17
	s_and_b64 s[18:19], s[2:3], exec
	s_cselect_b32 s5, s17, s23
	s_cselect_b32 s15, s16, s22
	s_ashr_i32 s13, s12, 31
	s_lshl_b64 s[18:19], s[12:13], 20
	s_add_u32 s18, s30, s18
	s_addc_u32 s19, s31, s19
	s_and_b64 s[26:27], s[2:3], exec
	s_cselect_b32 s13, s19, s25
	s_cselect_b32 s47, s18, s24
	s_add_u32 s22, s22, 0x80080
	s_addc_u32 s23, s23, 0
	s_add_u32 s48, s24, 0x100
	v_mov_b32_e32 v0, 0
	s_addc_u32 s49, s25, 0
	s_mov_b32 s50, -2
	ds_read_b128 v[144:147], v151
	ds_read_b128 v[154:157], v151 offset:1024
	ds_read_b128 v[158:161], v151 offset:2048
	ds_read_b128 v[162:165], v151 offset:3072
	ds_read_b128 v[166:169], v152
	ds_read_b128 v[170:173], v152 offset:1024
	ds_read_b128 v[174:177], v152 offset:2048
	ds_read_b128 v[178:181], v152 offset:3072
	s_add_u32 s24, s22, 0xfff80080
	s_addc_u32 s25, s23, -1
	s_cmp_eq_u32 s50, 28
	s_cselect_b32 s27, s5, s25
	s_cselect_b32 s26, s15, s24
	s_cselect_b32 s25, s13, s49
	s_cselect_b32 s24, s47, s48
	v_lshl_add_u64 v[214:215], s[22:23], 0, v[136:137]
	s_add_i32 m0, s21, 0xc000
	ds_read_b128 v[182:185], v153
	ds_read_b128 v[186:189], v153 offset:1024
	ds_read_b128 v[190:193], v153 offset:2048
	ds_read_b128 v[194:197], v153 offset:3072
	ds_read_b128 v[198:201], v153 offset:4096
	ds_read_b128 v[202:205], v153 offset:5120
	ds_read_b128 v[206:209], v153 offset:6144
	ds_read_b128 v[210:213], v153 offset:7168
	global_load_lds_dwordx4 v[214:215], off
	v_lshl_add_u64 v[214:215], s[22:23], 0, v[138:139]
	s_add_i32 m0, s21, 0xe000
	s_nop 0
	global_load_lds_dwordx4 v[214:215], off
	s_waitcnt vmcnt(8)
	s_waitcnt lgkmcnt(0)
	s_barrier
	s_setprio 1
	s_waitcnt lgkmcnt(0)
	v_mfma_f32_16x16x32_bf16 v[124:127], v[144:147], v[182:185], 0
	v_mfma_f32_16x16x32_bf16 v[120:123], v[158:161], v[182:185], 0
	v_mfma_f32_16x16x32_bf16 v[108:111], v[144:147], v[190:193], 0
	v_mfma_f32_16x16x32_bf16 v[104:107], v[158:161], v[190:193], 0
	v_mfma_f32_16x16x32_bf16 v[92:95], v[144:147], v[198:201], 0
	v_mfma_f32_16x16x32_bf16 v[88:91], v[158:161], v[198:201], 0
	v_mfma_f32_16x16x32_bf16 v[76:79], v[144:147], v[206:209], 0
	v_mfma_f32_16x16x32_bf16 v[72:75], v[158:161], v[206:209], 0
	v_mfma_f32_16x16x32_bf16 v[124:127], v[154:157], v[186:189], v[124:127]
	v_mfma_f32_16x16x32_bf16 v[120:123], v[162:165], v[186:189], v[120:123]
	v_mfma_f32_16x16x32_bf16 v[108:111], v[154:157], v[194:197], v[108:111]
	v_mfma_f32_16x16x32_bf16 v[104:107], v[162:165], v[194:197], v[104:107]
	v_mfma_f32_16x16x32_bf16 v[92:95], v[154:157], v[202:205], v[92:95]
	v_mfma_f32_16x16x32_bf16 v[88:91], v[162:165], v[202:205], v[88:91]
	v_mfma_f32_16x16x32_bf16 v[76:79], v[154:157], v[210:213], v[76:79]
	v_mfma_f32_16x16x32_bf16 v[72:75], v[162:165], v[210:213], v[72:75]
	s_setprio 0
	s_setprio 1
	v_mfma_f32_16x16x32_bf16 v[116:119], v[166:169], v[182:185], 0
	v_mfma_f32_16x16x32_bf16 v[112:115], v[174:177], v[182:185], 0
	v_mfma_f32_16x16x32_bf16 v[100:103], v[166:169], v[190:193], 0
	v_mfma_f32_16x16x32_bf16 v[96:99], v[174:177], v[190:193], 0
	v_mfma_f32_16x16x32_bf16 v[84:87], v[166:169], v[198:201], 0
	v_mfma_f32_16x16x32_bf16 v[80:83], v[174:177], v[198:201], 0
	v_mfma_f32_16x16x32_bf16 v[68:71], v[166:169], v[206:209], 0
	v_mfma_f32_16x16x32_bf16 v[64:67], v[174:177], v[206:209], 0
	v_mfma_f32_16x16x32_bf16 v[116:119], v[170:173], v[186:189], v[116:119]
	v_mfma_f32_16x16x32_bf16 v[112:115], v[178:181], v[186:189], v[112:115]
	v_mfma_f32_16x16x32_bf16 v[100:103], v[170:173], v[194:197], v[100:103]
	v_mfma_f32_16x16x32_bf16 v[96:99], v[178:181], v[194:197], v[96:99]
	v_mfma_f32_16x16x32_bf16 v[84:87], v[170:173], v[202:205], v[84:87]
	v_mfma_f32_16x16x32_bf16 v[80:83], v[178:181], v[202:205], v[80:83]
	v_mfma_f32_16x16x32_bf16 v[68:71], v[170:173], v[210:213], v[68:71]
	v_mfma_f32_16x16x32_bf16 v[64:67], v[178:181], v[210:213], v[64:67]
	s_setprio 0
	s_barrier
	s_add_i32 s51, s44, s34
	v_lshl_add_u64 v[214:215], s[24:25], 0, v[130:131]
	s_mov_b32 m0, s51
	ds_read_b128 v[182:185], v153 offset:16384
	ds_read_b128 v[186:189], v153 offset:17408
	ds_read_b128 v[190:193], v153 offset:18432
	ds_read_b128 v[194:197], v153 offset:19456
	ds_read_b128 v[198:201], v153 offset:20480
	ds_read_b128 v[202:205], v153 offset:21504
	ds_read_b128 v[206:209], v153 offset:22528
	ds_read_b128 v[210:213], v153 offset:23552
	global_load_lds_dwordx4 v[214:215], off
	s_add_i32 m0, s51, 0x2000
	s_add_u32 s52, s24, 0x80000
	v_lshl_add_u64 v[216:217], s[24:25], 0, v[134:135]
	s_addc_u32 s53, s25, 0
	s_add_i32 s51, s45, s34
	global_load_lds_dwordx4 v[216:217], off
	v_lshl_add_u64 v[218:219], s[52:53], 0, v[130:131]
	s_mov_b32 m0, s51
	v_lshl_add_u64 v[220:221], s[26:27], 0, v[132:133]
	global_load_lds_dwordx4 v[218:219], off
	v_lshl_add_u64 v[218:219], s[52:53], 0, v[134:135]
	s_add_i32 m0, s51, 0x2000
	s_nop 0
	global_load_lds_dwordx4 v[218:219], off
	v_lshl_add_u64 v[218:219], s[26:27], 0, v[128:129]
	s_mov_b32 m0, s21
	s_nop 0
	global_load_lds_dwordx4 v[218:219], off
	s_mov_b32 m0, s35
	s_nop 0
	global_load_lds_dwordx4 v[220:221], off
	s_waitcnt vmcnt(8)
	s_waitcnt lgkmcnt(0)
	s_barrier
; #define PG8_STAGE(bufoff, gbase, voff) do { _Pragma("unroll") for (int _i = 0; _i < 2; ++_i) \
;         __builtin_amdgcn_global_load_lds((const unsigned*)((const char*)(gbase) + (voff)[_i]), (PG8_LAS unsigned*)(lds + (bufoff) + ldsw + _i * 8192), 16, 0, 0); } while (0)
; #define PG8_LDA(dst, b, h) do { _Pragma("unroll") for (int m = 0; m < 4; ++m) _Pragma("unroll") for (int k = 0; k < 2; ++k) dst[m][k] = *(const PG8_LAS bf16x8*)(lds + PG8_SA(b, h) + aoff + m * 2048 + k * 1024); } while (0)
; #define PG8_LDB(dst, b, h) do { _Pragma("unroll") for (int n = 0; n < 2; ++n) _Pragma("unroll") for (int k = 0; k < 2; ++k) dst[n][k] = *(const PG8_LAS bf16x8*)(lds + PG8_SB(b, h) + boff + n * 2048 + k * 1024); } while (0)
; #define PG8_MMA(ai, bj, At, Bt) do { __builtin_amdgcn_s_setprio(1); _Pragma("unroll") for (int m = 0; m < 4; ++m) _Pragma("unroll") for (int n = 0; n < 2; ++n) _Pragma("unroll") for (int k = 0; k < 2; ++k) \
;         acc[ai][bj][m][n] = __builtin_amdgcn_mfma_f32_16x16x32_bf16(Bt[n][k], At[m][k], acc[ai][bj][m][n], 0, 0, 0); __builtin_amdgcn_s_setprio(0); } while (0)
; #define PG8_WAIT_V(n) asm volatile("s_waitcnt vmcnt(" #n ")" ::: "memory")
; #define PG8_WAIT_L(n) asm volatile("s_waitcnt lgkmcnt(" #n ")" ::: "memory")
; #define PG8_BAR __builtin_amdgcn_s_barrier()
; #define PG8_SCHED __builtin_amdgcn_sched_barrier(0)
; template <class Epi, class Sched, bool ALIGN_EPI = false, bool SP2 = false>
; __device__ __forceinline__ void gemm_phase(PG8_LAS unsigned char* lds, const Gemm g, const Sched& S, const Epi& E, const int wave_in) {
;     ...
;             PG8_WAIT_V(8); PG8_WAIT_L(0); PG8_BAR; PG8_MMA(1, 0, At, B0); PG8_MMA(1, 1, At, B1); PG8_BAR; PG8_SCHED;
;             PG8_LDB(B0, 1, 0); PG8_LDB(B1, 1, 1); PG8_SCHED; PG8_LDA(At, 1, 0); PG8_STAGE(PG8_SA(0, 1), a2 + hstepA, voffA);
;             PG8_WAIT_V(8); PG8_WAIT_L(0); PG8_BAR; PG8_MMA(0, 0, At, B0); PG8_MMA(0, 1, At, B1); PG8_BAR; PG8_SCHED;
	s_setprio 1
	s_waitcnt lgkmcnt(0)
	v_mfma_f32_16x16x32_bf16 v[60:63], v[144:147], v[182:185], 0
	v_mfma_f32_16x16x32_bf16 v[56:59], v[158:161], v[182:185], 0
	v_mfma_f32_16x16x32_bf16 v[44:47], v[144:147], v[190:193], 0
	v_mfma_f32_16x16x32_bf16 v[40:43], v[158:161], v[190:193], 0
	v_mfma_f32_16x16x32_bf16 v[28:31], v[144:147], v[198:201], 0
	v_mfma_f32_16x16x32_bf16 v[24:27], v[158:161], v[198:201], 0
	v_mfma_f32_16x16x32_bf16 v[12:15], v[144:147], v[206:209], 0
	v_mfma_f32_16x16x32_bf16 v[8:11], v[158:161], v[206:209], 0
	v_mfma_f32_16x16x32_bf16 v[60:63], v[154:157], v[186:189], v[60:63]
	v_mfma_f32_16x16x32_bf16 v[56:59], v[162:165], v[186:189], v[56:59]
	v_mfma_f32_16x16x32_bf16 v[44:47], v[154:157], v[194:197], v[44:47]
	v_mfma_f32_16x16x32_bf16 v[40:43], v[162:165], v[194:197], v[40:43]
	v_mfma_f32_16x16x32_bf16 v[28:31], v[154:157], v[202:205], v[28:31]
	v_mfma_f32_16x16x32_bf16 v[24:27], v[162:165], v[202:205], v[24:27]
	v_mfma_f32_16x16x32_bf16 v[12:15], v[154:157], v[210:213], v[12:15]
	v_mfma_f32_16x16x32_bf16 v[8:11], v[162:165], v[210:213], v[8:11]
	s_setprio 0
	s_setprio 1
	v_mfma_f32_16x16x32_bf16 v[52:55], v[166:169], v[182:185], 0
	v_mfma_f32_16x16x32_bf16 v[48:51], v[174:177], v[182:185], 0
	v_mfma_f32_16x16x32_bf16 v[36:39], v[166:169], v[190:193], 0
	v_mfma_f32_16x16x32_bf16 v[32:35], v[174:177], v[190:193], 0
	v_mfma_f32_16x16x32_bf16 v[20:23], v[166:169], v[198:201], 0
	v_mfma_f32_16x16x32_bf16 v[16:19], v[174:177], v[198:201], 0
	v_mfma_f32_16x16x32_bf16 v[4:7], v[166:169], v[206:209], 0
	v_mfma_f32_16x16x32_bf16 v[0:3], v[174:177], v[206:209], 0
	v_mfma_f32_16x16x32_bf16 v[52:55], v[170:173], v[186:189], v[52:55]
	v_mfma_f32_16x16x32_bf16 v[48:51], v[178:181], v[186:189], v[48:51]
	v_mfma_f32_16x16x32_bf16 v[36:39], v[170:173], v[194:197], v[36:39]
	v_mfma_f32_16x16x32_bf16 v[32:35], v[178:181], v[194:197], v[32:35]
	v_mfma_f32_16x16x32_bf16 v[20:23], v[170:173], v[202:205], v[20:23]
	v_mfma_f32_16x16x32_bf16 v[16:19], v[178:181], v[202:205], v[16:19]
	v_mfma_f32_16x16x32_bf16 v[4:7], v[170:173], v[210:213], v[4:7]
	v_mfma_f32_16x16x32_bf16 v[0:3], v[178:181], v[210:213], v[0:3]
	s_setprio 0
	s_barrier
	s_add_i32 s51, 0, 0x18000
	s_add_i32 s52, 0, 0x1c000
	v_add_u32_e32 v162, s51, v149
	v_add_u32_e32 v178, s52, v149
	ds_read_b128 v[144:147], v162
	ds_read_b128 v[154:157], v162 offset:1024
	ds_read_b128 v[158:161], v162 offset:2048
	ds_read_b128 v[162:165], v162 offset:3072
	ds_read_b128 v[166:169], v178
	ds_read_b128 v[170:173], v178 offset:1024
	ds_read_b128 v[174:177], v178 offset:2048
	ds_read_b128 v[178:181], v178 offset:3072
	s_add_u32 s26, s26, 0x80000
	s_addc_u32 s27, s27, 0
	s_mov_b32 m0, s36
	v_lshl_add_u64 v[222:223], s[26:27], 0, v[128:129]
	ds_read_b128 v[182:185], v153 offset:32768
	ds_read_b128 v[186:189], v153 offset:33792
	ds_read_b128 v[190:193], v153 offset:34816
	ds_read_b128 v[194:197], v153 offset:35840
	ds_read_b128 v[198:201], v153 offset:36864
	ds_read_b128 v[202:205], v153 offset:37888
	ds_read_b128 v[206:209], v153 offset:38912
	ds_read_b128 v[210:213], v153 offset:39936
	global_load_lds_dwordx4 v[222:223], off
	v_lshl_add_u64 v[222:223], s[26:27], 0, v[132:133]
	s_mov_b32 m0, s37
	s_nop 0
	global_load_lds_dwordx4 v[222:223], off
	s_waitcnt vmcnt(8)
	s_waitcnt lgkmcnt(0)
	s_barrier
	s_setprio 1
	s_waitcnt lgkmcnt(0)
	v_mfma_f32_16x16x32_bf16 v[124:127], v[144:147], v[182:185], v[124:127]
	v_mfma_f32_16x16x32_bf16 v[120:123], v[158:161], v[182:185], v[120:123]
	v_mfma_f32_16x16x32_bf16 v[108:111], v[144:147], v[190:193], v[108:111]
	v_mfma_f32_16x16x32_bf16 v[104:107], v[158:161], v[190:193], v[104:107]
	v_mfma_f32_16x16x32_bf16 v[92:95], v[144:147], v[198:201], v[92:95]
	v_mfma_f32_16x16x32_bf16 v[88:91], v[158:161], v[198:201], v[88:91]
	v_mfma_f32_16x16x32_bf16 v[76:79], v[144:147], v[206:209], v[76:79]
	v_mfma_f32_16x16x32_bf16 v[72:75], v[158:161], v[206:209], v[72:75]
	v_mfma_f32_16x16x32_bf16 v[124:127], v[154:157], v[186:189], v[124:127]
	v_mfma_f32_16x16x32_bf16 v[120:123], v[162:165], v[186:189], v[120:123]
	v_mfma_f32_16x16x32_bf16 v[108:111], v[154:157], v[194:197], v[108:111]
	v_mfma_f32_16x16x32_bf16 v[104:107], v[162:165], v[194:197], v[104:107]
	v_mfma_f32_16x16x32_bf16 v[92:95], v[154:157], v[202:205], v[92:95]
	v_mfma_f32_16x16x32_bf16 v[88:91], v[162:165], v[202:205], v[88:91]
	v_mfma_f32_16x16x32_bf16 v[76:79], v[154:157], v[210:213], v[76:79]
	v_mfma_f32_16x16x32_bf16 v[72:75], v[162:165], v[210:213], v[72:75]
	s_setprio 0
	s_setprio 1
	v_mfma_f32_16x16x32_bf16 v[116:119], v[166:169], v[182:185], v[116:119]
	v_mfma_f32_16x16x32_bf16 v[112:115], v[174:177], v[182:185], v[112:115]
	v_mfma_f32_16x16x32_bf16 v[100:103], v[166:169], v[190:193], v[100:103]
	v_mfma_f32_16x16x32_bf16 v[96:99], v[174:177], v[190:193], v[96:99]
	v_mfma_f32_16x16x32_bf16 v[84:87], v[166:169], v[198:201], v[84:87]
	v_mfma_f32_16x16x32_bf16 v[80:83], v[174:177], v[198:201], v[80:83]
	v_mfma_f32_16x16x32_bf16 v[68:71], v[166:169], v[206:209], v[68:71]
	v_mfma_f32_16x16x32_bf16 v[64:67], v[174:177], v[206:209], v[64:67]
	v_mfma_f32_16x16x32_bf16 v[116:119], v[170:173], v[186:189], v[116:119]
	v_mfma_f32_16x16x32_bf16 v[112:115], v[178:181], v[186:189], v[112:115]
	v_mfma_f32_16x16x32_bf16 v[100:103], v[170:173], v[194:197], v[100:103]
	v_mfma_f32_16x16x32_bf16 v[96:99], v[178:181], v[194:197], v[96:99]
	v_mfma_f32_16x16x32_bf16 v[84:87], v[170:173], v[202:205], v[84:87]
	v_mfma_f32_16x16x32_bf16 v[80:83], v[178:181], v[202:205], v[80:83]
	v_mfma_f32_16x16x32_bf16 v[68:71], v[170:173], v[210:213], v[68:71]
	v_mfma_f32_16x16x32_bf16 v[64:67], v[178:181], v[210:213], v[64:67]
	s_setprio 0
	s_barrier
; #define PG8_STAGE(bufoff, gbase, voff) do { _Pragma("unroll") for (int _i = 0; _i < 2; ++_i) \
;         __builtin_amdgcn_global_load_lds((const unsigned*)((const char*)(gbase) + (voff)[_i]), (PG8_LAS unsigned*)(lds + (bufoff) + ldsw + _i * 8192), 16, 0, 0); } while (0)
; #define PG8_LDA(dst, b, h) do { _Pragma("unroll") for (int m = 0; m < 4; ++m) _Pragma("unroll") for (int k = 0; k < 2; ++k) dst[m][k] = *(const PG8_LAS bf16x8*)(lds + PG8_SA(b, h) + aoff + m * 2048 + k * 1024); } while (0)
; #define PG8_MMA(ai, bj, At, Bt) do { __builtin_amdgcn_s_setprio(1); _Pragma("unroll") for (int m = 0; m < 4; ++m) _Pragma("unroll") for (int n = 0; n < 2; ++n) _Pragma("unroll") for (int k = 0; k < 2; ++k) \
;         acc[ai][bj][m][n] = __builtin_amdgcn_mfma_f32_16x16x32_bf16(Bt[n][k], At[m][k], acc[ai][bj][m][n], 0, 0, 0); __builtin_amdgcn_s_setprio(0); } while (0)
; #define PG8_WAIT_V(n) asm volatile("s_waitcnt vmcnt(" #n ")" ::: "memory")
; #define PG8_WAIT_L(n) asm volatile("s_waitcnt lgkmcnt(" #n ")" ::: "memory")
; #define PG8_BAR __builtin_amdgcn_s_barrier()
; #define PG8_SCHED __builtin_amdgcn_sched_barrier(0)
; template <class Epi, class Sched, bool ALIGN_EPI = false, bool SP2 = false>
; __device__ __forceinline__ void gemm_phase(PG8_LAS unsigned char* lds, const Gemm g, const Sched& S, const Epi& E, const int wave_in) {
;     ...
;         for (int t = 0; t < nt; t += 2) {
;             const bool last = (t == nt - 2);
;     ...
;             PG8_LDA(At, 1, 1); PG8_STAGE(PG8_SB(1, 0), b3, voffB); PG8_STAGE(PG8_SB(1, 1), b3 + hstepB, voffB); PG8_STAGE(PG8_SA(1, 0), a3, voffA);
;             PG8_WAIT_V(8); PG8_WAIT_L(0); PG8_BAR; PG8_MMA(1, 0, At, B0); PG8_MMA(1, 1, At, B1); PG8_BAR; PG8_SCHED;
	s_add_i32 s26, s51, s34
	v_lshl_add_u64 v[214:215], v[214:215], 0, s[8:9]
	s_mov_b32 m0, s26
	ds_read_b128 v[182:185], v153 offset:49152
	ds_read_b128 v[186:189], v153 offset:50176
	ds_read_b128 v[190:193], v153 offset:51200
	ds_read_b128 v[194:197], v153 offset:52224
	ds_read_b128 v[198:201], v153 offset:53248
	ds_read_b128 v[202:205], v153 offset:54272
	ds_read_b128 v[206:209], v153 offset:55296
	ds_read_b128 v[210:213], v153 offset:56320
	global_load_lds_dwordx4 v[214:215], off
	s_add_i32 m0, s26, 0x2000
	s_add_u32 s24, s24, 0x80080
	v_lshl_add_u64 v[214:215], v[216:217], 0, s[8:9]
	s_addc_u32 s25, s25, 0
	s_add_i32 s26, s52, s34
	global_load_lds_dwordx4 v[214:215], off
	v_lshl_add_u64 v[214:215], s[24:25], 0, v[130:131]
	s_mov_b32 m0, s26
	s_nop 0
	global_load_lds_dwordx4 v[214:215], off
	v_lshl_add_u64 v[214:215], s[24:25], 0, v[134:135]
	s_add_i32 m0, s26, 0x2000
	s_nop 0
	global_load_lds_dwordx4 v[214:215], off
	v_lshl_add_u64 v[214:215], v[218:219], 0, s[8:9]
	s_mov_b32 m0, s39
	s_nop 0
	global_load_lds_dwordx4 v[214:215], off
	v_lshl_add_u64 v[214:215], v[220:221], 0, s[8:9]
	s_mov_b32 m0, s40
	s_nop 0
	global_load_lds_dwordx4 v[214:215], off
	s_waitcnt vmcnt(8)
	s_waitcnt lgkmcnt(0)
	s_barrier
	s_setprio 1
	s_waitcnt lgkmcnt(0)
	v_mfma_f32_16x16x32_bf16 v[60:63], v[144:147], v[182:185], v[60:63]
	v_mfma_f32_16x16x32_bf16 v[56:59], v[158:161], v[182:185], v[56:59]
	v_mfma_f32_16x16x32_bf16 v[44:47], v[144:147], v[190:193], v[44:47]
	v_mfma_f32_16x16x32_bf16 v[40:43], v[158:161], v[190:193], v[40:43]
	v_mfma_f32_16x16x32_bf16 v[28:31], v[144:147], v[198:201], v[28:31]
	v_mfma_f32_16x16x32_bf16 v[24:27], v[158:161], v[198:201], v[24:27]
	v_mfma_f32_16x16x32_bf16 v[12:15], v[144:147], v[206:209], v[12:15]
	v_mfma_f32_16x16x32_bf16 v[8:11], v[158:161], v[206:209], v[8:11]
	v_mfma_f32_16x16x32_bf16 v[60:63], v[154:157], v[186:189], v[60:63]
	v_mfma_f32_16x16x32_bf16 v[56:59], v[162:165], v[186:189], v[56:59]
	v_mfma_f32_16x16x32_bf16 v[44:47], v[154:157], v[194:197], v[44:47]
	v_mfma_f32_16x16x32_bf16 v[40:43], v[162:165], v[194:197], v[40:43]
	v_mfma_f32_16x16x32_bf16 v[28:31], v[154:157], v[202:205], v[28:31]
	v_mfma_f32_16x16x32_bf16 v[24:27], v[162:165], v[202:205], v[24:27]
	v_mfma_f32_16x16x32_bf16 v[12:15], v[154:157], v[210:213], v[12:15]
	v_mfma_f32_16x16x32_bf16 v[8:11], v[162:165], v[210:213], v[8:11]
	s_setprio 0
	s_setprio 1
	v_mfma_f32_16x16x32_bf16 v[52:55], v[166:169], v[182:185], v[52:55]
	v_mfma_f32_16x16x32_bf16 v[48:51], v[174:177], v[182:185], v[48:51]
	v_mfma_f32_16x16x32_bf16 v[36:39], v[166:169], v[190:193], v[36:39]
	v_mfma_f32_16x16x32_bf16 v[32:35], v[174:177], v[190:193], v[32:35]
	v_mfma_f32_16x16x32_bf16 v[20:23], v[166:169], v[198:201], v[20:23]
	v_mfma_f32_16x16x32_bf16 v[16:19], v[174:177], v[198:201], v[16:19]
	v_mfma_f32_16x16x32_bf16 v[4:7], v[166:169], v[206:209], v[4:7]
	v_mfma_f32_16x16x32_bf16 v[0:3], v[174:177], v[206:209], v[0:3]
	v_mfma_f32_16x16x32_bf16 v[52:55], v[170:173], v[186:189], v[52:55]
	v_mfma_f32_16x16x32_bf16 v[48:51], v[178:181], v[186:189], v[48:51]
	v_mfma_f32_16x16x32_bf16 v[36:39], v[170:173], v[194:197], v[36:39]
	v_mfma_f32_16x16x32_bf16 v[32:35], v[178:181], v[194:197], v[32:35]
	v_mfma_f32_16x16x32_bf16 v[20:23], v[170:173], v[202:205], v[20:23]
	v_mfma_f32_16x16x32_bf16 v[16:19], v[178:181], v[202:205], v[16:19]
	v_mfma_f32_16x16x32_bf16 v[4:7], v[170:173], v[210:213], v[4:7]
	v_mfma_f32_16x16x32_bf16 v[0:3], v[178:181], v[210:213], v[0:3]
	s_setprio 0
	s_barrier
	s_add_i32 s50, s50, 2
	s_add_u32 s22, s22, 0x100
	s_addc_u32 s23, s23, 0
	s_add_u32 s48, s48, 0x100
	s_addc_u32 s49, s49, 0
	s_cmp_gt_u32 s50, 29
	s_cbranch_scc0 .LBB0_2248
	s_branch .Lkx_26

;     __host__ __device__ bool next(int i, Unit& u) const { const bool ok = StaticOrder::next(i, u); u.pm = 0; u.pn = 0; return ok; }
; #define PG8_STAGE(bufoff, gbase, voff) do { _Pragma("unroll") for (int _i = 0; _i < 2; ++_i) \
;         __builtin_amdgcn_global_load_lds((const unsigned*)((const char*)(gbase) + (voff)[_i]), (PG8_LAS unsigned*)(lds + (bufoff) + ldsw + _i * 8192), 16, 0, 0); } while (0)
; #define PG8_LDA(dst, b, h) do { _Pragma("unroll") for (int m = 0; m < 4; ++m) _Pragma("unroll") for (int k = 0; k < 2; ++k) dst[m][k] = *(const PG8_LAS bf16x8*)(lds + PG8_SA(b, h) + aoff + m * 2048 + k * 1024); } while (0)
; #define PG8_WAIT_V(n) asm volatile("s_waitcnt vmcnt(" #n ")" ::: "memory")
; #define PG8_WAIT_L(n) asm volatile("s_waitcnt lgkmcnt(" #n ")" ::: "memory")
; #define PG8_BAR __builtin_amdgcn_s_barrier()
; template <class Epi, class Sched, bool ALIGN_EPI = false, bool SP2 = false>
; __device__ __forceinline__ void gemm_phase(PG8_LAS unsigned char* lds, const Gemm g, const Sched& S, const Epi& E, const int wave_in) {
;     ...
;         const bool has_next = S.next(ui + 1, nxt);
;         const char* nA = has_next ? (const char*)g.A + (size_t)nxt.pm * tstepA : cA; const char* nB = has_next ? (const char*)g.Bt + (size_t)nxt.pn * tstepB : cB;
;         for (int t = 0; t < nt; t += 2) {
;             const bool last = (t == nt - 2);
;             const char* a1 = cA + (size_t)(t + 1) * kstep;
;             const char* a2 = last ? nA : cA + (size_t)(t + 2) * kstep; const char* b2 = last ? nB : cB + (size_t)(t + 2) * kstep;
;             const char* a3 = a2 + kstep; const char* b3 = b2 + kstep;
;             if (last && has_next) S.a_ready(nxt);
;             if constexpr (SP2) {
;             PG8_LDB(B0, 0, 0); PG8_LDB(B1, 0, 1); PG8_SCHED; PG8_LDA(At, 0, 0); PG8_STAGE(PG8_SA(1, 1), a1 + hstepA, voffA);
;             PG8_WAIT_V(8); PG8_WAIT_L(0); PG8_BAR; PG8_MMA(0, 0, At, B0); PG8_MMA(0, 1, At, B1); PG8_BAR; PG8_SCHED;
;             PG8_LDA(At, 0, 1); PG8_STAGE(PG8_SB(0, 0), b2, voffB); PG8_STAGE(PG8_SB(0, 1), b2 + hstepB, voffB); PG8_STAGE(PG8_SA(0, 0), a2, voffA);
;     ...
; #pragma unroll
;         for (int a = 0; a < 2; ++a)
; #pragma unroll
;             for (int b = 0; b < 2; ++b)
; #pragma unroll
;                 for (int m = 0; m < 4; ++m)
; #pragma unroll
;                     for (int n = 0; n < 2; ++n) acc[a][b][m][n] = (f32x4){0.f, 0.f, 0.f, 0.f};
.LBB0_2450:
	s_ashr_i32 s19, s18, 31
	s_lshl_b64 s[22:23], s[18:19], 20
	s_add_u32 s22, s37, s22
	s_addc_u32 s23, s38, s23
	s_and_b64 s[4:5], s[4:5], exec
	s_cselect_b32 s19, s23, s29
	s_cselect_b32 s25, s22, s28
	s_add_u32 s58, s28, 0x100
	v_mov_b32_e32 v0, 0
	s_addc_u32 s59, s29, 0
	s_mov_b32 s60, -2
	s_waitcnt vmcnt(0)
	ds_read_b128 v[128:131], v170
	ds_read_b128 v[132:135], v170 offset:1024
	ds_read_b128 v[136:139], v170 offset:2048
	ds_read_b128 v[140:143], v170 offset:3072
	ds_read_b128 v[162:165], v171
	ds_read_b128 v[174:177], v171 offset:1024
	ds_read_b128 v[178:181], v171 offset:2048
	ds_read_b128 v[182:185], v171 offset:3072
	s_add_u32 s4, s26, 0x100
	s_addc_u32 s5, s27, 0
	s_cmp_eq_u32 s60, 28
	s_cselect_b32 s31, s21, s5
	s_cselect_b32 s30, s20, s4
	s_cselect_b32 s29, s19, s59
	s_cselect_b32 s28, s25, s58
	v_lshl_add_u64 v[166:167], s[26:27], 0, v[154:155]
	s_add_i32 m0, s40, 0xc000
	ds_read_b128 v[186:189], v172
	ds_read_b128 v[190:193], v172 offset:1024
	ds_read_b128 v[194:197], v172 offset:2048
	ds_read_b128 v[198:201], v172 offset:3072
	ds_read_b128 v[202:205], v172 offset:4096
	ds_read_b128 v[206:209], v172 offset:5120
	ds_read_b128 v[210:213], v172 offset:6144
	ds_read_b128 v[214:217], v172 offset:7168
	global_load_lds_dwordx4 v[166:167], off
	v_lshl_add_u64 v[166:167], s[26:27], 0, v[156:157]
	s_add_i32 m0, s40, 0xe000
	s_nop 0
	global_load_lds_dwordx4 v[166:167], off
	s_waitcnt vmcnt(8)
	s_waitcnt lgkmcnt(0)
	s_barrier
	s_setprio 1
	s_waitcnt lgkmcnt(0)
	v_mfma_f32_16x16x32_bf16 v[124:127], v[128:131], v[186:189], 0
	v_mfma_f32_16x16x32_bf16 v[120:123], v[136:139], v[186:189], 0
	v_mfma_f32_16x16x32_bf16 v[112:115], v[128:131], v[194:197], 0
	v_mfma_f32_16x16x32_bf16 v[104:107], v[136:139], v[194:197], 0
	v_mfma_f32_16x16x32_bf16 v[96:99], v[128:131], v[202:205], 0
	v_mfma_f32_16x16x32_bf16 v[88:91], v[136:139], v[202:205], 0
	v_mfma_f32_16x16x32_bf16 v[80:83], v[128:131], v[210:213], 0
	v_mfma_f32_16x16x32_bf16 v[72:75], v[136:139], v[210:213], 0
	v_mfma_f32_16x16x32_bf16 v[124:127], v[132:135], v[190:193], v[124:127]
	v_mfma_f32_16x16x32_bf16 v[120:123], v[140:143], v[190:193], v[120:123]
	v_mfma_f32_16x16x32_bf16 v[112:115], v[132:135], v[198:201], v[112:115]
	v_mfma_f32_16x16x32_bf16 v[104:107], v[140:143], v[198:201], v[104:107]
	v_mfma_f32_16x16x32_bf16 v[96:99], v[132:135], v[206:209], v[96:99]
	v_mfma_f32_16x16x32_bf16 v[88:91], v[140:143], v[206:209], v[88:91]
	v_mfma_f32_16x16x32_bf16 v[80:83], v[132:135], v[214:217], v[80:83]
	v_mfma_f32_16x16x32_bf16 v[72:75], v[140:143], v[214:217], v[72:75]
	s_setprio 0
	s_setprio 1
	v_mfma_f32_16x16x32_bf16 v[116:119], v[162:165], v[186:189], 0
	v_mfma_f32_16x16x32_bf16 v[108:111], v[178:181], v[186:189], 0
	v_mfma_f32_16x16x32_bf16 v[100:103], v[162:165], v[194:197], 0
	v_mfma_f32_16x16x32_bf16 v[92:95], v[178:181], v[194:197], 0
	v_mfma_f32_16x16x32_bf16 v[84:87], v[162:165], v[202:205], 0
	v_mfma_f32_16x16x32_bf16 v[76:79], v[178:181], v[202:205], 0
	v_mfma_f32_16x16x32_bf16 v[68:71], v[162:165], v[210:213], 0
	v_mfma_f32_16x16x32_bf16 v[64:67], v[178:181], v[210:213], 0
	v_mfma_f32_16x16x32_bf16 v[116:119], v[174:177], v[190:193], v[116:119]
	v_mfma_f32_16x16x32_bf16 v[108:111], v[182:185], v[190:193], v[108:111]
	v_mfma_f32_16x16x32_bf16 v[100:103], v[174:177], v[198:201], v[100:103]
	v_mfma_f32_16x16x32_bf16 v[92:95], v[182:185], v[198:201], v[92:95]
	v_mfma_f32_16x16x32_bf16 v[84:87], v[174:177], v[206:209], v[84:87]
	v_mfma_f32_16x16x32_bf16 v[76:79], v[182:185], v[206:209], v[76:79]
	v_mfma_f32_16x16x32_bf16 v[68:71], v[174:177], v[214:217], v[68:71]
	v_mfma_f32_16x16x32_bf16 v[64:67], v[182:185], v[214:217], v[64:67]
	s_setprio 0
	s_barrier
	s_add_i32 s26, s50, s39
	v_lshl_add_u64 v[166:167], s[28:29], 0, v[146:147]
	s_mov_b32 m0, s26
	ds_read_b128 v[186:189], v172 offset:16384
	ds_read_b128 v[190:193], v172 offset:17408
	ds_read_b128 v[194:197], v172 offset:18432
	ds_read_b128 v[198:201], v172 offset:19456
	ds_read_b128 v[202:205], v172 offset:20480
	ds_read_b128 v[206:209], v172 offset:21504
	ds_read_b128 v[210:213], v172 offset:22528
	ds_read_b128 v[214:217], v172 offset:23552
	global_load_lds_dwordx4 v[166:167], off
	s_add_i32 m0, s26, 0x2000
	s_add_u32 s26, s28, 0x80000
	v_lshl_add_u64 v[218:219], s[28:29], 0, v[150:151]
	s_addc_u32 s27, s29, 0
	s_add_i32 s61, s51, s39
	global_load_lds_dwordx4 v[218:219], off
	v_lshl_add_u64 v[220:221], s[26:27], 0, v[146:147]
	s_mov_b32 m0, s61
	v_lshl_add_u64 v[222:223], s[30:31], 0, v[148:149]
	global_load_lds_dwordx4 v[220:221], off
	v_lshl_add_u64 v[220:221], s[26:27], 0, v[150:151]
	s_add_i32 m0, s61, 0x2000
	s_nop 0
	global_load_lds_dwordx4 v[220:221], off
	v_lshl_add_u64 v[220:221], s[30:31], 0, v[144:145]
	s_mov_b32 m0, s40
	s_nop 0
	global_load_lds_dwordx4 v[220:221], off
	s_mov_b32 m0, s41
	s_nop 0
	global_load_lds_dwordx4 v[222:223], off
	s_waitcnt vmcnt(8)
	s_waitcnt lgkmcnt(0)
	s_barrier
; #define PG8_STAGE(bufoff, gbase, voff) do { _Pragma("unroll") for (int _i = 0; _i < 2; ++_i) \
;         __builtin_amdgcn_global_load_lds((const unsigned*)((const char*)(gbase) + (voff)[_i]), (PG8_LAS unsigned*)(lds + (bufoff) + ldsw + _i * 8192), 16, 0, 0); } while (0)
; #define PG8_LDA(dst, b, h) do { _Pragma("unroll") for (int m = 0; m < 4; ++m) _Pragma("unroll") for (int k = 0; k < 2; ++k) dst[m][k] = *(const PG8_LAS bf16x8*)(lds + PG8_SA(b, h) + aoff + m * 2048 + k * 1024); } while (0)
; #define PG8_LDB(dst, b, h) do { _Pragma("unroll") for (int n = 0; n < 2; ++n) _Pragma("unroll") for (int k = 0; k < 2; ++k) dst[n][k] = *(const PG8_LAS bf16x8*)(lds + PG8_SB(b, h) + boff + n * 2048 + k * 1024); } while (0)
; #define PG8_MMA(ai, bj, At, Bt) do { __builtin_amdgcn_s_setprio(1); _Pragma("unroll") for (int m = 0; m < 4; ++m) _Pragma("unroll") for (int n = 0; n < 2; ++n) _Pragma("unroll") for (int k = 0; k < 2; ++k) \
;         acc[ai][bj][m][n] = __builtin_amdgcn_mfma_f32_16x16x32_bf16(Bt[n][k], At[m][k], acc[ai][bj][m][n], 0, 0, 0); __builtin_amdgcn_s_setprio(0); } while (0)
; #define PG8_WAIT_V(n) asm volatile("s_waitcnt vmcnt(" #n ")" ::: "memory")
; #define PG8_WAIT_L(n) asm volatile("s_waitcnt lgkmcnt(" #n ")" ::: "memory")
; #define PG8_BAR __builtin_amdgcn_s_barrier()
; #define PG8_SCHED __builtin_amdgcn_sched_barrier(0)
; template <class Epi, class Sched, bool ALIGN_EPI = false, bool SP2 = false>
; __device__ __forceinline__ void gemm_phase(PG8_LAS unsigned char* lds, const Gemm g, const Sched& S, const Epi& E, const int wave_in) {
;     ...
;             PG8_WAIT_V(8); PG8_WAIT_L(0); PG8_BAR; PG8_MMA(1, 0, At, B0); PG8_MMA(1, 1, At, B1); PG8_BAR; PG8_SCHED;
;             PG8_LDB(B0, 1, 0); PG8_LDB(B1, 1, 1); PG8_SCHED; PG8_LDA(At, 1, 0); PG8_STAGE(PG8_SA(0, 1), a2 + hstepA, voffA);
;             PG8_WAIT_V(8); PG8_WAIT_L(0); PG8_BAR; PG8_MMA(0, 0, At, B0); PG8_MMA(0, 1, At, B1); PG8_BAR; PG8_SCHED;
	s_setprio 1
	s_waitcnt lgkmcnt(0)
	v_mfma_f32_16x16x32_bf16 v[60:63], v[128:131], v[186:189], 0
	v_mfma_f32_16x16x32_bf16 v[56:59], v[136:139], v[186:189], 0
	v_mfma_f32_16x16x32_bf16 v[48:51], v[128:131], v[194:197], 0
	v_mfma_f32_16x16x32_bf16 v[40:43], v[136:139], v[194:197], 0
	v_mfma_f32_16x16x32_bf16 v[32:35], v[128:131], v[202:205], 0
	v_mfma_f32_16x16x32_bf16 v[24:27], v[136:139], v[202:205], 0
	v_mfma_f32_16x16x32_bf16 v[16:19], v[128:131], v[210:213], 0
	v_mfma_f32_16x16x32_bf16 v[8:11], v[136:139], v[210:213], 0
	v_mfma_f32_16x16x32_bf16 v[60:63], v[132:135], v[190:193], v[60:63]
	v_mfma_f32_16x16x32_bf16 v[56:59], v[140:143], v[190:193], v[56:59]
	v_mfma_f32_16x16x32_bf16 v[48:51], v[132:135], v[198:201], v[48:51]
	v_mfma_f32_16x16x32_bf16 v[40:43], v[140:143], v[198:201], v[40:43]
	v_mfma_f32_16x16x32_bf16 v[32:35], v[132:135], v[206:209], v[32:35]
	v_mfma_f32_16x16x32_bf16 v[24:27], v[140:143], v[206:209], v[24:27]
	v_mfma_f32_16x16x32_bf16 v[16:19], v[132:135], v[214:217], v[16:19]
	v_mfma_f32_16x16x32_bf16 v[8:11], v[140:143], v[214:217], v[8:11]
	s_setprio 0
	s_setprio 1
	v_mfma_f32_16x16x32_bf16 v[52:55], v[162:165], v[186:189], 0
	v_mfma_f32_16x16x32_bf16 v[44:47], v[178:181], v[186:189], 0
	v_mfma_f32_16x16x32_bf16 v[36:39], v[162:165], v[194:197], 0
	v_mfma_f32_16x16x32_bf16 v[28:31], v[178:181], v[194:197], 0
	v_mfma_f32_16x16x32_bf16 v[20:23], v[162:165], v[202:205], 0
	v_mfma_f32_16x16x32_bf16 v[12:15], v[178:181], v[202:205], 0
	v_mfma_f32_16x16x32_bf16 v[4:7], v[162:165], v[210:213], 0
	v_mfma_f32_16x16x32_bf16 v[0:3], v[178:181], v[210:213], 0
	v_mfma_f32_16x16x32_bf16 v[52:55], v[174:177], v[190:193], v[52:55]
	v_mfma_f32_16x16x32_bf16 v[44:47], v[182:185], v[190:193], v[44:47]
	v_mfma_f32_16x16x32_bf16 v[36:39], v[174:177], v[198:201], v[36:39]
	v_mfma_f32_16x16x32_bf16 v[28:31], v[182:185], v[198:201], v[28:31]
	v_mfma_f32_16x16x32_bf16 v[20:23], v[174:177], v[206:209], v[20:23]
	v_mfma_f32_16x16x32_bf16 v[12:15], v[182:185], v[206:209], v[12:15]
	v_mfma_f32_16x16x32_bf16 v[4:7], v[174:177], v[214:217], v[4:7]
	v_mfma_f32_16x16x32_bf16 v[0:3], v[182:185], v[214:217], v[0:3]
	s_setprio 0
	s_barrier
	s_add_i32 s61, 0, 0x18000
	s_add_i32 s62, 0, 0x1c000
	v_add_u32_e32 v140, s61, v168
	v_add_u32_e32 v173, s62, v168
	ds_read_b128 v[128:131], v140
	ds_read_b128 v[132:135], v140 offset:1024
	ds_read_b128 v[136:139], v140 offset:2048
	ds_read_b128 v[140:143], v140 offset:3072
	ds_read_b128 v[162:165], v173
	ds_read_b128 v[174:177], v173 offset:1024
	ds_read_b128 v[178:181], v173 offset:2048
	ds_read_b128 v[182:185], v173 offset:3072
	s_add_u32 s26, s30, 0x280000
	s_addc_u32 s27, s31, 0
	s_mov_b32 m0, s42
	v_lshl_add_u64 v[224:225], s[26:27], 0, v[144:145]
	ds_read_b128 v[186:189], v172 offset:32768
	ds_read_b128 v[190:193], v172 offset:33792
	ds_read_b128 v[194:197], v172 offset:34816
	ds_read_b128 v[198:201], v172 offset:35840
	ds_read_b128 v[202:205], v172 offset:36864
	ds_read_b128 v[206:209], v172 offset:37888
	ds_read_b128 v[210:213], v172 offset:38912
	ds_read_b128 v[214:217], v172 offset:39936
	global_load_lds_dwordx4 v[224:225], off
	v_lshl_add_u64 v[224:225], s[26:27], 0, v[148:149]
	s_mov_b32 m0, s43
	s_nop 0
	global_load_lds_dwordx4 v[224:225], off
	s_waitcnt vmcnt(8)
	s_waitcnt lgkmcnt(0)
	s_barrier
	s_setprio 1
	s_waitcnt lgkmcnt(0)
	v_mfma_f32_16x16x32_bf16 v[124:127], v[128:131], v[186:189], v[124:127]
	v_mfma_f32_16x16x32_bf16 v[120:123], v[136:139], v[186:189], v[120:123]
	v_mfma_f32_16x16x32_bf16 v[112:115], v[128:131], v[194:197], v[112:115]
	v_mfma_f32_16x16x32_bf16 v[104:107], v[136:139], v[194:197], v[104:107]
	v_mfma_f32_16x16x32_bf16 v[96:99], v[128:131], v[202:205], v[96:99]
	v_mfma_f32_16x16x32_bf16 v[88:91], v[136:139], v[202:205], v[88:91]
	v_mfma_f32_16x16x32_bf16 v[80:83], v[128:131], v[210:213], v[80:83]
	v_mfma_f32_16x16x32_bf16 v[72:75], v[136:139], v[210:213], v[72:75]
	v_mfma_f32_16x16x32_bf16 v[124:127], v[132:135], v[190:193], v[124:127]
	v_mfma_f32_16x16x32_bf16 v[120:123], v[140:143], v[190:193], v[120:123]
	v_mfma_f32_16x16x32_bf16 v[112:115], v[132:135], v[198:201], v[112:115]
	v_mfma_f32_16x16x32_bf16 v[104:107], v[140:143], v[198:201], v[104:107]
	v_mfma_f32_16x16x32_bf16 v[96:99], v[132:135], v[206:209], v[96:99]
	v_mfma_f32_16x16x32_bf16 v[88:91], v[140:143], v[206:209], v[88:91]
	v_mfma_f32_16x16x32_bf16 v[80:83], v[132:135], v[214:217], v[80:83]
	v_mfma_f32_16x16x32_bf16 v[72:75], v[140:143], v[214:217], v[72:75]
	s_setprio 0
	s_setprio 1
	v_mfma_f32_16x16x32_bf16 v[116:119], v[162:165], v[186:189], v[116:119]
	v_mfma_f32_16x16x32_bf16 v[108:111], v[178:181], v[186:189], v[108:111]
	v_mfma_f32_16x16x32_bf16 v[100:103], v[162:165], v[194:197], v[100:103]
	v_mfma_f32_16x16x32_bf16 v[92:95], v[178:181], v[194:197], v[92:95]
	v_mfma_f32_16x16x32_bf16 v[84:87], v[162:165], v[202:205], v[84:87]
	v_mfma_f32_16x16x32_bf16 v[76:79], v[178:181], v[202:205], v[76:79]
	v_mfma_f32_16x16x32_bf16 v[68:71], v[162:165], v[210:213], v[68:71]
	v_mfma_f32_16x16x32_bf16 v[64:67], v[178:181], v[210:213], v[64:67]
	v_mfma_f32_16x16x32_bf16 v[116:119], v[174:177], v[190:193], v[116:119]
	v_mfma_f32_16x16x32_bf16 v[108:111], v[182:185], v[190:193], v[108:111]
	v_mfma_f32_16x16x32_bf16 v[100:103], v[174:177], v[198:201], v[100:103]
	v_mfma_f32_16x16x32_bf16 v[92:95], v[182:185], v[198:201], v[92:95]
	v_mfma_f32_16x16x32_bf16 v[84:87], v[174:177], v[206:209], v[84:87]
	v_mfma_f32_16x16x32_bf16 v[76:79], v[182:185], v[206:209], v[76:79]
	v_mfma_f32_16x16x32_bf16 v[68:71], v[174:177], v[214:217], v[68:71]
	v_mfma_f32_16x16x32_bf16 v[64:67], v[182:185], v[214:217], v[64:67]
	s_setprio 0
	s_barrier
; #define PG8_STAGE(bufoff, gbase, voff) do { _Pragma("unroll") for (int _i = 0; _i < 2; ++_i) \
;         __builtin_amdgcn_global_load_lds((const unsigned*)((const char*)(gbase) + (voff)[_i]), (PG8_LAS unsigned*)(lds + (bufoff) + ldsw + _i * 8192), 16, 0, 0); } while (0)
; #define PG8_LDA(dst, b, h) do { _Pragma("unroll") for (int m = 0; m < 4; ++m) _Pragma("unroll") for (int k = 0; k < 2; ++k) dst[m][k] = *(const PG8_LAS bf16x8*)(lds + PG8_SA(b, h) + aoff + m * 2048 + k * 1024); } while (0)
; #define PG8_MMA(ai, bj, At, Bt) do { __builtin_amdgcn_s_setprio(1); _Pragma("unroll") for (int m = 0; m < 4; ++m) _Pragma("unroll") for (int n = 0; n < 2; ++n) _Pragma("unroll") for (int k = 0; k < 2; ++k) \
;         acc[ai][bj][m][n] = __builtin_amdgcn_mfma_f32_16x16x32_bf16(Bt[n][k], At[m][k], acc[ai][bj][m][n], 0, 0, 0); __builtin_amdgcn_s_setprio(0); } while (0)
; #define PG8_WAIT_V(n) asm volatile("s_waitcnt vmcnt(" #n ")" ::: "memory")
; #define PG8_WAIT_L(n) asm volatile("s_waitcnt lgkmcnt(" #n ")" ::: "memory")
; #define PG8_BAR __builtin_amdgcn_s_barrier()
; #define PG8_SCHED __builtin_amdgcn_sched_barrier(0)
; template <class Epi, class Sched, bool ALIGN_EPI = false, bool SP2 = false>
; __device__ __forceinline__ void gemm_phase(PG8_LAS unsigned char* lds, const Gemm g, const Sched& S, const Epi& E, const int wave_in) {
;     ...
;         for (int t = 0; t < nt; t += 2) {
;             const bool last = (t == nt - 2);
;     ...
;             PG8_LDA(At, 1, 1); PG8_STAGE(PG8_SB(1, 0), b3, voffB); PG8_STAGE(PG8_SB(1, 1), b3 + hstepB, voffB); PG8_STAGE(PG8_SA(1, 0), a3, voffA);
;             PG8_WAIT_V(8); PG8_WAIT_L(0); PG8_BAR; PG8_MMA(1, 0, At, B0); PG8_MMA(1, 1, At, B1); PG8_BAR; PG8_SCHED;
	s_add_i32 s26, s61, s39
	v_lshl_add_u64 v[166:167], v[166:167], 0, s[8:9]
	s_mov_b32 m0, s26
	ds_read_b128 v[186:189], v172 offset:49152
	ds_read_b128 v[190:193], v172 offset:50176
	ds_read_b128 v[194:197], v172 offset:51200
	ds_read_b128 v[198:201], v172 offset:52224
	ds_read_b128 v[202:205], v172 offset:53248
	ds_read_b128 v[206:209], v172 offset:54272
	ds_read_b128 v[210:213], v172 offset:55296
	ds_read_b128 v[214:217], v172 offset:56320
	global_load_lds_dwordx4 v[166:167], off
	s_add_i32 m0, s26, 0x2000
	s_add_u32 s26, s28, 0x80080
	v_lshl_add_u64 v[166:167], v[218:219], 0, s[8:9]
	s_addc_u32 s27, s29, 0
	s_add_i32 s28, s62, s39
	global_load_lds_dwordx4 v[166:167], off
	v_lshl_add_u64 v[166:167], s[26:27], 0, v[146:147]
	s_mov_b32 m0, s28
	s_nop 0
	global_load_lds_dwordx4 v[166:167], off
	v_lshl_add_u64 v[166:167], s[26:27], 0, v[150:151]
	s_add_i32 m0, s28, 0x2000
	s_nop 0
	global_load_lds_dwordx4 v[166:167], off
	v_lshl_add_u64 v[166:167], v[220:221], 0, s[8:9]
	s_mov_b32 m0, s47
	s_nop 0
	global_load_lds_dwordx4 v[166:167], off
	v_lshl_add_u64 v[166:167], v[222:223], 0, s[8:9]
	s_mov_b32 m0, s48
	s_nop 0
	global_load_lds_dwordx4 v[166:167], off
	s_waitcnt vmcnt(8)
	s_waitcnt lgkmcnt(0)
	s_barrier
	s_setprio 1
	s_waitcnt lgkmcnt(0)
	v_mfma_f32_16x16x32_bf16 v[60:63], v[128:131], v[186:189], v[60:63]
	v_mfma_f32_16x16x32_bf16 v[56:59], v[136:139], v[186:189], v[56:59]
	v_mfma_f32_16x16x32_bf16 v[48:51], v[128:131], v[194:197], v[48:51]
	v_mfma_f32_16x16x32_bf16 v[40:43], v[136:139], v[194:197], v[40:43]
	v_mfma_f32_16x16x32_bf16 v[32:35], v[128:131], v[202:205], v[32:35]
	v_mfma_f32_16x16x32_bf16 v[24:27], v[136:139], v[202:205], v[24:27]
	v_mfma_f32_16x16x32_bf16 v[16:19], v[128:131], v[210:213], v[16:19]
	v_mfma_f32_16x16x32_bf16 v[8:11], v[136:139], v[210:213], v[8:11]
	v_mfma_f32_16x16x32_bf16 v[60:63], v[132:135], v[190:193], v[60:63]
	v_mfma_f32_16x16x32_bf16 v[56:59], v[140:143], v[190:193], v[56:59]
	v_mfma_f32_16x16x32_bf16 v[48:51], v[132:135], v[198:201], v[48:51]
	v_mfma_f32_16x16x32_bf16 v[40:43], v[140:143], v[198:201], v[40:43]
	v_mfma_f32_16x16x32_bf16 v[32:35], v[132:135], v[206:209], v[32:35]
	v_mfma_f32_16x16x32_bf16 v[24:27], v[140:143], v[206:209], v[24:27]
	v_mfma_f32_16x16x32_bf16 v[16:19], v[132:135], v[214:217], v[16:19]
	v_mfma_f32_16x16x32_bf16 v[8:11], v[140:143], v[214:217], v[8:11]
	s_setprio 0
	s_setprio 1
	v_mfma_f32_16x16x32_bf16 v[52:55], v[162:165], v[186:189], v[52:55]
	v_mfma_f32_16x16x32_bf16 v[44:47], v[178:181], v[186:189], v[44:47]
	v_mfma_f32_16x16x32_bf16 v[36:39], v[162:165], v[194:197], v[36:39]
	v_mfma_f32_16x16x32_bf16 v[28:31], v[178:181], v[194:197], v[28:31]
	v_mfma_f32_16x16x32_bf16 v[20:23], v[162:165], v[202:205], v[20:23]
	v_mfma_f32_16x16x32_bf16 v[12:15], v[178:181], v[202:205], v[12:15]
	v_mfma_f32_16x16x32_bf16 v[4:7], v[162:165], v[210:213], v[4:7]
	v_mfma_f32_16x16x32_bf16 v[0:3], v[178:181], v[210:213], v[0:3]
	v_mfma_f32_16x16x32_bf16 v[52:55], v[174:177], v[190:193], v[52:55]
	v_mfma_f32_16x16x32_bf16 v[44:47], v[182:185], v[190:193], v[44:47]
	v_mfma_f32_16x16x32_bf16 v[36:39], v[174:177], v[198:201], v[36:39]
	v_mfma_f32_16x16x32_bf16 v[28:31], v[182:185], v[198:201], v[28:31]
	v_mfma_f32_16x16x32_bf16 v[20:23], v[174:177], v[206:209], v[20:23]
	v_mfma_f32_16x16x32_bf16 v[12:15], v[182:185], v[206:209], v[12:15]
	v_mfma_f32_16x16x32_bf16 v[4:7], v[174:177], v[214:217], v[4:7]
	v_mfma_f32_16x16x32_bf16 v[0:3], v[182:185], v[214:217], v[0:3]
	s_setprio 0
	s_barrier
	s_add_i32 s60, s60, 2
	s_add_u32 s58, s58, 0x100
	s_addc_u32 s59, s59, 0
	s_cmp_gt_u32 s60, 29
	s_mov_b64 s[26:27], s[4:5]
	s_cbranch_scc0 .LBB0_2451
	s_branch .Lkx_28

;     __host__ __device__ bool next(int i, Unit& u) const { const bool ok = StaticOrder::next(i, u); u.pm = 0; u.pn = 0; return ok; }
; #define PG8_STAGE(bufoff, gbase, voff) do { _Pragma("unroll") for (int _i = 0; _i < 2; ++_i) \
;         __builtin_amdgcn_global_load_lds((const unsigned*)((const char*)(gbase) + (voff)[_i]), (PG8_LAS unsigned*)(lds + (bufoff) + ldsw + _i * 8192), 16, 0, 0); } while (0)
; #define PG8_LDA(dst, b, h) do { _Pragma("unroll") for (int m = 0; m < 4; ++m) _Pragma("unroll") for (int k = 0; k < 2; ++k) dst[m][k] = *(const PG8_LAS bf16x8*)(lds + PG8_SA(b, h) + aoff + m * 2048 + k * 1024); } while (0)
; #define PG8_WAIT_V(n) asm volatile("s_waitcnt vmcnt(" #n ")" ::: "memory")
; #define PG8_WAIT_L(n) asm volatile("s_waitcnt lgkmcnt(" #n ")" ::: "memory")
; #define PG8_BAR __builtin_amdgcn_s_barrier()
; template <class Epi, class Sched, bool ALIGN_EPI = false, bool SP2 = false>
; __device__ __forceinline__ void gemm_phase(PG8_LAS unsigned char* lds, const Gemm g, const Sched& S, const Epi& E, const int wave_in) {
;     ...
;         const bool has_next = S.next(ui + 1, nxt);
;         const char* nA = has_next ? (const char*)g.A + (size_t)nxt.pm * tstepA : cA; const char* nB = has_next ? (const char*)g.Bt + (size_t)nxt.pn * tstepB : cB;
;         for (int t = 0; t < nt; t += 2) {
;             const bool last = (t == nt - 2);
;             const char* a1 = cA + (size_t)(t + 1) * kstep;
;             const char* a2 = last ? nA : cA + (size_t)(t + 2) * kstep; const char* b2 = last ? nB : cB + (size_t)(t + 2) * kstep;
;             const char* a3 = a2 + kstep; const char* b3 = b2 + kstep;
;             if (last && has_next) S.a_ready(nxt);
;             if constexpr (SP2) {
;             PG8_LDB(B0, 0, 0); PG8_LDB(B1, 0, 1); PG8_SCHED; PG8_LDA(At, 0, 0); PG8_STAGE(PG8_SA(1, 1), a1 + hstepA, voffA);
;             PG8_WAIT_V(8); PG8_WAIT_L(0); PG8_BAR; PG8_MMA(0, 0, At, B0); PG8_MMA(0, 1, At, B1); PG8_BAR; PG8_SCHED;
;             PG8_LDA(At, 0, 1); PG8_STAGE(PG8_SB(0, 0), b2, voffB); PG8_STAGE(PG8_SB(0, 1), b2 + hstepB, voffB); PG8_STAGE(PG8_SA(0, 0), a2, voffA);
;     ...
; #pragma unroll
;         for (int a = 0; a < 2; ++a)
; #pragma unroll
;             for (int b = 0; b < 2; ++b)
; #pragma unroll
;                 for (int m = 0; m < 4; ++m)
; #pragma unroll
;                     for (int n = 0; n < 2; ++n) acc[a][b][m][n] = (f32x4){0.f, 0.f, 0.f, 0.f};
.LBB0_2576:
	s_ashr_i32 s39, s38, 31
	s_lshl_b64 s[40:41], s[38:39], 20
	s_add_u32 s40, s52, s40
	s_addc_u32 s41, s53, s41
	s_and_b64 s[42:43], s[8:9], exec
	s_cselect_b32 s11, s41, s47
	s_cselect_b32 s39, s40, s46
	s_ashr_i32 s37, s36, 31
	s_lshl_b64 s[42:43], s[36:37], 20
	s_add_u32 s42, s54, s42
	s_addc_u32 s43, s55, s43
	s_and_b64 s[50:51], s[8:9], exec
	s_cselect_b32 s37, s43, s49
	s_cselect_b32 s45, s42, s48
	s_add_u32 s46, s46, 0x80080
	s_addc_u32 s47, s47, 0
	s_add_u32 s72, s48, 0x100
	v_mov_b32_e32 v0, 0
	s_addc_u32 s73, s49, 0
	s_mov_b32 s75, -2
	s_waitcnt vmcnt(0)
	ds_read_b128 v[64:67], v189
	ds_read_b128 v[68:71], v189 offset:1024
	ds_read_b128 v[72:75], v189 offset:2048
	ds_read_b128 v[76:79], v189 offset:3072
	ds_read_b128 v[80:83], v197
	ds_read_b128 v[84:87], v197 offset:1024
	ds_read_b128 v[88:91], v197 offset:2048
	ds_read_b128 v[92:95], v197 offset:3072
	s_add_u32 s48, s46, 0xfff80080
	s_addc_u32 s49, s47, -1
	s_cmp_eq_u32 s75, 28
	s_cselect_b32 s51, s11, s49
	s_cselect_b32 s50, s39, s48
	s_cselect_b32 s49, s37, s73
	s_cselect_b32 s48, s45, s72
	v_lshl_add_u64 v[224:225], s[46:47], 0, v[206:207]
	s_add_i32 m0, s57, 0xc000
	ds_read_b128 v[96:99], v199
	ds_read_b128 v[100:103], v199 offset:1024
	ds_read_b128 v[104:107], v199 offset:2048
	ds_read_b128 v[108:111], v199 offset:3072
	ds_read_b128 v[176:179], v199 offset:4096
	ds_read_b128 v[212:215], v199 offset:5120
	ds_read_b128 v[216:219], v199 offset:6144
	ds_read_b128 v[220:223], v199 offset:7168
	global_load_lds_dwordx4 v[224:225], off
	v_lshl_add_u64 v[224:225], s[46:47], 0, v[208:209]
	s_add_i32 m0, s57, 0xe000
	s_nop 0
	global_load_lds_dwordx4 v[224:225], off
	s_waitcnt vmcnt(8)
	s_waitcnt lgkmcnt(0)
	s_barrier
	s_setprio 1
	s_waitcnt lgkmcnt(0)
	v_mfma_f32_16x16x32_bf16 v[172:175], v[64:67], v[96:99], 0
	v_mfma_f32_16x16x32_bf16 v[164:167], v[72:75], v[96:99], 0
	v_mfma_f32_16x16x32_bf16 v[156:159], v[64:67], v[104:107], 0
	v_mfma_f32_16x16x32_bf16 v[148:151], v[72:75], v[104:107], 0
	v_mfma_f32_16x16x32_bf16 v[140:143], v[64:67], v[176:179], 0
	v_mfma_f32_16x16x32_bf16 v[132:135], v[72:75], v[176:179], 0
	v_mfma_f32_16x16x32_bf16 v[124:127], v[64:67], v[216:219], 0
	v_mfma_f32_16x16x32_bf16 v[120:123], v[72:75], v[216:219], 0
	v_mfma_f32_16x16x32_bf16 v[172:175], v[68:71], v[100:103], v[172:175]
	v_mfma_f32_16x16x32_bf16 v[164:167], v[76:79], v[100:103], v[164:167]
	v_mfma_f32_16x16x32_bf16 v[156:159], v[68:71], v[108:111], v[156:159]
	v_mfma_f32_16x16x32_bf16 v[148:151], v[76:79], v[108:111], v[148:151]
	v_mfma_f32_16x16x32_bf16 v[140:143], v[68:71], v[212:215], v[140:143]
	v_mfma_f32_16x16x32_bf16 v[132:135], v[76:79], v[212:215], v[132:135]
	v_mfma_f32_16x16x32_bf16 v[124:127], v[68:71], v[220:223], v[124:127]
	v_mfma_f32_16x16x32_bf16 v[120:123], v[76:79], v[220:223], v[120:123]
	s_setprio 0
	s_setprio 1
	v_mfma_f32_16x16x32_bf16 v[168:171], v[80:83], v[96:99], 0
	v_mfma_f32_16x16x32_bf16 v[96:99], v[88:91], v[96:99], 0
	v_mfma_f32_16x16x32_bf16 v[168:171], v[84:87], v[100:103], v[168:171]
	v_mfma_f32_16x16x32_bf16 v[96:99], v[92:95], v[100:103], v[96:99]
	v_mfma_f32_16x16x32_bf16 v[100:103], v[80:83], v[104:107], 0
	v_mfma_f32_16x16x32_bf16 v[104:107], v[88:91], v[104:107], 0
	v_mfma_f32_16x16x32_bf16 v[128:131], v[88:91], v[176:179], 0
	v_mfma_f32_16x16x32_bf16 v[116:119], v[80:83], v[216:219], 0
	v_mfma_f32_16x16x32_bf16 v[112:115], v[88:91], v[216:219], 0
	v_mfma_f32_16x16x32_bf16 v[100:103], v[84:87], v[108:111], v[100:103]
	v_mfma_f32_16x16x32_bf16 v[104:107], v[92:95], v[108:111], v[104:107]
	v_mfma_f32_16x16x32_bf16 v[108:111], v[80:83], v[176:179], 0
	v_mfma_f32_16x16x32_bf16 v[128:131], v[92:95], v[212:215], v[128:131]
	v_mfma_f32_16x16x32_bf16 v[116:119], v[84:87], v[220:223], v[116:119]
	v_mfma_f32_16x16x32_bf16 v[112:115], v[92:95], v[220:223], v[112:115]
	v_mfma_f32_16x16x32_bf16 v[108:111], v[84:87], v[212:215], v[108:111]
	s_setprio 0
	s_barrier
	s_add_i32 s76, s69, s56
	v_lshl_add_u64 v[232:233], s[48:49], 0, v[182:183]
	s_mov_b32 m0, s76
	ds_read_b128 v[136:139], v199 offset:16384
	ds_read_b128 v[144:147], v199 offset:17408
	ds_read_b128 v[152:155], v199 offset:18432
	ds_read_b128 v[160:163], v199 offset:19456
	ds_read_b128 v[176:179], v199 offset:20480
	ds_read_b128 v[212:215], v199 offset:21504
	ds_read_b128 v[216:219], v199 offset:22528
	ds_read_b128 v[220:223], v199 offset:23552
	global_load_lds_dwordx4 v[232:233], off
	s_add_i32 m0, s76, 0x2000
	s_add_u32 s76, s48, 0x80000
	v_lshl_add_u64 v[234:235], s[48:49], 0, v[186:187]
	s_addc_u32 s77, s49, 0
	s_add_i32 s78, s70, s56
	global_load_lds_dwordx4 v[234:235], off
	v_lshl_add_u64 v[224:225], s[76:77], 0, v[182:183]
	s_mov_b32 m0, s78
	v_lshl_add_u64 v[236:237], s[50:51], 0, v[180:181]
	global_load_lds_dwordx4 v[224:225], off
	v_lshl_add_u64 v[224:225], s[76:77], 0, v[186:187]
	s_add_i32 m0, s78, 0x2000
	v_lshl_add_u64 v[238:239], s[50:51], 0, v[184:185]
	global_load_lds_dwordx4 v[224:225], off
	s_mov_b32 m0, s57
	s_nop 0
	global_load_lds_dwordx4 v[236:237], off
	s_mov_b32 m0, s58
	s_nop 0
	global_load_lds_dwordx4 v[238:239], off
	s_waitcnt vmcnt(8)
	s_waitcnt lgkmcnt(0)
	s_barrier
; #define PG8_STAGE(bufoff, gbase, voff) do { _Pragma("unroll") for (int _i = 0; _i < 2; ++_i) \
;         __builtin_amdgcn_global_load_lds((const unsigned*)((const char*)(gbase) + (voff)[_i]), (PG8_LAS unsigned*)(lds + (bufoff) + ldsw + _i * 8192), 16, 0, 0); } while (0)
; #define PG8_LDA(dst, b, h) do { _Pragma("unroll") for (int m = 0; m < 4; ++m) _Pragma("unroll") for (int k = 0; k < 2; ++k) dst[m][k] = *(const PG8_LAS bf16x8*)(lds + PG8_SA(b, h) + aoff + m * 2048 + k * 1024); } while (0)
; #define PG8_LDB(dst, b, h) do { _Pragma("unroll") for (int n = 0; n < 2; ++n) _Pragma("unroll") for (int k = 0; k < 2; ++k) dst[n][k] = *(const PG8_LAS bf16x8*)(lds + PG8_SB(b, h) + boff + n * 2048 + k * 1024); } while (0)
; #define PG8_MMA(ai, bj, At, Bt) do { __builtin_amdgcn_s_setprio(1); _Pragma("unroll") for (int m = 0; m < 4; ++m) _Pragma("unroll") for (int n = 0; n < 2; ++n) _Pragma("unroll") for (int k = 0; k < 2; ++k) \
;         acc[ai][bj][m][n] = __builtin_amdgcn_mfma_f32_16x16x32_bf16(Bt[n][k], At[m][k], acc[ai][bj][m][n], 0, 0, 0); __builtin_amdgcn_s_setprio(0); } while (0)
; #define PG8_WAIT_V(n) asm volatile("s_waitcnt vmcnt(" #n ")" ::: "memory")
; #define PG8_WAIT_L(n) asm volatile("s_waitcnt lgkmcnt(" #n ")" ::: "memory")
; #define PG8_BAR __builtin_amdgcn_s_barrier()
; #define PG8_SCHED __builtin_amdgcn_sched_barrier(0)
; template <class Epi, class Sched, bool ALIGN_EPI = false, bool SP2 = false>
; __device__ __forceinline__ void gemm_phase(PG8_LAS unsigned char* lds, const Gemm g, const Sched& S, const Epi& E, const int wave_in) {
;     ...
;             PG8_WAIT_V(8); PG8_WAIT_L(0); PG8_BAR; PG8_MMA(1, 0, At, B0); PG8_MMA(1, 1, At, B1); PG8_BAR; PG8_SCHED;
;             PG8_LDB(B0, 1, 0); PG8_LDB(B1, 1, 1); PG8_SCHED; PG8_LDA(At, 1, 0); PG8_STAGE(PG8_SA(0, 1), a2 + hstepA, voffA);
;             PG8_WAIT_V(8); PG8_WAIT_L(0); PG8_BAR; PG8_MMA(0, 0, At, B0); PG8_MMA(0, 1, At, B1); PG8_BAR; PG8_SCHED;
	s_setprio 1
	s_waitcnt lgkmcnt(0)
	v_mfma_f32_16x16x32_bf16 v[60:63], v[64:67], v[136:139], 0
	v_mfma_f32_16x16x32_bf16 v[52:55], v[72:75], v[136:139], 0
	v_mfma_f32_16x16x32_bf16 v[44:47], v[64:67], v[152:155], 0
	v_mfma_f32_16x16x32_bf16 v[36:39], v[72:75], v[152:155], 0
	v_mfma_f32_16x16x32_bf16 v[28:31], v[64:67], v[176:179], 0
	v_mfma_f32_16x16x32_bf16 v[20:23], v[72:75], v[176:179], 0
	v_mfma_f32_16x16x32_bf16 v[12:15], v[64:67], v[216:219], 0
	v_mfma_f32_16x16x32_bf16 v[8:11], v[72:75], v[216:219], 0
	v_mfma_f32_16x16x32_bf16 v[60:63], v[68:71], v[144:147], v[60:63]
	v_mfma_f32_16x16x32_bf16 v[52:55], v[76:79], v[144:147], v[52:55]
	v_mfma_f32_16x16x32_bf16 v[44:47], v[68:71], v[160:163], v[44:47]
	v_mfma_f32_16x16x32_bf16 v[36:39], v[76:79], v[160:163], v[36:39]
	v_mfma_f32_16x16x32_bf16 v[28:31], v[68:71], v[212:215], v[28:31]
	v_mfma_f32_16x16x32_bf16 v[20:23], v[76:79], v[212:215], v[20:23]
	v_mfma_f32_16x16x32_bf16 v[12:15], v[68:71], v[220:223], v[12:15]
	v_mfma_f32_16x16x32_bf16 v[8:11], v[76:79], v[220:223], v[8:11]
	s_setprio 0
	s_setprio 1
	v_mfma_f32_16x16x32_bf16 v[56:59], v[80:83], v[136:139], 0
	v_mfma_f32_16x16x32_bf16 v[48:51], v[88:91], v[136:139], 0
	v_mfma_f32_16x16x32_bf16 v[40:43], v[80:83], v[152:155], 0
	v_mfma_f32_16x16x32_bf16 v[32:35], v[88:91], v[152:155], 0
	v_mfma_f32_16x16x32_bf16 v[24:27], v[80:83], v[176:179], 0
	v_mfma_f32_16x16x32_bf16 v[16:19], v[88:91], v[176:179], 0
	v_mfma_f32_16x16x32_bf16 v[4:7], v[80:83], v[216:219], 0
	v_mfma_f32_16x16x32_bf16 v[0:3], v[88:91], v[216:219], 0
	v_mfma_f32_16x16x32_bf16 v[56:59], v[84:87], v[144:147], v[56:59]
	v_mfma_f32_16x16x32_bf16 v[48:51], v[92:95], v[144:147], v[48:51]
	v_mfma_f32_16x16x32_bf16 v[40:43], v[84:87], v[160:163], v[40:43]
	v_mfma_f32_16x16x32_bf16 v[32:35], v[92:95], v[160:163], v[32:35]
	v_mfma_f32_16x16x32_bf16 v[24:27], v[84:87], v[212:215], v[24:27]
	v_mfma_f32_16x16x32_bf16 v[16:19], v[92:95], v[212:215], v[16:19]
	v_mfma_f32_16x16x32_bf16 v[4:7], v[84:87], v[220:223], v[4:7]
	v_mfma_f32_16x16x32_bf16 v[0:3], v[92:95], v[220:223], v[0:3]
	s_setprio 0
	s_barrier
	s_add_i32 s76, 0, 0x18000
	s_add_i32 s77, 0, 0x1c000
	v_add_u32_e32 v76, s76, v195
	v_add_u32_e32 v92, s77, v195
	ds_read_b128 v[64:67], v76
	ds_read_b128 v[68:71], v76 offset:1024
	ds_read_b128 v[72:75], v76 offset:2048
	ds_read_b128 v[76:79], v76 offset:3072
	ds_read_b128 v[80:83], v92
	ds_read_b128 v[84:87], v92 offset:1024
	ds_read_b128 v[88:91], v92 offset:2048
	ds_read_b128 v[92:95], v92 offset:3072
	s_add_u32 s50, s50, 0x80000
	s_addc_u32 s51, s51, 0
	s_mov_b32 m0, s59
	v_lshl_add_u64 v[152:153], s[50:51], 0, v[180:181]
	ds_read_b128 v[136:139], v199 offset:32768
	ds_read_b128 v[144:147], v199 offset:33792
	ds_read_b128 v[176:179], v199 offset:34816
	ds_read_b128 v[212:215], v199 offset:35840
	ds_read_b128 v[216:219], v199 offset:36864
	ds_read_b128 v[220:223], v199 offset:37888
	ds_read_b128 v[224:227], v199 offset:38912
	ds_read_b128 v[228:231], v199 offset:39936
	global_load_lds_dwordx4 v[152:153], off
	v_lshl_add_u64 v[152:153], s[50:51], 0, v[184:185]
	s_mov_b32 m0, s60
	s_nop 0
	global_load_lds_dwordx4 v[152:153], off
	s_waitcnt vmcnt(8)
	s_waitcnt lgkmcnt(0)
	s_barrier
	s_setprio 1
	s_waitcnt lgkmcnt(0)
	v_mfma_f32_16x16x32_bf16 v[152:155], v[64:67], v[136:139], v[172:175]
	v_mfma_f32_16x16x32_bf16 v[172:175], v[68:71], v[144:147], v[152:155]
	v_mfma_f32_16x16x32_bf16 v[152:155], v[72:75], v[136:139], v[164:167]
	v_mfma_f32_16x16x32_bf16 v[164:167], v[76:79], v[144:147], v[152:155]
	v_mfma_f32_16x16x32_bf16 v[152:155], v[64:67], v[176:179], v[156:159]
	v_mfma_f32_16x16x32_bf16 v[148:151], v[72:75], v[176:179], v[148:151]
	v_mfma_f32_16x16x32_bf16 v[140:143], v[64:67], v[216:219], v[140:143]
	v_mfma_f32_16x16x32_bf16 v[132:135], v[72:75], v[216:219], v[132:135]
	v_mfma_f32_16x16x32_bf16 v[124:127], v[64:67], v[224:227], v[124:127]
	v_mfma_f32_16x16x32_bf16 v[120:123], v[72:75], v[224:227], v[120:123]
	v_mfma_f32_16x16x32_bf16 v[156:159], v[68:71], v[212:215], v[152:155]
	v_mfma_f32_16x16x32_bf16 v[148:151], v[76:79], v[212:215], v[148:151]
	v_mfma_f32_16x16x32_bf16 v[140:143], v[68:71], v[220:223], v[140:143]
	v_mfma_f32_16x16x32_bf16 v[132:135], v[76:79], v[220:223], v[132:135]
	v_mfma_f32_16x16x32_bf16 v[124:127], v[68:71], v[228:231], v[124:127]
	v_mfma_f32_16x16x32_bf16 v[120:123], v[76:79], v[228:231], v[120:123]
	s_setprio 0
	s_setprio 1
	v_mfma_f32_16x16x32_bf16 v[96:99], v[88:91], v[136:139], v[96:99]
	v_mfma_f32_16x16x32_bf16 v[152:155], v[80:83], v[136:139], v[168:171]
	v_mfma_f32_16x16x32_bf16 v[160:163], v[92:95], v[144:147], v[96:99]
	v_mfma_f32_16x16x32_bf16 v[96:99], v[80:83], v[176:179], v[100:103]
	v_mfma_f32_16x16x32_bf16 v[168:171], v[84:87], v[144:147], v[152:155]
	v_mfma_f32_16x16x32_bf16 v[152:155], v[84:87], v[212:215], v[96:99]
	v_mfma_f32_16x16x32_bf16 v[96:99], v[88:91], v[176:179], v[104:107]
	v_mfma_f32_16x16x32_bf16 v[144:147], v[92:95], v[212:215], v[96:99]
	v_mfma_f32_16x16x32_bf16 v[96:99], v[80:83], v[216:219], v[108:111]
	v_mfma_f32_16x16x32_bf16 v[136:139], v[84:87], v[220:223], v[96:99]
	v_mfma_f32_16x16x32_bf16 v[96:99], v[88:91], v[216:219], v[128:131]
	v_mfma_f32_16x16x32_bf16 v[128:131], v[92:95], v[220:223], v[96:99]
	v_mfma_f32_16x16x32_bf16 v[96:99], v[80:83], v[224:227], v[116:119]
	v_mfma_f32_16x16x32_bf16 v[116:119], v[84:87], v[228:231], v[96:99]
	v_mfma_f32_16x16x32_bf16 v[96:99], v[88:91], v[224:227], v[112:115]
	v_mfma_f32_16x16x32_bf16 v[112:115], v[92:95], v[228:231], v[96:99]
	s_setprio 0
	s_barrier
; #define PG8_STAGE(bufoff, gbase, voff) do { _Pragma("unroll") for (int _i = 0; _i < 2; ++_i) \
;         __builtin_amdgcn_global_load_lds((const unsigned*)((const char*)(gbase) + (voff)[_i]), (PG8_LAS unsigned*)(lds + (bufoff) + ldsw + _i * 8192), 16, 0, 0); } while (0)
; #define PG8_LDA(dst, b, h) do { _Pragma("unroll") for (int m = 0; m < 4; ++m) _Pragma("unroll") for (int k = 0; k < 2; ++k) dst[m][k] = *(const PG8_LAS bf16x8*)(lds + PG8_SA(b, h) + aoff + m * 2048 + k * 1024); } while (0)
; #define PG8_MMA(ai, bj, At, Bt) do { __builtin_amdgcn_s_setprio(1); _Pragma("unroll") for (int m = 0; m < 4; ++m) _Pragma("unroll") for (int n = 0; n < 2; ++n) _Pragma("unroll") for (int k = 0; k < 2; ++k) \
;         acc[ai][bj][m][n] = __builtin_amdgcn_mfma_f32_16x16x32_bf16(Bt[n][k], At[m][k], acc[ai][bj][m][n], 0, 0, 0); __builtin_amdgcn_s_setprio(0); } while (0)
; #define PG8_WAIT_V(n) asm volatile("s_waitcnt vmcnt(" #n ")" ::: "memory")
; #define PG8_WAIT_L(n) asm volatile("s_waitcnt lgkmcnt(" #n ")" ::: "memory")
; #define PG8_BAR __builtin_amdgcn_s_barrier()
; #define PG8_SCHED __builtin_amdgcn_sched_barrier(0)
; template <class Epi, class Sched, bool ALIGN_EPI = false, bool SP2 = false>
; __device__ __forceinline__ void gemm_phase(PG8_LAS unsigned char* lds, const Gemm g, const Sched& S, const Epi& E, const int wave_in) {
;     ...
;         for (int t = 0; t < nt; t += 2) {
;             const bool last = (t == nt - 2);
;     ...
;             PG8_LDA(At, 1, 1); PG8_STAGE(PG8_SB(1, 0), b3, voffB); PG8_STAGE(PG8_SB(1, 1), b3 + hstepB, voffB); PG8_STAGE(PG8_SA(1, 0), a3, voffA);
;             PG8_WAIT_V(8); PG8_WAIT_L(0); PG8_BAR; PG8_MMA(1, 0, At, B0); PG8_MMA(1, 1, At, B1); PG8_BAR; PG8_SCHED;
	s_add_i32 s50, s76, s56
	v_lshl_add_u64 v[224:225], v[232:233], 0, s[20:21]
	s_mov_b32 m0, s50
	s_nop 1
	ds_read_b128 v[96:99], v199 offset:49152
	ds_read_b128 v[100:103], v199 offset:50176
	ds_read_b128 v[104:107], v199 offset:51200
	ds_read_b128 v[108:111], v199 offset:52224
	ds_read_b128 v[176:179], v199 offset:53248
	ds_read_b128 v[212:215], v199 offset:54272
	ds_read_b128 v[216:219], v199 offset:55296
	ds_read_b128 v[220:223], v199 offset:56320
	global_load_lds_dwordx4 v[224:225], off
	s_add_i32 m0, s50, 0x2000
	s_add_u32 s48, s48, 0x80080
	v_lshl_add_u64 v[224:225], v[234:235], 0, s[20:21]
	s_addc_u32 s49, s49, 0
	s_add_i32 s50, s77, s56
	global_load_lds_dwordx4 v[224:225], off
	v_lshl_add_u64 v[224:225], s[48:49], 0, v[182:183]
	s_mov_b32 m0, s50
	s_nop 0
	global_load_lds_dwordx4 v[224:225], off
	v_lshl_add_u64 v[224:225], s[48:49], 0, v[186:187]
	s_add_i32 m0, s50, 0x2000
	s_nop 0
	global_load_lds_dwordx4 v[224:225], off
	v_lshl_add_u64 v[224:225], v[236:237], 0, s[20:21]
	s_mov_b32 m0, s63
	s_nop 0
	global_load_lds_dwordx4 v[224:225], off
	v_lshl_add_u64 v[224:225], v[238:239], 0, s[20:21]
	s_mov_b32 m0, s64
	s_nop 0
	global_load_lds_dwordx4 v[224:225], off
	s_waitcnt vmcnt(8)
	s_waitcnt lgkmcnt(0)
	s_barrier
	s_setprio 1
	s_waitcnt lgkmcnt(0)
	v_mfma_f32_16x16x32_bf16 v[60:63], v[64:67], v[96:99], v[60:63]
	v_mfma_f32_16x16x32_bf16 v[52:55], v[72:75], v[96:99], v[52:55]
	v_mfma_f32_16x16x32_bf16 v[44:47], v[64:67], v[104:107], v[44:47]
	v_mfma_f32_16x16x32_bf16 v[36:39], v[72:75], v[104:107], v[36:39]
	v_mfma_f32_16x16x32_bf16 v[28:31], v[64:67], v[176:179], v[28:31]
	v_mfma_f32_16x16x32_bf16 v[20:23], v[72:75], v[176:179], v[20:23]
	v_mfma_f32_16x16x32_bf16 v[12:15], v[64:67], v[216:219], v[12:15]
	v_mfma_f32_16x16x32_bf16 v[8:11], v[72:75], v[216:219], v[8:11]
	v_mfma_f32_16x16x32_bf16 v[60:63], v[68:71], v[100:103], v[60:63]
	v_mfma_f32_16x16x32_bf16 v[52:55], v[76:79], v[100:103], v[52:55]
	v_mfma_f32_16x16x32_bf16 v[44:47], v[68:71], v[108:111], v[44:47]
	v_mfma_f32_16x16x32_bf16 v[36:39], v[76:79], v[108:111], v[36:39]
	v_mfma_f32_16x16x32_bf16 v[28:31], v[68:71], v[212:215], v[28:31]
	v_mfma_f32_16x16x32_bf16 v[20:23], v[76:79], v[212:215], v[20:23]
	v_mfma_f32_16x16x32_bf16 v[12:15], v[68:71], v[220:223], v[12:15]
	v_mfma_f32_16x16x32_bf16 v[8:11], v[76:79], v[220:223], v[8:11]
	s_setprio 0
	s_setprio 1
	v_mfma_f32_16x16x32_bf16 v[56:59], v[80:83], v[96:99], v[56:59]
	v_mfma_f32_16x16x32_bf16 v[48:51], v[88:91], v[96:99], v[48:51]
	v_mfma_f32_16x16x32_bf16 v[40:43], v[80:83], v[104:107], v[40:43]
	v_mfma_f32_16x16x32_bf16 v[32:35], v[88:91], v[104:107], v[32:35]
	v_mfma_f32_16x16x32_bf16 v[24:27], v[80:83], v[176:179], v[24:27]
	v_mfma_f32_16x16x32_bf16 v[16:19], v[88:91], v[176:179], v[16:19]
	v_mfma_f32_16x16x32_bf16 v[4:7], v[80:83], v[216:219], v[4:7]
	v_mfma_f32_16x16x32_bf16 v[0:3], v[88:91], v[216:219], v[0:3]
	v_mfma_f32_16x16x32_bf16 v[56:59], v[84:87], v[100:103], v[56:59]
	v_mfma_f32_16x16x32_bf16 v[48:51], v[92:95], v[100:103], v[48:51]
	v_mfma_f32_16x16x32_bf16 v[40:43], v[84:87], v[108:111], v[40:43]
	v_mfma_f32_16x16x32_bf16 v[32:35], v[92:95], v[108:111], v[32:35]
	v_mfma_f32_16x16x32_bf16 v[24:27], v[84:87], v[212:215], v[24:27]
	v_mfma_f32_16x16x32_bf16 v[16:19], v[92:95], v[212:215], v[16:19]
	v_mfma_f32_16x16x32_bf16 v[4:7], v[84:87], v[220:223], v[4:7]
	v_mfma_f32_16x16x32_bf16 v[0:3], v[92:95], v[220:223], v[0:3]
	s_setprio 0
	s_barrier
	s_add_i32 s75, s75, 2
	s_add_u32 s46, s46, 0x100
	s_addc_u32 s47, s47, 0
	s_add_u32 s72, s72, 0x100
	s_addc_u32 s73, s73, 0
	s_cmp_gt_u32 s75, 29
	s_cbranch_scc0 .LBB0_2577
	s_branch .Lkx_30

; #define PG8_BAR __builtin_amdgcn_s_barrier()
; template <class Epi, class Sched, bool ALIGN_EPI = false, bool SP2 = false>
; __device__ __forceinline__ void gemm_phase(PG8_LAS unsigned char* lds, const Gemm g, const Sched& S, const Epi& E, const int wave_in) {
;     ...
;         if constexpr (ALIGN_EPI) { if (wr == 0) PG8_BAR; }
.Lkx_30:
	s_and_b64 vcc, exec, s[22:23]
	s_cbranch_vccz .LBB0_2580
	s_barrier

; #define PG8_STAGE(bufoff, gbase, voff) do { _Pragma("unroll") for (int _i = 0; _i < 2; ++_i) \
;         __builtin_amdgcn_global_load_lds((const unsigned*)((const char*)(gbase) + (voff)[_i]), (PG8_LAS unsigned*)(lds + (bufoff) + ldsw + _i * 8192), 16, 0, 0); } while (0)
; #define PG8_LDA(dst, b, h) do { _Pragma("unroll") for (int m = 0; m < 4; ++m) _Pragma("unroll") for (int k = 0; k < 2; ++k) dst[m][k] = *(const PG8_LAS bf16x8*)(lds + PG8_SA(b, h) + aoff + m * 2048 + k * 1024); } while (0)
; #define PG8_LDB(dst, b, h) do { _Pragma("unroll") for (int n = 0; n < 2; ++n) _Pragma("unroll") for (int k = 0; k < 2; ++k) dst[n][k] = *(const PG8_LAS bf16x8*)(lds + PG8_SB(b, h) + boff + n * 2048 + k * 1024); } while (0)
; #define PG8_MMA(ai, bj, At, Bt) do { __builtin_amdgcn_s_setprio(1); _Pragma("unroll") for (int m = 0; m < 4; ++m) _Pragma("unroll") for (int n = 0; n < 2; ++n) _Pragma("unroll") for (int k = 0; k < 2; ++k) \
;         acc[ai][bj][m][n] = __builtin_amdgcn_mfma_f32_16x16x32_bf16(Bt[n][k], At[m][k], acc[ai][bj][m][n], 0, 0, 0); __builtin_amdgcn_s_setprio(0); } while (0)
; #define PG8_WAIT_V(n) asm volatile("s_waitcnt vmcnt(" #n ")" ::: "memory")
; #define PG8_WAIT_L(n) asm volatile("s_waitcnt lgkmcnt(" #n ")" ::: "memory")
; #define PG8_BAR __builtin_amdgcn_s_barrier()
; #define PG8_SCHED __builtin_amdgcn_sched_barrier(0)
; template <class Epi, class Sched, bool ALIGN_EPI = false, bool SP2 = false>
; __device__ __forceinline__ void gemm_phase(PG8_LAS unsigned char* lds, const Gemm g, const Sched& S, const Epi& E, const int wave_in) {
;     ...
;             if constexpr (SP2) {
;             PG8_LDB(B0, 0, 0); PG8_LDB(B1, 0, 1); PG8_SCHED; PG8_LDA(At, 0, 0); PG8_STAGE(PG8_SA(1, 1), a1 + hstepA, voffA);
;             PG8_WAIT_V(8); PG8_WAIT_L(0); PG8_BAR; PG8_MMA(0, 0, At, B0); PG8_MMA(0, 1, At, B1); PG8_BAR; PG8_SCHED;
;             PG8_LDA(At, 0, 1); PG8_STAGE(PG8_SB(0, 0), b2, voffB); PG8_STAGE(PG8_SB(0, 1), b2 + hstepB, voffB); PG8_STAGE(PG8_SA(0, 0), a2, voffA);
;     ...
; #pragma unroll
;         for (int a = 0; a < 2; ++a)
; #pragma unroll
;             for (int b = 0; b < 2; ++b)
; #pragma unroll
;                 for (int m = 0; m < 4; ++m)
; #pragma unroll
;                     for (int n = 0; n < 2; ++n) acc[a][b][m][n] = (f32x4){0.f, 0.f, 0.f, 0.f};
.LBB0_2740:
	s_add_u32 s25, s28, 0x100
	v_mov_b32_e32 v0, 0
	s_addc_u32 s65, s29, 0
	s_mov_b32 s66, -2
	s_waitcnt vmcnt(0)
	ds_read_b128 v[128:131], v170
	ds_read_b128 v[132:135], v170 offset:1024
	ds_read_b128 v[136:139], v170 offset:2048
	ds_read_b128 v[140:143], v170 offset:3072
	ds_read_b128 v[162:165], v171
	ds_read_b128 v[174:177], v171 offset:1024
	ds_read_b128 v[178:181], v171 offset:2048
	ds_read_b128 v[182:185], v171 offset:3072
	s_add_u32 s2, s26, 0x100
	s_addc_u32 s3, s27, 0
	s_cmpk_eq_i32 s66, 0x52
	s_cselect_b32 s31, s21, s3
	s_cselect_b32 s30, s20, s2
	s_cselect_b32 s29, s23, s65
	s_cselect_b32 s28, s22, s25
	v_lshl_add_u64 v[166:167], s[26:27], 0, v[154:155]
	s_add_i32 m0, s40, 0xc000
	ds_read_b128 v[186:189], v172
	ds_read_b128 v[190:193], v172 offset:1024
	ds_read_b128 v[194:197], v172 offset:2048
	ds_read_b128 v[198:201], v172 offset:3072
	ds_read_b128 v[202:205], v172 offset:4096
	ds_read_b128 v[206:209], v172 offset:5120
	ds_read_b128 v[210:213], v172 offset:6144
	ds_read_b128 v[214:217], v172 offset:7168
	global_load_lds_dwordx4 v[166:167], off
	v_lshl_add_u64 v[166:167], s[26:27], 0, v[156:157]
	s_add_i32 m0, s40, 0xe000
	s_nop 0
	global_load_lds_dwordx4 v[166:167], off
	s_waitcnt vmcnt(8)
	s_waitcnt lgkmcnt(0)
	s_barrier
	s_setprio 1
	s_waitcnt lgkmcnt(0)
	v_mfma_f32_16x16x32_bf16 v[124:127], v[128:131], v[186:189], 0
	v_mfma_f32_16x16x32_bf16 v[120:123], v[136:139], v[186:189], 0
	v_mfma_f32_16x16x32_bf16 v[104:107], v[128:131], v[194:197], 0
	v_mfma_f32_16x16x32_bf16 v[108:111], v[136:139], v[194:197], 0
	v_mfma_f32_16x16x32_bf16 v[88:91], v[128:131], v[202:205], 0
	v_mfma_f32_16x16x32_bf16 v[92:95], v[136:139], v[202:205], 0
	v_mfma_f32_16x16x32_bf16 v[72:75], v[128:131], v[210:213], 0
	v_mfma_f32_16x16x32_bf16 v[76:79], v[136:139], v[210:213], 0
	v_mfma_f32_16x16x32_bf16 v[124:127], v[132:135], v[190:193], v[124:127]
	v_mfma_f32_16x16x32_bf16 v[120:123], v[140:143], v[190:193], v[120:123]
	v_mfma_f32_16x16x32_bf16 v[104:107], v[132:135], v[198:201], v[104:107]
	v_mfma_f32_16x16x32_bf16 v[108:111], v[140:143], v[198:201], v[108:111]
	v_mfma_f32_16x16x32_bf16 v[88:91], v[132:135], v[206:209], v[88:91]
	v_mfma_f32_16x16x32_bf16 v[92:95], v[140:143], v[206:209], v[92:95]
	v_mfma_f32_16x16x32_bf16 v[72:75], v[132:135], v[214:217], v[72:75]
	v_mfma_f32_16x16x32_bf16 v[76:79], v[140:143], v[214:217], v[76:79]
	s_setprio 0
	s_setprio 1
	v_mfma_f32_16x16x32_bf16 v[112:115], v[162:165], v[186:189], 0
	v_mfma_f32_16x16x32_bf16 v[116:119], v[178:181], v[186:189], 0
	v_mfma_f32_16x16x32_bf16 v[96:99], v[162:165], v[194:197], 0
	v_mfma_f32_16x16x32_bf16 v[100:103], v[178:181], v[194:197], 0
	v_mfma_f32_16x16x32_bf16 v[80:83], v[162:165], v[202:205], 0
	v_mfma_f32_16x16x32_bf16 v[84:87], v[178:181], v[202:205], 0
	v_mfma_f32_16x16x32_bf16 v[64:67], v[162:165], v[210:213], 0
	v_mfma_f32_16x16x32_bf16 v[68:71], v[178:181], v[210:213], 0
	v_mfma_f32_16x16x32_bf16 v[112:115], v[174:177], v[190:193], v[112:115]
	v_mfma_f32_16x16x32_bf16 v[116:119], v[182:185], v[190:193], v[116:119]
	v_mfma_f32_16x16x32_bf16 v[96:99], v[174:177], v[198:201], v[96:99]
	v_mfma_f32_16x16x32_bf16 v[100:103], v[182:185], v[198:201], v[100:103]
	v_mfma_f32_16x16x32_bf16 v[80:83], v[174:177], v[206:209], v[80:83]
	v_mfma_f32_16x16x32_bf16 v[84:87], v[182:185], v[206:209], v[84:87]
	v_mfma_f32_16x16x32_bf16 v[64:67], v[174:177], v[214:217], v[64:67]
	v_mfma_f32_16x16x32_bf16 v[68:71], v[182:185], v[214:217], v[68:71]
	s_setprio 0
	s_barrier
	s_add_i32 s26, s50, s39
	v_lshl_add_u64 v[166:167], s[28:29], 0, v[146:147]
	s_mov_b32 m0, s26
	ds_read_b128 v[186:189], v172 offset:16384
	ds_read_b128 v[190:193], v172 offset:17408
	ds_read_b128 v[194:197], v172 offset:18432
	ds_read_b128 v[198:201], v172 offset:19456
	ds_read_b128 v[202:205], v172 offset:20480
	ds_read_b128 v[206:209], v172 offset:21504
	ds_read_b128 v[210:213], v172 offset:22528
	ds_read_b128 v[214:217], v172 offset:23552
	global_load_lds_dwordx4 v[166:167], off
	s_add_i32 m0, s26, 0x2000
	s_add_u32 s26, s28, 0x158000
	v_lshl_add_u64 v[218:219], s[28:29], 0, v[150:151]
	s_addc_u32 s27, s29, 0
	s_add_i32 s67, s51, s39
	global_load_lds_dwordx4 v[218:219], off
	v_lshl_add_u64 v[220:221], s[26:27], 0, v[146:147]
	s_mov_b32 m0, s67
	v_lshl_add_u64 v[222:223], s[30:31], 0, v[148:149]
	global_load_lds_dwordx4 v[220:221], off
	v_lshl_add_u64 v[220:221], s[26:27], 0, v[150:151]
	s_add_i32 m0, s67, 0x2000
	s_nop 0
	global_load_lds_dwordx4 v[220:221], off
	v_lshl_add_u64 v[220:221], s[30:31], 0, v[144:145]
	s_mov_b32 m0, s40
	s_nop 0
	global_load_lds_dwordx4 v[220:221], off
	s_mov_b32 m0, s41
	s_nop 0
	global_load_lds_dwordx4 v[222:223], off
	s_waitcnt vmcnt(8)
	s_waitcnt lgkmcnt(0)
	s_barrier
; #define PG8_STAGE(bufoff, gbase, voff) do { _Pragma("unroll") for (int _i = 0; _i < 2; ++_i) \
;         __builtin_amdgcn_global_load_lds((const unsigned*)((const char*)(gbase) + (voff)[_i]), (PG8_LAS unsigned*)(lds + (bufoff) + ldsw + _i * 8192), 16, 0, 0); } while (0)
; #define PG8_LDA(dst, b, h) do { _Pragma("unroll") for (int m = 0; m < 4; ++m) _Pragma("unroll") for (int k = 0; k < 2; ++k) dst[m][k] = *(const PG8_LAS bf16x8*)(lds + PG8_SA(b, h) + aoff + m * 2048 + k * 1024); } while (0)
; #define PG8_LDB(dst, b, h) do { _Pragma("unroll") for (int n = 0; n < 2; ++n) _Pragma("unroll") for (int k = 0; k < 2; ++k) dst[n][k] = *(const PG8_LAS bf16x8*)(lds + PG8_SB(b, h) + boff + n * 2048 + k * 1024); } while (0)
; #define PG8_MMA(ai, bj, At, Bt) do { __builtin_amdgcn_s_setprio(1); _Pragma("unroll") for (int m = 0; m < 4; ++m) _Pragma("unroll") for (int n = 0; n < 2; ++n) _Pragma("unroll") for (int k = 0; k < 2; ++k) \
;         acc[ai][bj][m][n] = __builtin_amdgcn_mfma_f32_16x16x32_bf16(Bt[n][k], At[m][k], acc[ai][bj][m][n], 0, 0, 0); __builtin_amdgcn_s_setprio(0); } while (0)
; #define PG8_WAIT_V(n) asm volatile("s_waitcnt vmcnt(" #n ")" ::: "memory")
; #define PG8_WAIT_L(n) asm volatile("s_waitcnt lgkmcnt(" #n ")" ::: "memory")
; #define PG8_BAR __builtin_amdgcn_s_barrier()
; #define PG8_SCHED __builtin_amdgcn_sched_barrier(0)
; template <class Epi, class Sched, bool ALIGN_EPI = false, bool SP2 = false>
; __device__ __forceinline__ void gemm_phase(PG8_LAS unsigned char* lds, const Gemm g, const Sched& S, const Epi& E, const int wave_in) {
;     ...
;             PG8_WAIT_V(8); PG8_WAIT_L(0); PG8_BAR; PG8_MMA(1, 0, At, B0); PG8_MMA(1, 1, At, B1); PG8_BAR; PG8_SCHED;
;             PG8_LDB(B0, 1, 0); PG8_LDB(B1, 1, 1); PG8_SCHED; PG8_LDA(At, 1, 0); PG8_STAGE(PG8_SA(0, 1), a2 + hstepA, voffA);
;             PG8_WAIT_V(8); PG8_WAIT_L(0); PG8_BAR; PG8_MMA(0, 0, At, B0); PG8_MMA(0, 1, At, B1); PG8_BAR; PG8_SCHED;
	s_setprio 1
	s_waitcnt lgkmcnt(0)
	v_mfma_f32_16x16x32_bf16 v[60:63], v[128:131], v[186:189], 0
	v_mfma_f32_16x16x32_bf16 v[56:59], v[136:139], v[186:189], 0
	v_mfma_f32_16x16x32_bf16 v[40:43], v[128:131], v[194:197], 0
	v_mfma_f32_16x16x32_bf16 v[48:51], v[136:139], v[194:197], 0
	v_mfma_f32_16x16x32_bf16 v[24:27], v[128:131], v[202:205], 0
	v_mfma_f32_16x16x32_bf16 v[32:35], v[136:139], v[202:205], 0
	v_mfma_f32_16x16x32_bf16 v[8:11], v[128:131], v[210:213], 0
	v_mfma_f32_16x16x32_bf16 v[16:19], v[136:139], v[210:213], 0
	v_mfma_f32_16x16x32_bf16 v[60:63], v[132:135], v[190:193], v[60:63]
	v_mfma_f32_16x16x32_bf16 v[56:59], v[140:143], v[190:193], v[56:59]
	v_mfma_f32_16x16x32_bf16 v[40:43], v[132:135], v[198:201], v[40:43]
	v_mfma_f32_16x16x32_bf16 v[48:51], v[140:143], v[198:201], v[48:51]
	v_mfma_f32_16x16x32_bf16 v[24:27], v[132:135], v[206:209], v[24:27]
	v_mfma_f32_16x16x32_bf16 v[32:35], v[140:143], v[206:209], v[32:35]
	v_mfma_f32_16x16x32_bf16 v[8:11], v[132:135], v[214:217], v[8:11]
	v_mfma_f32_16x16x32_bf16 v[16:19], v[140:143], v[214:217], v[16:19]
	s_setprio 0
	s_setprio 1
	v_mfma_f32_16x16x32_bf16 v[44:47], v[162:165], v[186:189], 0
	v_mfma_f32_16x16x32_bf16 v[52:55], v[178:181], v[186:189], 0
	v_mfma_f32_16x16x32_bf16 v[28:31], v[162:165], v[194:197], 0
	v_mfma_f32_16x16x32_bf16 v[36:39], v[178:181], v[194:197], 0
	v_mfma_f32_16x16x32_bf16 v[12:15], v[162:165], v[202:205], 0
	v_mfma_f32_16x16x32_bf16 v[20:23], v[178:181], v[202:205], 0
	v_mfma_f32_16x16x32_bf16 v[4:7], v[162:165], v[210:213], 0
	v_mfma_f32_16x16x32_bf16 v[0:3], v[178:181], v[210:213], 0
	v_mfma_f32_16x16x32_bf16 v[44:47], v[174:177], v[190:193], v[44:47]
	v_mfma_f32_16x16x32_bf16 v[52:55], v[182:185], v[190:193], v[52:55]
	v_mfma_f32_16x16x32_bf16 v[28:31], v[174:177], v[198:201], v[28:31]
	v_mfma_f32_16x16x32_bf16 v[36:39], v[182:185], v[198:201], v[36:39]
	v_mfma_f32_16x16x32_bf16 v[12:15], v[174:177], v[206:209], v[12:15]
	v_mfma_f32_16x16x32_bf16 v[20:23], v[182:185], v[206:209], v[20:23]
	v_mfma_f32_16x16x32_bf16 v[4:7], v[174:177], v[214:217], v[4:7]
	v_mfma_f32_16x16x32_bf16 v[0:3], v[182:185], v[214:217], v[0:3]
	s_setprio 0
	s_barrier
	s_add_i32 s67, 0, 0x18000
	s_add_i32 s68, 0, 0x1c000
	v_add_u32_e32 v140, s67, v168
	v_add_u32_e32 v173, s68, v168
	ds_read_b128 v[128:131], v140
	ds_read_b128 v[132:135], v140 offset:1024
	ds_read_b128 v[136:139], v140 offset:2048
	ds_read_b128 v[140:143], v140 offset:3072
	ds_read_b128 v[162:165], v173
	ds_read_b128 v[174:177], v173 offset:1024
	ds_read_b128 v[178:181], v173 offset:2048
	ds_read_b128 v[182:185], v173 offset:3072
	s_add_u32 s26, s30, 0x158000
	s_addc_u32 s27, s31, 0
	s_mov_b32 m0, s42
	v_lshl_add_u64 v[224:225], s[26:27], 0, v[144:145]
	ds_read_b128 v[186:189], v172 offset:32768
	ds_read_b128 v[190:193], v172 offset:33792
	ds_read_b128 v[194:197], v172 offset:34816
	ds_read_b128 v[198:201], v172 offset:35840
	ds_read_b128 v[202:205], v172 offset:36864
	ds_read_b128 v[206:209], v172 offset:37888
	ds_read_b128 v[210:213], v172 offset:38912
	ds_read_b128 v[214:217], v172 offset:39936
	global_load_lds_dwordx4 v[224:225], off
	v_lshl_add_u64 v[224:225], s[26:27], 0, v[148:149]
	s_mov_b32 m0, s43
	s_nop 0
	global_load_lds_dwordx4 v[224:225], off
	s_waitcnt vmcnt(8)
	s_waitcnt lgkmcnt(0)
	s_barrier
	s_setprio 1
	s_waitcnt lgkmcnt(0)
	v_mfma_f32_16x16x32_bf16 v[124:127], v[128:131], v[186:189], v[124:127]
	v_mfma_f32_16x16x32_bf16 v[120:123], v[136:139], v[186:189], v[120:123]
	v_mfma_f32_16x16x32_bf16 v[104:107], v[128:131], v[194:197], v[104:107]
	v_mfma_f32_16x16x32_bf16 v[108:111], v[136:139], v[194:197], v[108:111]
	v_mfma_f32_16x16x32_bf16 v[88:91], v[128:131], v[202:205], v[88:91]
	v_mfma_f32_16x16x32_bf16 v[92:95], v[136:139], v[202:205], v[92:95]
	v_mfma_f32_16x16x32_bf16 v[72:75], v[128:131], v[210:213], v[72:75]
	v_mfma_f32_16x16x32_bf16 v[76:79], v[136:139], v[210:213], v[76:79]
	v_mfma_f32_16x16x32_bf16 v[124:127], v[132:135], v[190:193], v[124:127]
	v_mfma_f32_16x16x32_bf16 v[120:123], v[140:143], v[190:193], v[120:123]
	v_mfma_f32_16x16x32_bf16 v[104:107], v[132:135], v[198:201], v[104:107]
	v_mfma_f32_16x16x32_bf16 v[108:111], v[140:143], v[198:201], v[108:111]
	v_mfma_f32_16x16x32_bf16 v[88:91], v[132:135], v[206:209], v[88:91]
	v_mfma_f32_16x16x32_bf16 v[92:95], v[140:143], v[206:209], v[92:95]
	v_mfma_f32_16x16x32_bf16 v[72:75], v[132:135], v[214:217], v[72:75]
	v_mfma_f32_16x16x32_bf16 v[76:79], v[140:143], v[214:217], v[76:79]
	s_setprio 0
	s_setprio 1
	v_mfma_f32_16x16x32_bf16 v[112:115], v[162:165], v[186:189], v[112:115]
	v_mfma_f32_16x16x32_bf16 v[116:119], v[178:181], v[186:189], v[116:119]
	v_mfma_f32_16x16x32_bf16 v[96:99], v[162:165], v[194:197], v[96:99]
	v_mfma_f32_16x16x32_bf16 v[100:103], v[178:181], v[194:197], v[100:103]
	v_mfma_f32_16x16x32_bf16 v[80:83], v[162:165], v[202:205], v[80:83]
	v_mfma_f32_16x16x32_bf16 v[84:87], v[178:181], v[202:205], v[84:87]
	v_mfma_f32_16x16x32_bf16 v[64:67], v[162:165], v[210:213], v[64:67]
	v_mfma_f32_16x16x32_bf16 v[68:71], v[178:181], v[210:213], v[68:71]
	v_mfma_f32_16x16x32_bf16 v[112:115], v[174:177], v[190:193], v[112:115]
	v_mfma_f32_16x16x32_bf16 v[116:119], v[182:185], v[190:193], v[116:119]
	v_mfma_f32_16x16x32_bf16 v[96:99], v[174:177], v[198:201], v[96:99]
	v_mfma_f32_16x16x32_bf16 v[100:103], v[182:185], v[198:201], v[100:103]
	v_mfma_f32_16x16x32_bf16 v[80:83], v[174:177], v[206:209], v[80:83]
	v_mfma_f32_16x16x32_bf16 v[84:87], v[182:185], v[206:209], v[84:87]
	v_mfma_f32_16x16x32_bf16 v[64:67], v[174:177], v[214:217], v[64:67]
	v_mfma_f32_16x16x32_bf16 v[68:71], v[182:185], v[214:217], v[68:71]
	s_setprio 0
	s_barrier
; #define PG8_STAGE(bufoff, gbase, voff) do { _Pragma("unroll") for (int _i = 0; _i < 2; ++_i) \
;         __builtin_amdgcn_global_load_lds((const unsigned*)((const char*)(gbase) + (voff)[_i]), (PG8_LAS unsigned*)(lds + (bufoff) + ldsw + _i * 8192), 16, 0, 0); } while (0)
; #define PG8_LDA(dst, b, h) do { _Pragma("unroll") for (int m = 0; m < 4; ++m) _Pragma("unroll") for (int k = 0; k < 2; ++k) dst[m][k] = *(const PG8_LAS bf16x8*)(lds + PG8_SA(b, h) + aoff + m * 2048 + k * 1024); } while (0)
; #define PG8_MMA(ai, bj, At, Bt) do { __builtin_amdgcn_s_setprio(1); _Pragma("unroll") for (int m = 0; m < 4; ++m) _Pragma("unroll") for (int n = 0; n < 2; ++n) _Pragma("unroll") for (int k = 0; k < 2; ++k) \
;         acc[ai][bj][m][n] = __builtin_amdgcn_mfma_f32_16x16x32_bf16(Bt[n][k], At[m][k], acc[ai][bj][m][n], 0, 0, 0); __builtin_amdgcn_s_setprio(0); } while (0)
; #define PG8_WAIT_V(n) asm volatile("s_waitcnt vmcnt(" #n ")" ::: "memory")
; #define PG8_WAIT_L(n) asm volatile("s_waitcnt lgkmcnt(" #n ")" ::: "memory")
; #define PG8_BAR __builtin_amdgcn_s_barrier()
; #define PG8_SCHED __builtin_amdgcn_sched_barrier(0)
; template <class Epi, class Sched, bool ALIGN_EPI = false, bool SP2 = false>
; __device__ __forceinline__ void gemm_phase(PG8_LAS unsigned char* lds, const Gemm g, const Sched& S, const Epi& E, const int wave_in) {
;     ...
;         for (int t = 0; t < nt; t += 2) {
;             const bool last = (t == nt - 2);
;     ...
;             PG8_LDA(At, 1, 1); PG8_STAGE(PG8_SB(1, 0), b3, voffB); PG8_STAGE(PG8_SB(1, 1), b3 + hstepB, voffB); PG8_STAGE(PG8_SA(1, 0), a3, voffA);
;             PG8_WAIT_V(8); PG8_WAIT_L(0); PG8_BAR; PG8_MMA(1, 0, At, B0); PG8_MMA(1, 1, At, B1); PG8_BAR; PG8_SCHED;
	s_add_i32 s26, s67, s39
	v_lshl_add_u64 v[166:167], v[166:167], 0, s[6:7]
	s_mov_b32 m0, s26
	ds_read_b128 v[186:189], v172 offset:49152
	ds_read_b128 v[190:193], v172 offset:50176
	ds_read_b128 v[194:197], v172 offset:51200
	ds_read_b128 v[198:201], v172 offset:52224
	ds_read_b128 v[202:205], v172 offset:53248
	ds_read_b128 v[206:209], v172 offset:54272
	ds_read_b128 v[210:213], v172 offset:55296
	ds_read_b128 v[214:217], v172 offset:56320
	global_load_lds_dwordx4 v[166:167], off
	s_add_i32 m0, s26, 0x2000
	s_add_u32 s26, s28, 0x158080
	v_lshl_add_u64 v[166:167], v[218:219], 0, s[6:7]
	s_addc_u32 s27, s29, 0
	s_add_i32 s28, s68, s39
	global_load_lds_dwordx4 v[166:167], off
	v_lshl_add_u64 v[166:167], s[26:27], 0, v[146:147]
	s_mov_b32 m0, s28
	s_nop 0
	global_load_lds_dwordx4 v[166:167], off
	v_lshl_add_u64 v[166:167], s[26:27], 0, v[150:151]
	s_add_i32 m0, s28, 0x2000
	s_nop 0
	global_load_lds_dwordx4 v[166:167], off
	v_lshl_add_u64 v[166:167], v[220:221], 0, s[6:7]
	s_mov_b32 m0, s48
	s_nop 0
	global_load_lds_dwordx4 v[166:167], off
	v_lshl_add_u64 v[166:167], v[222:223], 0, s[6:7]
	s_mov_b32 m0, s49
	s_nop 0
	global_load_lds_dwordx4 v[166:167], off
	s_waitcnt vmcnt(8)
	s_waitcnt lgkmcnt(0)
	s_barrier
	s_setprio 1
	s_waitcnt lgkmcnt(0)
	v_mfma_f32_16x16x32_bf16 v[60:63], v[128:131], v[186:189], v[60:63]
	v_mfma_f32_16x16x32_bf16 v[56:59], v[136:139], v[186:189], v[56:59]
	v_mfma_f32_16x16x32_bf16 v[40:43], v[128:131], v[194:197], v[40:43]
	v_mfma_f32_16x16x32_bf16 v[48:51], v[136:139], v[194:197], v[48:51]
	v_mfma_f32_16x16x32_bf16 v[24:27], v[128:131], v[202:205], v[24:27]
	v_mfma_f32_16x16x32_bf16 v[32:35], v[136:139], v[202:205], v[32:35]
	v_mfma_f32_16x16x32_bf16 v[8:11], v[128:131], v[210:213], v[8:11]
	v_mfma_f32_16x16x32_bf16 v[16:19], v[136:139], v[210:213], v[16:19]
	v_mfma_f32_16x16x32_bf16 v[60:63], v[132:135], v[190:193], v[60:63]
	v_mfma_f32_16x16x32_bf16 v[56:59], v[140:143], v[190:193], v[56:59]
	v_mfma_f32_16x16x32_bf16 v[40:43], v[132:135], v[198:201], v[40:43]
	v_mfma_f32_16x16x32_bf16 v[48:51], v[140:143], v[198:201], v[48:51]
	v_mfma_f32_16x16x32_bf16 v[24:27], v[132:135], v[206:209], v[24:27]
	v_mfma_f32_16x16x32_bf16 v[32:35], v[140:143], v[206:209], v[32:35]
	v_mfma_f32_16x16x32_bf16 v[8:11], v[132:135], v[214:217], v[8:11]
	v_mfma_f32_16x16x32_bf16 v[16:19], v[140:143], v[214:217], v[16:19]
	s_setprio 0
	s_setprio 1
	v_mfma_f32_16x16x32_bf16 v[44:47], v[162:165], v[186:189], v[44:47]
	v_mfma_f32_16x16x32_bf16 v[52:55], v[178:181], v[186:189], v[52:55]
	v_mfma_f32_16x16x32_bf16 v[28:31], v[162:165], v[194:197], v[28:31]
	v_mfma_f32_16x16x32_bf16 v[36:39], v[178:181], v[194:197], v[36:39]
	v_mfma_f32_16x16x32_bf16 v[12:15], v[162:165], v[202:205], v[12:15]
	v_mfma_f32_16x16x32_bf16 v[20:23], v[178:181], v[202:205], v[20:23]
	v_mfma_f32_16x16x32_bf16 v[4:7], v[162:165], v[210:213], v[4:7]
	v_mfma_f32_16x16x32_bf16 v[0:3], v[178:181], v[210:213], v[0:3]
	v_mfma_f32_16x16x32_bf16 v[44:47], v[174:177], v[190:193], v[44:47]
	v_mfma_f32_16x16x32_bf16 v[52:55], v[182:185], v[190:193], v[52:55]
	v_mfma_f32_16x16x32_bf16 v[28:31], v[174:177], v[198:201], v[28:31]
	v_mfma_f32_16x16x32_bf16 v[36:39], v[182:185], v[198:201], v[36:39]
	v_mfma_f32_16x16x32_bf16 v[12:15], v[174:177], v[206:209], v[12:15]
	v_mfma_f32_16x16x32_bf16 v[20:23], v[182:185], v[206:209], v[20:23]
	v_mfma_f32_16x16x32_bf16 v[4:7], v[174:177], v[214:217], v[4:7]
	v_mfma_f32_16x16x32_bf16 v[0:3], v[182:185], v[214:217], v[0:3]
	s_setprio 0
	s_barrier
	s_add_i32 s66, s66, 2
	s_add_u32 s25, s25, 0x100
	s_addc_u32 s65, s65, 0
	s_cmpk_gt_u32 s66, 0x53
	s_mov_b64 s[26:27], s[2:3]
	s_cbranch_scc0 .LBB0_2741
	s_branch .Lkx_32
